# attention v3 (mid-step barrier, cross-step LDS prefetch) + hand-written ConvFFN epilogues (both layers) + pipelined modnorm for layer-1 phases
# speedup vs baseline: 1.0793x; 1.0200x over previous
; #define LAS __attribute__((address_space(3)))
; #define ROR1(x) __int_as_float(__builtin_amdgcn_update_dpp(0, __float_as_int(x), 0x121, 0xf, 0xf, false))
;     DEV void operator()(const Acc& acc, const Unit& u, int wr, int wc, int fr, int fq, LAS unsigned char* misc) const {
;     ...
;         const int lane = fq * 16 + fr;
;         const int sbase = u.pm * 256, s0 = 0;
;         float* sbp = sb + (size_t)u.pm * 6 * DFF;
;         LAS float* xl = (LAS float*)misc;
;         LAS float* xf = xl + 512;
; #pragma unroll
;         for (int ai = 0; ai < 2; ++ai) { const int q = 2 * ai + wr;
; #pragma unroll
;             for (int n = 0; n < 2; ++n) { const int cc = wc * 32 + 8 * fq + 4 * n;
;                 if (fr == 15) *(LAS f32x4*)(xl + q * 128 + cc) = acc[ai][0][3][n];
;                 if (fr == 0) *(LAS f32x4*)(xf + q * 128 + cc) = acc[ai][0][0][n]; } }
;         asm volatile("s_waitcnt lgkmcnt(0)" ::: "memory"); __builtin_amdgcn_s_barrier(); asm volatile("" ::: "memory");
;     ...
; #pragma unroll
;         for (int n = 0; n < 2; ++n) { const int cc = wc * 32 + 8 * fq + 4 * n, j = u.pn * 128 + cc;
;             const f32x4 w0 = *(const f32x4*)(cw + j), w1 = *(const f32x4*)(cw + DFF + j), w2 = *(const f32x4*)(cw + 2 * DFF + j), bb = *(const f32x4*)(cb + j);
; #pragma unroll
;             for (int ai = 0; ai < 2; ++ai) { const int q = 2 * ai + wr;
;                 const f32x4 bup = (q > 0) ? *(LAS f32x4*)(xl + (q - 1) * 128 + cc) : (f32x4){0.f, 0.f, 0.f, 0.f};
;                 const f32x4 bdn = (q < 3) ? *(LAS f32x4*)(xf + (q + 1) * 128 + cc) : (f32x4){0.f, 0.f, 0.f, 0.f};
;                 f32x4 Rprev = bup, Dcur;
; #pragma unroll
;                 for (int e = 0; e < 4; ++e) Dcur[e] = ROR15(acc[ai][0][0][n][e]);
; #pragma unroll
;                 for (int m = 0; m < 4; ++m) {
;                     f32x4 Rm, Dnext = bdn;
; #pragma unroll
;                     for (int e = 0; e < 4; ++e) { Rm[e] = ROR1(acc[ai][0][m][n][e]); if (m < 3) Dnext[e] = ROR15(acc[ai][0][m < 3 ? m + 1 : 3][n][e]); }
;                     const f32x4 up = (fr > 0) ? Rm : Rprev;
;                     const f32x4 dn = (fr < 15) ? Dcur : Dnext;
;                     Rprev = Rm; Dcur = Dnext;
;                     const int rr = q * 64 + m * 16 + fr, sq = s0 + rr;
;                     const f32x4 g = acc[ai][0][m][n], v = acc[ai][1][m][n];
;                     f32x4 o;
; #pragma unroll
.LBB0_302:
	v_mbcnt_lo_u32_b32 v214, -1, 0
	v_mbcnt_hi_u32_b32 v214, -1, v214
	v_readlane_b32 s4, v251, 4
	v_and_b32_e32 v172, 15, v214
	v_lshrrev_b32_e32 v214, 4, v214
	s_lshr_b32 s4, s4, 6
	s_lshr_b32 s7, s4, 2
	s_and_b32 s4, s4, 3
	s_lshl_b32 s4, s4, 5
	v_lshl_add_u32 v214, v214, 3, s4
	s_lshl_b32 s5, s6, 7
	v_add_u32_e32 v173, s5, v214
	v_lshlrev_b32_e32 v173, 2, v173
	s_lshl_b32 s5, s7, 9
	s_add_u32 s5, s5, 0x1fe00
	v_lshl_add_u32 v176, v214, 2, s5
	v_cmp_eq_u32_e64 s[8:9], 0, v172
	v_cmp_eq_u32_e64 s[10:11], 15, v172
	s_add_u32 s20, s52, 0x2c00
	s_addc_u32 s21, s53, 0
	s_add_u32 s22, s52, 0x5800
	s_addc_u32 s23, s53, 0
	global_load_dwordx4 v[106:109], v173, s[52:53]
	global_load_dwordx4 v[110:113], v173, s[20:21]
	global_load_dwordx4 v[114:117], v173, s[22:23]
	global_load_dwordx4 v[118:121], v173, s[54:55]
	s_lshl_b32 s4, s14, 8
	s_lshl_b32 s5, s7, 6
	s_add_u32 s4, s4, s5
	v_add_u32_e32 v174, s4, v172
	v_mul_u32_u24_e32 v174, 0x1600, v174
	v_lshrrev_b32_e32 v215, 1, v173
	v_add_u32_e32 v174, v174, v215
	s_mul_i32 s4, s14, 0x10800
	s_add_u32 s24, s50, s4
	s_addc_u32 s25, s51, 0
	s_add_u32 s26, s24, 0xb000
	s_addc_u32 s27, s25, 0
	s_add_u32 s28, s24, 0x5800
	s_addc_u32 s29, s25, 0
	v_readlane_b32 s18, v250, 21
	v_readlane_b32 s19, v250, 22
	s_not_b64 s[12:13], s[8:9]
	s_not_b64 s[16:17], s[10:11]
	s_cmp_eq_u32 s7, 0
	s_cselect_b64 s[12:13], s[12:13], -1
	s_cmp_eq_u32 s7, 1
	s_cselect_b64 s[16:17], s[16:17], -1
	s_mov_b64 exec, s[10:11]
	ds_write_b128 v176, v[98:101] offset:512
	ds_write_b128 v176, v[34:37] offset:528
	ds_write_b128 v176, v[70:73] offset:1536
	ds_write_b128 v176, v[6:9] offset:1552
	s_mov_b64 exec, s[8:9]
	ds_write_b128 v176, v[138:141] offset:2560
	ds_write_b128 v176, v[58:61] offset:2576
	ds_write_b128 v176, v[94:97] offset:3584
	ds_write_b128 v176, v[30:33] offset:3600
	s_mov_b64 exec, -1
	s_waitcnt lgkmcnt(0)
	s_barrier
	s_cmp_eq_u32 s7, 0
	s_cbranch_scc1 .LffnA_bz_1
	ds_read_b128 v[146:149], v176 offset:0
	s_branch .LffnA_bj_2
.LffnA_bz_1:
	v_mov_b32_e32 v146, 0
	v_mov_b32_e32 v147, 0
	v_mov_b32_e32 v148, 0
	v_mov_b32_e32 v149, 0
.LffnA_bj_2:
	v_mov_b32_dpp v198, v138 row_ror:15 row_mask:0xf bank_mask:0xf
	v_mov_b32_dpp v199, v139 row_ror:15 row_mask:0xf bank_mask:0xf
	v_mov_b32_dpp v200, v140 row_ror:15 row_mask:0xf bank_mask:0xf
	v_mov_b32_dpp v201, v141 row_ror:15 row_mask:0xf bank_mask:0xf
	s_waitcnt vmcnt(0)
	s_cmp_eq_u32 s7, 0
	s_cbranch_scc0 .LffnA_ns_3
	v_mul_u32_u24_e32 v177, 0x2c00, v172
	v_cmp_gt_u32_e64 s[30:31], 2, v172
	v_add_u32_e32 v177, v177, v173
	s_nop 1
	s_mov_b64 exec, s[30:31]
	global_store_dwordx4 v177, v[138:141], s[24:25]
	s_mov_b64 exec, s[8:9]
	global_store_dwordx4 v177, v[142:145], s[26:27]
	s_mov_b64 exec, -1
	s_nop 4
.LffnA_ns_3:
	v_mov_b32_dpp v150, v138 row_ror:1 row_mask:0xf bank_mask:0xf
	v_mov_b32_dpp v151, v139 row_ror:1 row_mask:0xf bank_mask:0xf
	v_mov_b32_dpp v152, v140 row_ror:1 row_mask:0xf bank_mask:0xf
	v_mov_b32_dpp v153, v141 row_ror:1 row_mask:0xf bank_mask:0xf
	v_mov_b32_dpp v202, v134 row_ror:15 row_mask:0xf bank_mask:0xf
	v_mov_b32_dpp v203, v135 row_ror:15 row_mask:0xf bank_mask:0xf
	v_mov_b32_dpp v204, v136 row_ror:15 row_mask:0xf bank_mask:0xf
	v_mov_b32_dpp v205, v137 row_ror:15 row_mask:0xf bank_mask:0xf
	s_waitcnt lgkmcnt(0)
	v_cndmask_b32_e64 v206, v150, v146, s[8:9]
	v_cndmask_b32_e64 v207, v151, v147, s[8:9]
	v_cndmask_b32_e64 v208, v152, v148, s[8:9]
	v_cndmask_b32_e64 v209, v153, v149, s[8:9]
	ds_read_b128 v[146:149], v176 offset:3072
	v_cndmask_b32_e64 v210, v198, v202, s[10:11]
	v_cndmask_b32_e64 v211, v199, v203, s[10:11]
	v_cndmask_b32_e64 v212, v200, v204, s[10:11]
	v_cndmask_b32_e64 v213, v201, v205, s[10:11]
	v_mul_f32_e32 v138, v110, v138
	v_mul_f32_e32 v139, v111, v139
	v_mul_f32_e32 v140, v112, v140
	v_mul_f32_e32 v141, v113, v141
	v_mul_f32_e32 v210, v114, v210
	v_mul_f32_e32 v211, v115, v211
	v_mul_f32_e32 v212, v116, v212
	v_mul_f32_e32 v213, v117, v213
	v_fmac_f32_e32 v138, v106, v206
	v_fmac_f32_e32 v139, v107, v207
	v_fmac_f32_e32 v140, v108, v208
	v_fmac_f32_e32 v141, v109, v209
	v_add_f32_e32 v138, v210, v138
	v_add_f32_e32 v139, v211, v139
	v_add_f32_e32 v140, v212, v140
	v_add_f32_e32 v141, v213, v141
	v_add_f32_e32 v138, v118, v138
	v_add_f32_e32 v139, v119, v139
	v_add_f32_e32 v140, v120, v140
	v_add_f32_e32 v141, v121, v141
	v_mul_f32_e32 v206, 0xbfb8aa3b, v138
	v_mul_f32_e32 v207, 0xbfb8aa3b, v139
	v_mul_f32_e32 v208, 0xbfb8aa3b, v140
	v_mul_f32_e32 v209, 0xbfb8aa3b, v141
	v_exp_f32_e32 v206, v206
	v_exp_f32_e32 v207, v207
	v_exp_f32_e32 v208, v208
	v_exp_f32_e32 v209, v209
	v_add_f32_e32 v206, 1.0, v206
	v_add_f32_e32 v207, 1.0, v207
	v_add_f32_e32 v208, 1.0, v208
	v_add_f32_e32 v209, 1.0, v209
	v_rcp_f32_e32 v206, v206
	v_rcp_f32_e32 v207, v207
	v_rcp_f32_e32 v208, v208
	v_rcp_f32_e32 v209, v209
	v_mul_f32_e32 v138, v138, v206
	v_mul_f32_e32 v139, v139, v207
	v_mul_f32_e32 v140, v140, v208
	v_mul_f32_e32 v141, v141, v209
	v_mul_f32_e32 v138, v142, v138
	v_mul_f32_e32 v139, v143, v139
	v_mul_f32_e32 v140, v144, v140
	v_mul_f32_e32 v141, v145, v141
	v_cvt_pk_bf16_f32 v210, v138, v139
	v_cvt_pk_bf16_f32 v211, v140, v141
	v_add_u32_e32 v175, 0x0, v174
	s_mov_b64 exec, s[12:13]
	global_store_dwordx2 v175, v[210:211], s[18:19]
	s_mov_b64 exec, -1
	s_nop 4
	v_mov_b32_dpp v194, v134 row_ror:1 row_mask:0xf bank_mask:0xf
	v_mov_b32_dpp v195, v135 row_ror:1 row_mask:0xf bank_mask:0xf
	v_mov_b32_dpp v196, v136 row_ror:1 row_mask:0xf bank_mask:0xf
	v_mov_b32_dpp v197, v137 row_ror:1 row_mask:0xf bank_mask:0xf
	v_mov_b32_dpp v198, v126 row_ror:15 row_mask:0xf bank_mask:0xf
	v_mov_b32_dpp v199, v127 row_ror:15 row_mask:0xf bank_mask:0xf
; #define LAS __attribute__((address_space(3)))
; DEV unsigned cvt_pk_bf16(float lo, float hi) { unsigned r; asm volatile("v_cvt_pk_bf16_f32 %0, %1, %2" : "=v"(r) : "v"(lo), "v"(hi)); return r; }
;     DEV void operator()(const Acc& acc, const Unit& u, int wr, int wc, int fr, int fq, LAS unsigned char* misc) const {
;     ...
;         for (int n = 0; n < 2; ++n) { const int cc = wc * 32 + 8 * fq + 4 * n, j = u.pn * 128 + cc;
;             const f32x4 w0 = *(const f32x4*)(cw + j), w1 = *(const f32x4*)(cw + DFF + j), w2 = *(const f32x4*)(cw + 2 * DFF + j), bb = *(const f32x4*)(cb + j);
; #pragma unroll
;             for (int ai = 0; ai < 2; ++ai) { const int q = 2 * ai + wr;
;                 const f32x4 bup = (q > 0) ? *(LAS f32x4*)(xl + (q - 1) * 128 + cc) : (f32x4){0.f, 0.f, 0.f, 0.f};
;                 const f32x4 bdn = (q < 3) ? *(LAS f32x4*)(xf + (q + 1) * 128 + cc) : (f32x4){0.f, 0.f, 0.f, 0.f};
;                 f32x4 Rprev = bup, Dcur;
; #pragma unroll
;                 for (int e = 0; e < 4; ++e) Dcur[e] = ROR15(acc[ai][0][0][n][e]);
; #pragma unroll
;                 for (int m = 0; m < 4; ++m) {
;                     f32x4 Rm, Dnext = bdn;
; #pragma unroll
;                     for (int e = 0; e < 4; ++e) { Rm[e] = ROR1(acc[ai][0][m][n][e]); if (m < 3) Dnext[e] = ROR15(acc[ai][0][m < 3 ? m + 1 : 3][n][e]); }
;                     const f32x4 up = (fr > 0) ? Rm : Rprev;
;                     const f32x4 dn = (fr < 15) ? Dcur : Dnext;
;                     Rprev = Rm; Dcur = Dnext;
;                     const int rr = q * 64 + m * 16 + fr, sq = s0 + rr;
;                     const f32x4 g = acc[ai][0][m][n], v = acc[ai][1][m][n];
;                     f32x4 o;
; #pragma unroll
;                     for (int e = 0; e < 4; ++e) { const float z = w0[e] * up[e] + w1[e] * g[e] + w2[e] * dn[e] + bb[e]; o[e] = z * __builtin_amdgcn_rcpf(1.f + __builtin_amdgcn_exp2f(-1.4426950408889634f * z)) * v[e]; }
;                     if (rr >= 1 && rr <= 254) { u32x2 w; w.x = cvt_pk_bf16(o[0], o[1]); w.y = cvt_pk_bf16(o[2], o[3]);
;                         *(u32x2*)(act + (size_t)(sbase + sq) * DFF + j) = w; }
;                     if (rr < 2 || rr > 253) { const int rid = rr < 2 ? rr : rr - 252; *(f32x4*)(sbp + (size_t)rid * DFF + j) = g;
;                         if (rr == 0 || rr == 255) *(f32x4*)(sbp + (size_t)(4 + (rr == 255)) * DFF + j) = v; }
	v_mov_b32_dpp v200, v128 row_ror:15 row_mask:0xf bank_mask:0xf
	v_mov_b32_dpp v201, v129 row_ror:15 row_mask:0xf bank_mask:0xf
	v_cndmask_b32_e64 v206, v194, v150, s[8:9]
	v_cndmask_b32_e64 v207, v195, v151, s[8:9]
	v_cndmask_b32_e64 v208, v196, v152, s[8:9]
	v_cndmask_b32_e64 v209, v197, v153, s[8:9]
	v_cndmask_b32_e64 v210, v202, v198, s[10:11]
	v_cndmask_b32_e64 v211, v203, v199, s[10:11]
	v_cndmask_b32_e64 v212, v204, v200, s[10:11]
	v_cndmask_b32_e64 v213, v205, v201, s[10:11]
	v_mul_f32_e32 v134, v110, v134
	v_mul_f32_e32 v135, v111, v135
	v_mul_f32_e32 v136, v112, v136
	v_mul_f32_e32 v137, v113, v137
	v_mul_f32_e32 v210, v114, v210
	v_mul_f32_e32 v211, v115, v211
	v_mul_f32_e32 v212, v116, v212
	v_mul_f32_e32 v213, v117, v213
	v_fmac_f32_e32 v134, v106, v206
	v_fmac_f32_e32 v135, v107, v207
	v_fmac_f32_e32 v136, v108, v208
	v_fmac_f32_e32 v137, v109, v209
	v_add_f32_e32 v134, v210, v134
	v_add_f32_e32 v135, v211, v135
	v_add_f32_e32 v136, v212, v136
	v_add_f32_e32 v137, v213, v137
	v_add_f32_e32 v134, v118, v134
	v_add_f32_e32 v135, v119, v135
	v_add_f32_e32 v136, v120, v136
	v_add_f32_e32 v137, v121, v137
	v_mul_f32_e32 v206, 0xbfb8aa3b, v134
	v_mul_f32_e32 v207, 0xbfb8aa3b, v135
	v_mul_f32_e32 v208, 0xbfb8aa3b, v136
	v_mul_f32_e32 v209, 0xbfb8aa3b, v137
	v_exp_f32_e32 v206, v206
	v_exp_f32_e32 v207, v207
	v_exp_f32_e32 v208, v208
	v_exp_f32_e32 v209, v209
	v_add_f32_e32 v206, 1.0, v206
	v_add_f32_e32 v207, 1.0, v207
	v_add_f32_e32 v208, 1.0, v208
	v_add_f32_e32 v209, 1.0, v209
	v_rcp_f32_e32 v206, v206
	v_rcp_f32_e32 v207, v207
	v_rcp_f32_e32 v208, v208
	v_rcp_f32_e32 v209, v209
	v_mul_f32_e32 v134, v134, v206
	v_mul_f32_e32 v135, v135, v207
	v_mul_f32_e32 v136, v136, v208
	v_mul_f32_e32 v137, v137, v209
	v_mul_f32_e32 v134, v130, v134
	v_mul_f32_e32 v135, v131, v135
	v_mul_f32_e32 v136, v132, v136
	v_mul_f32_e32 v137, v133, v137
	v_cvt_pk_bf16_f32 v210, v134, v135
	v_cvt_pk_bf16_f32 v211, v136, v137
	v_add_u32_e32 v175, 0x16000, v174
	global_store_dwordx2 v175, v[210:211], s[18:19]
	v_mov_b32_dpp v150, v126 row_ror:1 row_mask:0xf bank_mask:0xf
	v_mov_b32_dpp v151, v127 row_ror:1 row_mask:0xf bank_mask:0xf
	v_mov_b32_dpp v152, v128 row_ror:1 row_mask:0xf bank_mask:0xf
	v_mov_b32_dpp v153, v129 row_ror:1 row_mask:0xf bank_mask:0xf
	v_mov_b32_dpp v202, v98 row_ror:15 row_mask:0xf bank_mask:0xf
	v_mov_b32_dpp v203, v99 row_ror:15 row_mask:0xf bank_mask:0xf
	v_mov_b32_dpp v204, v100 row_ror:15 row_mask:0xf bank_mask:0xf
	v_mov_b32_dpp v205, v101 row_ror:15 row_mask:0xf bank_mask:0xf
	v_cndmask_b32_e64 v206, v150, v194, s[8:9]
	v_cndmask_b32_e64 v207, v151, v195, s[8:9]
	v_cndmask_b32_e64 v208, v152, v196, s[8:9]
	v_cndmask_b32_e64 v209, v153, v197, s[8:9]
	v_cndmask_b32_e64 v210, v198, v202, s[10:11]
	v_cndmask_b32_e64 v211, v199, v203, s[10:11]
	v_cndmask_b32_e64 v212, v200, v204, s[10:11]
	v_cndmask_b32_e64 v213, v201, v205, s[10:11]
	v_mul_f32_e32 v126, v110, v126
	v_mul_f32_e32 v127, v111, v127
	v_mul_f32_e32 v128, v112, v128
	v_mul_f32_e32 v129, v113, v129
	v_mul_f32_e32 v210, v114, v210
	v_mul_f32_e32 v211, v115, v211
	v_mul_f32_e32 v212, v116, v212
	v_mul_f32_e32 v213, v117, v213
	v_fmac_f32_e32 v126, v106, v206
	v_fmac_f32_e32 v127, v107, v207
	v_fmac_f32_e32 v128, v108, v208
	v_fmac_f32_e32 v129, v109, v209
	v_add_f32_e32 v126, v210, v126
	v_add_f32_e32 v127, v211, v127
	v_add_f32_e32 v128, v212, v128
	v_add_f32_e32 v129, v213, v129
	v_add_f32_e32 v126, v118, v126
	v_add_f32_e32 v127, v119, v127
	v_add_f32_e32 v128, v120, v128
	v_add_f32_e32 v129, v121, v129
	v_mul_f32_e32 v206, 0xbfb8aa3b, v126
	v_mul_f32_e32 v207, 0xbfb8aa3b, v127
	v_mul_f32_e32 v208, 0xbfb8aa3b, v128
	v_mul_f32_e32 v209, 0xbfb8aa3b, v129
	v_exp_f32_e32 v206, v206
	v_exp_f32_e32 v207, v207
	v_exp_f32_e32 v208, v208
	v_exp_f32_e32 v209, v209
	v_add_f32_e32 v206, 1.0, v206
	v_add_f32_e32 v207, 1.0, v207
	v_add_f32_e32 v208, 1.0, v208
	v_add_f32_e32 v209, 1.0, v209
	v_rcp_f32_e32 v206, v206
	v_rcp_f32_e32 v207, v207
	v_rcp_f32_e32 v208, v208
	v_rcp_f32_e32 v209, v209
	v_mul_f32_e32 v126, v126, v206
	v_mul_f32_e32 v127, v127, v207
	v_mul_f32_e32 v128, v128, v208
	v_mul_f32_e32 v129, v129, v209
	v_mul_f32_e32 v126, v122, v126
	v_mul_f32_e32 v127, v123, v127
	v_mul_f32_e32 v128, v124, v128
	v_mul_f32_e32 v129, v125, v129
	v_cvt_pk_bf16_f32 v210, v126, v127
	v_cvt_pk_bf16_f32 v211, v128, v129
	v_add_u32_e32 v175, 0x2c000, v174
	global_store_dwordx2 v175, v[210:211], s[18:19]
	v_mov_b32_dpp v194, v98 row_ror:1 row_mask:0xf bank_mask:0xf
	v_mov_b32_dpp v195, v99 row_ror:1 row_mask:0xf bank_mask:0xf
	v_mov_b32_dpp v196, v100 row_ror:1 row_mask:0xf bank_mask:0xf
	v_mov_b32_dpp v197, v101 row_ror:1 row_mask:0xf bank_mask:0xf
	v_cndmask_b32_e64 v206, v194, v150, s[8:9]
	v_cndmask_b32_e64 v207, v195, v151, s[8:9]
	v_cndmask_b32_e64 v208, v196, v152, s[8:9]
	v_cndmask_b32_e64 v209, v197, v153, s[8:9]
	s_waitcnt lgkmcnt(0)
; #define LAS __attribute__((address_space(3)))
; DEV unsigned cvt_pk_bf16(float lo, float hi) { unsigned r; asm volatile("v_cvt_pk_bf16_f32 %0, %1, %2" : "=v"(r) : "v"(lo), "v"(hi)); return r; }
;     DEV void operator()(const Acc& acc, const Unit& u, int wr, int wc, int fr, int fq, LAS unsigned char* misc) const {
;     ...
;         for (int n = 0; n < 2; ++n) { const int cc = wc * 32 + 8 * fq + 4 * n, j = u.pn * 128 + cc;
;             const f32x4 w0 = *(const f32x4*)(cw + j), w1 = *(const f32x4*)(cw + DFF + j), w2 = *(const f32x4*)(cw + 2 * DFF + j), bb = *(const f32x4*)(cb + j);
; #pragma unroll
;             for (int ai = 0; ai < 2; ++ai) { const int q = 2 * ai + wr;
;                 const f32x4 bup = (q > 0) ? *(LAS f32x4*)(xl + (q - 1) * 128 + cc) : (f32x4){0.f, 0.f, 0.f, 0.f};
;                 const f32x4 bdn = (q < 3) ? *(LAS f32x4*)(xf + (q + 1) * 128 + cc) : (f32x4){0.f, 0.f, 0.f, 0.f};
;                 f32x4 Rprev = bup, Dcur;
; #pragma unroll
;                 for (int e = 0; e < 4; ++e) Dcur[e] = ROR15(acc[ai][0][0][n][e]);
; #pragma unroll
;                 for (int m = 0; m < 4; ++m) {
;                     f32x4 Rm, Dnext = bdn;
; #pragma unroll
;                     for (int e = 0; e < 4; ++e) { Rm[e] = ROR1(acc[ai][0][m][n][e]); if (m < 3) Dnext[e] = ROR15(acc[ai][0][m < 3 ? m + 1 : 3][n][e]); }
;                     const f32x4 up = (fr > 0) ? Rm : Rprev;
;                     const f32x4 dn = (fr < 15) ? Dcur : Dnext;
;                     Rprev = Rm; Dcur = Dnext;
;                     const int rr = q * 64 + m * 16 + fr, sq = s0 + rr;
;                     const f32x4 g = acc[ai][0][m][n], v = acc[ai][1][m][n];
;                     f32x4 o;
; #pragma unroll
;                     for (int e = 0; e < 4; ++e) { const float z = w0[e] * up[e] + w1[e] * g[e] + w2[e] * dn[e] + bb[e]; o[e] = z * __builtin_amdgcn_rcpf(1.f + __builtin_amdgcn_exp2f(-1.4426950408889634f * z)) * v[e]; }
;                     if (rr >= 1 && rr <= 254) { u32x2 w; w.x = cvt_pk_bf16(o[0], o[1]); w.y = cvt_pk_bf16(o[2], o[3]);
;                         *(u32x2*)(act + (size_t)(sbase + sq) * DFF + j) = w; }
;                     if (rr < 2 || rr > 253) { const int rid = rr < 2 ? rr : rr - 252; *(f32x4*)(sbp + (size_t)rid * DFF + j) = g;
;                         if (rr == 0 || rr == 255) *(f32x4*)(sbp + (size_t)(4 + (rr == 255)) * DFF + j) = v; }
	v_cndmask_b32_e64 v210, v202, v146, s[10:11]
	v_cndmask_b32_e64 v211, v203, v147, s[10:11]
	v_cndmask_b32_e64 v212, v204, v148, s[10:11]
	v_cndmask_b32_e64 v213, v205, v149, s[10:11]
	v_mul_f32_e32 v98, v110, v98
	v_mul_f32_e32 v99, v111, v99
	v_mul_f32_e32 v100, v112, v100
	v_mul_f32_e32 v101, v113, v101
	v_mul_f32_e32 v210, v114, v210
	v_mul_f32_e32 v211, v115, v211
	v_mul_f32_e32 v212, v116, v212
	v_mul_f32_e32 v213, v117, v213
	v_fmac_f32_e32 v98, v106, v206
	v_fmac_f32_e32 v99, v107, v207
	v_fmac_f32_e32 v100, v108, v208
	v_fmac_f32_e32 v101, v109, v209
	v_add_f32_e32 v98, v210, v98
	v_add_f32_e32 v99, v211, v99
	v_add_f32_e32 v100, v212, v100
	v_add_f32_e32 v101, v213, v101
	v_add_f32_e32 v98, v118, v98
	v_add_f32_e32 v99, v119, v99
	v_add_f32_e32 v100, v120, v100
	v_add_f32_e32 v101, v121, v101
	v_mul_f32_e32 v206, 0xbfb8aa3b, v98
	v_mul_f32_e32 v207, 0xbfb8aa3b, v99
	v_mul_f32_e32 v208, 0xbfb8aa3b, v100
	v_mul_f32_e32 v209, 0xbfb8aa3b, v101
	v_exp_f32_e32 v206, v206
	v_exp_f32_e32 v207, v207
	v_exp_f32_e32 v208, v208
	v_exp_f32_e32 v209, v209
	v_add_f32_e32 v206, 1.0, v206
	v_add_f32_e32 v207, 1.0, v207
	v_add_f32_e32 v208, 1.0, v208
	v_add_f32_e32 v209, 1.0, v209
	v_rcp_f32_e32 v206, v206
	v_rcp_f32_e32 v207, v207
	v_rcp_f32_e32 v208, v208
	v_rcp_f32_e32 v209, v209
	v_mul_f32_e32 v98, v98, v206
	v_mul_f32_e32 v99, v99, v207
	v_mul_f32_e32 v100, v100, v208
	v_mul_f32_e32 v101, v101, v209
	v_mul_f32_e32 v98, v102, v98
	v_mul_f32_e32 v99, v103, v99
	v_mul_f32_e32 v100, v104, v100
	v_mul_f32_e32 v101, v105, v101
	v_cvt_pk_bf16_f32 v210, v98, v99
	v_cvt_pk_bf16_f32 v211, v100, v101
	v_add_u32_e32 v175, 0x42000, v174
	global_store_dwordx2 v175, v[210:211], s[18:19]
	global_load_dwordx4 v[122:125], v173, s[52:53] offset:16
	global_load_dwordx4 v[126:129], v173, s[20:21] offset:16
	global_load_dwordx4 v[130:133], v173, s[22:23] offset:16
	global_load_dwordx4 v[134:137], v173, s[54:55] offset:16
	ds_read_b128 v[146:149], v176 offset:1024
	v_mov_b32_dpp v198, v94 row_ror:15 row_mask:0xf bank_mask:0xf
	v_mov_b32_dpp v199, v95 row_ror:15 row_mask:0xf bank_mask:0xf
	v_mov_b32_dpp v200, v96 row_ror:15 row_mask:0xf bank_mask:0xf
	v_mov_b32_dpp v201, v97 row_ror:15 row_mask:0xf bank_mask:0xf
	v_mov_b32_dpp v150, v94 row_ror:1 row_mask:0xf bank_mask:0xf
	v_mov_b32_dpp v151, v95 row_ror:1 row_mask:0xf bank_mask:0xf
	v_mov_b32_dpp v152, v96 row_ror:1 row_mask:0xf bank_mask:0xf
	v_mov_b32_dpp v153, v97 row_ror:1 row_mask:0xf bank_mask:0xf
	v_mov_b32_dpp v202, v86 row_ror:15 row_mask:0xf bank_mask:0xf
	v_mov_b32_dpp v203, v87 row_ror:15 row_mask:0xf bank_mask:0xf
	v_mov_b32_dpp v204, v88 row_ror:15 row_mask:0xf bank_mask:0xf
	v_mov_b32_dpp v205, v89 row_ror:15 row_mask:0xf bank_mask:0xf
	s_waitcnt lgkmcnt(0)
	v_cndmask_b32_e64 v206, v150, v146, s[8:9]
	v_cndmask_b32_e64 v207, v151, v147, s[8:9]
	v_cndmask_b32_e64 v208, v152, v148, s[8:9]
	v_cndmask_b32_e64 v209, v153, v149, s[8:9]
	s_cmp_eq_u32 s7, 0
	s_cbranch_scc0 .LffnA_bz_4
	ds_read_b128 v[146:149], v176 offset:4096
	s_branch .LffnA_bj_5

; #define LAS __attribute__((address_space(3)))
; DEV unsigned cvt_pk_bf16(float lo, float hi) { unsigned r; asm volatile("v_cvt_pk_bf16_f32 %0, %1, %2" : "=v"(r) : "v"(lo), "v"(hi)); return r; }
;     DEV void operator()(const Acc& acc, const Unit& u, int wr, int wc, int fr, int fq, LAS unsigned char* misc) const {
;     ...
;         for (int n = 0; n < 2; ++n) { const int cc = wc * 32 + 8 * fq + 4 * n, j = u.pn * 128 + cc;
;             const f32x4 w0 = *(const f32x4*)(cw + j), w1 = *(const f32x4*)(cw + DFF + j), w2 = *(const f32x4*)(cw + 2 * DFF + j), bb = *(const f32x4*)(cb + j);
; #pragma unroll
;             for (int ai = 0; ai < 2; ++ai) { const int q = 2 * ai + wr;
;                 const f32x4 bup = (q > 0) ? *(LAS f32x4*)(xl + (q - 1) * 128 + cc) : (f32x4){0.f, 0.f, 0.f, 0.f};
;                 const f32x4 bdn = (q < 3) ? *(LAS f32x4*)(xf + (q + 1) * 128 + cc) : (f32x4){0.f, 0.f, 0.f, 0.f};
;                 f32x4 Rprev = bup, Dcur;
; #pragma unroll
;                 for (int e = 0; e < 4; ++e) Dcur[e] = ROR15(acc[ai][0][0][n][e]);
; #pragma unroll
;                 for (int m = 0; m < 4; ++m) {
;                     f32x4 Rm, Dnext = bdn;
; #pragma unroll
;                     for (int e = 0; e < 4; ++e) { Rm[e] = ROR1(acc[ai][0][m][n][e]); if (m < 3) Dnext[e] = ROR15(acc[ai][0][m < 3 ? m + 1 : 3][n][e]); }
;                     const f32x4 up = (fr > 0) ? Rm : Rprev;
;                     const f32x4 dn = (fr < 15) ? Dcur : Dnext;
;                     Rprev = Rm; Dcur = Dnext;
;                     const int rr = q * 64 + m * 16 + fr, sq = s0 + rr;
;                     const f32x4 g = acc[ai][0][m][n], v = acc[ai][1][m][n];
;                     f32x4 o;
; #pragma unroll
;                     for (int e = 0; e < 4; ++e) { const float z = w0[e] * up[e] + w1[e] * g[e] + w2[e] * dn[e] + bb[e]; o[e] = z * __builtin_amdgcn_rcpf(1.f + __builtin_amdgcn_exp2f(-1.4426950408889634f * z)) * v[e]; }
;                     if (rr >= 1 && rr <= 254) { u32x2 w; w.x = cvt_pk_bf16(o[0], o[1]); w.y = cvt_pk_bf16(o[2], o[3]);
;                         *(u32x2*)(act + (size_t)(sbase + sq) * DFF + j) = w; }
;                     if (rr < 2 || rr > 253) { const int rid = rr < 2 ? rr : rr - 252; *(f32x4*)(sbp + (size_t)rid * DFF + j) = g;
;                         if (rr == 0 || rr == 255) *(f32x4*)(sbp + (size_t)(4 + (rr == 255)) * DFF + j) = v; }
.LffnA_bj_5:
	v_cndmask_b32_e64 v210, v198, v202, s[10:11]
	v_cndmask_b32_e64 v211, v199, v203, s[10:11]
	v_cndmask_b32_e64 v212, v200, v204, s[10:11]
	v_cndmask_b32_e64 v213, v201, v205, s[10:11]
	v_mul_f32_e32 v94, v110, v94
	v_mul_f32_e32 v95, v111, v95
	v_mul_f32_e32 v96, v112, v96
	v_mul_f32_e32 v97, v113, v97
	v_mul_f32_e32 v210, v114, v210
	v_mul_f32_e32 v211, v115, v211
	v_mul_f32_e32 v212, v116, v212
	v_mul_f32_e32 v213, v117, v213
	v_fmac_f32_e32 v94, v106, v206
	v_fmac_f32_e32 v95, v107, v207
	v_fmac_f32_e32 v96, v108, v208
	v_fmac_f32_e32 v97, v109, v209
	v_add_f32_e32 v94, v210, v94
	v_add_f32_e32 v95, v211, v95
	v_add_f32_e32 v96, v212, v96
	v_add_f32_e32 v97, v213, v97
	v_add_f32_e32 v94, v118, v94
	v_add_f32_e32 v95, v119, v95
	v_add_f32_e32 v96, v120, v96
	v_add_f32_e32 v97, v121, v97
	v_mul_f32_e32 v206, 0xbfb8aa3b, v94
	v_mul_f32_e32 v207, 0xbfb8aa3b, v95
	v_mul_f32_e32 v208, 0xbfb8aa3b, v96
	v_mul_f32_e32 v209, 0xbfb8aa3b, v97
	v_exp_f32_e32 v206, v206
	v_exp_f32_e32 v207, v207
	v_exp_f32_e32 v208, v208
	v_exp_f32_e32 v209, v209
	v_add_f32_e32 v206, 1.0, v206
	v_add_f32_e32 v207, 1.0, v207
	v_add_f32_e32 v208, 1.0, v208
	v_add_f32_e32 v209, 1.0, v209
	v_rcp_f32_e32 v206, v206
	v_rcp_f32_e32 v207, v207
	v_rcp_f32_e32 v208, v208
	v_rcp_f32_e32 v209, v209
	v_mul_f32_e32 v94, v94, v206
	v_mul_f32_e32 v95, v95, v207
	v_mul_f32_e32 v96, v96, v208
	v_mul_f32_e32 v97, v97, v209
	v_mul_f32_e32 v94, v90, v94
	v_mul_f32_e32 v95, v91, v95
	v_mul_f32_e32 v96, v92, v96
	v_mul_f32_e32 v97, v93, v97
	v_cvt_pk_bf16_f32 v210, v94, v95
	v_cvt_pk_bf16_f32 v211, v96, v97
	v_add_u32_e32 v175, 0xb0000, v174
	global_store_dwordx2 v175, v[210:211], s[18:19]
	v_mov_b32_dpp v194, v86 row_ror:1 row_mask:0xf bank_mask:0xf
	v_mov_b32_dpp v195, v87 row_ror:1 row_mask:0xf bank_mask:0xf
	v_mov_b32_dpp v196, v88 row_ror:1 row_mask:0xf bank_mask:0xf
	v_mov_b32_dpp v197, v89 row_ror:1 row_mask:0xf bank_mask:0xf
	v_mov_b32_dpp v198, v78 row_ror:15 row_mask:0xf bank_mask:0xf
	v_mov_b32_dpp v199, v79 row_ror:15 row_mask:0xf bank_mask:0xf
	v_mov_b32_dpp v200, v80 row_ror:15 row_mask:0xf bank_mask:0xf
	v_mov_b32_dpp v201, v81 row_ror:15 row_mask:0xf bank_mask:0xf
	v_cndmask_b32_e64 v206, v194, v150, s[8:9]
	v_cndmask_b32_e64 v207, v195, v151, s[8:9]
	v_cndmask_b32_e64 v208, v196, v152, s[8:9]
	v_cndmask_b32_e64 v209, v197, v153, s[8:9]
	v_cndmask_b32_e64 v210, v202, v198, s[10:11]
	v_cndmask_b32_e64 v211, v203, v199, s[10:11]
	v_cndmask_b32_e64 v212, v204, v200, s[10:11]
	v_cndmask_b32_e64 v213, v205, v201, s[10:11]
	v_mul_f32_e32 v86, v110, v86
	v_mul_f32_e32 v87, v111, v87
	v_mul_f32_e32 v88, v112, v88
	v_mul_f32_e32 v89, v113, v89
	v_mul_f32_e32 v210, v114, v210
	v_mul_f32_e32 v211, v115, v211
	v_mul_f32_e32 v212, v116, v212
	v_mul_f32_e32 v213, v117, v213
	v_fmac_f32_e32 v86, v106, v206
	v_fmac_f32_e32 v87, v107, v207
	v_fmac_f32_e32 v88, v108, v208
	v_fmac_f32_e32 v89, v109, v209
	v_add_f32_e32 v86, v210, v86
	v_add_f32_e32 v87, v211, v87
	v_add_f32_e32 v88, v212, v88
	v_add_f32_e32 v89, v213, v89
	v_add_f32_e32 v86, v118, v86
	v_add_f32_e32 v87, v119, v87
	v_add_f32_e32 v88, v120, v88
	v_add_f32_e32 v89, v121, v89
	v_mul_f32_e32 v206, 0xbfb8aa3b, v86
	v_mul_f32_e32 v207, 0xbfb8aa3b, v87
	v_mul_f32_e32 v208, 0xbfb8aa3b, v88
	v_mul_f32_e32 v209, 0xbfb8aa3b, v89
	v_exp_f32_e32 v206, v206
	v_exp_f32_e32 v207, v207
	v_exp_f32_e32 v208, v208
	v_exp_f32_e32 v209, v209
	v_add_f32_e32 v206, 1.0, v206
	v_add_f32_e32 v207, 1.0, v207
	v_add_f32_e32 v208, 1.0, v208
	v_add_f32_e32 v209, 1.0, v209
	v_rcp_f32_e32 v206, v206
	v_rcp_f32_e32 v207, v207
	v_rcp_f32_e32 v208, v208
	v_rcp_f32_e32 v209, v209
	v_mul_f32_e32 v86, v86, v206
	v_mul_f32_e32 v87, v87, v207
	v_mul_f32_e32 v88, v88, v208
	v_mul_f32_e32 v89, v89, v209
	v_mul_f32_e32 v86, v82, v86
	v_mul_f32_e32 v87, v83, v87
	v_mul_f32_e32 v88, v84, v88
	v_mul_f32_e32 v89, v85, v89
	v_cvt_pk_bf16_f32 v210, v86, v87
	v_cvt_pk_bf16_f32 v211, v88, v89
	v_add_u32_e32 v175, 0xc6000, v174
	global_store_dwordx2 v175, v[210:211], s[18:19]
	v_mov_b32_dpp v150, v78 row_ror:1 row_mask:0xf bank_mask:0xf
	v_mov_b32_dpp v151, v79 row_ror:1 row_mask:0xf bank_mask:0xf
	v_mov_b32_dpp v152, v80 row_ror:1 row_mask:0xf bank_mask:0xf
	v_mov_b32_dpp v153, v81 row_ror:1 row_mask:0xf bank_mask:0xf
	v_mov_b32_dpp v202, v70 row_ror:15 row_mask:0xf bank_mask:0xf
	v_mov_b32_dpp v203, v71 row_ror:15 row_mask:0xf bank_mask:0xf
	v_mov_b32_dpp v204, v72 row_ror:15 row_mask:0xf bank_mask:0xf
	v_mov_b32_dpp v205, v73 row_ror:15 row_mask:0xf bank_mask:0xf
	v_cndmask_b32_e64 v206, v150, v194, s[8:9]
	v_cndmask_b32_e64 v207, v151, v195, s[8:9]
	v_cndmask_b32_e64 v208, v152, v196, s[8:9]
	v_cndmask_b32_e64 v209, v153, v197, s[8:9]
	v_cndmask_b32_e64 v210, v198, v202, s[10:11]
	v_cndmask_b32_e64 v211, v199, v203, s[10:11]
	v_cndmask_b32_e64 v212, v200, v204, s[10:11]
	v_cndmask_b32_e64 v213, v201, v205, s[10:11]
	v_mul_f32_e32 v78, v110, v78
	v_mul_f32_e32 v79, v111, v79
	v_mul_f32_e32 v80, v112, v80
	v_mul_f32_e32 v81, v113, v81
	v_mul_f32_e32 v210, v114, v210
	v_mul_f32_e32 v211, v115, v211
	v_mul_f32_e32 v212, v116, v212
	v_mul_f32_e32 v213, v117, v213
	v_fmac_f32_e32 v78, v106, v206
	v_fmac_f32_e32 v79, v107, v207
	v_fmac_f32_e32 v80, v108, v208
	v_fmac_f32_e32 v81, v109, v209
	v_add_f32_e32 v78, v210, v78
	v_add_f32_e32 v79, v211, v79
	v_add_f32_e32 v80, v212, v80
	v_add_f32_e32 v81, v213, v81
	v_add_f32_e32 v78, v118, v78
	v_add_f32_e32 v79, v119, v79
	v_add_f32_e32 v80, v120, v80
	v_add_f32_e32 v81, v121, v81
	v_mul_f32_e32 v206, 0xbfb8aa3b, v78
	v_mul_f32_e32 v207, 0xbfb8aa3b, v79
	v_mul_f32_e32 v208, 0xbfb8aa3b, v80
	v_mul_f32_e32 v209, 0xbfb8aa3b, v81
	v_exp_f32_e32 v206, v206
	v_exp_f32_e32 v207, v207
	v_exp_f32_e32 v208, v208
	v_exp_f32_e32 v209, v209
	v_add_f32_e32 v206, 1.0, v206
	v_add_f32_e32 v207, 1.0, v207
	v_add_f32_e32 v208, 1.0, v208
	v_add_f32_e32 v209, 1.0, v209
	v_rcp_f32_e32 v206, v206
	v_rcp_f32_e32 v207, v207
	v_rcp_f32_e32 v208, v208
	v_rcp_f32_e32 v209, v209
	v_mul_f32_e32 v78, v78, v206
	v_mul_f32_e32 v79, v79, v207
	v_mul_f32_e32 v80, v80, v208
	v_mul_f32_e32 v81, v81, v209
	v_mul_f32_e32 v78, v74, v78
	v_mul_f32_e32 v79, v75, v79
	v_mul_f32_e32 v80, v76, v80
	v_mul_f32_e32 v81, v77, v81
	v_cvt_pk_bf16_f32 v210, v78, v79
	v_cvt_pk_bf16_f32 v211, v80, v81
	v_add_u32_e32 v175, 0xdc000, v174
	global_store_dwordx2 v175, v[210:211], s[18:19]
	s_cmp_eq_u32 s7, 1
	s_cbranch_scc0 .LffnA_ns_6
	v_mul_u32_u24_e32 v177, 0x2c00, v172
	v_cmp_lt_u32_e64 s[30:31], 13, v172
	v_add_u32_e32 v177, v177, v173
	v_add_u32_e32 v177, 0xfffdf000, v177
	s_nop 1
	s_mov_b64 exec, s[30:31]
	global_store_dwordx4 v177, v[70:73], s[24:25]
	s_mov_b64 exec, s[10:11]
	global_store_dwordx4 v177, v[66:69], s[28:29]
	s_mov_b64 exec, -1
	s_nop 4
; #define LAS __attribute__((address_space(3)))
; DEV unsigned cvt_pk_bf16(float lo, float hi) { unsigned r; asm volatile("v_cvt_pk_bf16_f32 %0, %1, %2" : "=v"(r) : "v"(lo), "v"(hi)); return r; }
;     DEV void operator()(const Acc& acc, const Unit& u, int wr, int wc, int fr, int fq, LAS unsigned char* misc) const {
;     ...
;         for (int n = 0; n < 2; ++n) { const int cc = wc * 32 + 8 * fq + 4 * n, j = u.pn * 128 + cc;
;             const f32x4 w0 = *(const f32x4*)(cw + j), w1 = *(const f32x4*)(cw + DFF + j), w2 = *(const f32x4*)(cw + 2 * DFF + j), bb = *(const f32x4*)(cb + j);
; #pragma unroll
;             for (int ai = 0; ai < 2; ++ai) { const int q = 2 * ai + wr;
;                 const f32x4 bup = (q > 0) ? *(LAS f32x4*)(xl + (q - 1) * 128 + cc) : (f32x4){0.f, 0.f, 0.f, 0.f};
;                 const f32x4 bdn = (q < 3) ? *(LAS f32x4*)(xf + (q + 1) * 128 + cc) : (f32x4){0.f, 0.f, 0.f, 0.f};
;                 f32x4 Rprev = bup, Dcur;
; #pragma unroll
;                 for (int e = 0; e < 4; ++e) Dcur[e] = ROR15(acc[ai][0][0][n][e]);
; #pragma unroll
;                 for (int m = 0; m < 4; ++m) {
;                     f32x4 Rm, Dnext = bdn;
; #pragma unroll
;                     for (int e = 0; e < 4; ++e) { Rm[e] = ROR1(acc[ai][0][m][n][e]); if (m < 3) Dnext[e] = ROR15(acc[ai][0][m < 3 ? m + 1 : 3][n][e]); }
;                     const f32x4 up = (fr > 0) ? Rm : Rprev;
;                     const f32x4 dn = (fr < 15) ? Dcur : Dnext;
;                     Rprev = Rm; Dcur = Dnext;
;                     const int rr = q * 64 + m * 16 + fr, sq = s0 + rr;
;                     const f32x4 g = acc[ai][0][m][n], v = acc[ai][1][m][n];
;                     f32x4 o;
; #pragma unroll
;                     for (int e = 0; e < 4; ++e) { const float z = w0[e] * up[e] + w1[e] * g[e] + w2[e] * dn[e] + bb[e]; o[e] = z * __builtin_amdgcn_rcpf(1.f + __builtin_amdgcn_exp2f(-1.4426950408889634f * z)) * v[e]; }
;                     if (rr >= 1 && rr <= 254) { u32x2 w; w.x = cvt_pk_bf16(o[0], o[1]); w.y = cvt_pk_bf16(o[2], o[3]);
;                         *(u32x2*)(act + (size_t)(sbase + sq) * DFF + j) = w; }
;                     if (rr < 2 || rr > 253) { const int rid = rr < 2 ? rr : rr - 252; *(f32x4*)(sbp + (size_t)rid * DFF + j) = g;
;                         if (rr == 0 || rr == 255) *(f32x4*)(sbp + (size_t)(4 + (rr == 255)) * DFF + j) = v; }
.LffnA_ns_6:
	v_mov_b32_dpp v194, v70 row_ror:1 row_mask:0xf bank_mask:0xf
	v_mov_b32_dpp v195, v71 row_ror:1 row_mask:0xf bank_mask:0xf
	v_mov_b32_dpp v196, v72 row_ror:1 row_mask:0xf bank_mask:0xf
	v_mov_b32_dpp v197, v73 row_ror:1 row_mask:0xf bank_mask:0xf
	v_cndmask_b32_e64 v206, v194, v150, s[8:9]
	v_cndmask_b32_e64 v207, v195, v151, s[8:9]
	v_cndmask_b32_e64 v208, v196, v152, s[8:9]
	v_cndmask_b32_e64 v209, v197, v153, s[8:9]
	s_waitcnt lgkmcnt(0)
	v_cndmask_b32_e64 v210, v202, v146, s[10:11]
	v_cndmask_b32_e64 v211, v203, v147, s[10:11]
	v_cndmask_b32_e64 v212, v204, v148, s[10:11]
	v_cndmask_b32_e64 v213, v205, v149, s[10:11]
	v_mul_f32_e32 v70, v110, v70
	v_mul_f32_e32 v71, v111, v71
	v_mul_f32_e32 v72, v112, v72
	v_mul_f32_e32 v73, v113, v73
	v_mul_f32_e32 v210, v114, v210
	v_mul_f32_e32 v211, v115, v211
	v_mul_f32_e32 v212, v116, v212
	v_mul_f32_e32 v213, v117, v213
	v_fmac_f32_e32 v70, v106, v206
	v_fmac_f32_e32 v71, v107, v207
	v_fmac_f32_e32 v72, v108, v208
	v_fmac_f32_e32 v73, v109, v209
	v_add_f32_e32 v70, v210, v70
	v_add_f32_e32 v71, v211, v71
	v_add_f32_e32 v72, v212, v72
	v_add_f32_e32 v73, v213, v73
	v_add_f32_e32 v70, v118, v70
	v_add_f32_e32 v71, v119, v71
	v_add_f32_e32 v72, v120, v72
	v_add_f32_e32 v73, v121, v73
	v_mul_f32_e32 v206, 0xbfb8aa3b, v70
	v_mul_f32_e32 v207, 0xbfb8aa3b, v71
	v_mul_f32_e32 v208, 0xbfb8aa3b, v72
	v_mul_f32_e32 v209, 0xbfb8aa3b, v73
	v_exp_f32_e32 v206, v206
	v_exp_f32_e32 v207, v207
	v_exp_f32_e32 v208, v208
	v_exp_f32_e32 v209, v209
	v_add_f32_e32 v206, 1.0, v206
	v_add_f32_e32 v207, 1.0, v207
	v_add_f32_e32 v208, 1.0, v208
	v_add_f32_e32 v209, 1.0, v209
	v_rcp_f32_e32 v206, v206
	v_rcp_f32_e32 v207, v207
	v_rcp_f32_e32 v208, v208
	v_rcp_f32_e32 v209, v209
	v_mul_f32_e32 v70, v70, v206
	v_mul_f32_e32 v71, v71, v207
	v_mul_f32_e32 v72, v72, v208
	v_mul_f32_e32 v73, v73, v209
	v_mul_f32_e32 v70, v66, v70
	v_mul_f32_e32 v71, v67, v71
	v_mul_f32_e32 v72, v68, v72
	v_mul_f32_e32 v73, v69, v73
	v_cvt_pk_bf16_f32 v210, v70, v71
	v_cvt_pk_bf16_f32 v211, v72, v73
	v_add_u32_e32 v175, 0xf2000, v174
	s_mov_b64 exec, s[16:17]
	global_store_dwordx2 v175, v[210:211], s[18:19]
	s_mov_b64 exec, -1
	s_nop 4
	s_cmp_eq_u32 s7, 0
	s_cbranch_scc1 .LffnA_bz_7
	ds_read_b128 v[146:149], v176 offset:16
	s_branch .LffnA_bj_8

; #define LAS __attribute__((address_space(3)))
; DEV unsigned cvt_pk_bf16(float lo, float hi) { unsigned r; asm volatile("v_cvt_pk_bf16_f32 %0, %1, %2" : "=v"(r) : "v"(lo), "v"(hi)); return r; }
;     DEV void operator()(const Acc& acc, const Unit& u, int wr, int wc, int fr, int fq, LAS unsigned char* misc) const {
;     ...
;         for (int n = 0; n < 2; ++n) { const int cc = wc * 32 + 8 * fq + 4 * n, j = u.pn * 128 + cc;
;             const f32x4 w0 = *(const f32x4*)(cw + j), w1 = *(const f32x4*)(cw + DFF + j), w2 = *(const f32x4*)(cw + 2 * DFF + j), bb = *(const f32x4*)(cb + j);
; #pragma unroll
;             for (int ai = 0; ai < 2; ++ai) { const int q = 2 * ai + wr;
;                 const f32x4 bup = (q > 0) ? *(LAS f32x4*)(xl + (q - 1) * 128 + cc) : (f32x4){0.f, 0.f, 0.f, 0.f};
;                 const f32x4 bdn = (q < 3) ? *(LAS f32x4*)(xf + (q + 1) * 128 + cc) : (f32x4){0.f, 0.f, 0.f, 0.f};
;                 f32x4 Rprev = bup, Dcur;
; #pragma unroll
;                 for (int e = 0; e < 4; ++e) Dcur[e] = ROR15(acc[ai][0][0][n][e]);
; #pragma unroll
;                 for (int m = 0; m < 4; ++m) {
;                     f32x4 Rm, Dnext = bdn;
; #pragma unroll
;                     for (int e = 0; e < 4; ++e) { Rm[e] = ROR1(acc[ai][0][m][n][e]); if (m < 3) Dnext[e] = ROR15(acc[ai][0][m < 3 ? m + 1 : 3][n][e]); }
;                     const f32x4 up = (fr > 0) ? Rm : Rprev;
;                     const f32x4 dn = (fr < 15) ? Dcur : Dnext;
;                     Rprev = Rm; Dcur = Dnext;
;                     const int rr = q * 64 + m * 16 + fr, sq = s0 + rr;
;                     const f32x4 g = acc[ai][0][m][n], v = acc[ai][1][m][n];
;                     f32x4 o;
; #pragma unroll
;                     for (int e = 0; e < 4; ++e) { const float z = w0[e] * up[e] + w1[e] * g[e] + w2[e] * dn[e] + bb[e]; o[e] = z * __builtin_amdgcn_rcpf(1.f + __builtin_amdgcn_exp2f(-1.4426950408889634f * z)) * v[e]; }
;                     if (rr >= 1 && rr <= 254) { u32x2 w; w.x = cvt_pk_bf16(o[0], o[1]); w.y = cvt_pk_bf16(o[2], o[3]);
;                         *(u32x2*)(act + (size_t)(sbase + sq) * DFF + j) = w; }
;                     if (rr < 2 || rr > 253) { const int rid = rr < 2 ? rr : rr - 252; *(f32x4*)(sbp + (size_t)rid * DFF + j) = g;
;                         if (rr == 0 || rr == 255) *(f32x4*)(sbp + (size_t)(4 + (rr == 255)) * DFF + j) = v; }
.LffnA_bj_8:
	v_mov_b32_dpp v198, v58 row_ror:15 row_mask:0xf bank_mask:0xf
	v_mov_b32_dpp v199, v59 row_ror:15 row_mask:0xf bank_mask:0xf
	v_mov_b32_dpp v200, v60 row_ror:15 row_mask:0xf bank_mask:0xf
	v_mov_b32_dpp v201, v61 row_ror:15 row_mask:0xf bank_mask:0xf
	s_waitcnt vmcnt(4)
	s_cmp_eq_u32 s7, 0
	s_cbranch_scc0 .LffnA_ns_9
	v_mul_u32_u24_e32 v177, 0x2c00, v172
	v_cmp_gt_u32_e64 s[30:31], 2, v172
	v_add_u32_e32 v177, v177, v173
	s_nop 1
	s_mov_b64 exec, s[30:31]
	global_store_dwordx4 v177, v[58:61], s[24:25] offset:16
	s_mov_b64 exec, s[8:9]
	global_store_dwordx4 v177, v[62:65], s[26:27] offset:16
	s_mov_b64 exec, -1
	s_nop 4
.LffnA_ns_9:
	v_mov_b32_dpp v150, v58 row_ror:1 row_mask:0xf bank_mask:0xf
	v_mov_b32_dpp v151, v59 row_ror:1 row_mask:0xf bank_mask:0xf
	v_mov_b32_dpp v152, v60 row_ror:1 row_mask:0xf bank_mask:0xf
	v_mov_b32_dpp v153, v61 row_ror:1 row_mask:0xf bank_mask:0xf
	v_mov_b32_dpp v202, v54 row_ror:15 row_mask:0xf bank_mask:0xf
	v_mov_b32_dpp v203, v55 row_ror:15 row_mask:0xf bank_mask:0xf
	v_mov_b32_dpp v204, v56 row_ror:15 row_mask:0xf bank_mask:0xf
	v_mov_b32_dpp v205, v57 row_ror:15 row_mask:0xf bank_mask:0xf
	s_waitcnt lgkmcnt(0)
	v_cndmask_b32_e64 v206, v150, v146, s[8:9]
	v_cndmask_b32_e64 v207, v151, v147, s[8:9]
	v_cndmask_b32_e64 v208, v152, v148, s[8:9]
	v_cndmask_b32_e64 v209, v153, v149, s[8:9]
	ds_read_b128 v[146:149], v176 offset:3088
	v_cndmask_b32_e64 v210, v198, v202, s[10:11]
	v_cndmask_b32_e64 v211, v199, v203, s[10:11]
	v_cndmask_b32_e64 v212, v200, v204, s[10:11]
	v_cndmask_b32_e64 v213, v201, v205, s[10:11]
	v_mul_f32_e32 v58, v126, v58
	v_mul_f32_e32 v59, v127, v59
	v_mul_f32_e32 v60, v128, v60
	v_mul_f32_e32 v61, v129, v61
	v_mul_f32_e32 v210, v130, v210
	v_mul_f32_e32 v211, v131, v211
	v_mul_f32_e32 v212, v132, v212
	v_mul_f32_e32 v213, v133, v213
	v_fmac_f32_e32 v58, v122, v206
	v_fmac_f32_e32 v59, v123, v207
	v_fmac_f32_e32 v60, v124, v208
	v_fmac_f32_e32 v61, v125, v209
	v_add_f32_e32 v58, v210, v58
	v_add_f32_e32 v59, v211, v59
	v_add_f32_e32 v60, v212, v60
	v_add_f32_e32 v61, v213, v61
	v_add_f32_e32 v58, v134, v58
	v_add_f32_e32 v59, v135, v59
	v_add_f32_e32 v60, v136, v60
	v_add_f32_e32 v61, v137, v61
	v_mul_f32_e32 v206, 0xbfb8aa3b, v58
	v_mul_f32_e32 v207, 0xbfb8aa3b, v59
	v_mul_f32_e32 v208, 0xbfb8aa3b, v60
	v_mul_f32_e32 v209, 0xbfb8aa3b, v61
	v_exp_f32_e32 v206, v206
	v_exp_f32_e32 v207, v207
	v_exp_f32_e32 v208, v208
	v_exp_f32_e32 v209, v209
	v_add_f32_e32 v206, 1.0, v206
	v_add_f32_e32 v207, 1.0, v207
	v_add_f32_e32 v208, 1.0, v208
	v_add_f32_e32 v209, 1.0, v209
	v_rcp_f32_e32 v206, v206
	v_rcp_f32_e32 v207, v207
	v_rcp_f32_e32 v208, v208
	v_rcp_f32_e32 v209, v209
	v_mul_f32_e32 v58, v58, v206
	v_mul_f32_e32 v59, v59, v207
	v_mul_f32_e32 v60, v60, v208
	v_mul_f32_e32 v61, v61, v209
	v_mul_f32_e32 v58, v62, v58
	v_mul_f32_e32 v59, v63, v59
	v_mul_f32_e32 v60, v64, v60
	v_mul_f32_e32 v61, v65, v61
	v_cvt_pk_bf16_f32 v210, v58, v59
	v_cvt_pk_bf16_f32 v211, v60, v61
	v_add_u32_e32 v175, 0x0, v174
	s_mov_b64 exec, s[12:13]
	global_store_dwordx2 v175, v[210:211], s[18:19] offset:8
	s_mov_b64 exec, -1
	s_nop 4
	v_mov_b32_dpp v194, v54 row_ror:1 row_mask:0xf bank_mask:0xf
	v_mov_b32_dpp v195, v55 row_ror:1 row_mask:0xf bank_mask:0xf
	v_mov_b32_dpp v196, v56 row_ror:1 row_mask:0xf bank_mask:0xf
	v_mov_b32_dpp v197, v57 row_ror:1 row_mask:0xf bank_mask:0xf
	v_mov_b32_dpp v198, v46 row_ror:15 row_mask:0xf bank_mask:0xf
	v_mov_b32_dpp v199, v47 row_ror:15 row_mask:0xf bank_mask:0xf
	v_mov_b32_dpp v200, v48 row_ror:15 row_mask:0xf bank_mask:0xf
	v_mov_b32_dpp v201, v49 row_ror:15 row_mask:0xf bank_mask:0xf
	v_cndmask_b32_e64 v206, v194, v150, s[8:9]
	v_cndmask_b32_e64 v207, v195, v151, s[8:9]
	v_cndmask_b32_e64 v208, v196, v152, s[8:9]
	v_cndmask_b32_e64 v209, v197, v153, s[8:9]
	v_cndmask_b32_e64 v210, v202, v198, s[10:11]
	v_cndmask_b32_e64 v211, v203, v199, s[10:11]
	v_cndmask_b32_e64 v212, v204, v200, s[10:11]
	v_cndmask_b32_e64 v213, v205, v201, s[10:11]
	v_mul_f32_e32 v54, v126, v54
	v_mul_f32_e32 v55, v127, v55
	v_mul_f32_e32 v56, v128, v56
	v_mul_f32_e32 v57, v129, v57
	v_mul_f32_e32 v210, v130, v210
	v_mul_f32_e32 v211, v131, v211
	v_mul_f32_e32 v212, v132, v212
	v_mul_f32_e32 v213, v133, v213
	v_fmac_f32_e32 v54, v122, v206
	v_fmac_f32_e32 v55, v123, v207
	v_fmac_f32_e32 v56, v124, v208
	v_fmac_f32_e32 v57, v125, v209
	v_add_f32_e32 v54, v210, v54
	v_add_f32_e32 v55, v211, v55
	v_add_f32_e32 v56, v212, v56
	v_add_f32_e32 v57, v213, v57
	v_add_f32_e32 v54, v134, v54
	v_add_f32_e32 v55, v135, v55
	v_add_f32_e32 v56, v136, v56
	v_add_f32_e32 v57, v137, v57
	v_mul_f32_e32 v206, 0xbfb8aa3b, v54
	v_mul_f32_e32 v207, 0xbfb8aa3b, v55
	v_mul_f32_e32 v208, 0xbfb8aa3b, v56
	v_mul_f32_e32 v209, 0xbfb8aa3b, v57
	v_exp_f32_e32 v206, v206
	v_exp_f32_e32 v207, v207
	v_exp_f32_e32 v208, v208
	v_exp_f32_e32 v209, v209
	v_add_f32_e32 v206, 1.0, v206
	v_add_f32_e32 v207, 1.0, v207
	v_add_f32_e32 v208, 1.0, v208
	v_add_f32_e32 v209, 1.0, v209
	v_rcp_f32_e32 v206, v206
	v_rcp_f32_e32 v207, v207
	v_rcp_f32_e32 v208, v208
	v_rcp_f32_e32 v209, v209
	v_mul_f32_e32 v54, v54, v206
	v_mul_f32_e32 v55, v55, v207
	v_mul_f32_e32 v56, v56, v208
	v_mul_f32_e32 v57, v57, v209
	v_mul_f32_e32 v54, v50, v54
	v_mul_f32_e32 v55, v51, v55
	v_mul_f32_e32 v56, v52, v56
	v_mul_f32_e32 v57, v53, v57
	v_cvt_pk_bf16_f32 v210, v54, v55
	v_cvt_pk_bf16_f32 v211, v56, v57
	v_add_u32_e32 v175, 0x16000, v174
	global_store_dwordx2 v175, v[210:211], s[18:19] offset:8
	v_mov_b32_dpp v150, v46 row_ror:1 row_mask:0xf bank_mask:0xf
; #define LAS __attribute__((address_space(3)))
; DEV unsigned cvt_pk_bf16(float lo, float hi) { unsigned r; asm volatile("v_cvt_pk_bf16_f32 %0, %1, %2" : "=v"(r) : "v"(lo), "v"(hi)); return r; }
;     DEV void operator()(const Acc& acc, const Unit& u, int wr, int wc, int fr, int fq, LAS unsigned char* misc) const {
;     ...
;         for (int n = 0; n < 2; ++n) { const int cc = wc * 32 + 8 * fq + 4 * n, j = u.pn * 128 + cc;
;             const f32x4 w0 = *(const f32x4*)(cw + j), w1 = *(const f32x4*)(cw + DFF + j), w2 = *(const f32x4*)(cw + 2 * DFF + j), bb = *(const f32x4*)(cb + j);
; #pragma unroll
;             for (int ai = 0; ai < 2; ++ai) { const int q = 2 * ai + wr;
;                 const f32x4 bup = (q > 0) ? *(LAS f32x4*)(xl + (q - 1) * 128 + cc) : (f32x4){0.f, 0.f, 0.f, 0.f};
;                 const f32x4 bdn = (q < 3) ? *(LAS f32x4*)(xf + (q + 1) * 128 + cc) : (f32x4){0.f, 0.f, 0.f, 0.f};
;                 f32x4 Rprev = bup, Dcur;
; #pragma unroll
;                 for (int e = 0; e < 4; ++e) Dcur[e] = ROR15(acc[ai][0][0][n][e]);
; #pragma unroll
;                 for (int m = 0; m < 4; ++m) {
;                     f32x4 Rm, Dnext = bdn;
; #pragma unroll
;                     for (int e = 0; e < 4; ++e) { Rm[e] = ROR1(acc[ai][0][m][n][e]); if (m < 3) Dnext[e] = ROR15(acc[ai][0][m < 3 ? m + 1 : 3][n][e]); }
;                     const f32x4 up = (fr > 0) ? Rm : Rprev;
;                     const f32x4 dn = (fr < 15) ? Dcur : Dnext;
;                     Rprev = Rm; Dcur = Dnext;
;                     const int rr = q * 64 + m * 16 + fr, sq = s0 + rr;
;                     const f32x4 g = acc[ai][0][m][n], v = acc[ai][1][m][n];
;                     f32x4 o;
; #pragma unroll
;                     for (int e = 0; e < 4; ++e) { const float z = w0[e] * up[e] + w1[e] * g[e] + w2[e] * dn[e] + bb[e]; o[e] = z * __builtin_amdgcn_rcpf(1.f + __builtin_amdgcn_exp2f(-1.4426950408889634f * z)) * v[e]; }
;                     if (rr >= 1 && rr <= 254) { u32x2 w; w.x = cvt_pk_bf16(o[0], o[1]); w.y = cvt_pk_bf16(o[2], o[3]);
;                         *(u32x2*)(act + (size_t)(sbase + sq) * DFF + j) = w; }
;                     if (rr < 2 || rr > 253) { const int rid = rr < 2 ? rr : rr - 252; *(f32x4*)(sbp + (size_t)rid * DFF + j) = g;
;                         if (rr == 0 || rr == 255) *(f32x4*)(sbp + (size_t)(4 + (rr == 255)) * DFF + j) = v; }
	v_mov_b32_dpp v151, v47 row_ror:1 row_mask:0xf bank_mask:0xf
	v_mov_b32_dpp v152, v48 row_ror:1 row_mask:0xf bank_mask:0xf
	v_mov_b32_dpp v153, v49 row_ror:1 row_mask:0xf bank_mask:0xf
	v_mov_b32_dpp v202, v34 row_ror:15 row_mask:0xf bank_mask:0xf
	v_mov_b32_dpp v203, v35 row_ror:15 row_mask:0xf bank_mask:0xf
	v_mov_b32_dpp v204, v36 row_ror:15 row_mask:0xf bank_mask:0xf
	v_mov_b32_dpp v205, v37 row_ror:15 row_mask:0xf bank_mask:0xf
	v_cndmask_b32_e64 v206, v150, v194, s[8:9]
	v_cndmask_b32_e64 v207, v151, v195, s[8:9]
	v_cndmask_b32_e64 v208, v152, v196, s[8:9]
	v_cndmask_b32_e64 v209, v153, v197, s[8:9]
	v_cndmask_b32_e64 v210, v198, v202, s[10:11]
	v_cndmask_b32_e64 v211, v199, v203, s[10:11]
	v_cndmask_b32_e64 v212, v200, v204, s[10:11]
	v_cndmask_b32_e64 v213, v201, v205, s[10:11]
	v_mul_f32_e32 v46, v126, v46
	v_mul_f32_e32 v47, v127, v47
	v_mul_f32_e32 v48, v128, v48
	v_mul_f32_e32 v49, v129, v49
	v_mul_f32_e32 v210, v130, v210
	v_mul_f32_e32 v211, v131, v211
	v_mul_f32_e32 v212, v132, v212
	v_mul_f32_e32 v213, v133, v213
	v_fmac_f32_e32 v46, v122, v206
	v_fmac_f32_e32 v47, v123, v207
	v_fmac_f32_e32 v48, v124, v208
	v_fmac_f32_e32 v49, v125, v209
	v_add_f32_e32 v46, v210, v46
	v_add_f32_e32 v47, v211, v47
	v_add_f32_e32 v48, v212, v48
	v_add_f32_e32 v49, v213, v49
	v_add_f32_e32 v46, v134, v46
	v_add_f32_e32 v47, v135, v47
	v_add_f32_e32 v48, v136, v48
	v_add_f32_e32 v49, v137, v49
	v_mul_f32_e32 v206, 0xbfb8aa3b, v46
	v_mul_f32_e32 v207, 0xbfb8aa3b, v47
	v_mul_f32_e32 v208, 0xbfb8aa3b, v48
	v_mul_f32_e32 v209, 0xbfb8aa3b, v49
	v_exp_f32_e32 v206, v206
	v_exp_f32_e32 v207, v207
	v_exp_f32_e32 v208, v208
	v_exp_f32_e32 v209, v209
	v_add_f32_e32 v206, 1.0, v206
	v_add_f32_e32 v207, 1.0, v207
	v_add_f32_e32 v208, 1.0, v208
	v_add_f32_e32 v209, 1.0, v209
	v_rcp_f32_e32 v206, v206
	v_rcp_f32_e32 v207, v207
	v_rcp_f32_e32 v208, v208
	v_rcp_f32_e32 v209, v209
	v_mul_f32_e32 v46, v46, v206
	v_mul_f32_e32 v47, v47, v207
	v_mul_f32_e32 v48, v48, v208
	v_mul_f32_e32 v49, v49, v209
	v_mul_f32_e32 v46, v42, v46
	v_mul_f32_e32 v47, v43, v47
	v_mul_f32_e32 v48, v44, v48
	v_mul_f32_e32 v49, v45, v49
	v_cvt_pk_bf16_f32 v210, v46, v47
	v_cvt_pk_bf16_f32 v211, v48, v49
	v_add_u32_e32 v175, 0x2c000, v174
	global_store_dwordx2 v175, v[210:211], s[18:19] offset:8
	v_mov_b32_dpp v194, v34 row_ror:1 row_mask:0xf bank_mask:0xf
	v_mov_b32_dpp v195, v35 row_ror:1 row_mask:0xf bank_mask:0xf
	v_mov_b32_dpp v196, v36 row_ror:1 row_mask:0xf bank_mask:0xf
	v_mov_b32_dpp v197, v37 row_ror:1 row_mask:0xf bank_mask:0xf
	v_cndmask_b32_e64 v206, v194, v150, s[8:9]
	v_cndmask_b32_e64 v207, v195, v151, s[8:9]
	v_cndmask_b32_e64 v208, v196, v152, s[8:9]
	v_cndmask_b32_e64 v209, v197, v153, s[8:9]
	s_waitcnt lgkmcnt(0)
	v_cndmask_b32_e64 v210, v202, v146, s[10:11]
	v_cndmask_b32_e64 v211, v203, v147, s[10:11]
	v_cndmask_b32_e64 v212, v204, v148, s[10:11]
	v_cndmask_b32_e64 v213, v205, v149, s[10:11]
	v_mul_f32_e32 v34, v126, v34
	v_mul_f32_e32 v35, v127, v35
	v_mul_f32_e32 v36, v128, v36
	v_mul_f32_e32 v37, v129, v37
	v_mul_f32_e32 v210, v130, v210
	v_mul_f32_e32 v211, v131, v211
	v_mul_f32_e32 v212, v132, v212
	v_mul_f32_e32 v213, v133, v213
	v_fmac_f32_e32 v34, v122, v206
	v_fmac_f32_e32 v35, v123, v207
	v_fmac_f32_e32 v36, v124, v208
	v_fmac_f32_e32 v37, v125, v209
	v_add_f32_e32 v34, v210, v34
	v_add_f32_e32 v35, v211, v35
	v_add_f32_e32 v36, v212, v36
	v_add_f32_e32 v37, v213, v37
	v_add_f32_e32 v34, v134, v34
	v_add_f32_e32 v35, v135, v35
	v_add_f32_e32 v36, v136, v36
	v_add_f32_e32 v37, v137, v37
	v_mul_f32_e32 v206, 0xbfb8aa3b, v34
	v_mul_f32_e32 v207, 0xbfb8aa3b, v35
	v_mul_f32_e32 v208, 0xbfb8aa3b, v36
	v_mul_f32_e32 v209, 0xbfb8aa3b, v37
	v_exp_f32_e32 v206, v206
	v_exp_f32_e32 v207, v207
	v_exp_f32_e32 v208, v208
	v_exp_f32_e32 v209, v209
	v_add_f32_e32 v206, 1.0, v206
	v_add_f32_e32 v207, 1.0, v207
	v_add_f32_e32 v208, 1.0, v208
	v_add_f32_e32 v209, 1.0, v209
	v_rcp_f32_e32 v206, v206
	v_rcp_f32_e32 v207, v207
	v_rcp_f32_e32 v208, v208
	v_rcp_f32_e32 v209, v209
	v_mul_f32_e32 v34, v34, v206
	v_mul_f32_e32 v35, v35, v207
	v_mul_f32_e32 v36, v36, v208
	v_mul_f32_e32 v37, v37, v209
	v_mul_f32_e32 v34, v38, v34
	v_mul_f32_e32 v35, v39, v35
	v_mul_f32_e32 v36, v40, v36
	v_mul_f32_e32 v37, v41, v37
	v_cvt_pk_bf16_f32 v210, v34, v35
	v_cvt_pk_bf16_f32 v211, v36, v37
	v_add_u32_e32 v175, 0x42000, v174
	global_store_dwordx2 v175, v[210:211], s[18:19] offset:8
	ds_read_b128 v[146:149], v176 offset:1040
	v_mov_b32_dpp v198, v30 row_ror:15 row_mask:0xf bank_mask:0xf
	v_mov_b32_dpp v199, v31 row_ror:15 row_mask:0xf bank_mask:0xf
	v_mov_b32_dpp v200, v32 row_ror:15 row_mask:0xf bank_mask:0xf
	v_mov_b32_dpp v201, v33 row_ror:15 row_mask:0xf bank_mask:0xf
	v_mov_b32_dpp v150, v30 row_ror:1 row_mask:0xf bank_mask:0xf
	v_mov_b32_dpp v151, v31 row_ror:1 row_mask:0xf bank_mask:0xf
	v_mov_b32_dpp v152, v32 row_ror:1 row_mask:0xf bank_mask:0xf
	v_mov_b32_dpp v153, v33 row_ror:1 row_mask:0xf bank_mask:0xf
	v_mov_b32_dpp v202, v22 row_ror:15 row_mask:0xf bank_mask:0xf
	v_mov_b32_dpp v203, v23 row_ror:15 row_mask:0xf bank_mask:0xf
	v_mov_b32_dpp v204, v24 row_ror:15 row_mask:0xf bank_mask:0xf
	v_mov_b32_dpp v205, v25 row_ror:15 row_mask:0xf bank_mask:0xf
	s_waitcnt lgkmcnt(0)
	v_cndmask_b32_e64 v206, v150, v146, s[8:9]
	v_cndmask_b32_e64 v207, v151, v147, s[8:9]
	v_cndmask_b32_e64 v208, v152, v148, s[8:9]
	v_cndmask_b32_e64 v209, v153, v149, s[8:9]
	s_cmp_eq_u32 s7, 0
	s_cbranch_scc0 .LffnA_bz_10
	ds_read_b128 v[146:149], v176 offset:4112
	s_branch .LffnA_bj_11

; #define LAS __attribute__((address_space(3)))
; DEV unsigned cvt_pk_bf16(float lo, float hi) { unsigned r; asm volatile("v_cvt_pk_bf16_f32 %0, %1, %2" : "=v"(r) : "v"(lo), "v"(hi)); return r; }
;     DEV void operator()(const Acc& acc, const Unit& u, int wr, int wc, int fr, int fq, LAS unsigned char* misc) const {
;     ...
;         for (int n = 0; n < 2; ++n) { const int cc = wc * 32 + 8 * fq + 4 * n, j = u.pn * 128 + cc;
;             const f32x4 w0 = *(const f32x4*)(cw + j), w1 = *(const f32x4*)(cw + DFF + j), w2 = *(const f32x4*)(cw + 2 * DFF + j), bb = *(const f32x4*)(cb + j);
; #pragma unroll
;             for (int ai = 0; ai < 2; ++ai) { const int q = 2 * ai + wr;
;                 const f32x4 bup = (q > 0) ? *(LAS f32x4*)(xl + (q - 1) * 128 + cc) : (f32x4){0.f, 0.f, 0.f, 0.f};
;                 const f32x4 bdn = (q < 3) ? *(LAS f32x4*)(xf + (q + 1) * 128 + cc) : (f32x4){0.f, 0.f, 0.f, 0.f};
;                 f32x4 Rprev = bup, Dcur;
; #pragma unroll
;                 for (int e = 0; e < 4; ++e) Dcur[e] = ROR15(acc[ai][0][0][n][e]);
; #pragma unroll
;                 for (int m = 0; m < 4; ++m) {
;                     f32x4 Rm, Dnext = bdn;
; #pragma unroll
;                     for (int e = 0; e < 4; ++e) { Rm[e] = ROR1(acc[ai][0][m][n][e]); if (m < 3) Dnext[e] = ROR15(acc[ai][0][m < 3 ? m + 1 : 3][n][e]); }
;                     const f32x4 up = (fr > 0) ? Rm : Rprev;
;                     const f32x4 dn = (fr < 15) ? Dcur : Dnext;
;                     Rprev = Rm; Dcur = Dnext;
;                     const int rr = q * 64 + m * 16 + fr, sq = s0 + rr;
;                     const f32x4 g = acc[ai][0][m][n], v = acc[ai][1][m][n];
;                     f32x4 o;
; #pragma unroll
;                     for (int e = 0; e < 4; ++e) { const float z = w0[e] * up[e] + w1[e] * g[e] + w2[e] * dn[e] + bb[e]; o[e] = z * __builtin_amdgcn_rcpf(1.f + __builtin_amdgcn_exp2f(-1.4426950408889634f * z)) * v[e]; }
;                     if (rr >= 1 && rr <= 254) { u32x2 w; w.x = cvt_pk_bf16(o[0], o[1]); w.y = cvt_pk_bf16(o[2], o[3]);
;                         *(u32x2*)(act + (size_t)(sbase + sq) * DFF + j) = w; }
;                     if (rr < 2 || rr > 253) { const int rid = rr < 2 ? rr : rr - 252; *(f32x4*)(sbp + (size_t)rid * DFF + j) = g;
;                         if (rr == 0 || rr == 255) *(f32x4*)(sbp + (size_t)(4 + (rr == 255)) * DFF + j) = v; }
.LffnA_bj_11:
	v_cndmask_b32_e64 v210, v198, v202, s[10:11]
	v_cndmask_b32_e64 v211, v199, v203, s[10:11]
	v_cndmask_b32_e64 v212, v200, v204, s[10:11]
	v_cndmask_b32_e64 v213, v201, v205, s[10:11]
	v_mul_f32_e32 v30, v126, v30
	v_mul_f32_e32 v31, v127, v31
	v_mul_f32_e32 v32, v128, v32
	v_mul_f32_e32 v33, v129, v33
	v_mul_f32_e32 v210, v130, v210
	v_mul_f32_e32 v211, v131, v211
	v_mul_f32_e32 v212, v132, v212
	v_mul_f32_e32 v213, v133, v213
	v_fmac_f32_e32 v30, v122, v206
	v_fmac_f32_e32 v31, v123, v207
	v_fmac_f32_e32 v32, v124, v208
	v_fmac_f32_e32 v33, v125, v209
	v_add_f32_e32 v30, v210, v30
	v_add_f32_e32 v31, v211, v31
	v_add_f32_e32 v32, v212, v32
	v_add_f32_e32 v33, v213, v33
	v_add_f32_e32 v30, v134, v30
	v_add_f32_e32 v31, v135, v31
	v_add_f32_e32 v32, v136, v32
	v_add_f32_e32 v33, v137, v33
	v_mul_f32_e32 v206, 0xbfb8aa3b, v30
	v_mul_f32_e32 v207, 0xbfb8aa3b, v31
	v_mul_f32_e32 v208, 0xbfb8aa3b, v32
	v_mul_f32_e32 v209, 0xbfb8aa3b, v33
	v_exp_f32_e32 v206, v206
	v_exp_f32_e32 v207, v207
	v_exp_f32_e32 v208, v208
	v_exp_f32_e32 v209, v209
	v_add_f32_e32 v206, 1.0, v206
	v_add_f32_e32 v207, 1.0, v207
	v_add_f32_e32 v208, 1.0, v208
	v_add_f32_e32 v209, 1.0, v209
	v_rcp_f32_e32 v206, v206
	v_rcp_f32_e32 v207, v207
	v_rcp_f32_e32 v208, v208
	v_rcp_f32_e32 v209, v209
	v_mul_f32_e32 v30, v30, v206
	v_mul_f32_e32 v31, v31, v207
	v_mul_f32_e32 v32, v32, v208
	v_mul_f32_e32 v33, v33, v209
	v_mul_f32_e32 v30, v26, v30
	v_mul_f32_e32 v31, v27, v31
	v_mul_f32_e32 v32, v28, v32
	v_mul_f32_e32 v33, v29, v33
	v_cvt_pk_bf16_f32 v210, v30, v31
	v_cvt_pk_bf16_f32 v211, v32, v33
	v_add_u32_e32 v175, 0xb0000, v174
	global_store_dwordx2 v175, v[210:211], s[18:19] offset:8
	v_mov_b32_dpp v194, v22 row_ror:1 row_mask:0xf bank_mask:0xf
	v_mov_b32_dpp v195, v23 row_ror:1 row_mask:0xf bank_mask:0xf
	v_mov_b32_dpp v196, v24 row_ror:1 row_mask:0xf bank_mask:0xf
	v_mov_b32_dpp v197, v25 row_ror:1 row_mask:0xf bank_mask:0xf
	v_mov_b32_dpp v198, v14 row_ror:15 row_mask:0xf bank_mask:0xf
	v_mov_b32_dpp v199, v15 row_ror:15 row_mask:0xf bank_mask:0xf
	v_mov_b32_dpp v200, v16 row_ror:15 row_mask:0xf bank_mask:0xf
	v_mov_b32_dpp v201, v17 row_ror:15 row_mask:0xf bank_mask:0xf
	v_cndmask_b32_e64 v206, v194, v150, s[8:9]
	v_cndmask_b32_e64 v207, v195, v151, s[8:9]
	v_cndmask_b32_e64 v208, v196, v152, s[8:9]
	v_cndmask_b32_e64 v209, v197, v153, s[8:9]
	v_cndmask_b32_e64 v210, v202, v198, s[10:11]
	v_cndmask_b32_e64 v211, v203, v199, s[10:11]
	v_cndmask_b32_e64 v212, v204, v200, s[10:11]
	v_cndmask_b32_e64 v213, v205, v201, s[10:11]
	v_mul_f32_e32 v22, v126, v22
	v_mul_f32_e32 v23, v127, v23
	v_mul_f32_e32 v24, v128, v24
	v_mul_f32_e32 v25, v129, v25
	v_mul_f32_e32 v210, v130, v210
	v_mul_f32_e32 v211, v131, v211
	v_mul_f32_e32 v212, v132, v212
	v_mul_f32_e32 v213, v133, v213
	v_fmac_f32_e32 v22, v122, v206
	v_fmac_f32_e32 v23, v123, v207
	v_fmac_f32_e32 v24, v124, v208
	v_fmac_f32_e32 v25, v125, v209
	v_add_f32_e32 v22, v210, v22
	v_add_f32_e32 v23, v211, v23
	v_add_f32_e32 v24, v212, v24
	v_add_f32_e32 v25, v213, v25
	v_add_f32_e32 v22, v134, v22
	v_add_f32_e32 v23, v135, v23
	v_add_f32_e32 v24, v136, v24
	v_add_f32_e32 v25, v137, v25
	v_mul_f32_e32 v206, 0xbfb8aa3b, v22
	v_mul_f32_e32 v207, 0xbfb8aa3b, v23
	v_mul_f32_e32 v208, 0xbfb8aa3b, v24
	v_mul_f32_e32 v209, 0xbfb8aa3b, v25
	v_exp_f32_e32 v206, v206
	v_exp_f32_e32 v207, v207
	v_exp_f32_e32 v208, v208
	v_exp_f32_e32 v209, v209
	v_add_f32_e32 v206, 1.0, v206
	v_add_f32_e32 v207, 1.0, v207
	v_add_f32_e32 v208, 1.0, v208
	v_add_f32_e32 v209, 1.0, v209
	v_rcp_f32_e32 v206, v206
	v_rcp_f32_e32 v207, v207
	v_rcp_f32_e32 v208, v208
	v_rcp_f32_e32 v209, v209
	v_mul_f32_e32 v22, v22, v206
	v_mul_f32_e32 v23, v23, v207
	v_mul_f32_e32 v24, v24, v208
	v_mul_f32_e32 v25, v25, v209
	v_mul_f32_e32 v22, v18, v22
	v_mul_f32_e32 v23, v19, v23
	v_mul_f32_e32 v24, v20, v24
	v_mul_f32_e32 v25, v21, v25
	v_cvt_pk_bf16_f32 v210, v22, v23
	v_cvt_pk_bf16_f32 v211, v24, v25
	v_add_u32_e32 v175, 0xc6000, v174
	global_store_dwordx2 v175, v[210:211], s[18:19] offset:8
	v_mov_b32_dpp v150, v14 row_ror:1 row_mask:0xf bank_mask:0xf
	v_mov_b32_dpp v151, v15 row_ror:1 row_mask:0xf bank_mask:0xf
	v_mov_b32_dpp v152, v16 row_ror:1 row_mask:0xf bank_mask:0xf
	v_mov_b32_dpp v153, v17 row_ror:1 row_mask:0xf bank_mask:0xf
	v_mov_b32_dpp v202, v6 row_ror:15 row_mask:0xf bank_mask:0xf
	v_mov_b32_dpp v203, v7 row_ror:15 row_mask:0xf bank_mask:0xf
	v_mov_b32_dpp v204, v8 row_ror:15 row_mask:0xf bank_mask:0xf
	v_mov_b32_dpp v205, v9 row_ror:15 row_mask:0xf bank_mask:0xf
	v_cndmask_b32_e64 v206, v150, v194, s[8:9]
	v_cndmask_b32_e64 v207, v151, v195, s[8:9]
	v_cndmask_b32_e64 v208, v152, v196, s[8:9]
	v_cndmask_b32_e64 v209, v153, v197, s[8:9]
	v_cndmask_b32_e64 v210, v198, v202, s[10:11]
	v_cndmask_b32_e64 v211, v199, v203, s[10:11]
	v_cndmask_b32_e64 v212, v200, v204, s[10:11]
	v_cndmask_b32_e64 v213, v201, v205, s[10:11]
	v_mul_f32_e32 v14, v126, v14
	v_mul_f32_e32 v15, v127, v15
	v_mul_f32_e32 v16, v128, v16
	v_mul_f32_e32 v17, v129, v17
	v_mul_f32_e32 v210, v130, v210
	v_mul_f32_e32 v211, v131, v211
	v_mul_f32_e32 v212, v132, v212
	v_mul_f32_e32 v213, v133, v213
	v_fmac_f32_e32 v14, v122, v206
	v_fmac_f32_e32 v15, v123, v207
	v_fmac_f32_e32 v16, v124, v208
	v_fmac_f32_e32 v17, v125, v209
	v_add_f32_e32 v14, v210, v14
	v_add_f32_e32 v15, v211, v15
	v_add_f32_e32 v16, v212, v16
	v_add_f32_e32 v17, v213, v17
	v_add_f32_e32 v14, v134, v14
	v_add_f32_e32 v15, v135, v15
	v_add_f32_e32 v16, v136, v16
	v_add_f32_e32 v17, v137, v17
	v_mul_f32_e32 v206, 0xbfb8aa3b, v14
	v_mul_f32_e32 v207, 0xbfb8aa3b, v15
	v_mul_f32_e32 v208, 0xbfb8aa3b, v16
	v_mul_f32_e32 v209, 0xbfb8aa3b, v17
	v_exp_f32_e32 v206, v206
	v_exp_f32_e32 v207, v207
	v_exp_f32_e32 v208, v208
	v_exp_f32_e32 v209, v209
	v_add_f32_e32 v206, 1.0, v206
	v_add_f32_e32 v207, 1.0, v207
	v_add_f32_e32 v208, 1.0, v208
	v_add_f32_e32 v209, 1.0, v209
	v_rcp_f32_e32 v206, v206
	v_rcp_f32_e32 v207, v207
	v_rcp_f32_e32 v208, v208
	v_rcp_f32_e32 v209, v209
	v_mul_f32_e32 v14, v14, v206
	v_mul_f32_e32 v15, v15, v207
	v_mul_f32_e32 v16, v16, v208
	v_mul_f32_e32 v17, v17, v209
	v_mul_f32_e32 v14, v10, v14
	v_mul_f32_e32 v15, v11, v15
	v_mul_f32_e32 v16, v12, v16
	v_mul_f32_e32 v17, v13, v17
	v_cvt_pk_bf16_f32 v210, v14, v15
	v_cvt_pk_bf16_f32 v211, v16, v17
	v_add_u32_e32 v175, 0xdc000, v174
	global_store_dwordx2 v175, v[210:211], s[18:19] offset:8
	s_cmp_eq_u32 s7, 1
	s_cbranch_scc0 .LffnA_ns_12
	v_mul_u32_u24_e32 v177, 0x2c00, v172
	v_cmp_lt_u32_e64 s[30:31], 13, v172
	v_add_u32_e32 v177, v177, v173
	v_add_u32_e32 v177, 0xfffdf000, v177
	s_nop 1
	s_mov_b64 exec, s[30:31]
	global_store_dwordx4 v177, v[6:9], s[24:25] offset:16
	s_mov_b64 exec, s[10:11]
	global_store_dwordx4 v177, v[2:5], s[28:29] offset:16
	s_mov_b64 exec, -1
	s_nop 4
; template <class Epi>
; DEV void gemm_phase(LAS unsigned char* lds, const Gemm g, const Sched& S, const Epi& E, const int tid) {
;     ...
;         if (!has_next) break;
; #pragma unroll
;         for (int a = 0; a < 2; ++a)
;     DEV void operator()(const Acc& acc, const Unit& u, int wr, int wc, int fr, int fq, LAS unsigned char* misc) const {
;     ...
;         for (int n = 0; n < 2; ++n) { const int cc = wc * 32 + 8 * fq + 4 * n, j = u.pn * 128 + cc;
;             const f32x4 w0 = *(const f32x4*)(cw + j), w1 = *(const f32x4*)(cw + DFF + j), w2 = *(const f32x4*)(cw + 2 * DFF + j), bb = *(const f32x4*)(cb + j);
; #pragma unroll
;             for (int ai = 0; ai < 2; ++ai) { const int q = 2 * ai + wr;
;                 const f32x4 bup = (q > 0) ? *(LAS f32x4*)(xl + (q - 1) * 128 + cc) : (f32x4){0.f, 0.f, 0.f, 0.f};
;                 const f32x4 bdn = (q < 3) ? *(LAS f32x4*)(xf + (q + 1) * 128 + cc) : (f32x4){0.f, 0.f, 0.f, 0.f};
;                 f32x4 Rprev = bup, Dcur;
; #pragma unroll
;                 for (int e = 0; e < 4; ++e) Dcur[e] = ROR15(acc[ai][0][0][n][e]);
; #pragma unroll
;                 for (int m = 0; m < 4; ++m) {
;                     f32x4 Rm, Dnext = bdn;
; #pragma unroll
;                     for (int e = 0; e < 4; ++e) { Rm[e] = ROR1(acc[ai][0][m][n][e]); if (m < 3) Dnext[e] = ROR15(acc[ai][0][m < 3 ? m + 1 : 3][n][e]); }
;                     const f32x4 up = (fr > 0) ? Rm : Rprev;
;                     const f32x4 dn = (fr < 15) ? Dcur : Dnext;
;                     Rprev = Rm; Dcur = Dnext;
;                     const int rr = q * 64 + m * 16 + fr, sq = s0 + rr;
;                     const f32x4 g = acc[ai][0][m][n], v = acc[ai][1][m][n];
;                     f32x4 o;
; #pragma unroll
;                     for (int e = 0; e < 4; ++e) { const float z = w0[e] * up[e] + w1[e] * g[e] + w2[e] * dn[e] + bb[e]; o[e] = z * __builtin_amdgcn_rcpf(1.f + __builtin_amdgcn_exp2f(-1.4426950408889634f * z)) * v[e]; }
;                     if (rr >= 1 && rr <= 254) { u32x2 w; w.x = cvt_pk_bf16(o[0], o[1]); w.y = cvt_pk_bf16(o[2], o[3]);
;                         *(u32x2*)(act + (size_t)(sbase + sq) * DFF + j) = w; }
;                     if (rr < 2 || rr > 253) { const int rid = rr < 2 ? rr : rr - 252; *(f32x4*)(sbp + (size_t)rid * DFF + j) = g;
;                         if (rr == 0 || rr == 255) *(f32x4*)(sbp + (size_t)(4 + (rr == 255)) * DFF + j) = v; }
.LffnA_ns_12:
	v_mov_b32_dpp v194, v6 row_ror:1 row_mask:0xf bank_mask:0xf
	v_mov_b32_dpp v195, v7 row_ror:1 row_mask:0xf bank_mask:0xf
	v_mov_b32_dpp v196, v8 row_ror:1 row_mask:0xf bank_mask:0xf
	v_mov_b32_dpp v197, v9 row_ror:1 row_mask:0xf bank_mask:0xf
	v_cndmask_b32_e64 v206, v194, v150, s[8:9]
	v_cndmask_b32_e64 v207, v195, v151, s[8:9]
	v_cndmask_b32_e64 v208, v196, v152, s[8:9]
	v_cndmask_b32_e64 v209, v197, v153, s[8:9]
	s_waitcnt lgkmcnt(0)
	v_cndmask_b32_e64 v210, v202, v146, s[10:11]
	v_cndmask_b32_e64 v211, v203, v147, s[10:11]
	v_cndmask_b32_e64 v212, v204, v148, s[10:11]
	v_cndmask_b32_e64 v213, v205, v149, s[10:11]
	v_mul_f32_e32 v6, v126, v6
	v_mul_f32_e32 v7, v127, v7
	v_mul_f32_e32 v8, v128, v8
	v_mul_f32_e32 v9, v129, v9
	v_mul_f32_e32 v210, v130, v210
	v_mul_f32_e32 v211, v131, v211
	v_mul_f32_e32 v212, v132, v212
	v_mul_f32_e32 v213, v133, v213
	v_fmac_f32_e32 v6, v122, v206
	v_fmac_f32_e32 v7, v123, v207
	v_fmac_f32_e32 v8, v124, v208
	v_fmac_f32_e32 v9, v125, v209
	v_add_f32_e32 v6, v210, v6
	v_add_f32_e32 v7, v211, v7
	v_add_f32_e32 v8, v212, v8
	v_add_f32_e32 v9, v213, v9
	v_add_f32_e32 v6, v134, v6
	v_add_f32_e32 v7, v135, v7
	v_add_f32_e32 v8, v136, v8
	v_add_f32_e32 v9, v137, v9
	v_mul_f32_e32 v206, 0xbfb8aa3b, v6
	v_mul_f32_e32 v207, 0xbfb8aa3b, v7
	v_mul_f32_e32 v208, 0xbfb8aa3b, v8
	v_mul_f32_e32 v209, 0xbfb8aa3b, v9
	v_exp_f32_e32 v206, v206
	v_exp_f32_e32 v207, v207
	v_exp_f32_e32 v208, v208
	v_exp_f32_e32 v209, v209
	v_add_f32_e32 v206, 1.0, v206
	v_add_f32_e32 v207, 1.0, v207
	v_add_f32_e32 v208, 1.0, v208
	v_add_f32_e32 v209, 1.0, v209
	v_rcp_f32_e32 v206, v206
	v_rcp_f32_e32 v207, v207
	v_rcp_f32_e32 v208, v208
	v_rcp_f32_e32 v209, v209
	v_mul_f32_e32 v6, v6, v206
	v_mul_f32_e32 v7, v7, v207
	v_mul_f32_e32 v8, v8, v208
	v_mul_f32_e32 v9, v9, v209
	v_mul_f32_e32 v6, v2, v6
	v_mul_f32_e32 v7, v3, v7
	v_mul_f32_e32 v8, v4, v8
	v_mul_f32_e32 v9, v5, v9
	v_cvt_pk_bf16_f32 v210, v6, v7
	v_cvt_pk_bf16_f32 v211, v8, v9
	v_add_u32_e32 v175, 0xf2000, v174
	s_mov_b64 exec, s[16:17]
	global_store_dwordx2 v175, v[210:211], s[18:19] offset:8
	s_mov_b64 exec, -1
	s_nop 4
	s_and_b64 vcc, exec, s[2:3]
	s_mov_b64 s[2:3], -1
	s_cbranch_vccnz .LBB0_284
	v_readlane_b32 s2, v249, 51
	v_readlane_b32 s3, v249, 52
	s_andn2_b64 vcc, exec, s[2:3]
	s_cbranch_vccnz .LBB0_283
	s_barrier
	s_branch .LBB0_283

; #define LAS __attribute__((address_space(3)))
;     DEV void operator()(const Acc& acc, const Unit& u, int wr, int wc, int fr, int fq, LAS unsigned char* misc) const {
;     ...
;         const int lane = fq * 16 + fr;
;         const int sbase = u.pm * 256, s0 = 0;
;         float* sbp = sb + (size_t)u.pm * 6 * DFF;
;         LAS float* xl = (LAS float*)misc;
;         LAS float* xf = xl + 512;
; #pragma unroll
;         for (int ai = 0; ai < 2; ++ai) { const int q = 2 * ai + wr;
; #pragma unroll
;             for (int n = 0; n < 2; ++n) { const int cc = wc * 32 + 8 * fq + 4 * n;
;                 if (fr == 15) *(LAS f32x4*)(xl + q * 128 + cc) = acc[ai][0][3][n];
;                 if (fr == 0) *(LAS f32x4*)(xf + q * 128 + cc) = acc[ai][0][0][n]; } }
;         asm volatile("s_waitcnt lgkmcnt(0)" ::: "memory"); __builtin_amdgcn_s_barrier(); asm volatile("" ::: "memory");
;     ...
; #pragma unroll
;         for (int n = 0; n < 2; ++n) { const int cc = wc * 32 + 8 * fq + 4 * n, j = u.pn * 128 + cc;
;             const f32x4 w0 = *(const f32x4*)(cw + j), w1 = *(const f32x4*)(cw + DFF + j), w2 = *(const f32x4*)(cw + 2 * DFF + j), bb = *(const f32x4*)(cb + j);
.LBB0_1763:
	v_mbcnt_lo_u32_b32 v178, -1, 0
	v_mbcnt_hi_u32_b32 v178, -1, v178
	v_readlane_b32 s4, v251, 4
	v_and_b32_e32 v166, 15, v178
	v_lshrrev_b32_e32 v178, 4, v178
	s_lshr_b32 s4, s4, 6
	s_lshr_b32 s7, s4, 2
	s_and_b32 s4, s4, 3
	s_lshl_b32 s4, s4, 5
	v_lshl_add_u32 v178, v178, 3, s4
	s_lshl_b32 s5, s6, 7
	v_add_u32_e32 v167, s5, v178
	v_lshlrev_b32_e32 v167, 2, v167
	s_lshl_b32 s5, s7, 9
	s_add_u32 s5, s5, 0x1fe00
	v_lshl_add_u32 v170, v178, 2, s5
	v_cmp_eq_u32_e64 s[8:9], 0, v166
	v_cmp_eq_u32_e64 s[10:11], 15, v166
	s_add_u32 s20, s54, 0x2c00
	s_addc_u32 s21, s55, 0
	s_add_u32 s22, s54, 0x5800
	s_addc_u32 s23, s55, 0
	global_load_dwordx4 v[106:109], v167, s[54:55]
	global_load_dwordx4 v[110:113], v167, s[20:21]
	global_load_dwordx4 v[114:117], v167, s[22:23]
	global_load_dwordx4 v[118:121], v167, s[50:51]
	s_lshl_b32 s4, s14, 8
	s_lshl_b32 s5, s7, 6
	s_add_u32 s4, s4, s5
	v_add_u32_e32 v168, s4, v166
	v_mul_u32_u24_e32 v168, 0x1600, v168
	v_lshrrev_b32_e32 v179, 1, v167
	v_add_u32_e32 v168, v168, v179
	s_mul_i32 s4, s14, 0x10800
	s_add_u32 s24, s68, s4
	s_addc_u32 s25, s69, 0
	s_add_u32 s26, s24, 0xb000
	s_addc_u32 s27, s25, 0
	s_add_u32 s28, s24, 0x5800
	s_addc_u32 s29, s25, 0
	s_mov_b64 s[18:19], s[74:75]
	s_not_b64 s[12:13], s[8:9]
	s_not_b64 s[16:17], s[10:11]
	s_cmp_eq_u32 s7, 0
	s_cselect_b64 s[12:13], s[12:13], -1
	s_cmp_eq_u32 s7, 1
	s_cselect_b64 s[16:17], s[16:17], -1
	s_mov_b64 exec, s[10:11]
	ds_write_b128 v170, v[98:101] offset:512
	ds_write_b128 v170, v[32:35] offset:528
	ds_write_b128 v170, v[68:71] offset:1536
	ds_write_b128 v170, v[4:7] offset:1552
	s_mov_b64 exec, s[8:9]
	ds_write_b128 v170, v[138:141] offset:2560
	ds_write_b128 v170, v[56:59] offset:2576
	ds_write_b128 v170, v[92:95] offset:3584
	ds_write_b128 v170, v[28:31] offset:3600
	s_mov_b64 exec, -1
	s_waitcnt lgkmcnt(0)
	s_barrier
	s_cmp_eq_u32 s7, 0
	s_cbranch_scc1 .LffnB_bz_1
	ds_read_b128 v[146:149], v170 offset:0
	s_branch .LffnB_bj_2

; #define LAS __attribute__((address_space(3)))
; DEV unsigned cvt_pk_bf16(float lo, float hi) { unsigned r; asm volatile("v_cvt_pk_bf16_f32 %0, %1, %2" : "=v"(r) : "v"(lo), "v"(hi)); return r; }
;     DEV void operator()(const Acc& acc, const Unit& u, int wr, int wc, int fr, int fq, LAS unsigned char* misc) const {
;     ...
;         for (int n = 0; n < 2; ++n) { const int cc = wc * 32 + 8 * fq + 4 * n, j = u.pn * 128 + cc;
;             const f32x4 w0 = *(const f32x4*)(cw + j), w1 = *(const f32x4*)(cw + DFF + j), w2 = *(const f32x4*)(cw + 2 * DFF + j), bb = *(const f32x4*)(cb + j);
; #pragma unroll
;             for (int ai = 0; ai < 2; ++ai) { const int q = 2 * ai + wr;
;                 const f32x4 bup = (q > 0) ? *(LAS f32x4*)(xl + (q - 1) * 128 + cc) : (f32x4){0.f, 0.f, 0.f, 0.f};
;                 const f32x4 bdn = (q < 3) ? *(LAS f32x4*)(xf + (q + 1) * 128 + cc) : (f32x4){0.f, 0.f, 0.f, 0.f};
;                 f32x4 Rprev = bup, Dcur;
; #pragma unroll
;                 for (int e = 0; e < 4; ++e) Dcur[e] = ROR15(acc[ai][0][0][n][e]);
; #pragma unroll
;                 for (int m = 0; m < 4; ++m) {
;                     f32x4 Rm, Dnext = bdn;
; #pragma unroll
;                     for (int e = 0; e < 4; ++e) { Rm[e] = ROR1(acc[ai][0][m][n][e]); if (m < 3) Dnext[e] = ROR15(acc[ai][0][m < 3 ? m + 1 : 3][n][e]); }
;                     const f32x4 up = (fr > 0) ? Rm : Rprev;
;                     const f32x4 dn = (fr < 15) ? Dcur : Dnext;
;                     Rprev = Rm; Dcur = Dnext;
;                     const int rr = q * 64 + m * 16 + fr, sq = s0 + rr;
;                     const f32x4 g = acc[ai][0][m][n], v = acc[ai][1][m][n];
;                     f32x4 o;
; #pragma unroll
;                     for (int e = 0; e < 4; ++e) { const float z = w0[e] * up[e] + w1[e] * g[e] + w2[e] * dn[e] + bb[e]; o[e] = z * __builtin_amdgcn_rcpf(1.f + __builtin_amdgcn_exp2f(-1.4426950408889634f * z)) * v[e]; }
;                     if (rr >= 1 && rr <= 254) { u32x2 w; w.x = cvt_pk_bf16(o[0], o[1]); w.y = cvt_pk_bf16(o[2], o[3]);
;                         *(u32x2*)(act + (size_t)(sbase + sq) * DFF + j) = w; }
;                     if (rr < 2 || rr > 253) { const int rid = rr < 2 ? rr : rr - 252; *(f32x4*)(sbp + (size_t)rid * DFF + j) = g;
;                         if (rr == 0 || rr == 255) *(f32x4*)(sbp + (size_t)(4 + (rr == 255)) * DFF + j) = v; }
.LffnB_bj_2:
	v_mov_b32_dpp v194, v138 row_ror:15 row_mask:0xf bank_mask:0xf
	v_mov_b32_dpp v195, v139 row_ror:15 row_mask:0xf bank_mask:0xf
	v_mov_b32_dpp v196, v140 row_ror:15 row_mask:0xf bank_mask:0xf
	v_mov_b32_dpp v197, v141 row_ror:15 row_mask:0xf bank_mask:0xf
	s_waitcnt vmcnt(0)
	s_cmp_eq_u32 s7, 0
	s_cbranch_scc0 .LffnB_ns_3
	v_mul_u32_u24_e32 v171, 0x2c00, v166
	v_cmp_gt_u32_e64 s[30:31], 2, v166
	v_add_u32_e32 v171, v171, v167
	s_nop 1
	s_mov_b64 exec, s[30:31]
	global_store_dwordx4 v171, v[138:141], s[24:25]
	s_mov_b64 exec, s[8:9]
	global_store_dwordx4 v171, v[142:145], s[26:27]
	s_mov_b64 exec, -1
	s_nop 4
.LffnB_ns_3:
	v_mov_b32_dpp v150, v138 row_ror:1 row_mask:0xf bank_mask:0xf
	v_mov_b32_dpp v151, v139 row_ror:1 row_mask:0xf bank_mask:0xf
	v_mov_b32_dpp v152, v140 row_ror:1 row_mask:0xf bank_mask:0xf
	v_mov_b32_dpp v153, v141 row_ror:1 row_mask:0xf bank_mask:0xf
	v_mov_b32_dpp v198, v134 row_ror:15 row_mask:0xf bank_mask:0xf
	v_mov_b32_dpp v199, v135 row_ror:15 row_mask:0xf bank_mask:0xf
	v_mov_b32_dpp v200, v136 row_ror:15 row_mask:0xf bank_mask:0xf
	v_mov_b32_dpp v201, v137 row_ror:15 row_mask:0xf bank_mask:0xf
	s_waitcnt lgkmcnt(0)
	v_cndmask_b32_e64 v202, v150, v146, s[8:9]
	v_cndmask_b32_e64 v203, v151, v147, s[8:9]
	v_cndmask_b32_e64 v204, v152, v148, s[8:9]
	v_cndmask_b32_e64 v205, v153, v149, s[8:9]
	ds_read_b128 v[146:149], v170 offset:3072
	v_cndmask_b32_e64 v206, v194, v198, s[10:11]
	v_cndmask_b32_e64 v207, v195, v199, s[10:11]
	v_cndmask_b32_e64 v208, v196, v200, s[10:11]
	v_cndmask_b32_e64 v209, v197, v201, s[10:11]
	v_mul_f32_e32 v138, v110, v138
	v_mul_f32_e32 v139, v111, v139
	v_mul_f32_e32 v140, v112, v140
	v_mul_f32_e32 v141, v113, v141
	v_mul_f32_e32 v206, v114, v206
	v_mul_f32_e32 v207, v115, v207
	v_mul_f32_e32 v208, v116, v208
	v_mul_f32_e32 v209, v117, v209
	v_fmac_f32_e32 v138, v106, v202
	v_fmac_f32_e32 v139, v107, v203
	v_fmac_f32_e32 v140, v108, v204
	v_fmac_f32_e32 v141, v109, v205
	v_add_f32_e32 v138, v206, v138
	v_add_f32_e32 v139, v207, v139
	v_add_f32_e32 v140, v208, v140
	v_add_f32_e32 v141, v209, v141
	v_add_f32_e32 v138, v118, v138
	v_add_f32_e32 v139, v119, v139
	v_add_f32_e32 v140, v120, v140
	v_add_f32_e32 v141, v121, v141
	v_mul_f32_e32 v202, 0xbfb8aa3b, v138
	v_mul_f32_e32 v203, 0xbfb8aa3b, v139
	v_mul_f32_e32 v204, 0xbfb8aa3b, v140
	v_mul_f32_e32 v205, 0xbfb8aa3b, v141
	v_exp_f32_e32 v202, v202
	v_exp_f32_e32 v203, v203
	v_exp_f32_e32 v204, v204
	v_exp_f32_e32 v205, v205
	v_add_f32_e32 v202, 1.0, v202
	v_add_f32_e32 v203, 1.0, v203
	v_add_f32_e32 v204, 1.0, v204
	v_add_f32_e32 v205, 1.0, v205
	v_rcp_f32_e32 v202, v202
	v_rcp_f32_e32 v203, v203
	v_rcp_f32_e32 v204, v204
	v_rcp_f32_e32 v205, v205
	v_mul_f32_e32 v138, v138, v202
	v_mul_f32_e32 v139, v139, v203
	v_mul_f32_e32 v140, v140, v204
	v_mul_f32_e32 v141, v141, v205
	v_mul_f32_e32 v138, v142, v138
	v_mul_f32_e32 v139, v143, v139
	v_mul_f32_e32 v140, v144, v140
	v_mul_f32_e32 v141, v145, v141
	v_cvt_pk_bf16_f32 v206, v138, v139
	v_cvt_pk_bf16_f32 v207, v140, v141
	v_add_u32_e32 v169, 0x0, v168
	s_mov_b64 exec, s[12:13]
	global_store_dwordx2 v169, v[206:207], s[18:19]
	s_mov_b64 exec, -1
	s_nop 4
	v_mov_b32_dpp v190, v134 row_ror:1 row_mask:0xf bank_mask:0xf
	v_mov_b32_dpp v191, v135 row_ror:1 row_mask:0xf bank_mask:0xf
	v_mov_b32_dpp v192, v136 row_ror:1 row_mask:0xf bank_mask:0xf
	v_mov_b32_dpp v193, v137 row_ror:1 row_mask:0xf bank_mask:0xf
	v_mov_b32_dpp v194, v126 row_ror:15 row_mask:0xf bank_mask:0xf
	v_mov_b32_dpp v195, v127 row_ror:15 row_mask:0xf bank_mask:0xf
	v_mov_b32_dpp v196, v128 row_ror:15 row_mask:0xf bank_mask:0xf
	v_mov_b32_dpp v197, v129 row_ror:15 row_mask:0xf bank_mask:0xf
	v_cndmask_b32_e64 v202, v190, v150, s[8:9]
	v_cndmask_b32_e64 v203, v191, v151, s[8:9]
	v_cndmask_b32_e64 v204, v192, v152, s[8:9]
	v_cndmask_b32_e64 v205, v193, v153, s[8:9]
	v_cndmask_b32_e64 v206, v198, v194, s[10:11]
	v_cndmask_b32_e64 v207, v199, v195, s[10:11]
	v_cndmask_b32_e64 v208, v200, v196, s[10:11]
	v_cndmask_b32_e64 v209, v201, v197, s[10:11]
	v_mul_f32_e32 v134, v110, v134
	v_mul_f32_e32 v135, v111, v135
	v_mul_f32_e32 v136, v112, v136
	v_mul_f32_e32 v137, v113, v137
	v_mul_f32_e32 v206, v114, v206
	v_mul_f32_e32 v207, v115, v207
	v_mul_f32_e32 v208, v116, v208
	v_mul_f32_e32 v209, v117, v209
	v_fmac_f32_e32 v134, v106, v202
	v_fmac_f32_e32 v135, v107, v203
	v_fmac_f32_e32 v136, v108, v204
	v_fmac_f32_e32 v137, v109, v205
	v_add_f32_e32 v134, v206, v134
	v_add_f32_e32 v135, v207, v135
	v_add_f32_e32 v136, v208, v136
	v_add_f32_e32 v137, v209, v137
	v_add_f32_e32 v134, v118, v134
	v_add_f32_e32 v135, v119, v135
	v_add_f32_e32 v136, v120, v136
	v_add_f32_e32 v137, v121, v137
	v_mul_f32_e32 v202, 0xbfb8aa3b, v134
	v_mul_f32_e32 v203, 0xbfb8aa3b, v135
	v_mul_f32_e32 v204, 0xbfb8aa3b, v136
	v_mul_f32_e32 v205, 0xbfb8aa3b, v137
	v_exp_f32_e32 v202, v202
	v_exp_f32_e32 v203, v203
	v_exp_f32_e32 v204, v204
	v_exp_f32_e32 v205, v205
	v_add_f32_e32 v202, 1.0, v202
	v_add_f32_e32 v203, 1.0, v203
	v_add_f32_e32 v204, 1.0, v204
	v_add_f32_e32 v205, 1.0, v205
	v_rcp_f32_e32 v202, v202
	v_rcp_f32_e32 v203, v203
	v_rcp_f32_e32 v204, v204
	v_rcp_f32_e32 v205, v205
	v_mul_f32_e32 v134, v134, v202
	v_mul_f32_e32 v135, v135, v203
	v_mul_f32_e32 v136, v136, v204
	v_mul_f32_e32 v137, v137, v205
	v_mul_f32_e32 v134, v130, v134
	v_mul_f32_e32 v135, v131, v135
	v_mul_f32_e32 v136, v132, v136
	v_mul_f32_e32 v137, v133, v137
	v_cvt_pk_bf16_f32 v206, v134, v135
	v_cvt_pk_bf16_f32 v207, v136, v137
	v_add_u32_e32 v169, 0x16000, v168
	global_store_dwordx2 v169, v[206:207], s[18:19]
	v_mov_b32_dpp v150, v126 row_ror:1 row_mask:0xf bank_mask:0xf
; #define LAS __attribute__((address_space(3)))
; DEV unsigned cvt_pk_bf16(float lo, float hi) { unsigned r; asm volatile("v_cvt_pk_bf16_f32 %0, %1, %2" : "=v"(r) : "v"(lo), "v"(hi)); return r; }
;     DEV void operator()(const Acc& acc, const Unit& u, int wr, int wc, int fr, int fq, LAS unsigned char* misc) const {
;     ...
;         for (int n = 0; n < 2; ++n) { const int cc = wc * 32 + 8 * fq + 4 * n, j = u.pn * 128 + cc;
;             const f32x4 w0 = *(const f32x4*)(cw + j), w1 = *(const f32x4*)(cw + DFF + j), w2 = *(const f32x4*)(cw + 2 * DFF + j), bb = *(const f32x4*)(cb + j);
; #pragma unroll
;             for (int ai = 0; ai < 2; ++ai) { const int q = 2 * ai + wr;
;                 const f32x4 bup = (q > 0) ? *(LAS f32x4*)(xl + (q - 1) * 128 + cc) : (f32x4){0.f, 0.f, 0.f, 0.f};
;                 const f32x4 bdn = (q < 3) ? *(LAS f32x4*)(xf + (q + 1) * 128 + cc) : (f32x4){0.f, 0.f, 0.f, 0.f};
;                 f32x4 Rprev = bup, Dcur;
; #pragma unroll
;                 for (int e = 0; e < 4; ++e) Dcur[e] = ROR15(acc[ai][0][0][n][e]);
; #pragma unroll
;                 for (int m = 0; m < 4; ++m) {
;                     f32x4 Rm, Dnext = bdn;
; #pragma unroll
;                     for (int e = 0; e < 4; ++e) { Rm[e] = ROR1(acc[ai][0][m][n][e]); if (m < 3) Dnext[e] = ROR15(acc[ai][0][m < 3 ? m + 1 : 3][n][e]); }
;                     const f32x4 up = (fr > 0) ? Rm : Rprev;
;                     const f32x4 dn = (fr < 15) ? Dcur : Dnext;
;                     Rprev = Rm; Dcur = Dnext;
;                     const int rr = q * 64 + m * 16 + fr, sq = s0 + rr;
;                     const f32x4 g = acc[ai][0][m][n], v = acc[ai][1][m][n];
;                     f32x4 o;
; #pragma unroll
;                     for (int e = 0; e < 4; ++e) { const float z = w0[e] * up[e] + w1[e] * g[e] + w2[e] * dn[e] + bb[e]; o[e] = z * __builtin_amdgcn_rcpf(1.f + __builtin_amdgcn_exp2f(-1.4426950408889634f * z)) * v[e]; }
;                     if (rr >= 1 && rr <= 254) { u32x2 w; w.x = cvt_pk_bf16(o[0], o[1]); w.y = cvt_pk_bf16(o[2], o[3]);
;                         *(u32x2*)(act + (size_t)(sbase + sq) * DFF + j) = w; }
;                     if (rr < 2 || rr > 253) { const int rid = rr < 2 ? rr : rr - 252; *(f32x4*)(sbp + (size_t)rid * DFF + j) = g;
;                         if (rr == 0 || rr == 255) *(f32x4*)(sbp + (size_t)(4 + (rr == 255)) * DFF + j) = v; }
	v_mov_b32_dpp v151, v127 row_ror:1 row_mask:0xf bank_mask:0xf
	v_mov_b32_dpp v152, v128 row_ror:1 row_mask:0xf bank_mask:0xf
	v_mov_b32_dpp v153, v129 row_ror:1 row_mask:0xf bank_mask:0xf
	v_mov_b32_dpp v198, v98 row_ror:15 row_mask:0xf bank_mask:0xf
	v_mov_b32_dpp v199, v99 row_ror:15 row_mask:0xf bank_mask:0xf
	v_mov_b32_dpp v200, v100 row_ror:15 row_mask:0xf bank_mask:0xf
	v_mov_b32_dpp v201, v101 row_ror:15 row_mask:0xf bank_mask:0xf
	v_cndmask_b32_e64 v202, v150, v190, s[8:9]
	v_cndmask_b32_e64 v203, v151, v191, s[8:9]
	v_cndmask_b32_e64 v204, v152, v192, s[8:9]
	v_cndmask_b32_e64 v205, v153, v193, s[8:9]
	v_cndmask_b32_e64 v206, v194, v198, s[10:11]
	v_cndmask_b32_e64 v207, v195, v199, s[10:11]
	v_cndmask_b32_e64 v208, v196, v200, s[10:11]
	v_cndmask_b32_e64 v209, v197, v201, s[10:11]
	v_mul_f32_e32 v126, v110, v126
	v_mul_f32_e32 v127, v111, v127
	v_mul_f32_e32 v128, v112, v128
	v_mul_f32_e32 v129, v113, v129
	v_mul_f32_e32 v206, v114, v206
	v_mul_f32_e32 v207, v115, v207
	v_mul_f32_e32 v208, v116, v208
	v_mul_f32_e32 v209, v117, v209
	v_fmac_f32_e32 v126, v106, v202
	v_fmac_f32_e32 v127, v107, v203
	v_fmac_f32_e32 v128, v108, v204
	v_fmac_f32_e32 v129, v109, v205
	v_add_f32_e32 v126, v206, v126
	v_add_f32_e32 v127, v207, v127
	v_add_f32_e32 v128, v208, v128
	v_add_f32_e32 v129, v209, v129
	v_add_f32_e32 v126, v118, v126
	v_add_f32_e32 v127, v119, v127
	v_add_f32_e32 v128, v120, v128
	v_add_f32_e32 v129, v121, v129
	v_mul_f32_e32 v202, 0xbfb8aa3b, v126
	v_mul_f32_e32 v203, 0xbfb8aa3b, v127
	v_mul_f32_e32 v204, 0xbfb8aa3b, v128
	v_mul_f32_e32 v205, 0xbfb8aa3b, v129
	v_exp_f32_e32 v202, v202
	v_exp_f32_e32 v203, v203
	v_exp_f32_e32 v204, v204
	v_exp_f32_e32 v205, v205
	v_add_f32_e32 v202, 1.0, v202
	v_add_f32_e32 v203, 1.0, v203
	v_add_f32_e32 v204, 1.0, v204
	v_add_f32_e32 v205, 1.0, v205
	v_rcp_f32_e32 v202, v202
	v_rcp_f32_e32 v203, v203
	v_rcp_f32_e32 v204, v204
	v_rcp_f32_e32 v205, v205
	v_mul_f32_e32 v126, v126, v202
	v_mul_f32_e32 v127, v127, v203
	v_mul_f32_e32 v128, v128, v204
	v_mul_f32_e32 v129, v129, v205
	v_mul_f32_e32 v126, v122, v126
	v_mul_f32_e32 v127, v123, v127
	v_mul_f32_e32 v128, v124, v128
	v_mul_f32_e32 v129, v125, v129
	v_cvt_pk_bf16_f32 v206, v126, v127
	v_cvt_pk_bf16_f32 v207, v128, v129
	v_add_u32_e32 v169, 0x2c000, v168
	global_store_dwordx2 v169, v[206:207], s[18:19]
	v_mov_b32_dpp v190, v98 row_ror:1 row_mask:0xf bank_mask:0xf
	v_mov_b32_dpp v191, v99 row_ror:1 row_mask:0xf bank_mask:0xf
	v_mov_b32_dpp v192, v100 row_ror:1 row_mask:0xf bank_mask:0xf
	v_mov_b32_dpp v193, v101 row_ror:1 row_mask:0xf bank_mask:0xf
	v_cndmask_b32_e64 v202, v190, v150, s[8:9]
	v_cndmask_b32_e64 v203, v191, v151, s[8:9]
	v_cndmask_b32_e64 v204, v192, v152, s[8:9]
	v_cndmask_b32_e64 v205, v193, v153, s[8:9]
	s_waitcnt lgkmcnt(0)
	v_cndmask_b32_e64 v206, v198, v146, s[10:11]
	v_cndmask_b32_e64 v207, v199, v147, s[10:11]
	v_cndmask_b32_e64 v208, v200, v148, s[10:11]
	v_cndmask_b32_e64 v209, v201, v149, s[10:11]
	v_mul_f32_e32 v98, v110, v98
	v_mul_f32_e32 v99, v111, v99
	v_mul_f32_e32 v100, v112, v100
	v_mul_f32_e32 v101, v113, v101
	v_mul_f32_e32 v206, v114, v206
	v_mul_f32_e32 v207, v115, v207
	v_mul_f32_e32 v208, v116, v208
	v_mul_f32_e32 v209, v117, v209
	v_fmac_f32_e32 v98, v106, v202
	v_fmac_f32_e32 v99, v107, v203
	v_fmac_f32_e32 v100, v108, v204
	v_fmac_f32_e32 v101, v109, v205
	v_add_f32_e32 v98, v206, v98
	v_add_f32_e32 v99, v207, v99
	v_add_f32_e32 v100, v208, v100
	v_add_f32_e32 v101, v209, v101
	v_add_f32_e32 v98, v118, v98
	v_add_f32_e32 v99, v119, v99
	v_add_f32_e32 v100, v120, v100
	v_add_f32_e32 v101, v121, v101
	v_mul_f32_e32 v202, 0xbfb8aa3b, v98
	v_mul_f32_e32 v203, 0xbfb8aa3b, v99
	v_mul_f32_e32 v204, 0xbfb8aa3b, v100
	v_mul_f32_e32 v205, 0xbfb8aa3b, v101
	v_exp_f32_e32 v202, v202
	v_exp_f32_e32 v203, v203
	v_exp_f32_e32 v204, v204
	v_exp_f32_e32 v205, v205
	v_add_f32_e32 v202, 1.0, v202
	v_add_f32_e32 v203, 1.0, v203
	v_add_f32_e32 v204, 1.0, v204
	v_add_f32_e32 v205, 1.0, v205
	v_rcp_f32_e32 v202, v202
	v_rcp_f32_e32 v203, v203
	v_rcp_f32_e32 v204, v204
	v_rcp_f32_e32 v205, v205
	v_mul_f32_e32 v98, v98, v202
	v_mul_f32_e32 v99, v99, v203
	v_mul_f32_e32 v100, v100, v204
	v_mul_f32_e32 v101, v101, v205
	v_mul_f32_e32 v98, v102, v98
	v_mul_f32_e32 v99, v103, v99
	v_mul_f32_e32 v100, v104, v100
	v_mul_f32_e32 v101, v105, v101
	v_cvt_pk_bf16_f32 v206, v98, v99
	v_cvt_pk_bf16_f32 v207, v100, v101
	v_add_u32_e32 v169, 0x42000, v168
	global_store_dwordx2 v169, v[206:207], s[18:19]
	global_load_dwordx4 v[122:125], v167, s[54:55] offset:16
	global_load_dwordx4 v[126:129], v167, s[20:21] offset:16
	global_load_dwordx4 v[130:133], v167, s[22:23] offset:16
	global_load_dwordx4 v[134:137], v167, s[50:51] offset:16
	ds_read_b128 v[146:149], v170 offset:1024
	v_mov_b32_dpp v194, v92 row_ror:15 row_mask:0xf bank_mask:0xf
	v_mov_b32_dpp v195, v93 row_ror:15 row_mask:0xf bank_mask:0xf
	v_mov_b32_dpp v196, v94 row_ror:15 row_mask:0xf bank_mask:0xf
	v_mov_b32_dpp v197, v95 row_ror:15 row_mask:0xf bank_mask:0xf
	v_mov_b32_dpp v150, v92 row_ror:1 row_mask:0xf bank_mask:0xf
	v_mov_b32_dpp v151, v93 row_ror:1 row_mask:0xf bank_mask:0xf
	v_mov_b32_dpp v152, v94 row_ror:1 row_mask:0xf bank_mask:0xf
	v_mov_b32_dpp v153, v95 row_ror:1 row_mask:0xf bank_mask:0xf
	v_mov_b32_dpp v198, v84 row_ror:15 row_mask:0xf bank_mask:0xf
	v_mov_b32_dpp v199, v85 row_ror:15 row_mask:0xf bank_mask:0xf
	v_mov_b32_dpp v200, v86 row_ror:15 row_mask:0xf bank_mask:0xf
	v_mov_b32_dpp v201, v87 row_ror:15 row_mask:0xf bank_mask:0xf
	s_waitcnt lgkmcnt(0)
	v_cndmask_b32_e64 v202, v150, v146, s[8:9]
	v_cndmask_b32_e64 v203, v151, v147, s[8:9]
	v_cndmask_b32_e64 v204, v152, v148, s[8:9]
	v_cndmask_b32_e64 v205, v153, v149, s[8:9]
	s_cmp_eq_u32 s7, 0
	s_cbranch_scc0 .LffnB_bz_4
	ds_read_b128 v[146:149], v170 offset:4096
	s_branch .LffnB_bj_5

; #define LAS __attribute__((address_space(3)))
; DEV unsigned cvt_pk_bf16(float lo, float hi) { unsigned r; asm volatile("v_cvt_pk_bf16_f32 %0, %1, %2" : "=v"(r) : "v"(lo), "v"(hi)); return r; }
;     DEV void operator()(const Acc& acc, const Unit& u, int wr, int wc, int fr, int fq, LAS unsigned char* misc) const {
;     ...
;         for (int n = 0; n < 2; ++n) { const int cc = wc * 32 + 8 * fq + 4 * n, j = u.pn * 128 + cc;
;             const f32x4 w0 = *(const f32x4*)(cw + j), w1 = *(const f32x4*)(cw + DFF + j), w2 = *(const f32x4*)(cw + 2 * DFF + j), bb = *(const f32x4*)(cb + j);
; #pragma unroll
;             for (int ai = 0; ai < 2; ++ai) { const int q = 2 * ai + wr;
;                 const f32x4 bup = (q > 0) ? *(LAS f32x4*)(xl + (q - 1) * 128 + cc) : (f32x4){0.f, 0.f, 0.f, 0.f};
;                 const f32x4 bdn = (q < 3) ? *(LAS f32x4*)(xf + (q + 1) * 128 + cc) : (f32x4){0.f, 0.f, 0.f, 0.f};
;                 f32x4 Rprev = bup, Dcur;
; #pragma unroll
;                 for (int e = 0; e < 4; ++e) Dcur[e] = ROR15(acc[ai][0][0][n][e]);
; #pragma unroll
;                 for (int m = 0; m < 4; ++m) {
;                     f32x4 Rm, Dnext = bdn;
; #pragma unroll
;                     for (int e = 0; e < 4; ++e) { Rm[e] = ROR1(acc[ai][0][m][n][e]); if (m < 3) Dnext[e] = ROR15(acc[ai][0][m < 3 ? m + 1 : 3][n][e]); }
;                     const f32x4 up = (fr > 0) ? Rm : Rprev;
;                     const f32x4 dn = (fr < 15) ? Dcur : Dnext;
;                     Rprev = Rm; Dcur = Dnext;
;                     const int rr = q * 64 + m * 16 + fr, sq = s0 + rr;
;                     const f32x4 g = acc[ai][0][m][n], v = acc[ai][1][m][n];
;                     f32x4 o;
; #pragma unroll
;                     for (int e = 0; e < 4; ++e) { const float z = w0[e] * up[e] + w1[e] * g[e] + w2[e] * dn[e] + bb[e]; o[e] = z * __builtin_amdgcn_rcpf(1.f + __builtin_amdgcn_exp2f(-1.4426950408889634f * z)) * v[e]; }
;                     if (rr >= 1 && rr <= 254) { u32x2 w; w.x = cvt_pk_bf16(o[0], o[1]); w.y = cvt_pk_bf16(o[2], o[3]);
;                         *(u32x2*)(act + (size_t)(sbase + sq) * DFF + j) = w; }
;                     if (rr < 2 || rr > 253) { const int rid = rr < 2 ? rr : rr - 252; *(f32x4*)(sbp + (size_t)rid * DFF + j) = g;
;                         if (rr == 0 || rr == 255) *(f32x4*)(sbp + (size_t)(4 + (rr == 255)) * DFF + j) = v; }
.LffnB_bj_5:
	v_cndmask_b32_e64 v206, v194, v198, s[10:11]
	v_cndmask_b32_e64 v207, v195, v199, s[10:11]
	v_cndmask_b32_e64 v208, v196, v200, s[10:11]
	v_cndmask_b32_e64 v209, v197, v201, s[10:11]
	v_mul_f32_e32 v92, v110, v92
	v_mul_f32_e32 v93, v111, v93
	v_mul_f32_e32 v94, v112, v94
	v_mul_f32_e32 v95, v113, v95
	v_mul_f32_e32 v206, v114, v206
	v_mul_f32_e32 v207, v115, v207
	v_mul_f32_e32 v208, v116, v208
	v_mul_f32_e32 v209, v117, v209
	v_fmac_f32_e32 v92, v106, v202
	v_fmac_f32_e32 v93, v107, v203
	v_fmac_f32_e32 v94, v108, v204
	v_fmac_f32_e32 v95, v109, v205
	v_add_f32_e32 v92, v206, v92
	v_add_f32_e32 v93, v207, v93
	v_add_f32_e32 v94, v208, v94
	v_add_f32_e32 v95, v209, v95
	v_add_f32_e32 v92, v118, v92
	v_add_f32_e32 v93, v119, v93
	v_add_f32_e32 v94, v120, v94
	v_add_f32_e32 v95, v121, v95
	v_mul_f32_e32 v202, 0xbfb8aa3b, v92
	v_mul_f32_e32 v203, 0xbfb8aa3b, v93
	v_mul_f32_e32 v204, 0xbfb8aa3b, v94
	v_mul_f32_e32 v205, 0xbfb8aa3b, v95
	v_exp_f32_e32 v202, v202
	v_exp_f32_e32 v203, v203
	v_exp_f32_e32 v204, v204
	v_exp_f32_e32 v205, v205
	v_add_f32_e32 v202, 1.0, v202
	v_add_f32_e32 v203, 1.0, v203
	v_add_f32_e32 v204, 1.0, v204
	v_add_f32_e32 v205, 1.0, v205
	v_rcp_f32_e32 v202, v202
	v_rcp_f32_e32 v203, v203
	v_rcp_f32_e32 v204, v204
	v_rcp_f32_e32 v205, v205
	v_mul_f32_e32 v92, v92, v202
	v_mul_f32_e32 v93, v93, v203
	v_mul_f32_e32 v94, v94, v204
	v_mul_f32_e32 v95, v95, v205
	v_mul_f32_e32 v92, v88, v92
	v_mul_f32_e32 v93, v89, v93
	v_mul_f32_e32 v94, v90, v94
	v_mul_f32_e32 v95, v91, v95
	v_cvt_pk_bf16_f32 v206, v92, v93
	v_cvt_pk_bf16_f32 v207, v94, v95
	v_add_u32_e32 v169, 0xb0000, v168
	global_store_dwordx2 v169, v[206:207], s[18:19]
	v_mov_b32_dpp v190, v84 row_ror:1 row_mask:0xf bank_mask:0xf
	v_mov_b32_dpp v191, v85 row_ror:1 row_mask:0xf bank_mask:0xf
	v_mov_b32_dpp v192, v86 row_ror:1 row_mask:0xf bank_mask:0xf
	v_mov_b32_dpp v193, v87 row_ror:1 row_mask:0xf bank_mask:0xf
	v_mov_b32_dpp v194, v76 row_ror:15 row_mask:0xf bank_mask:0xf
	v_mov_b32_dpp v195, v77 row_ror:15 row_mask:0xf bank_mask:0xf
	v_mov_b32_dpp v196, v78 row_ror:15 row_mask:0xf bank_mask:0xf
	v_mov_b32_dpp v197, v79 row_ror:15 row_mask:0xf bank_mask:0xf
	v_cndmask_b32_e64 v202, v190, v150, s[8:9]
	v_cndmask_b32_e64 v203, v191, v151, s[8:9]
	v_cndmask_b32_e64 v204, v192, v152, s[8:9]
	v_cndmask_b32_e64 v205, v193, v153, s[8:9]
	v_cndmask_b32_e64 v206, v198, v194, s[10:11]
	v_cndmask_b32_e64 v207, v199, v195, s[10:11]
	v_cndmask_b32_e64 v208, v200, v196, s[10:11]
	v_cndmask_b32_e64 v209, v201, v197, s[10:11]
	v_mul_f32_e32 v84, v110, v84
	v_mul_f32_e32 v85, v111, v85
	v_mul_f32_e32 v86, v112, v86
	v_mul_f32_e32 v87, v113, v87
	v_mul_f32_e32 v206, v114, v206
	v_mul_f32_e32 v207, v115, v207
	v_mul_f32_e32 v208, v116, v208
	v_mul_f32_e32 v209, v117, v209
	v_fmac_f32_e32 v84, v106, v202
	v_fmac_f32_e32 v85, v107, v203
	v_fmac_f32_e32 v86, v108, v204
	v_fmac_f32_e32 v87, v109, v205
	v_add_f32_e32 v84, v206, v84
	v_add_f32_e32 v85, v207, v85
	v_add_f32_e32 v86, v208, v86
	v_add_f32_e32 v87, v209, v87
	v_add_f32_e32 v84, v118, v84
	v_add_f32_e32 v85, v119, v85
	v_add_f32_e32 v86, v120, v86
	v_add_f32_e32 v87, v121, v87
	v_mul_f32_e32 v202, 0xbfb8aa3b, v84
	v_mul_f32_e32 v203, 0xbfb8aa3b, v85
	v_mul_f32_e32 v204, 0xbfb8aa3b, v86
	v_mul_f32_e32 v205, 0xbfb8aa3b, v87
	v_exp_f32_e32 v202, v202
	v_exp_f32_e32 v203, v203
	v_exp_f32_e32 v204, v204
	v_exp_f32_e32 v205, v205
	v_add_f32_e32 v202, 1.0, v202
	v_add_f32_e32 v203, 1.0, v203
	v_add_f32_e32 v204, 1.0, v204
	v_add_f32_e32 v205, 1.0, v205
	v_rcp_f32_e32 v202, v202
	v_rcp_f32_e32 v203, v203
	v_rcp_f32_e32 v204, v204
	v_rcp_f32_e32 v205, v205
	v_mul_f32_e32 v84, v84, v202
	v_mul_f32_e32 v85, v85, v203
	v_mul_f32_e32 v86, v86, v204
	v_mul_f32_e32 v87, v87, v205
	v_mul_f32_e32 v84, v80, v84
	v_mul_f32_e32 v85, v81, v85
	v_mul_f32_e32 v86, v82, v86
	v_mul_f32_e32 v87, v83, v87
	v_cvt_pk_bf16_f32 v206, v84, v85
	v_cvt_pk_bf16_f32 v207, v86, v87
	v_add_u32_e32 v169, 0xc6000, v168
	global_store_dwordx2 v169, v[206:207], s[18:19]
	v_mov_b32_dpp v150, v76 row_ror:1 row_mask:0xf bank_mask:0xf
	v_mov_b32_dpp v151, v77 row_ror:1 row_mask:0xf bank_mask:0xf
	v_mov_b32_dpp v152, v78 row_ror:1 row_mask:0xf bank_mask:0xf
	v_mov_b32_dpp v153, v79 row_ror:1 row_mask:0xf bank_mask:0xf
	v_mov_b32_dpp v198, v68 row_ror:15 row_mask:0xf bank_mask:0xf
	v_mov_b32_dpp v199, v69 row_ror:15 row_mask:0xf bank_mask:0xf
	v_mov_b32_dpp v200, v70 row_ror:15 row_mask:0xf bank_mask:0xf
	v_mov_b32_dpp v201, v71 row_ror:15 row_mask:0xf bank_mask:0xf
	v_cndmask_b32_e64 v202, v150, v190, s[8:9]
	v_cndmask_b32_e64 v203, v151, v191, s[8:9]
	v_cndmask_b32_e64 v204, v152, v192, s[8:9]
	v_cndmask_b32_e64 v205, v153, v193, s[8:9]
	v_cndmask_b32_e64 v206, v194, v198, s[10:11]
	v_cndmask_b32_e64 v207, v195, v199, s[10:11]
	v_cndmask_b32_e64 v208, v196, v200, s[10:11]
	v_cndmask_b32_e64 v209, v197, v201, s[10:11]
	v_mul_f32_e32 v76, v110, v76
	v_mul_f32_e32 v77, v111, v77
	v_mul_f32_e32 v78, v112, v78
	v_mul_f32_e32 v79, v113, v79
	v_mul_f32_e32 v206, v114, v206
	v_mul_f32_e32 v207, v115, v207
	v_mul_f32_e32 v208, v116, v208
	v_mul_f32_e32 v209, v117, v209
	v_fmac_f32_e32 v76, v106, v202
	v_fmac_f32_e32 v77, v107, v203
	v_fmac_f32_e32 v78, v108, v204
	v_fmac_f32_e32 v79, v109, v205
	v_add_f32_e32 v76, v206, v76
	v_add_f32_e32 v77, v207, v77
	v_add_f32_e32 v78, v208, v78
	v_add_f32_e32 v79, v209, v79
	v_add_f32_e32 v76, v118, v76
	v_add_f32_e32 v77, v119, v77
	v_add_f32_e32 v78, v120, v78
	v_add_f32_e32 v79, v121, v79
	v_mul_f32_e32 v202, 0xbfb8aa3b, v76
	v_mul_f32_e32 v203, 0xbfb8aa3b, v77
	v_mul_f32_e32 v204, 0xbfb8aa3b, v78
	v_mul_f32_e32 v205, 0xbfb8aa3b, v79
	v_exp_f32_e32 v202, v202
	v_exp_f32_e32 v203, v203
	v_exp_f32_e32 v204, v204
	v_exp_f32_e32 v205, v205
	v_add_f32_e32 v202, 1.0, v202
	v_add_f32_e32 v203, 1.0, v203
	v_add_f32_e32 v204, 1.0, v204
	v_add_f32_e32 v205, 1.0, v205
	v_rcp_f32_e32 v202, v202
	v_rcp_f32_e32 v203, v203
	v_rcp_f32_e32 v204, v204
	v_rcp_f32_e32 v205, v205
	v_mul_f32_e32 v76, v76, v202
	v_mul_f32_e32 v77, v77, v203
	v_mul_f32_e32 v78, v78, v204
	v_mul_f32_e32 v79, v79, v205
	v_mul_f32_e32 v76, v72, v76
	v_mul_f32_e32 v77, v73, v77
	v_mul_f32_e32 v78, v74, v78
	v_mul_f32_e32 v79, v75, v79
	v_cvt_pk_bf16_f32 v206, v76, v77
	v_cvt_pk_bf16_f32 v207, v78, v79
	v_add_u32_e32 v169, 0xdc000, v168
	global_store_dwordx2 v169, v[206:207], s[18:19]
	s_cmp_eq_u32 s7, 1
	s_cbranch_scc0 .LffnB_ns_6
	v_mul_u32_u24_e32 v171, 0x2c00, v166
	v_cmp_lt_u32_e64 s[30:31], 13, v166
	v_add_u32_e32 v171, v171, v167
	v_add_u32_e32 v171, 0xfffdf000, v171
	s_nop 1
	s_mov_b64 exec, s[30:31]
	global_store_dwordx4 v171, v[68:71], s[24:25]
	s_mov_b64 exec, s[10:11]
	global_store_dwordx4 v171, v[64:67], s[28:29]
	s_mov_b64 exec, -1
	s_nop 4
; #define LAS __attribute__((address_space(3)))
; DEV unsigned cvt_pk_bf16(float lo, float hi) { unsigned r; asm volatile("v_cvt_pk_bf16_f32 %0, %1, %2" : "=v"(r) : "v"(lo), "v"(hi)); return r; }
;     DEV void operator()(const Acc& acc, const Unit& u, int wr, int wc, int fr, int fq, LAS unsigned char* misc) const {
;     ...
;         for (int n = 0; n < 2; ++n) { const int cc = wc * 32 + 8 * fq + 4 * n, j = u.pn * 128 + cc;
;             const f32x4 w0 = *(const f32x4*)(cw + j), w1 = *(const f32x4*)(cw + DFF + j), w2 = *(const f32x4*)(cw + 2 * DFF + j), bb = *(const f32x4*)(cb + j);
; #pragma unroll
;             for (int ai = 0; ai < 2; ++ai) { const int q = 2 * ai + wr;
;                 const f32x4 bup = (q > 0) ? *(LAS f32x4*)(xl + (q - 1) * 128 + cc) : (f32x4){0.f, 0.f, 0.f, 0.f};
;                 const f32x4 bdn = (q < 3) ? *(LAS f32x4*)(xf + (q + 1) * 128 + cc) : (f32x4){0.f, 0.f, 0.f, 0.f};
;                 f32x4 Rprev = bup, Dcur;
; #pragma unroll
;                 for (int e = 0; e < 4; ++e) Dcur[e] = ROR15(acc[ai][0][0][n][e]);
; #pragma unroll
;                 for (int m = 0; m < 4; ++m) {
;                     f32x4 Rm, Dnext = bdn;
; #pragma unroll
;                     for (int e = 0; e < 4; ++e) { Rm[e] = ROR1(acc[ai][0][m][n][e]); if (m < 3) Dnext[e] = ROR15(acc[ai][0][m < 3 ? m + 1 : 3][n][e]); }
;                     const f32x4 up = (fr > 0) ? Rm : Rprev;
;                     const f32x4 dn = (fr < 15) ? Dcur : Dnext;
;                     Rprev = Rm; Dcur = Dnext;
;                     const int rr = q * 64 + m * 16 + fr, sq = s0 + rr;
;                     const f32x4 g = acc[ai][0][m][n], v = acc[ai][1][m][n];
;                     f32x4 o;
; #pragma unroll
;                     for (int e = 0; e < 4; ++e) { const float z = w0[e] * up[e] + w1[e] * g[e] + w2[e] * dn[e] + bb[e]; o[e] = z * __builtin_amdgcn_rcpf(1.f + __builtin_amdgcn_exp2f(-1.4426950408889634f * z)) * v[e]; }
;                     if (rr >= 1 && rr <= 254) { u32x2 w; w.x = cvt_pk_bf16(o[0], o[1]); w.y = cvt_pk_bf16(o[2], o[3]);
;                         *(u32x2*)(act + (size_t)(sbase + sq) * DFF + j) = w; }
;                     if (rr < 2 || rr > 253) { const int rid = rr < 2 ? rr : rr - 252; *(f32x4*)(sbp + (size_t)rid * DFF + j) = g;
;                         if (rr == 0 || rr == 255) *(f32x4*)(sbp + (size_t)(4 + (rr == 255)) * DFF + j) = v; }
.LffnB_ns_6:
	v_mov_b32_dpp v190, v68 row_ror:1 row_mask:0xf bank_mask:0xf
	v_mov_b32_dpp v191, v69 row_ror:1 row_mask:0xf bank_mask:0xf
	v_mov_b32_dpp v192, v70 row_ror:1 row_mask:0xf bank_mask:0xf
	v_mov_b32_dpp v193, v71 row_ror:1 row_mask:0xf bank_mask:0xf
	v_cndmask_b32_e64 v202, v190, v150, s[8:9]
	v_cndmask_b32_e64 v203, v191, v151, s[8:9]
	v_cndmask_b32_e64 v204, v192, v152, s[8:9]
	v_cndmask_b32_e64 v205, v193, v153, s[8:9]
	s_waitcnt lgkmcnt(0)
	v_cndmask_b32_e64 v206, v198, v146, s[10:11]
	v_cndmask_b32_e64 v207, v199, v147, s[10:11]
	v_cndmask_b32_e64 v208, v200, v148, s[10:11]
	v_cndmask_b32_e64 v209, v201, v149, s[10:11]
	v_mul_f32_e32 v68, v110, v68
	v_mul_f32_e32 v69, v111, v69
	v_mul_f32_e32 v70, v112, v70
	v_mul_f32_e32 v71, v113, v71
	v_mul_f32_e32 v206, v114, v206
	v_mul_f32_e32 v207, v115, v207
	v_mul_f32_e32 v208, v116, v208
	v_mul_f32_e32 v209, v117, v209
	v_fmac_f32_e32 v68, v106, v202
	v_fmac_f32_e32 v69, v107, v203
	v_fmac_f32_e32 v70, v108, v204
	v_fmac_f32_e32 v71, v109, v205
	v_add_f32_e32 v68, v206, v68
	v_add_f32_e32 v69, v207, v69
	v_add_f32_e32 v70, v208, v70
	v_add_f32_e32 v71, v209, v71
	v_add_f32_e32 v68, v118, v68
	v_add_f32_e32 v69, v119, v69
	v_add_f32_e32 v70, v120, v70
	v_add_f32_e32 v71, v121, v71
	v_mul_f32_e32 v202, 0xbfb8aa3b, v68
	v_mul_f32_e32 v203, 0xbfb8aa3b, v69
	v_mul_f32_e32 v204, 0xbfb8aa3b, v70
	v_mul_f32_e32 v205, 0xbfb8aa3b, v71
	v_exp_f32_e32 v202, v202
	v_exp_f32_e32 v203, v203
	v_exp_f32_e32 v204, v204
	v_exp_f32_e32 v205, v205
	v_add_f32_e32 v202, 1.0, v202
	v_add_f32_e32 v203, 1.0, v203
	v_add_f32_e32 v204, 1.0, v204
	v_add_f32_e32 v205, 1.0, v205
	v_rcp_f32_e32 v202, v202
	v_rcp_f32_e32 v203, v203
	v_rcp_f32_e32 v204, v204
	v_rcp_f32_e32 v205, v205
	v_mul_f32_e32 v68, v68, v202
	v_mul_f32_e32 v69, v69, v203
	v_mul_f32_e32 v70, v70, v204
	v_mul_f32_e32 v71, v71, v205
	v_mul_f32_e32 v68, v64, v68
	v_mul_f32_e32 v69, v65, v69
	v_mul_f32_e32 v70, v66, v70
	v_mul_f32_e32 v71, v67, v71
	v_cvt_pk_bf16_f32 v206, v68, v69
	v_cvt_pk_bf16_f32 v207, v70, v71
	v_add_u32_e32 v169, 0xf2000, v168
	s_mov_b64 exec, s[16:17]
	global_store_dwordx2 v169, v[206:207], s[18:19]
	s_mov_b64 exec, -1
	s_nop 4
	s_cmp_eq_u32 s7, 0
	s_cbranch_scc1 .LffnB_bz_7
	ds_read_b128 v[146:149], v170 offset:16
	s_branch .LffnB_bj_8

; #define LAS __attribute__((address_space(3)))
; DEV unsigned cvt_pk_bf16(float lo, float hi) { unsigned r; asm volatile("v_cvt_pk_bf16_f32 %0, %1, %2" : "=v"(r) : "v"(lo), "v"(hi)); return r; }
;     DEV void operator()(const Acc& acc, const Unit& u, int wr, int wc, int fr, int fq, LAS unsigned char* misc) const {
;     ...
;         for (int n = 0; n < 2; ++n) { const int cc = wc * 32 + 8 * fq + 4 * n, j = u.pn * 128 + cc;
;             const f32x4 w0 = *(const f32x4*)(cw + j), w1 = *(const f32x4*)(cw + DFF + j), w2 = *(const f32x4*)(cw + 2 * DFF + j), bb = *(const f32x4*)(cb + j);
; #pragma unroll
;             for (int ai = 0; ai < 2; ++ai) { const int q = 2 * ai + wr;
;                 const f32x4 bup = (q > 0) ? *(LAS f32x4*)(xl + (q - 1) * 128 + cc) : (f32x4){0.f, 0.f, 0.f, 0.f};
;                 const f32x4 bdn = (q < 3) ? *(LAS f32x4*)(xf + (q + 1) * 128 + cc) : (f32x4){0.f, 0.f, 0.f, 0.f};
;                 f32x4 Rprev = bup, Dcur;
; #pragma unroll
;                 for (int e = 0; e < 4; ++e) Dcur[e] = ROR15(acc[ai][0][0][n][e]);
; #pragma unroll
;                 for (int m = 0; m < 4; ++m) {
;                     f32x4 Rm, Dnext = bdn;
; #pragma unroll
;                     for (int e = 0; e < 4; ++e) { Rm[e] = ROR1(acc[ai][0][m][n][e]); if (m < 3) Dnext[e] = ROR15(acc[ai][0][m < 3 ? m + 1 : 3][n][e]); }
;                     const f32x4 up = (fr > 0) ? Rm : Rprev;
;                     const f32x4 dn = (fr < 15) ? Dcur : Dnext;
;                     Rprev = Rm; Dcur = Dnext;
;                     const int rr = q * 64 + m * 16 + fr, sq = s0 + rr;
;                     const f32x4 g = acc[ai][0][m][n], v = acc[ai][1][m][n];
;                     f32x4 o;
; #pragma unroll
;                     for (int e = 0; e < 4; ++e) { const float z = w0[e] * up[e] + w1[e] * g[e] + w2[e] * dn[e] + bb[e]; o[e] = z * __builtin_amdgcn_rcpf(1.f + __builtin_amdgcn_exp2f(-1.4426950408889634f * z)) * v[e]; }
;                     if (rr >= 1 && rr <= 254) { u32x2 w; w.x = cvt_pk_bf16(o[0], o[1]); w.y = cvt_pk_bf16(o[2], o[3]);
;                         *(u32x2*)(act + (size_t)(sbase + sq) * DFF + j) = w; }
;                     if (rr < 2 || rr > 253) { const int rid = rr < 2 ? rr : rr - 252; *(f32x4*)(sbp + (size_t)rid * DFF + j) = g;
;                         if (rr == 0 || rr == 255) *(f32x4*)(sbp + (size_t)(4 + (rr == 255)) * DFF + j) = v; }
.LffnB_bj_8:
	v_mov_b32_dpp v194, v56 row_ror:15 row_mask:0xf bank_mask:0xf
	v_mov_b32_dpp v195, v57 row_ror:15 row_mask:0xf bank_mask:0xf
	v_mov_b32_dpp v196, v58 row_ror:15 row_mask:0xf bank_mask:0xf
	v_mov_b32_dpp v197, v59 row_ror:15 row_mask:0xf bank_mask:0xf
	s_waitcnt vmcnt(4)
	s_cmp_eq_u32 s7, 0
	s_cbranch_scc0 .LffnB_ns_9
	v_mul_u32_u24_e32 v171, 0x2c00, v166
	v_cmp_gt_u32_e64 s[30:31], 2, v166
	v_add_u32_e32 v171, v171, v167
	s_nop 1
	s_mov_b64 exec, s[30:31]
	global_store_dwordx4 v171, v[56:59], s[24:25] offset:16
	s_mov_b64 exec, s[8:9]
	global_store_dwordx4 v171, v[60:63], s[26:27] offset:16
	s_mov_b64 exec, -1
	s_nop 4
.LffnB_ns_9:
	v_mov_b32_dpp v150, v56 row_ror:1 row_mask:0xf bank_mask:0xf
	v_mov_b32_dpp v151, v57 row_ror:1 row_mask:0xf bank_mask:0xf
	v_mov_b32_dpp v152, v58 row_ror:1 row_mask:0xf bank_mask:0xf
	v_mov_b32_dpp v153, v59 row_ror:1 row_mask:0xf bank_mask:0xf
	v_mov_b32_dpp v198, v52 row_ror:15 row_mask:0xf bank_mask:0xf
	v_mov_b32_dpp v199, v53 row_ror:15 row_mask:0xf bank_mask:0xf
	v_mov_b32_dpp v200, v54 row_ror:15 row_mask:0xf bank_mask:0xf
	v_mov_b32_dpp v201, v55 row_ror:15 row_mask:0xf bank_mask:0xf
	s_waitcnt lgkmcnt(0)
	v_cndmask_b32_e64 v202, v150, v146, s[8:9]
	v_cndmask_b32_e64 v203, v151, v147, s[8:9]
	v_cndmask_b32_e64 v204, v152, v148, s[8:9]
	v_cndmask_b32_e64 v205, v153, v149, s[8:9]
	ds_read_b128 v[146:149], v170 offset:3088
	v_cndmask_b32_e64 v206, v194, v198, s[10:11]
	v_cndmask_b32_e64 v207, v195, v199, s[10:11]
	v_cndmask_b32_e64 v208, v196, v200, s[10:11]
	v_cndmask_b32_e64 v209, v197, v201, s[10:11]
	v_mul_f32_e32 v56, v126, v56
	v_mul_f32_e32 v57, v127, v57
	v_mul_f32_e32 v58, v128, v58
	v_mul_f32_e32 v59, v129, v59
	v_mul_f32_e32 v206, v130, v206
	v_mul_f32_e32 v207, v131, v207
	v_mul_f32_e32 v208, v132, v208
	v_mul_f32_e32 v209, v133, v209
	v_fmac_f32_e32 v56, v122, v202
	v_fmac_f32_e32 v57, v123, v203
	v_fmac_f32_e32 v58, v124, v204
	v_fmac_f32_e32 v59, v125, v205
	v_add_f32_e32 v56, v206, v56
	v_add_f32_e32 v57, v207, v57
	v_add_f32_e32 v58, v208, v58
	v_add_f32_e32 v59, v209, v59
	v_add_f32_e32 v56, v134, v56
	v_add_f32_e32 v57, v135, v57
	v_add_f32_e32 v58, v136, v58
	v_add_f32_e32 v59, v137, v59
	v_mul_f32_e32 v202, 0xbfb8aa3b, v56
	v_mul_f32_e32 v203, 0xbfb8aa3b, v57
	v_mul_f32_e32 v204, 0xbfb8aa3b, v58
	v_mul_f32_e32 v205, 0xbfb8aa3b, v59
	v_exp_f32_e32 v202, v202
	v_exp_f32_e32 v203, v203
	v_exp_f32_e32 v204, v204
	v_exp_f32_e32 v205, v205
	v_add_f32_e32 v202, 1.0, v202
	v_add_f32_e32 v203, 1.0, v203
	v_add_f32_e32 v204, 1.0, v204
	v_add_f32_e32 v205, 1.0, v205
	v_rcp_f32_e32 v202, v202
	v_rcp_f32_e32 v203, v203
	v_rcp_f32_e32 v204, v204
	v_rcp_f32_e32 v205, v205
	v_mul_f32_e32 v56, v56, v202
	v_mul_f32_e32 v57, v57, v203
	v_mul_f32_e32 v58, v58, v204
	v_mul_f32_e32 v59, v59, v205
	v_mul_f32_e32 v56, v60, v56
	v_mul_f32_e32 v57, v61, v57
	v_mul_f32_e32 v58, v62, v58
	v_mul_f32_e32 v59, v63, v59
	v_cvt_pk_bf16_f32 v206, v56, v57
	v_cvt_pk_bf16_f32 v207, v58, v59
	v_add_u32_e32 v169, 0x0, v168
	s_mov_b64 exec, s[12:13]
	global_store_dwordx2 v169, v[206:207], s[18:19] offset:8
	s_mov_b64 exec, -1
	s_nop 4
	v_mov_b32_dpp v190, v52 row_ror:1 row_mask:0xf bank_mask:0xf
	v_mov_b32_dpp v191, v53 row_ror:1 row_mask:0xf bank_mask:0xf
	v_mov_b32_dpp v192, v54 row_ror:1 row_mask:0xf bank_mask:0xf
	v_mov_b32_dpp v193, v55 row_ror:1 row_mask:0xf bank_mask:0xf
	v_mov_b32_dpp v194, v44 row_ror:15 row_mask:0xf bank_mask:0xf
	v_mov_b32_dpp v195, v45 row_ror:15 row_mask:0xf bank_mask:0xf
	v_mov_b32_dpp v196, v46 row_ror:15 row_mask:0xf bank_mask:0xf
	v_mov_b32_dpp v197, v47 row_ror:15 row_mask:0xf bank_mask:0xf
	v_cndmask_b32_e64 v202, v190, v150, s[8:9]
	v_cndmask_b32_e64 v203, v191, v151, s[8:9]
	v_cndmask_b32_e64 v204, v192, v152, s[8:9]
	v_cndmask_b32_e64 v205, v193, v153, s[8:9]
	v_cndmask_b32_e64 v206, v198, v194, s[10:11]
	v_cndmask_b32_e64 v207, v199, v195, s[10:11]
	v_cndmask_b32_e64 v208, v200, v196, s[10:11]
	v_cndmask_b32_e64 v209, v201, v197, s[10:11]
	v_mul_f32_e32 v52, v126, v52
	v_mul_f32_e32 v53, v127, v53
	v_mul_f32_e32 v54, v128, v54
	v_mul_f32_e32 v55, v129, v55
	v_mul_f32_e32 v206, v130, v206
	v_mul_f32_e32 v207, v131, v207
	v_mul_f32_e32 v208, v132, v208
	v_mul_f32_e32 v209, v133, v209
	v_fmac_f32_e32 v52, v122, v202
	v_fmac_f32_e32 v53, v123, v203
	v_fmac_f32_e32 v54, v124, v204
	v_fmac_f32_e32 v55, v125, v205
	v_add_f32_e32 v52, v206, v52
	v_add_f32_e32 v53, v207, v53
	v_add_f32_e32 v54, v208, v54
	v_add_f32_e32 v55, v209, v55
	v_add_f32_e32 v52, v134, v52
	v_add_f32_e32 v53, v135, v53
	v_add_f32_e32 v54, v136, v54
	v_add_f32_e32 v55, v137, v55
	v_mul_f32_e32 v202, 0xbfb8aa3b, v52
	v_mul_f32_e32 v203, 0xbfb8aa3b, v53
	v_mul_f32_e32 v204, 0xbfb8aa3b, v54
	v_mul_f32_e32 v205, 0xbfb8aa3b, v55
	v_exp_f32_e32 v202, v202
	v_exp_f32_e32 v203, v203
	v_exp_f32_e32 v204, v204
	v_exp_f32_e32 v205, v205
	v_add_f32_e32 v202, 1.0, v202
	v_add_f32_e32 v203, 1.0, v203
	v_add_f32_e32 v204, 1.0, v204
	v_add_f32_e32 v205, 1.0, v205
	v_rcp_f32_e32 v202, v202
	v_rcp_f32_e32 v203, v203
	v_rcp_f32_e32 v204, v204
	v_rcp_f32_e32 v205, v205
	v_mul_f32_e32 v52, v52, v202
	v_mul_f32_e32 v53, v53, v203
	v_mul_f32_e32 v54, v54, v204
	v_mul_f32_e32 v55, v55, v205
	v_mul_f32_e32 v52, v48, v52
	v_mul_f32_e32 v53, v49, v53
	v_mul_f32_e32 v54, v50, v54
	v_mul_f32_e32 v55, v51, v55
	v_cvt_pk_bf16_f32 v206, v52, v53
	v_cvt_pk_bf16_f32 v207, v54, v55
	v_add_u32_e32 v169, 0x16000, v168
	global_store_dwordx2 v169, v[206:207], s[18:19] offset:8
	v_mov_b32_dpp v150, v44 row_ror:1 row_mask:0xf bank_mask:0xf
; #define LAS __attribute__((address_space(3)))
; DEV unsigned cvt_pk_bf16(float lo, float hi) { unsigned r; asm volatile("v_cvt_pk_bf16_f32 %0, %1, %2" : "=v"(r) : "v"(lo), "v"(hi)); return r; }
;     DEV void operator()(const Acc& acc, const Unit& u, int wr, int wc, int fr, int fq, LAS unsigned char* misc) const {
;     ...
;         for (int n = 0; n < 2; ++n) { const int cc = wc * 32 + 8 * fq + 4 * n, j = u.pn * 128 + cc;
;             const f32x4 w0 = *(const f32x4*)(cw + j), w1 = *(const f32x4*)(cw + DFF + j), w2 = *(const f32x4*)(cw + 2 * DFF + j), bb = *(const f32x4*)(cb + j);
; #pragma unroll
;             for (int ai = 0; ai < 2; ++ai) { const int q = 2 * ai + wr;
;                 const f32x4 bup = (q > 0) ? *(LAS f32x4*)(xl + (q - 1) * 128 + cc) : (f32x4){0.f, 0.f, 0.f, 0.f};
;                 const f32x4 bdn = (q < 3) ? *(LAS f32x4*)(xf + (q + 1) * 128 + cc) : (f32x4){0.f, 0.f, 0.f, 0.f};
;                 f32x4 Rprev = bup, Dcur;
; #pragma unroll
;                 for (int e = 0; e < 4; ++e) Dcur[e] = ROR15(acc[ai][0][0][n][e]);
; #pragma unroll
;                 for (int m = 0; m < 4; ++m) {
;                     f32x4 Rm, Dnext = bdn;
; #pragma unroll
;                     for (int e = 0; e < 4; ++e) { Rm[e] = ROR1(acc[ai][0][m][n][e]); if (m < 3) Dnext[e] = ROR15(acc[ai][0][m < 3 ? m + 1 : 3][n][e]); }
;                     const f32x4 up = (fr > 0) ? Rm : Rprev;
;                     const f32x4 dn = (fr < 15) ? Dcur : Dnext;
;                     Rprev = Rm; Dcur = Dnext;
;                     const int rr = q * 64 + m * 16 + fr, sq = s0 + rr;
;                     const f32x4 g = acc[ai][0][m][n], v = acc[ai][1][m][n];
;                     f32x4 o;
; #pragma unroll
;                     for (int e = 0; e < 4; ++e) { const float z = w0[e] * up[e] + w1[e] * g[e] + w2[e] * dn[e] + bb[e]; o[e] = z * __builtin_amdgcn_rcpf(1.f + __builtin_amdgcn_exp2f(-1.4426950408889634f * z)) * v[e]; }
;                     if (rr >= 1 && rr <= 254) { u32x2 w; w.x = cvt_pk_bf16(o[0], o[1]); w.y = cvt_pk_bf16(o[2], o[3]);
;                         *(u32x2*)(act + (size_t)(sbase + sq) * DFF + j) = w; }
;                     if (rr < 2 || rr > 253) { const int rid = rr < 2 ? rr : rr - 252; *(f32x4*)(sbp + (size_t)rid * DFF + j) = g;
;                         if (rr == 0 || rr == 255) *(f32x4*)(sbp + (size_t)(4 + (rr == 255)) * DFF + j) = v; }
	v_mov_b32_dpp v151, v45 row_ror:1 row_mask:0xf bank_mask:0xf
	v_mov_b32_dpp v152, v46 row_ror:1 row_mask:0xf bank_mask:0xf
	v_mov_b32_dpp v153, v47 row_ror:1 row_mask:0xf bank_mask:0xf
	v_mov_b32_dpp v198, v32 row_ror:15 row_mask:0xf bank_mask:0xf
	v_mov_b32_dpp v199, v33 row_ror:15 row_mask:0xf bank_mask:0xf
	v_mov_b32_dpp v200, v34 row_ror:15 row_mask:0xf bank_mask:0xf
	v_mov_b32_dpp v201, v35 row_ror:15 row_mask:0xf bank_mask:0xf
	v_cndmask_b32_e64 v202, v150, v190, s[8:9]
	v_cndmask_b32_e64 v203, v151, v191, s[8:9]
	v_cndmask_b32_e64 v204, v152, v192, s[8:9]
	v_cndmask_b32_e64 v205, v153, v193, s[8:9]
	v_cndmask_b32_e64 v206, v194, v198, s[10:11]
	v_cndmask_b32_e64 v207, v195, v199, s[10:11]
	v_cndmask_b32_e64 v208, v196, v200, s[10:11]
	v_cndmask_b32_e64 v209, v197, v201, s[10:11]
	v_mul_f32_e32 v44, v126, v44
	v_mul_f32_e32 v45, v127, v45
	v_mul_f32_e32 v46, v128, v46
	v_mul_f32_e32 v47, v129, v47
	v_mul_f32_e32 v206, v130, v206
	v_mul_f32_e32 v207, v131, v207
	v_mul_f32_e32 v208, v132, v208
	v_mul_f32_e32 v209, v133, v209
	v_fmac_f32_e32 v44, v122, v202
	v_fmac_f32_e32 v45, v123, v203
	v_fmac_f32_e32 v46, v124, v204
	v_fmac_f32_e32 v47, v125, v205
	v_add_f32_e32 v44, v206, v44
	v_add_f32_e32 v45, v207, v45
	v_add_f32_e32 v46, v208, v46
	v_add_f32_e32 v47, v209, v47
	v_add_f32_e32 v44, v134, v44
	v_add_f32_e32 v45, v135, v45
	v_add_f32_e32 v46, v136, v46
	v_add_f32_e32 v47, v137, v47
	v_mul_f32_e32 v202, 0xbfb8aa3b, v44
	v_mul_f32_e32 v203, 0xbfb8aa3b, v45
	v_mul_f32_e32 v204, 0xbfb8aa3b, v46
	v_mul_f32_e32 v205, 0xbfb8aa3b, v47
	v_exp_f32_e32 v202, v202
	v_exp_f32_e32 v203, v203
	v_exp_f32_e32 v204, v204
	v_exp_f32_e32 v205, v205
	v_add_f32_e32 v202, 1.0, v202
	v_add_f32_e32 v203, 1.0, v203
	v_add_f32_e32 v204, 1.0, v204
	v_add_f32_e32 v205, 1.0, v205
	v_rcp_f32_e32 v202, v202
	v_rcp_f32_e32 v203, v203
	v_rcp_f32_e32 v204, v204
	v_rcp_f32_e32 v205, v205
	v_mul_f32_e32 v44, v44, v202
	v_mul_f32_e32 v45, v45, v203
	v_mul_f32_e32 v46, v46, v204
	v_mul_f32_e32 v47, v47, v205
	v_mul_f32_e32 v44, v40, v44
	v_mul_f32_e32 v45, v41, v45
	v_mul_f32_e32 v46, v42, v46
	v_mul_f32_e32 v47, v43, v47
	v_cvt_pk_bf16_f32 v206, v44, v45
	v_cvt_pk_bf16_f32 v207, v46, v47
	v_add_u32_e32 v169, 0x2c000, v168
	global_store_dwordx2 v169, v[206:207], s[18:19] offset:8
	v_mov_b32_dpp v190, v32 row_ror:1 row_mask:0xf bank_mask:0xf
	v_mov_b32_dpp v191, v33 row_ror:1 row_mask:0xf bank_mask:0xf
	v_mov_b32_dpp v192, v34 row_ror:1 row_mask:0xf bank_mask:0xf
	v_mov_b32_dpp v193, v35 row_ror:1 row_mask:0xf bank_mask:0xf
	v_cndmask_b32_e64 v202, v190, v150, s[8:9]
	v_cndmask_b32_e64 v203, v191, v151, s[8:9]
	v_cndmask_b32_e64 v204, v192, v152, s[8:9]
	v_cndmask_b32_e64 v205, v193, v153, s[8:9]
	s_waitcnt lgkmcnt(0)
	v_cndmask_b32_e64 v206, v198, v146, s[10:11]
	v_cndmask_b32_e64 v207, v199, v147, s[10:11]
	v_cndmask_b32_e64 v208, v200, v148, s[10:11]
	v_cndmask_b32_e64 v209, v201, v149, s[10:11]
	v_mul_f32_e32 v32, v126, v32
	v_mul_f32_e32 v33, v127, v33
	v_mul_f32_e32 v34, v128, v34
	v_mul_f32_e32 v35, v129, v35
	v_mul_f32_e32 v206, v130, v206
	v_mul_f32_e32 v207, v131, v207
	v_mul_f32_e32 v208, v132, v208
	v_mul_f32_e32 v209, v133, v209
	v_fmac_f32_e32 v32, v122, v202
	v_fmac_f32_e32 v33, v123, v203
	v_fmac_f32_e32 v34, v124, v204
	v_fmac_f32_e32 v35, v125, v205
	v_add_f32_e32 v32, v206, v32
	v_add_f32_e32 v33, v207, v33
	v_add_f32_e32 v34, v208, v34
	v_add_f32_e32 v35, v209, v35
	v_add_f32_e32 v32, v134, v32
	v_add_f32_e32 v33, v135, v33
	v_add_f32_e32 v34, v136, v34
	v_add_f32_e32 v35, v137, v35
	v_mul_f32_e32 v202, 0xbfb8aa3b, v32
	v_mul_f32_e32 v203, 0xbfb8aa3b, v33
	v_mul_f32_e32 v204, 0xbfb8aa3b, v34
	v_mul_f32_e32 v205, 0xbfb8aa3b, v35
	v_exp_f32_e32 v202, v202
	v_exp_f32_e32 v203, v203
	v_exp_f32_e32 v204, v204
	v_exp_f32_e32 v205, v205
	v_add_f32_e32 v202, 1.0, v202
	v_add_f32_e32 v203, 1.0, v203
	v_add_f32_e32 v204, 1.0, v204
	v_add_f32_e32 v205, 1.0, v205
	v_rcp_f32_e32 v202, v202
	v_rcp_f32_e32 v203, v203
	v_rcp_f32_e32 v204, v204
	v_rcp_f32_e32 v205, v205
	v_mul_f32_e32 v32, v32, v202
	v_mul_f32_e32 v33, v33, v203
	v_mul_f32_e32 v34, v34, v204
	v_mul_f32_e32 v35, v35, v205
	v_mul_f32_e32 v32, v36, v32
	v_mul_f32_e32 v33, v37, v33
	v_mul_f32_e32 v34, v38, v34
	v_mul_f32_e32 v35, v39, v35
	v_cvt_pk_bf16_f32 v206, v32, v33
	v_cvt_pk_bf16_f32 v207, v34, v35
	v_add_u32_e32 v169, 0x42000, v168
	global_store_dwordx2 v169, v[206:207], s[18:19] offset:8
	ds_read_b128 v[146:149], v170 offset:1040
	v_mov_b32_dpp v194, v28 row_ror:15 row_mask:0xf bank_mask:0xf
	v_mov_b32_dpp v195, v29 row_ror:15 row_mask:0xf bank_mask:0xf
	v_mov_b32_dpp v196, v30 row_ror:15 row_mask:0xf bank_mask:0xf
	v_mov_b32_dpp v197, v31 row_ror:15 row_mask:0xf bank_mask:0xf
	v_mov_b32_dpp v150, v28 row_ror:1 row_mask:0xf bank_mask:0xf
	v_mov_b32_dpp v151, v29 row_ror:1 row_mask:0xf bank_mask:0xf
	v_mov_b32_dpp v152, v30 row_ror:1 row_mask:0xf bank_mask:0xf
	v_mov_b32_dpp v153, v31 row_ror:1 row_mask:0xf bank_mask:0xf
	v_mov_b32_dpp v198, v20 row_ror:15 row_mask:0xf bank_mask:0xf
	v_mov_b32_dpp v199, v21 row_ror:15 row_mask:0xf bank_mask:0xf
	v_mov_b32_dpp v200, v22 row_ror:15 row_mask:0xf bank_mask:0xf
	v_mov_b32_dpp v201, v23 row_ror:15 row_mask:0xf bank_mask:0xf
	s_waitcnt lgkmcnt(0)
	v_cndmask_b32_e64 v202, v150, v146, s[8:9]
	v_cndmask_b32_e64 v203, v151, v147, s[8:9]
	v_cndmask_b32_e64 v204, v152, v148, s[8:9]
	v_cndmask_b32_e64 v205, v153, v149, s[8:9]
	s_cmp_eq_u32 s7, 0
	s_cbranch_scc0 .LffnB_bz_10
	ds_read_b128 v[146:149], v170 offset:4112
	s_branch .LffnB_bj_11

; #define LAS __attribute__((address_space(3)))
; DEV unsigned cvt_pk_bf16(float lo, float hi) { unsigned r; asm volatile("v_cvt_pk_bf16_f32 %0, %1, %2" : "=v"(r) : "v"(lo), "v"(hi)); return r; }
;     DEV void operator()(const Acc& acc, const Unit& u, int wr, int wc, int fr, int fq, LAS unsigned char* misc) const {
;     ...
;         for (int n = 0; n < 2; ++n) { const int cc = wc * 32 + 8 * fq + 4 * n, j = u.pn * 128 + cc;
;             const f32x4 w0 = *(const f32x4*)(cw + j), w1 = *(const f32x4*)(cw + DFF + j), w2 = *(const f32x4*)(cw + 2 * DFF + j), bb = *(const f32x4*)(cb + j);
; #pragma unroll
;             for (int ai = 0; ai < 2; ++ai) { const int q = 2 * ai + wr;
;                 const f32x4 bup = (q > 0) ? *(LAS f32x4*)(xl + (q - 1) * 128 + cc) : (f32x4){0.f, 0.f, 0.f, 0.f};
;                 const f32x4 bdn = (q < 3) ? *(LAS f32x4*)(xf + (q + 1) * 128 + cc) : (f32x4){0.f, 0.f, 0.f, 0.f};
;                 f32x4 Rprev = bup, Dcur;
; #pragma unroll
;                 for (int e = 0; e < 4; ++e) Dcur[e] = ROR15(acc[ai][0][0][n][e]);
; #pragma unroll
;                 for (int m = 0; m < 4; ++m) {
;                     f32x4 Rm, Dnext = bdn;
; #pragma unroll
;                     for (int e = 0; e < 4; ++e) { Rm[e] = ROR1(acc[ai][0][m][n][e]); if (m < 3) Dnext[e] = ROR15(acc[ai][0][m < 3 ? m + 1 : 3][n][e]); }
;                     const f32x4 up = (fr > 0) ? Rm : Rprev;
;                     const f32x4 dn = (fr < 15) ? Dcur : Dnext;
;                     Rprev = Rm; Dcur = Dnext;
;                     const int rr = q * 64 + m * 16 + fr, sq = s0 + rr;
;                     const f32x4 g = acc[ai][0][m][n], v = acc[ai][1][m][n];
;                     f32x4 o;
; #pragma unroll
;                     for (int e = 0; e < 4; ++e) { const float z = w0[e] * up[e] + w1[e] * g[e] + w2[e] * dn[e] + bb[e]; o[e] = z * __builtin_amdgcn_rcpf(1.f + __builtin_amdgcn_exp2f(-1.4426950408889634f * z)) * v[e]; }
;                     if (rr >= 1 && rr <= 254) { u32x2 w; w.x = cvt_pk_bf16(o[0], o[1]); w.y = cvt_pk_bf16(o[2], o[3]);
;                         *(u32x2*)(act + (size_t)(sbase + sq) * DFF + j) = w; }
;                     if (rr < 2 || rr > 253) { const int rid = rr < 2 ? rr : rr - 252; *(f32x4*)(sbp + (size_t)rid * DFF + j) = g;
;                         if (rr == 0 || rr == 255) *(f32x4*)(sbp + (size_t)(4 + (rr == 255)) * DFF + j) = v; }
.LffnB_bj_11:
	v_cndmask_b32_e64 v206, v194, v198, s[10:11]
	v_cndmask_b32_e64 v207, v195, v199, s[10:11]
	v_cndmask_b32_e64 v208, v196, v200, s[10:11]
	v_cndmask_b32_e64 v209, v197, v201, s[10:11]
	v_mul_f32_e32 v28, v126, v28
	v_mul_f32_e32 v29, v127, v29
	v_mul_f32_e32 v30, v128, v30
	v_mul_f32_e32 v31, v129, v31
	v_mul_f32_e32 v206, v130, v206
	v_mul_f32_e32 v207, v131, v207
	v_mul_f32_e32 v208, v132, v208
	v_mul_f32_e32 v209, v133, v209
	v_fmac_f32_e32 v28, v122, v202
	v_fmac_f32_e32 v29, v123, v203
	v_fmac_f32_e32 v30, v124, v204
	v_fmac_f32_e32 v31, v125, v205
	v_add_f32_e32 v28, v206, v28
	v_add_f32_e32 v29, v207, v29
	v_add_f32_e32 v30, v208, v30
	v_add_f32_e32 v31, v209, v31
	v_add_f32_e32 v28, v134, v28
	v_add_f32_e32 v29, v135, v29
	v_add_f32_e32 v30, v136, v30
	v_add_f32_e32 v31, v137, v31
	v_mul_f32_e32 v202, 0xbfb8aa3b, v28
	v_mul_f32_e32 v203, 0xbfb8aa3b, v29
	v_mul_f32_e32 v204, 0xbfb8aa3b, v30
	v_mul_f32_e32 v205, 0xbfb8aa3b, v31
	v_exp_f32_e32 v202, v202
	v_exp_f32_e32 v203, v203
	v_exp_f32_e32 v204, v204
	v_exp_f32_e32 v205, v205
	v_add_f32_e32 v202, 1.0, v202
	v_add_f32_e32 v203, 1.0, v203
	v_add_f32_e32 v204, 1.0, v204
	v_add_f32_e32 v205, 1.0, v205
	v_rcp_f32_e32 v202, v202
	v_rcp_f32_e32 v203, v203
	v_rcp_f32_e32 v204, v204
	v_rcp_f32_e32 v205, v205
	v_mul_f32_e32 v28, v28, v202
	v_mul_f32_e32 v29, v29, v203
	v_mul_f32_e32 v30, v30, v204
	v_mul_f32_e32 v31, v31, v205
	v_mul_f32_e32 v28, v24, v28
	v_mul_f32_e32 v29, v25, v29
	v_mul_f32_e32 v30, v26, v30
	v_mul_f32_e32 v31, v27, v31
	v_cvt_pk_bf16_f32 v206, v28, v29
	v_cvt_pk_bf16_f32 v207, v30, v31
	v_add_u32_e32 v169, 0xb0000, v168
	global_store_dwordx2 v169, v[206:207], s[18:19] offset:8
	v_mov_b32_dpp v190, v20 row_ror:1 row_mask:0xf bank_mask:0xf
	v_mov_b32_dpp v191, v21 row_ror:1 row_mask:0xf bank_mask:0xf
	v_mov_b32_dpp v192, v22 row_ror:1 row_mask:0xf bank_mask:0xf
	v_mov_b32_dpp v193, v23 row_ror:1 row_mask:0xf bank_mask:0xf
	v_mov_b32_dpp v194, v12 row_ror:15 row_mask:0xf bank_mask:0xf
	v_mov_b32_dpp v195, v13 row_ror:15 row_mask:0xf bank_mask:0xf
	v_mov_b32_dpp v196, v14 row_ror:15 row_mask:0xf bank_mask:0xf
	v_mov_b32_dpp v197, v15 row_ror:15 row_mask:0xf bank_mask:0xf
	v_cndmask_b32_e64 v202, v190, v150, s[8:9]
	v_cndmask_b32_e64 v203, v191, v151, s[8:9]
	v_cndmask_b32_e64 v204, v192, v152, s[8:9]
	v_cndmask_b32_e64 v205, v193, v153, s[8:9]
	v_cndmask_b32_e64 v206, v198, v194, s[10:11]
	v_cndmask_b32_e64 v207, v199, v195, s[10:11]
	v_cndmask_b32_e64 v208, v200, v196, s[10:11]
	v_cndmask_b32_e64 v209, v201, v197, s[10:11]
	v_mul_f32_e32 v20, v126, v20
	v_mul_f32_e32 v21, v127, v21
	v_mul_f32_e32 v22, v128, v22
	v_mul_f32_e32 v23, v129, v23
	v_mul_f32_e32 v206, v130, v206
	v_mul_f32_e32 v207, v131, v207
	v_mul_f32_e32 v208, v132, v208
	v_mul_f32_e32 v209, v133, v209
	v_fmac_f32_e32 v20, v122, v202
	v_fmac_f32_e32 v21, v123, v203
	v_fmac_f32_e32 v22, v124, v204
	v_fmac_f32_e32 v23, v125, v205
	v_add_f32_e32 v20, v206, v20
	v_add_f32_e32 v21, v207, v21
	v_add_f32_e32 v22, v208, v22
	v_add_f32_e32 v23, v209, v23
	v_add_f32_e32 v20, v134, v20
	v_add_f32_e32 v21, v135, v21
	v_add_f32_e32 v22, v136, v22
	v_add_f32_e32 v23, v137, v23
	v_mul_f32_e32 v202, 0xbfb8aa3b, v20
	v_mul_f32_e32 v203, 0xbfb8aa3b, v21
	v_mul_f32_e32 v204, 0xbfb8aa3b, v22
	v_mul_f32_e32 v205, 0xbfb8aa3b, v23
	v_exp_f32_e32 v202, v202
	v_exp_f32_e32 v203, v203
	v_exp_f32_e32 v204, v204
	v_exp_f32_e32 v205, v205
	v_add_f32_e32 v202, 1.0, v202
	v_add_f32_e32 v203, 1.0, v203
	v_add_f32_e32 v204, 1.0, v204
	v_add_f32_e32 v205, 1.0, v205
	v_rcp_f32_e32 v202, v202
	v_rcp_f32_e32 v203, v203
	v_rcp_f32_e32 v204, v204
	v_rcp_f32_e32 v205, v205
	v_mul_f32_e32 v20, v20, v202
	v_mul_f32_e32 v21, v21, v203
	v_mul_f32_e32 v22, v22, v204
	v_mul_f32_e32 v23, v23, v205
	v_mul_f32_e32 v20, v16, v20
	v_mul_f32_e32 v21, v17, v21
	v_mul_f32_e32 v22, v18, v22
	v_mul_f32_e32 v23, v19, v23
	v_cvt_pk_bf16_f32 v206, v20, v21
	v_cvt_pk_bf16_f32 v207, v22, v23
	v_add_u32_e32 v169, 0xc6000, v168
	global_store_dwordx2 v169, v[206:207], s[18:19] offset:8
	v_mov_b32_dpp v150, v12 row_ror:1 row_mask:0xf bank_mask:0xf
	v_mov_b32_dpp v151, v13 row_ror:1 row_mask:0xf bank_mask:0xf
	v_mov_b32_dpp v152, v14 row_ror:1 row_mask:0xf bank_mask:0xf
	v_mov_b32_dpp v153, v15 row_ror:1 row_mask:0xf bank_mask:0xf
	v_mov_b32_dpp v198, v4 row_ror:15 row_mask:0xf bank_mask:0xf
	v_mov_b32_dpp v199, v5 row_ror:15 row_mask:0xf bank_mask:0xf
	v_mov_b32_dpp v200, v6 row_ror:15 row_mask:0xf bank_mask:0xf
	v_mov_b32_dpp v201, v7 row_ror:15 row_mask:0xf bank_mask:0xf
	v_cndmask_b32_e64 v202, v150, v190, s[8:9]
	v_cndmask_b32_e64 v203, v151, v191, s[8:9]
	v_cndmask_b32_e64 v204, v152, v192, s[8:9]
	v_cndmask_b32_e64 v205, v153, v193, s[8:9]
	v_cndmask_b32_e64 v206, v194, v198, s[10:11]
	v_cndmask_b32_e64 v207, v195, v199, s[10:11]
	v_cndmask_b32_e64 v208, v196, v200, s[10:11]
	v_cndmask_b32_e64 v209, v197, v201, s[10:11]
	v_mul_f32_e32 v12, v126, v12
	v_mul_f32_e32 v13, v127, v13
	v_mul_f32_e32 v14, v128, v14
	v_mul_f32_e32 v15, v129, v15
	v_mul_f32_e32 v206, v130, v206
	v_mul_f32_e32 v207, v131, v207
	v_mul_f32_e32 v208, v132, v208
	v_mul_f32_e32 v209, v133, v209
	v_fmac_f32_e32 v12, v122, v202
	v_fmac_f32_e32 v13, v123, v203
	v_fmac_f32_e32 v14, v124, v204
	v_fmac_f32_e32 v15, v125, v205
	v_add_f32_e32 v12, v206, v12
	v_add_f32_e32 v13, v207, v13
	v_add_f32_e32 v14, v208, v14
	v_add_f32_e32 v15, v209, v15
	v_add_f32_e32 v12, v134, v12
	v_add_f32_e32 v13, v135, v13
	v_add_f32_e32 v14, v136, v14
	v_add_f32_e32 v15, v137, v15
	v_mul_f32_e32 v202, 0xbfb8aa3b, v12
	v_mul_f32_e32 v203, 0xbfb8aa3b, v13
	v_mul_f32_e32 v204, 0xbfb8aa3b, v14
	v_mul_f32_e32 v205, 0xbfb8aa3b, v15
	v_exp_f32_e32 v202, v202
	v_exp_f32_e32 v203, v203
	v_exp_f32_e32 v204, v204
	v_exp_f32_e32 v205, v205
	v_add_f32_e32 v202, 1.0, v202
	v_add_f32_e32 v203, 1.0, v203
	v_add_f32_e32 v204, 1.0, v204
	v_add_f32_e32 v205, 1.0, v205
	v_rcp_f32_e32 v202, v202
	v_rcp_f32_e32 v203, v203
	v_rcp_f32_e32 v204, v204
	v_rcp_f32_e32 v205, v205
	v_mul_f32_e32 v12, v12, v202
	v_mul_f32_e32 v13, v13, v203
	v_mul_f32_e32 v14, v14, v204
	v_mul_f32_e32 v15, v15, v205
	v_mul_f32_e32 v12, v8, v12
	v_mul_f32_e32 v13, v9, v13
	v_mul_f32_e32 v14, v10, v14
	v_mul_f32_e32 v15, v11, v15
	v_cvt_pk_bf16_f32 v206, v12, v13
	v_cvt_pk_bf16_f32 v207, v14, v15
	v_add_u32_e32 v169, 0xdc000, v168
	global_store_dwordx2 v169, v[206:207], s[18:19] offset:8
	s_cmp_eq_u32 s7, 1
	s_cbranch_scc0 .LffnB_ns_12
	v_mul_u32_u24_e32 v171, 0x2c00, v166
	v_cmp_lt_u32_e64 s[30:31], 13, v166
	v_add_u32_e32 v171, v171, v167
	v_add_u32_e32 v171, 0xfffdf000, v171
	s_nop 1
	s_mov_b64 exec, s[30:31]
	global_store_dwordx4 v171, v[4:7], s[24:25] offset:16
	s_mov_b64 exec, s[10:11]
	global_store_dwordx4 v171, v[0:3], s[28:29] offset:16
	s_mov_b64 exec, -1
	s_nop 4
; template <class Epi>
; DEV void gemm_phase(LAS unsigned char* lds, const Gemm g, const Sched& S, const Epi& E, const int tid) {
;     ...
;         if (!has_next) break;
; #pragma unroll
;         for (int a = 0; a < 2; ++a)
;     DEV void operator()(const Acc& acc, const Unit& u, int wr, int wc, int fr, int fq, LAS unsigned char* misc) const {
;     ...
;         for (int n = 0; n < 2; ++n) { const int cc = wc * 32 + 8 * fq + 4 * n, j = u.pn * 128 + cc;
;             const f32x4 w0 = *(const f32x4*)(cw + j), w1 = *(const f32x4*)(cw + DFF + j), w2 = *(const f32x4*)(cw + 2 * DFF + j), bb = *(const f32x4*)(cb + j);
; #pragma unroll
;             for (int ai = 0; ai < 2; ++ai) { const int q = 2 * ai + wr;
;                 const f32x4 bup = (q > 0) ? *(LAS f32x4*)(xl + (q - 1) * 128 + cc) : (f32x4){0.f, 0.f, 0.f, 0.f};
;                 const f32x4 bdn = (q < 3) ? *(LAS f32x4*)(xf + (q + 1) * 128 + cc) : (f32x4){0.f, 0.f, 0.f, 0.f};
;                 f32x4 Rprev = bup, Dcur;
; #pragma unroll
;                 for (int e = 0; e < 4; ++e) Dcur[e] = ROR15(acc[ai][0][0][n][e]);
; #pragma unroll
;                 for (int m = 0; m < 4; ++m) {
;                     f32x4 Rm, Dnext = bdn;
; #pragma unroll
;                     for (int e = 0; e < 4; ++e) { Rm[e] = ROR1(acc[ai][0][m][n][e]); if (m < 3) Dnext[e] = ROR15(acc[ai][0][m < 3 ? m + 1 : 3][n][e]); }
;                     const f32x4 up = (fr > 0) ? Rm : Rprev;
;                     const f32x4 dn = (fr < 15) ? Dcur : Dnext;
;                     Rprev = Rm; Dcur = Dnext;
;                     const int rr = q * 64 + m * 16 + fr, sq = s0 + rr;
;                     const f32x4 g = acc[ai][0][m][n], v = acc[ai][1][m][n];
;                     f32x4 o;
; #pragma unroll
;                     for (int e = 0; e < 4; ++e) { const float z = w0[e] * up[e] + w1[e] * g[e] + w2[e] * dn[e] + bb[e]; o[e] = z * __builtin_amdgcn_rcpf(1.f + __builtin_amdgcn_exp2f(-1.4426950408889634f * z)) * v[e]; }
;                     if (rr >= 1 && rr <= 254) { u32x2 w; w.x = cvt_pk_bf16(o[0], o[1]); w.y = cvt_pk_bf16(o[2], o[3]);
;                         *(u32x2*)(act + (size_t)(sbase + sq) * DFF + j) = w; }
;                     if (rr < 2 || rr > 253) { const int rid = rr < 2 ? rr : rr - 252; *(f32x4*)(sbp + (size_t)rid * DFF + j) = g;
;                         if (rr == 0 || rr == 255) *(f32x4*)(sbp + (size_t)(4 + (rr == 255)) * DFF + j) = v; }
.LffnB_ns_12:
	v_mov_b32_dpp v190, v4 row_ror:1 row_mask:0xf bank_mask:0xf
	v_mov_b32_dpp v191, v5 row_ror:1 row_mask:0xf bank_mask:0xf
	v_mov_b32_dpp v192, v6 row_ror:1 row_mask:0xf bank_mask:0xf
	v_mov_b32_dpp v193, v7 row_ror:1 row_mask:0xf bank_mask:0xf
	v_cndmask_b32_e64 v202, v190, v150, s[8:9]
	v_cndmask_b32_e64 v203, v191, v151, s[8:9]
	v_cndmask_b32_e64 v204, v192, v152, s[8:9]
	v_cndmask_b32_e64 v205, v193, v153, s[8:9]
	s_waitcnt lgkmcnt(0)
	v_cndmask_b32_e64 v206, v198, v146, s[10:11]
	v_cndmask_b32_e64 v207, v199, v147, s[10:11]
	v_cndmask_b32_e64 v208, v200, v148, s[10:11]
	v_cndmask_b32_e64 v209, v201, v149, s[10:11]
	v_mul_f32_e32 v4, v126, v4
	v_mul_f32_e32 v5, v127, v5
	v_mul_f32_e32 v6, v128, v6
	v_mul_f32_e32 v7, v129, v7
	v_mul_f32_e32 v206, v130, v206
	v_mul_f32_e32 v207, v131, v207
	v_mul_f32_e32 v208, v132, v208
	v_mul_f32_e32 v209, v133, v209
	v_fmac_f32_e32 v4, v122, v202
	v_fmac_f32_e32 v5, v123, v203
	v_fmac_f32_e32 v6, v124, v204
	v_fmac_f32_e32 v7, v125, v205
	v_add_f32_e32 v4, v206, v4
	v_add_f32_e32 v5, v207, v5
	v_add_f32_e32 v6, v208, v6
	v_add_f32_e32 v7, v209, v7
	v_add_f32_e32 v4, v134, v4
	v_add_f32_e32 v5, v135, v5
	v_add_f32_e32 v6, v136, v6
	v_add_f32_e32 v7, v137, v7
	v_mul_f32_e32 v202, 0xbfb8aa3b, v4
	v_mul_f32_e32 v203, 0xbfb8aa3b, v5
	v_mul_f32_e32 v204, 0xbfb8aa3b, v6
	v_mul_f32_e32 v205, 0xbfb8aa3b, v7
	v_exp_f32_e32 v202, v202
	v_exp_f32_e32 v203, v203
	v_exp_f32_e32 v204, v204
	v_exp_f32_e32 v205, v205
	v_add_f32_e32 v202, 1.0, v202
	v_add_f32_e32 v203, 1.0, v203
	v_add_f32_e32 v204, 1.0, v204
	v_add_f32_e32 v205, 1.0, v205
	v_rcp_f32_e32 v202, v202
	v_rcp_f32_e32 v203, v203
	v_rcp_f32_e32 v204, v204
	v_rcp_f32_e32 v205, v205
	v_mul_f32_e32 v4, v4, v202
	v_mul_f32_e32 v5, v5, v203
	v_mul_f32_e32 v6, v6, v204
	v_mul_f32_e32 v7, v7, v205
	v_mul_f32_e32 v4, v0, v4
	v_mul_f32_e32 v5, v1, v5
	v_mul_f32_e32 v6, v2, v6
	v_mul_f32_e32 v7, v3, v7
	v_cvt_pk_bf16_f32 v206, v4, v5
	v_cvt_pk_bf16_f32 v207, v6, v7
	v_add_u32_e32 v169, 0xf2000, v168
	s_mov_b64 exec, s[16:17]
	global_store_dwordx2 v169, v[206:207], s[18:19] offset:8
	s_mov_b64 exec, -1
	s_nop 4
	v_readlane_b32 s79, v249, 16
	s_and_b64 vcc, exec, s[2:3]
	s_mov_b64 s[2:3], -1
	s_cbranch_vccnz .LBB0_1745
	v_readlane_b32 s2, v251, 24
	v_readlane_b32 s3, v251, 25
	s_andn2_b64 vcc, exec, s[2:3]
	s_cbranch_vccnz .LBB0_1744
	s_barrier
	s_branch .LBB0_1744

; DEV unsigned cvt_pk_bf16(float lo, float hi) { unsigned r; asm volatile("v_cvt_pk_bf16_f32 %0, %1, %2" : "=v"(r) : "v"(lo), "v"(hi)); return r; }
; DEV void modnorm_rows(const float* srcX, const float* srcC, int nrows, const float* g, const float* shift, const float* scale, bf16_t* dst, int gw, int NGW, int lane) {
;     for (int row0 = gw; row0 < nrows; row0 += 2 * NGW) {
;         const int row1 = row0 + NGW; const bool has1 = row1 < nrows;
;         const float* xr0 = (row0 < TX) ? srcX + (size_t)row0 * DM : srcC + (size_t)(row0 - TX) * DM;
;         const float* xr1 = !has1 ? xr0 : ((row1 < TX) ? srcX + (size_t)row1 * DM : srcC + (size_t)(row1 - TX) * DM);
;         f32x4 v0[4], v1[4]; float s0 = 0.f, s1 = 0.f;
; #pragma unroll
;         for (int j = 0; j < 4; ++j) { v0[j] = __builtin_nontemporal_load((const f32x4*)(xr0 + 256 * j + 4 * lane)); v1[j] = __builtin_nontemporal_load((const f32x4*)(xr1 + 256 * j + 4 * lane)); }
; #pragma unroll
;         for (int j = 0; j < 4; ++j) { s0 += (v0[j][0] * v0[j][0] + v0[j][1] * v0[j][1]) + (v0[j][2] * v0[j][2] + v0[j][3] * v0[j][3]); s1 += (v1[j][0] * v1[j][0] + v1[j][1] * v1[j][1]) + (v1[j][2] * v1[j][2] + v1[j][3] * v1[j][3]); }
;         const float rstd0 = 1.0f / sqrtf(wave_sum(s0) * (1.f / DM) + EPS), rstd1 = 1.0f / sqrtf(wave_sum(s1) * (1.f / DM) + EPS);
;         const int mr0 = (row0 < TX) ? (row0 >> 12) : 8, mr1 = (row1 < TX) ? (row1 >> 12) : 8;
; #pragma unroll
;         for (int j = 0; j < 4; ++j) { const int col = 256 * j + 4 * lane; const f32x4 gg = *(const f32x4*)(g + col);
;             { const f32x4 sh = *(const f32x4*)(shift + (size_t)mr0 * 6144 + col), sc = *(const f32x4*)(scale + (size_t)mr0 * 6144 + col); f32x4 y;
; #pragma unroll
;                 for (int e = 0; e < 4; ++e) y[e] = (v0[j][e] * rstd0 * gg[e]) * (1.f + sc[e]) + sh[e];
;                 u32x2 w; w.x = cvt_pk_bf16(y[0], y[1]); w.y = cvt_pk_bf16(y[2], y[3]); *(u32x2*)(dst + (size_t)row0 * DM + col) = w; }
;             if (has1) { const f32x4 sh = *(const f32x4*)(shift + (size_t)mr1 * 6144 + col), sc = *(const f32x4*)(scale + (size_t)mr1 * 6144 + col); f32x4 y;
; #pragma unroll
;                 for (int e = 0; e < 4; ++e) y[e] = (v1[j][e] * rstd1 * gg[e]) * (1.f + sc[e]) + sh[e];
;                 u32x2 w; w.x = cvt_pk_bf16(y[0], y[1]); w.y = cvt_pk_bf16(y[2], y[3]); *(u32x2*)(dst + (size_t)row1 * DM + col) = w; } }
;     }
; }
.LBB0_2080:
	v_readlane_b32 s0, v251, 4
	v_mbcnt_lo_u32_b32 v0, -1, 0
	v_mbcnt_hi_u32_b32 v0, -1, v0
	v_readlane_b32 s22, v248, 8
	s_lshl_b32 s29, s22, 3
	v_add_u32_e32 v131, s0, v0
	s_mov_b64 s[2:3], -1
	v_readfirstlane_b32 s0, v131
	s_ashr_i32 s28, s0, 6
	s_add_i32 s0, s28, s29
	v_and_b32_e32 v133, 63, v131
	s_cmp_lt_i32 s82, 14
	s_cbranch_scc1 .LBB0_2156
	s_cmp_lt_i32 s82, 15
	s_cbranch_scc1 .LBB0_2147
	s_cmp_lt_i32 s82, 17
	s_cbranch_scc1 .LBB0_2096
	s_cmp_eq_u32 s82, 17
	s_cbranch_scc0 .LBB0_2095
	s_cmpk_gt_i32 s0, 0x7fff
	s_cbranch_scc1 .LBB0_2095
	v_readlane_b32 s2, v251, 2
	v_readlane_b32 s3, v251, 3
	v_readlane_b32 s1, v251, 1
	v_readlane_b32 s14, v251, 0
	v_readlane_b32 s20, v251, 4
	v_mbcnt_lo_u32_b32 v122, -1, 0
	v_mbcnt_hi_u32_b32 v122, -1, v122
	s_load_dwordx2 s[12:13], s[2:3], 0x110
	s_load_dwordx2 s[16:17], s[2:3], 0x28
	s_lshl_b32 s1, s1, 3
	s_lshl_b32 s14, s14, 3
	s_lshr_b32 s20, s20, 6
	s_add_u32 s14, s14, s20
	s_mov_b32 s15, s14
	v_lshlrev_b32_e32 v123, 3, v122
	v_lshlrev_b32_e32 v122, 4, v122
	v_mov_b32_e32 v140, 0x358637bd
	v_mov_b32_e32 v141, 0x260
	s_waitcnt lgkmcnt(0)
	s_add_u32 s16, s16, 0x1000
	s_addc_u32 s17, s17, 0
	global_load_dwordx4 v[98:101], v122, s[16:17] offset:0
	global_load_dwordx4 v[102:105], v122, s[16:17] offset:1024
	global_load_dwordx4 v[106:109], v122, s[16:17] offset:2048
	global_load_dwordx4 v[110:113], v122, s[16:17] offset:3072
	s_add_u32 s4, s12, 0x1c00000
	s_addc_u32 s5, s13, 0
	s_add_u32 s6, s4, 0x8000000
	s_addc_u32 s7, s5, 0
	s_add_u32 s8, s12, 0x39000
	s_addc_u32 s9, s13, 0
	s_add_u32 s10, s12, 0x3a000
	s_addc_u32 s11, s13, 0
	s_add_u32 s12, s12, 0xa400000
	s_addc_u32 s13, s13, 0
	s_cmp_ge_i32 s14, 0x8000
	s_cbranch_scc1 .Lmn17_ni_2
	s_sub_i32 s21, s14, 0x8000
	s_lshr_b32 s20, s14, 12
	s_cmp_lt_i32 s14, 0x8000
	s_cselect_b32 s21, s14, s21
	s_cselect_b32 s20, s20, 8
	s_cselect_b32 s16, s4, s6
	s_cselect_b32 s17, s5, s7
	s_lshl_b32 s21, s21, 12
	s_mul_i32 s20, s20, 0x6000
	s_add_u32 s16, s16, s21
	s_addc_u32 s17, s17, 0
	s_add_u32 s18, s8, s20
	s_addc_u32 s19, s9, 0
	global_load_dwordx4 v[0:3], v122, s[16:17] offset:0 nt
	global_load_dwordx4 v[4:7], v122, s[16:17] offset:1024 nt
	global_load_dwordx4 v[8:11], v122, s[16:17] offset:2048 nt
	global_load_dwordx4 v[12:15], v122, s[16:17] offset:3072 nt
	global_load_dwordx4 v[16:19], v122, s[18:19] offset:0
	global_load_dwordx4 v[20:23], v122, s[18:19] offset:1024
	global_load_dwordx4 v[24:27], v122, s[18:19] offset:2048
	global_load_dwordx4 v[28:31], v122, s[18:19] offset:3072
	s_add_u32 s18, s10, s20
	s_addc_u32 s19, s11, 0
	global_load_dwordx4 v[32:35], v122, s[18:19] offset:0
	global_load_dwordx4 v[36:39], v122, s[18:19] offset:1024
	global_load_dwordx4 v[40:43], v122, s[18:19] offset:2048
	global_load_dwordx4 v[44:47], v122, s[18:19] offset:3072
.Lmn17_ni_2:
	s_add_u32 s14, s14, s1
	s_cmp_ge_i32 s14, 0x8000
	s_cbranch_scc1 .Lmn17_ni_3
	s_sub_i32 s21, s14, 0x8000
	s_lshr_b32 s20, s14, 12
	s_cmp_lt_i32 s14, 0x8000
	s_cselect_b32 s21, s14, s21
	s_cselect_b32 s20, s20, 8
	s_cselect_b32 s16, s4, s6
	s_cselect_b32 s17, s5, s7
	s_lshl_b32 s21, s21, 12
	s_mul_i32 s20, s20, 0x6000
	s_add_u32 s16, s16, s21
	s_addc_u32 s17, s17, 0
	s_add_u32 s18, s8, s20
	s_addc_u32 s19, s9, 0
	global_load_dwordx4 v[48:51], v122, s[16:17] offset:0 nt
	global_load_dwordx4 v[52:55], v122, s[16:17] offset:1024 nt
	global_load_dwordx4 v[56:59], v122, s[16:17] offset:2048 nt
	global_load_dwordx4 v[60:63], v122, s[16:17] offset:3072 nt
	global_load_dwordx4 v[64:67], v122, s[18:19] offset:0
	global_load_dwordx4 v[68:71], v122, s[18:19] offset:1024
	global_load_dwordx4 v[72:75], v122, s[18:19] offset:2048
	global_load_dwordx4 v[76:79], v122, s[18:19] offset:3072
	s_add_u32 s18, s10, s20
	s_addc_u32 s19, s11, 0
	global_load_dwordx4 v[80:83], v122, s[18:19] offset:0
	global_load_dwordx4 v[84:87], v122, s[18:19] offset:1024
	global_load_dwordx4 v[88:91], v122, s[18:19] offset:2048
	global_load_dwordx4 v[92:95], v122, s[18:19] offset:3072
.Lmn17_ni_3:
	s_add_u32 s14, s14, s1
	s_waitcnt vmcnt(24)
	s_cmp_ge_i32 s15, 0x8000
	s_cbranch_scc1 .Lmn17_done_1
	s_add_u32 s20, s15, s1
	s_cmp_ge_i32 s20, 0x8000
	s_cbranch_scc1 .Lmn17_wl_4
	s_waitcnt vmcnt(12)
	s_branch .Lmn17_wj_5

; DEV unsigned cvt_pk_bf16(float lo, float hi) { unsigned r; asm volatile("v_cvt_pk_bf16_f32 %0, %1, %2" : "=v"(r) : "v"(lo), "v"(hi)); return r; }
; DEV void modnorm_rows(const float* srcX, const float* srcC, int nrows, const float* g, const float* shift, const float* scale, bf16_t* dst, int gw, int NGW, int lane) {
;     ...
;         f32x4 v0[4], v1[4]; float s0 = 0.f, s1 = 0.f;
; #pragma unroll
;         for (int j = 0; j < 4; ++j) { v0[j] = __builtin_nontemporal_load((const f32x4*)(xr0 + 256 * j + 4 * lane)); v1[j] = __builtin_nontemporal_load((const f32x4*)(xr1 + 256 * j + 4 * lane)); }
; #pragma unroll
;         for (int j = 0; j < 4; ++j) { s0 += (v0[j][0] * v0[j][0] + v0[j][1] * v0[j][1]) + (v0[j][2] * v0[j][2] + v0[j][3] * v0[j][3]); s1 += (v1[j][0] * v1[j][0] + v1[j][1] * v1[j][1]) + (v1[j][2] * v1[j][2] + v1[j][3] * v1[j][3]); }
;         const float rstd0 = 1.0f / sqrtf(wave_sum(s0) * (1.f / DM) + EPS), rstd1 = 1.0f / sqrtf(wave_sum(s1) * (1.f / DM) + EPS);
;         const int mr0 = (row0 < TX) ? (row0 >> 12) : 8, mr1 = (row1 < TX) ? (row1 >> 12) : 8;
; #pragma unroll
;         for (int j = 0; j < 4; ++j) { const int col = 256 * j + 4 * lane; const f32x4 gg = *(const f32x4*)(g + col);
;             { const f32x4 sh = *(const f32x4*)(shift + (size_t)mr0 * 6144 + col), sc = *(const f32x4*)(scale + (size_t)mr0 * 6144 + col); f32x4 y;
; #pragma unroll
;                 for (int e = 0; e < 4; ++e) y[e] = (v0[j][e] * rstd0 * gg[e]) * (1.f + sc[e]) + sh[e];
;                 u32x2 w; w.x = cvt_pk_bf16(y[0], y[1]); w.y = cvt_pk_bf16(y[2], y[3]); *(u32x2*)(dst + (size_t)row0 * DM + col) = w; }
;             if (has1) { const f32x4 sh = *(const f32x4*)(shift + (size_t)mr1 * 6144 + col), sc = *(const f32x4*)(scale + (size_t)mr1 * 6144 + col); f32x4 y;
; #pragma unroll
;                 for (int e = 0; e < 4; ++e) y[e] = (v1[j][e] * rstd1 * gg[e]) * (1.f + sc[e]) + sh[e];
;                 u32x2 w; w.x = cvt_pk_bf16(y[0], y[1]); w.y = cvt_pk_bf16(y[2], y[3]); *(u32x2*)(dst + (size_t)row1 * DM + col) = w; } }
.Lmn17_wj_5:
	v_mul_f32_e32 v114, v1, v1
	v_mul_f32_e32 v115, v3, v3
	v_mul_f32_e32 v116, v5, v5
	v_mul_f32_e32 v117, v7, v7
	v_mul_f32_e32 v118, v9, v9
	v_mul_f32_e32 v119, v11, v11
	v_mul_f32_e32 v120, v13, v13
	v_mul_f32_e32 v121, v15, v15
	v_fmac_f32_e32 v114, v0, v0
	v_fmac_f32_e32 v115, v2, v2
	v_fmac_f32_e32 v116, v4, v4
	v_fmac_f32_e32 v117, v6, v6
	v_fmac_f32_e32 v118, v8, v8
	v_fmac_f32_e32 v119, v10, v10
	v_fmac_f32_e32 v120, v12, v12
	v_fmac_f32_e32 v121, v14, v14
	v_add_f32_e32 v114, v114, v115
	v_add_f32_e32 v116, v116, v117
	v_add_f32_e32 v118, v118, v119
	v_add_f32_e32 v120, v120, v121
	v_add_f32_e32 v124, v114, v116
	v_add_f32_e32 v124, v124, v118
	v_add_f32_e32 v124, v124, v120
	v_add_f32_e32 v32, 1.0, v32
	v_add_f32_e32 v33, 1.0, v33
	v_add_f32_dpp v124, v124, v124 quad_perm:[1,0,3,2] row_mask:0xf bank_mask:0xf
	v_add_f32_e32 v34, 1.0, v34
	v_add_f32_e32 v35, 1.0, v35
	v_add_f32_dpp v124, v124, v124 quad_perm:[2,3,0,1] row_mask:0xf bank_mask:0xf
	v_add_f32_e32 v36, 1.0, v36
	v_add_f32_e32 v37, 1.0, v37
	v_add_f32_dpp v124, v124, v124 row_half_mirror row_mask:0xf bank_mask:0xf
	v_add_f32_e32 v38, 1.0, v38
	v_add_f32_e32 v39, 1.0, v39
	v_add_f32_dpp v124, v124, v124 row_mirror row_mask:0xf bank_mask:0xf
	v_add_f32_e32 v40, 1.0, v40
	v_add_f32_e32 v41, 1.0, v41
	v_mov_b32_e32 v125, v124
	v_mov_b32_e32 v126, v124
	v_add_f32_e32 v42, 1.0, v42
	v_add_f32_e32 v43, 1.0, v43
	v_permlane16_swap_b32_e32 v125, v126
	v_add_f32_e32 v124, v125, v126
	v_mov_b32_e32 v125, v124
	v_mov_b32_e32 v126, v124
	v_add_f32_e32 v44, 1.0, v44
	v_add_f32_e32 v45, 1.0, v45
	v_permlane32_swap_b32_e32 v125, v126
	v_add_f32_e32 v124, v125, v126
	v_add_f32_e32 v46, 1.0, v46
	v_add_f32_e32 v47, 1.0, v47
	v_fmamk_f32 v124, v124, 0x3a800000, v140
	v_mul_f32_e32 v125, 0x4f800000, v124
	v_cmp_gt_f32_e32 vcc, 0xf800000, v124
	s_nop 1
	v_cndmask_b32_e32 v124, v124, v125, vcc
	v_sqrt_f32_e32 v127, v124
	s_nop 0
	v_add_u32_e32 v128, -1, v127
	v_add_u32_e32 v129, 1, v127
	v_fma_f32 v134, -v128, v127, v124
	v_fma_f32 v135, -v129, v127, v124
	v_cmp_ge_f32_e64 s[16:17], 0, v134
	v_cmp_lt_f32_e64 s[18:19], 0, v135
	s_nop 1
	v_cndmask_b32_e64 v127, v127, v128, s[16:17]
	v_cndmask_b32_e64 v127, v127, v129, s[18:19]
	v_mul_f32_e32 v125, 0x37800000, v127
	v_cndmask_b32_e32 v127, v127, v125, vcc
	v_cmp_class_f32_e32 vcc, v124, v141
	s_nop 1
	v_cndmask_b32_e32 v127, v127, v124, vcc
	v_div_scale_f32 v136, s[16:17], v127, v127, 1.0
	v_div_scale_f32 v138, vcc, 1.0, v127, 1.0
	v_rcp_f32_e32 v137, v136
	s_nop 0
	v_fma_f32 v134, -v136, v137, 1.0
	v_fmac_f32_e32 v137, v134, v137
	v_mul_f32_e32 v139, v138, v137
	v_fma_f32 v134, -v136, v139, v138
	v_fmac_f32_e32 v139, v134, v137
	v_fma_f32 v134, -v136, v139, v138
	v_div_fmas_f32 v134, v134, v137, v139
	v_div_fixup_f32 v134, v134, v127, 1.0
	v_mul_f32_e32 v0, v0, v134
	v_mul_f32_e32 v1, v1, v134
	v_mul_f32_e32 v2, v2, v134
	v_mul_f32_e32 v3, v3, v134
	v_mul_f32_e32 v4, v4, v134
	v_mul_f32_e32 v5, v5, v134
	v_mul_f32_e32 v6, v6, v134
	v_mul_f32_e32 v7, v7, v134
	v_mul_f32_e32 v8, v8, v134
	v_mul_f32_e32 v9, v9, v134
	v_mul_f32_e32 v10, v10, v134
	v_mul_f32_e32 v11, v11, v134
	v_mul_f32_e32 v12, v12, v134
	v_mul_f32_e32 v13, v13, v134
	v_mul_f32_e32 v14, v14, v134
	v_mul_f32_e32 v15, v15, v134
	v_mul_f32_e32 v0, v98, v0
	v_mul_f32_e32 v1, v99, v1
	v_mul_f32_e32 v2, v100, v2
	v_mul_f32_e32 v3, v101, v3
	v_mul_f32_e32 v4, v102, v4
	v_mul_f32_e32 v5, v103, v5
	v_mul_f32_e32 v6, v104, v6
	v_mul_f32_e32 v7, v105, v7
	v_mul_f32_e32 v8, v106, v8
	v_mul_f32_e32 v9, v107, v9
	v_mul_f32_e32 v10, v108, v10
	v_mul_f32_e32 v11, v109, v11
	v_mul_f32_e32 v12, v110, v12
	v_mul_f32_e32 v13, v111, v13
	v_mul_f32_e32 v14, v112, v14
	v_mul_f32_e32 v15, v113, v15
	v_fma_f32 v0, v0, v32, v16
	v_fma_f32 v1, v1, v33, v17
	v_fma_f32 v2, v2, v34, v18
	v_fma_f32 v3, v3, v35, v19
	v_fma_f32 v4, v4, v36, v20
	v_fma_f32 v5, v5, v37, v21
	v_fma_f32 v6, v6, v38, v22
	v_fma_f32 v7, v7, v39, v23
	v_fma_f32 v8, v8, v40, v24
	v_fma_f32 v9, v9, v41, v25
	v_fma_f32 v10, v10, v42, v26
	v_fma_f32 v11, v11, v43, v27
	v_fma_f32 v12, v12, v44, v28
	v_fma_f32 v13, v13, v45, v29
	v_fma_f32 v14, v14, v46, v30
	v_fma_f32 v15, v15, v47, v31
	v_cvt_pk_bf16_f32 v114, v0, v1
	v_cvt_pk_bf16_f32 v115, v2, v3
	v_cvt_pk_bf16_f32 v116, v4, v5
	v_cvt_pk_bf16_f32 v117, v6, v7
	v_cvt_pk_bf16_f32 v118, v8, v9
	v_cvt_pk_bf16_f32 v119, v10, v11
	v_cvt_pk_bf16_f32 v120, v12, v13
	v_cvt_pk_bf16_f32 v121, v14, v15
	s_lshl_b32 s21, s15, 11
	s_add_u32 s22, s12, s21
	s_addc_u32 s23, s13, 0
	s_cmp_ge_i32 s14, 0x8000
	s_cbranch_scc1 .Lmn17_ni_6
	s_sub_i32 s21, s14, 0x8000
	s_lshr_b32 s20, s14, 12
	s_cmp_lt_i32 s14, 0x8000
	s_cselect_b32 s21, s14, s21
	s_cselect_b32 s20, s20, 8
	s_cselect_b32 s16, s4, s6
	s_cselect_b32 s17, s5, s7
	s_lshl_b32 s21, s21, 12
	s_mul_i32 s20, s20, 0x6000
	s_add_u32 s16, s16, s21
	s_addc_u32 s17, s17, 0
	s_add_u32 s18, s8, s20
	s_addc_u32 s19, s9, 0
	global_load_dwordx4 v[0:3], v122, s[16:17] offset:0 nt
	global_load_dwordx4 v[4:7], v122, s[16:17] offset:1024 nt
	global_load_dwordx4 v[8:11], v122, s[16:17] offset:2048 nt
	global_load_dwordx4 v[12:15], v122, s[16:17] offset:3072 nt
	global_load_dwordx4 v[16:19], v122, s[18:19] offset:0
	global_load_dwordx4 v[20:23], v122, s[18:19] offset:1024
	global_load_dwordx4 v[24:27], v122, s[18:19] offset:2048
	global_load_dwordx4 v[28:31], v122, s[18:19] offset:3072
	s_add_u32 s18, s10, s20
	s_addc_u32 s19, s11, 0
	global_load_dwordx4 v[32:35], v122, s[18:19] offset:0
	global_load_dwordx4 v[36:39], v122, s[18:19] offset:1024
	global_load_dwordx4 v[40:43], v122, s[18:19] offset:2048
	global_load_dwordx4 v[44:47], v122, s[18:19] offset:3072
.Lmn17_ni_6:
	s_add_u32 s14, s14, s1
	global_store_dwordx2 v123, v[114:115], s[22:23] offset:0
	global_store_dwordx2 v123, v[116:117], s[22:23] offset:512
	global_store_dwordx2 v123, v[118:119], s[22:23] offset:1024
	global_store_dwordx2 v123, v[120:121], s[22:23] offset:1536
	s_add_u32 s15, s15, s1
	s_cmp_ge_i32 s15, 0x8000
	s_cbranch_scc1 .Lmn17_done_1
	s_add_u32 s20, s15, s1
	s_cmp_ge_i32 s20, 0x8000
	s_cbranch_scc1 .Lmn17_wl_7
	s_waitcnt vmcnt(16)
	s_branch .Lmn17_wj_8

; DEV unsigned cvt_pk_bf16(float lo, float hi) { unsigned r; asm volatile("v_cvt_pk_bf16_f32 %0, %1, %2" : "=v"(r) : "v"(lo), "v"(hi)); return r; }
; DEV void modnorm_rows(const float* srcX, const float* srcC, int nrows, const float* g, const float* shift, const float* scale, bf16_t* dst, int gw, int NGW, int lane) {
;     ...
;         f32x4 v0[4], v1[4]; float s0 = 0.f, s1 = 0.f;
; #pragma unroll
;         for (int j = 0; j < 4; ++j) { v0[j] = __builtin_nontemporal_load((const f32x4*)(xr0 + 256 * j + 4 * lane)); v1[j] = __builtin_nontemporal_load((const f32x4*)(xr1 + 256 * j + 4 * lane)); }
; #pragma unroll
;         for (int j = 0; j < 4; ++j) { s0 += (v0[j][0] * v0[j][0] + v0[j][1] * v0[j][1]) + (v0[j][2] * v0[j][2] + v0[j][3] * v0[j][3]); s1 += (v1[j][0] * v1[j][0] + v1[j][1] * v1[j][1]) + (v1[j][2] * v1[j][2] + v1[j][3] * v1[j][3]); }
;         const float rstd0 = 1.0f / sqrtf(wave_sum(s0) * (1.f / DM) + EPS), rstd1 = 1.0f / sqrtf(wave_sum(s1) * (1.f / DM) + EPS);
;         const int mr0 = (row0 < TX) ? (row0 >> 12) : 8, mr1 = (row1 < TX) ? (row1 >> 12) : 8;
; #pragma unroll
;         for (int j = 0; j < 4; ++j) { const int col = 256 * j + 4 * lane; const f32x4 gg = *(const f32x4*)(g + col);
;             { const f32x4 sh = *(const f32x4*)(shift + (size_t)mr0 * 6144 + col), sc = *(const f32x4*)(scale + (size_t)mr0 * 6144 + col); f32x4 y;
; #pragma unroll
;                 for (int e = 0; e < 4; ++e) y[e] = (v0[j][e] * rstd0 * gg[e]) * (1.f + sc[e]) + sh[e];
;                 u32x2 w; w.x = cvt_pk_bf16(y[0], y[1]); w.y = cvt_pk_bf16(y[2], y[3]); *(u32x2*)(dst + (size_t)row0 * DM + col) = w; }
;             if (has1) { const f32x4 sh = *(const f32x4*)(shift + (size_t)mr1 * 6144 + col), sc = *(const f32x4*)(scale + (size_t)mr1 * 6144 + col); f32x4 y;
; #pragma unroll
;                 for (int e = 0; e < 4; ++e) y[e] = (v1[j][e] * rstd1 * gg[e]) * (1.f + sc[e]) + sh[e];
;                 u32x2 w; w.x = cvt_pk_bf16(y[0], y[1]); w.y = cvt_pk_bf16(y[2], y[3]); *(u32x2*)(dst + (size_t)row1 * DM + col) = w; } }
.Lmn17_wj_8:
	v_mul_f32_e32 v114, v49, v49
	v_mul_f32_e32 v115, v51, v51
	v_mul_f32_e32 v116, v53, v53
	v_mul_f32_e32 v117, v55, v55
	v_mul_f32_e32 v118, v57, v57
	v_mul_f32_e32 v119, v59, v59
	v_mul_f32_e32 v120, v61, v61
	v_mul_f32_e32 v121, v63, v63
	v_fmac_f32_e32 v114, v48, v48
	v_fmac_f32_e32 v115, v50, v50
	v_fmac_f32_e32 v116, v52, v52
	v_fmac_f32_e32 v117, v54, v54
	v_fmac_f32_e32 v118, v56, v56
	v_fmac_f32_e32 v119, v58, v58
	v_fmac_f32_e32 v120, v60, v60
	v_fmac_f32_e32 v121, v62, v62
	v_add_f32_e32 v114, v114, v115
	v_add_f32_e32 v116, v116, v117
	v_add_f32_e32 v118, v118, v119
	v_add_f32_e32 v120, v120, v121
	v_add_f32_e32 v124, v114, v116
	v_add_f32_e32 v124, v124, v118
	v_add_f32_e32 v124, v124, v120
	v_add_f32_e32 v80, 1.0, v80
	v_add_f32_e32 v81, 1.0, v81
	v_add_f32_dpp v124, v124, v124 quad_perm:[1,0,3,2] row_mask:0xf bank_mask:0xf
	v_add_f32_e32 v82, 1.0, v82
	v_add_f32_e32 v83, 1.0, v83
	v_add_f32_dpp v124, v124, v124 quad_perm:[2,3,0,1] row_mask:0xf bank_mask:0xf
	v_add_f32_e32 v84, 1.0, v84
	v_add_f32_e32 v85, 1.0, v85
	v_add_f32_dpp v124, v124, v124 row_half_mirror row_mask:0xf bank_mask:0xf
	v_add_f32_e32 v86, 1.0, v86
	v_add_f32_e32 v87, 1.0, v87
	v_add_f32_dpp v124, v124, v124 row_mirror row_mask:0xf bank_mask:0xf
	v_add_f32_e32 v88, 1.0, v88
	v_add_f32_e32 v89, 1.0, v89
	v_mov_b32_e32 v125, v124
	v_mov_b32_e32 v126, v124
	v_add_f32_e32 v90, 1.0, v90
	v_add_f32_e32 v91, 1.0, v91
	v_permlane16_swap_b32_e32 v125, v126
	v_add_f32_e32 v124, v125, v126
	v_mov_b32_e32 v125, v124
	v_mov_b32_e32 v126, v124
	v_add_f32_e32 v92, 1.0, v92
	v_add_f32_e32 v93, 1.0, v93
	v_permlane32_swap_b32_e32 v125, v126
	v_add_f32_e32 v124, v125, v126
	v_add_f32_e32 v94, 1.0, v94
	v_add_f32_e32 v95, 1.0, v95
	v_fmamk_f32 v124, v124, 0x3a800000, v140
	v_mul_f32_e32 v125, 0x4f800000, v124
	v_cmp_gt_f32_e32 vcc, 0xf800000, v124
	s_nop 1
	v_cndmask_b32_e32 v124, v124, v125, vcc
	v_sqrt_f32_e32 v127, v124
	s_nop 0
	v_add_u32_e32 v128, -1, v127
	v_add_u32_e32 v129, 1, v127
	v_fma_f32 v134, -v128, v127, v124
	v_fma_f32 v135, -v129, v127, v124
	v_cmp_ge_f32_e64 s[16:17], 0, v134
	v_cmp_lt_f32_e64 s[18:19], 0, v135
	s_nop 1
	v_cndmask_b32_e64 v127, v127, v128, s[16:17]
	v_cndmask_b32_e64 v127, v127, v129, s[18:19]
	v_mul_f32_e32 v125, 0x37800000, v127
	v_cndmask_b32_e32 v127, v127, v125, vcc
	v_cmp_class_f32_e32 vcc, v124, v141
	s_nop 1
	v_cndmask_b32_e32 v127, v127, v124, vcc
	v_div_scale_f32 v136, s[16:17], v127, v127, 1.0
	v_div_scale_f32 v138, vcc, 1.0, v127, 1.0
	v_rcp_f32_e32 v137, v136
	s_nop 0
	v_fma_f32 v134, -v136, v137, 1.0
	v_fmac_f32_e32 v137, v134, v137
	v_mul_f32_e32 v139, v138, v137
	v_fma_f32 v134, -v136, v139, v138
	v_fmac_f32_e32 v139, v134, v137
	v_fma_f32 v134, -v136, v139, v138
	v_div_fmas_f32 v134, v134, v137, v139
	v_div_fixup_f32 v134, v134, v127, 1.0
	v_mul_f32_e32 v48, v48, v134
	v_mul_f32_e32 v49, v49, v134
	v_mul_f32_e32 v50, v50, v134
	v_mul_f32_e32 v51, v51, v134
	v_mul_f32_e32 v52, v52, v134
	v_mul_f32_e32 v53, v53, v134
	v_mul_f32_e32 v54, v54, v134
	v_mul_f32_e32 v55, v55, v134
	v_mul_f32_e32 v56, v56, v134
	v_mul_f32_e32 v57, v57, v134
	v_mul_f32_e32 v58, v58, v134
	v_mul_f32_e32 v59, v59, v134
	v_mul_f32_e32 v60, v60, v134
	v_mul_f32_e32 v61, v61, v134
	v_mul_f32_e32 v62, v62, v134
	v_mul_f32_e32 v63, v63, v134
	v_mul_f32_e32 v48, v98, v48
	v_mul_f32_e32 v49, v99, v49
	v_mul_f32_e32 v50, v100, v50
	v_mul_f32_e32 v51, v101, v51
	v_mul_f32_e32 v52, v102, v52
	v_mul_f32_e32 v53, v103, v53
	v_mul_f32_e32 v54, v104, v54
	v_mul_f32_e32 v55, v105, v55
	v_mul_f32_e32 v56, v106, v56
	v_mul_f32_e32 v57, v107, v57
	v_mul_f32_e32 v58, v108, v58
	v_mul_f32_e32 v59, v109, v59
	v_mul_f32_e32 v60, v110, v60
	v_mul_f32_e32 v61, v111, v61
	v_mul_f32_e32 v62, v112, v62
	v_mul_f32_e32 v63, v113, v63
	v_fma_f32 v48, v48, v80, v64
	v_fma_f32 v49, v49, v81, v65
	v_fma_f32 v50, v50, v82, v66
	v_fma_f32 v51, v51, v83, v67
	v_fma_f32 v52, v52, v84, v68
	v_fma_f32 v53, v53, v85, v69
	v_fma_f32 v54, v54, v86, v70
	v_fma_f32 v55, v55, v87, v71
	v_fma_f32 v56, v56, v88, v72
	v_fma_f32 v57, v57, v89, v73
	v_fma_f32 v58, v58, v90, v74
	v_fma_f32 v59, v59, v91, v75
	v_fma_f32 v60, v60, v92, v76
	v_fma_f32 v61, v61, v93, v77
	v_fma_f32 v62, v62, v94, v78
	v_fma_f32 v63, v63, v95, v79
	v_cvt_pk_bf16_f32 v114, v48, v49
	v_cvt_pk_bf16_f32 v115, v50, v51
	v_cvt_pk_bf16_f32 v116, v52, v53
	v_cvt_pk_bf16_f32 v117, v54, v55
	v_cvt_pk_bf16_f32 v118, v56, v57
	v_cvt_pk_bf16_f32 v119, v58, v59
	v_cvt_pk_bf16_f32 v120, v60, v61
	v_cvt_pk_bf16_f32 v121, v62, v63
	s_lshl_b32 s21, s15, 11
	s_add_u32 s22, s12, s21
	s_addc_u32 s23, s13, 0
	s_cmp_ge_i32 s14, 0x8000
	s_cbranch_scc1 .Lmn17_ni_9
	s_sub_i32 s21, s14, 0x8000
	s_lshr_b32 s20, s14, 12
	s_cmp_lt_i32 s14, 0x8000
	s_cselect_b32 s21, s14, s21
	s_cselect_b32 s20, s20, 8
	s_cselect_b32 s16, s4, s6
	s_cselect_b32 s17, s5, s7
	s_lshl_b32 s21, s21, 12
	s_mul_i32 s20, s20, 0x6000
	s_add_u32 s16, s16, s21
	s_addc_u32 s17, s17, 0
	s_add_u32 s18, s8, s20
	s_addc_u32 s19, s9, 0
	global_load_dwordx4 v[48:51], v122, s[16:17] offset:0 nt
	global_load_dwordx4 v[52:55], v122, s[16:17] offset:1024 nt
	global_load_dwordx4 v[56:59], v122, s[16:17] offset:2048 nt
	global_load_dwordx4 v[60:63], v122, s[16:17] offset:3072 nt
	global_load_dwordx4 v[64:67], v122, s[18:19] offset:0
	global_load_dwordx4 v[68:71], v122, s[18:19] offset:1024
	global_load_dwordx4 v[72:75], v122, s[18:19] offset:2048
	global_load_dwordx4 v[76:79], v122, s[18:19] offset:3072
	s_add_u32 s18, s10, s20
	s_addc_u32 s19, s11, 0
	global_load_dwordx4 v[80:83], v122, s[18:19] offset:0
	global_load_dwordx4 v[84:87], v122, s[18:19] offset:1024
	global_load_dwordx4 v[88:91], v122, s[18:19] offset:2048
	global_load_dwordx4 v[92:95], v122, s[18:19] offset:3072
.Lmn17_ni_9:
	s_add_u32 s14, s14, s1
	global_store_dwordx2 v123, v[114:115], s[22:23] offset:0
	global_store_dwordx2 v123, v[116:117], s[22:23] offset:512
	global_store_dwordx2 v123, v[118:119], s[22:23] offset:1024
	global_store_dwordx2 v123, v[120:121], s[22:23] offset:1536
	s_add_u32 s15, s15, s1
.Lmn17_loop_10:
	s_cmp_ge_i32 s15, 0x8000
	s_cbranch_scc1 .Lmn17_done_1
	s_add_u32 s20, s15, s1
	s_cmp_ge_i32 s20, 0x8000
	s_cbranch_scc1 .Lmn17_wl_11
	s_waitcnt vmcnt(20)
	s_branch .Lmn17_wj_12

; DEV unsigned cvt_pk_bf16(float lo, float hi) { unsigned r; asm volatile("v_cvt_pk_bf16_f32 %0, %1, %2" : "=v"(r) : "v"(lo), "v"(hi)); return r; }
; DEV void modnorm_rows(const float* srcX, const float* srcC, int nrows, const float* g, const float* shift, const float* scale, bf16_t* dst, int gw, int NGW, int lane) {
;     for (int row0 = gw; row0 < nrows; row0 += 2 * NGW) {
;         const int row1 = row0 + NGW; const bool has1 = row1 < nrows;
;         const float* xr0 = (row0 < TX) ? srcX + (size_t)row0 * DM : srcC + (size_t)(row0 - TX) * DM;
;         const float* xr1 = !has1 ? xr0 : ((row1 < TX) ? srcX + (size_t)row1 * DM : srcC + (size_t)(row1 - TX) * DM);
;         f32x4 v0[4], v1[4]; float s0 = 0.f, s1 = 0.f;
; #pragma unroll
;         for (int j = 0; j < 4; ++j) { v0[j] = __builtin_nontemporal_load((const f32x4*)(xr0 + 256 * j + 4 * lane)); v1[j] = __builtin_nontemporal_load((const f32x4*)(xr1 + 256 * j + 4 * lane)); }
; #pragma unroll
;         for (int j = 0; j < 4; ++j) { s0 += (v0[j][0] * v0[j][0] + v0[j][1] * v0[j][1]) + (v0[j][2] * v0[j][2] + v0[j][3] * v0[j][3]); s1 += (v1[j][0] * v1[j][0] + v1[j][1] * v1[j][1]) + (v1[j][2] * v1[j][2] + v1[j][3] * v1[j][3]); }
;         const float rstd0 = 1.0f / sqrtf(wave_sum(s0) * (1.f / DM) + EPS), rstd1 = 1.0f / sqrtf(wave_sum(s1) * (1.f / DM) + EPS);
;         const int mr0 = (row0 < TX) ? (row0 >> 12) : 8, mr1 = (row1 < TX) ? (row1 >> 12) : 8;
; #pragma unroll
;         for (int j = 0; j < 4; ++j) { const int col = 256 * j + 4 * lane; const f32x4 gg = *(const f32x4*)(g + col);
;             { const f32x4 sh = *(const f32x4*)(shift + (size_t)mr0 * 6144 + col), sc = *(const f32x4*)(scale + (size_t)mr0 * 6144 + col); f32x4 y;
; #pragma unroll
;                 for (int e = 0; e < 4; ++e) y[e] = (v0[j][e] * rstd0 * gg[e]) * (1.f + sc[e]) + sh[e];
;                 u32x2 w; w.x = cvt_pk_bf16(y[0], y[1]); w.y = cvt_pk_bf16(y[2], y[3]); *(u32x2*)(dst + (size_t)row0 * DM + col) = w; }
.Lmn17_ni_13:
	s_add_u32 s14, s14, s1
	global_store_dwordx2 v123, v[114:115], s[22:23] offset:0
	global_store_dwordx2 v123, v[116:117], s[22:23] offset:512
	global_store_dwordx2 v123, v[118:119], s[22:23] offset:1024
	global_store_dwordx2 v123, v[120:121], s[22:23] offset:1536
	s_add_u32 s15, s15, s1
	s_cmp_ge_i32 s15, 0x8000
	s_cbranch_scc1 .Lmn17_done_1
	s_add_u32 s20, s15, s1
	s_cmp_ge_i32 s20, 0x8000
	s_cbranch_scc1 .Lmn17_wl_14
	s_waitcnt vmcnt(20)
	s_branch .Lmn17_wj_15

; DEV unsigned cvt_pk_bf16(float lo, float hi) { unsigned r; asm volatile("v_cvt_pk_bf16_f32 %0, %1, %2" : "=v"(r) : "v"(lo), "v"(hi)); return r; }
; DEV void modnorm_rows(const float* srcX, const float* srcC, int nrows, const float* g, const float* shift, const float* scale, bf16_t* dst, int gw, int NGW, int lane) {
;     for (int row0 = gw; row0 < nrows; row0 += 2 * NGW) {
;         const int row1 = row0 + NGW; const bool has1 = row1 < nrows;
;         const float* xr0 = (row0 < TX) ? srcX + (size_t)row0 * DM : srcC + (size_t)(row0 - TX) * DM;
;         const float* xr1 = !has1 ? xr0 : ((row1 < TX) ? srcX + (size_t)row1 * DM : srcC + (size_t)(row1 - TX) * DM);
;         f32x4 v0[4], v1[4]; float s0 = 0.f, s1 = 0.f;
; #pragma unroll
;         for (int j = 0; j < 4; ++j) { v0[j] = __builtin_nontemporal_load((const f32x4*)(xr0 + 256 * j + 4 * lane)); v1[j] = __builtin_nontemporal_load((const f32x4*)(xr1 + 256 * j + 4 * lane)); }
; #pragma unroll
;         for (int j = 0; j < 4; ++j) { s0 += (v0[j][0] * v0[j][0] + v0[j][1] * v0[j][1]) + (v0[j][2] * v0[j][2] + v0[j][3] * v0[j][3]); s1 += (v1[j][0] * v1[j][0] + v1[j][1] * v1[j][1]) + (v1[j][2] * v1[j][2] + v1[j][3] * v1[j][3]); }
;         const float rstd0 = 1.0f / sqrtf(wave_sum(s0) * (1.f / DM) + EPS), rstd1 = 1.0f / sqrtf(wave_sum(s1) * (1.f / DM) + EPS);
;         const int mr0 = (row0 < TX) ? (row0 >> 12) : 8, mr1 = (row1 < TX) ? (row1 >> 12) : 8;
; #pragma unroll
;         for (int j = 0; j < 4; ++j) { const int col = 256 * j + 4 * lane; const f32x4 gg = *(const f32x4*)(g + col);
;             { const f32x4 sh = *(const f32x4*)(shift + (size_t)mr0 * 6144 + col), sc = *(const f32x4*)(scale + (size_t)mr0 * 6144 + col); f32x4 y;
; #pragma unroll
;                 for (int e = 0; e < 4; ++e) y[e] = (v0[j][e] * rstd0 * gg[e]) * (1.f + sc[e]) + sh[e];
;                 u32x2 w; w.x = cvt_pk_bf16(y[0], y[1]); w.y = cvt_pk_bf16(y[2], y[3]); *(u32x2*)(dst + (size_t)row0 * DM + col) = w; }
;             if (has1) { const f32x4 sh = *(const f32x4*)(shift + (size_t)mr1 * 6144 + col), sc = *(const f32x4*)(scale + (size_t)mr1 * 6144 + col); f32x4 y;
; #pragma unroll
;                 for (int e = 0; e < 4; ++e) y[e] = (v1[j][e] * rstd1 * gg[e]) * (1.f + sc[e]) + sh[e];
;                 u32x2 w; w.x = cvt_pk_bf16(y[0], y[1]); w.y = cvt_pk_bf16(y[2], y[3]); *(u32x2*)(dst + (size_t)row1 * DM + col) = w; } }
;     }
.Lmn17_ni_16:
	s_add_u32 s14, s14, s1
	global_store_dwordx2 v123, v[114:115], s[22:23] offset:0
	global_store_dwordx2 v123, v[116:117], s[22:23] offset:512
	global_store_dwordx2 v123, v[118:119], s[22:23] offset:1024
	global_store_dwordx2 v123, v[120:121], s[22:23] offset:1536
	s_add_u32 s15, s15, s1
	s_branch .Lmn17_loop_10
.Lmn17_done_1:
	s_branch .LBB0_2095
.LBB0_2095:
	s_mov_b64 s[2:3], 0

; DEV float max3f(float a, float b, float c) { return fmaxf(fmaxf(a, b), c); }
; #define LOADK(t) do { const long kb_ = KBASE(t); kreg0 = *(const u32x4*)(K + (kb_ + lane) * 1536 + h * 96 + wid * 8); \
;         if (k2) kreg1 = *(const u32x4*)(K + (kb_ + lane) * 1536 + h * 96 + (8 + wid) * 8); } while (0)
; #define LOADV(t) do { const long kb_ = KBASE(t); vreg = *(const u32x4*)(V + (kb_ + 16 * (wid & 3) + (lane >> 2)) * 1024 + h * 64 + (wid >> 2) * 32 + (lane & 3) * 8); } while (0)
; #define STOREK(s) do { LAS unsigned char* st_ = sh + (s) * STG; *(LAS u32x4*)(st_ + wid * 1024 + lane * 16) = kreg0; if (k2) *(LAS u32x4*)(st_ + (8 + wid) * 1024 + lane * 16) = kreg1; } while (0)
; #define STOREV(s) do { LAS unsigned char* st_ = sh + (s) * STG; *(LAS u32x4*)(st_ + KST + wid * 1024 + lane * 16) = vreg; } while (0)
; DEV void attn_unit(int b, int h, int qb, const bf16_t* Q, const bf16_t* K, const bf16_t* V, bf16_t* O, LAS unsigned char* sh, const int tid, const float* qgain) {
;     ...
;     float mrun = 0.f, lsum = 0.f; f32x16 o[2]; o[0] = f32x16{}; o[1] = f32x16{}; const f32x16 zero16 = f32x16{};
;     ...
;     LOADK(0); LOADV(0); STOREK(0); STOREV(0); LOADK(1); STOREK(1); __syncthreads();
;     f32x16 pA0, pA1, pB0 = f32x16{}, pB1 = f32x16{};
;     QKT(pA0, pA1, 0);
;     { float m0 = pA0[0];
; #pragma unroll
;         for (int r = 0; r < 16; ++r) m0 = max3f(m0, pA0[r], pA1[r]);
;         mrun = fmaxf(m0, __shfl_xor(m0, 32)); }
.Lat_k2_3:
	s_add_u32 s12, s12, 0x30000
	s_addc_u32 s13, s13, 0
	v_mov_b32_e32 v0, 0
	v_mov_b32_e32 v1, 0
	v_mov_b32_e32 v2, 0
	v_mov_b32_e32 v3, 0
	v_mov_b32_e32 v4, 0
	v_mov_b32_e32 v5, 0
	v_mov_b32_e32 v6, 0
	v_mov_b32_e32 v7, 0
	v_mov_b32_e32 v8, 0
	v_mov_b32_e32 v9, 0
	v_mov_b32_e32 v10, 0
	v_mov_b32_e32 v11, 0
	v_mov_b32_e32 v12, 0
	v_mov_b32_e32 v13, 0
	v_mov_b32_e32 v14, 0
	v_mov_b32_e32 v15, 0
	v_mov_b32_e32 v16, 0
	v_mov_b32_e32 v17, 0
	v_mov_b32_e32 v18, 0
	v_mov_b32_e32 v19, 0
	v_mov_b32_e32 v20, 0
	v_mov_b32_e32 v21, 0
	v_mov_b32_e32 v22, 0
	v_mov_b32_e32 v23, 0
	v_mov_b32_e32 v24, 0
	v_mov_b32_e32 v25, 0
	v_mov_b32_e32 v26, 0
	v_mov_b32_e32 v27, 0
	v_mov_b32_e32 v28, 0
	v_mov_b32_e32 v29, 0
	v_mov_b32_e32 v30, 0
	v_mov_b32_e32 v31, 0
	v_mov_b32_e32 v147, 0
	s_waitcnt vmcnt(0)
	s_barrier
	ds_read_b128 v[196:199], v194 offset:0
	ds_read_b128 v[200:203], v194 offset:512
	ds_read_b128 v[204:207], v194 offset:2048
	ds_read_b128 v[208:211], v194 offset:2560
	ds_read_b128 v[212:215], v194 offset:4096
	ds_read_b128 v[216:219], v194 offset:4608
	s_waitcnt lgkmcnt(4)
	v_mfma_f32_32x32x16_bf16 v[48:63], v[196:199], v[110:113], 0
	ds_read_b128 v[196:199], v194 offset:6144
	v_mfma_f32_32x32x16_bf16 v[32:47], v[200:203], v[110:113], 0
	ds_read_b128 v[200:203], v194 offset:6656
	s_waitcnt lgkmcnt(4)
	v_mfma_f32_32x32x16_bf16 v[48:63], v[204:207], v[106:109], v[48:63]
	ds_read_b128 v[204:207], v194 offset:8192
	v_mfma_f32_32x32x16_bf16 v[32:47], v[208:211], v[106:109], v[32:47]
	ds_read_b128 v[208:211], v194 offset:8704
	s_waitcnt lgkmcnt(4)
	v_mfma_f32_32x32x16_bf16 v[48:63], v[212:215], v[114:117], v[48:63]
	ds_read_b128 v[212:215], v194 offset:10240
	v_mfma_f32_32x32x16_bf16 v[32:47], v[216:219], v[114:117], v[32:47]
	ds_read_b128 v[216:219], v194 offset:10752
	s_waitcnt lgkmcnt(4)
	v_mfma_f32_32x32x16_bf16 v[48:63], v[196:199], v[118:121], v[48:63]
	v_mfma_f32_32x32x16_bf16 v[32:47], v[200:203], v[118:121], v[32:47]
	s_waitcnt lgkmcnt(2)
	v_mfma_f32_32x32x16_bf16 v[48:63], v[204:207], v[102:105], v[48:63]
	v_mfma_f32_32x32x16_bf16 v[32:47], v[208:211], v[102:105], v[32:47]
	s_waitcnt lgkmcnt(0)
	v_mfma_f32_32x32x16_bf16 v[48:63], v[212:215], v[98:101], v[48:63]
	v_mfma_f32_32x32x16_bf16 v[32:47], v[216:219], v[98:101], v[32:47]
	s_nop 15
	s_nop 3
	v_max_f32_e32 v149, v48, v32
	v_max3_f32 v149, v149, v49, v33
	v_max3_f32 v149, v149, v50, v34
	v_max3_f32 v149, v149, v51, v35
	v_max3_f32 v149, v149, v52, v36
	v_max3_f32 v149, v149, v53, v37
	v_max3_f32 v149, v149, v54, v38
	v_max3_f32 v149, v149, v55, v39
	v_max3_f32 v149, v149, v56, v40
	v_max3_f32 v149, v149, v57, v41
	v_max3_f32 v149, v149, v58, v42
	v_max3_f32 v149, v149, v59, v43
	v_max3_f32 v149, v149, v60, v44
	v_max3_f32 v149, v149, v61, v45
	v_max3_f32 v149, v149, v62, v46
	v_max3_f32 v149, v149, v63, v47
	v_mov_b32_e32 v175, v149
	v_mov_b32_e32 v178, v149
	s_nop 1
	v_permlane32_swap_b32_e32 v175, v178
	v_max_f32_e32 v175, v175, v178
	ds_read_b128 v[196:199], v194 offset:20480
	ds_read_b128 v[200:203], v194 offset:20992
	ds_read_b128 v[204:207], v194 offset:22528
	ds_read_b128 v[208:211], v194 offset:23040
	ds_read_b64_tr_b16 v[220:221], v139 offset:0
	ds_read_b64_tr_b16 v[222:223], v139 offset:512
	ds_read_b64_tr_b16 v[244:245], v139 offset:4096
	ds_read_b64_tr_b16 v[246:247], v139 offset:4608
	ds_read_b128 v[212:215], v194 offset:24576
	ds_read_b128 v[216:219], v194 offset:25088
	v_xor_b32_e32 v224, 0x80000000, v175
	v_mov_b32_e32 v225, v224
	v_mov_b32_e32 v226, v224
	v_mov_b32_e32 v227, v224
	v_mov_b32_e32 v228, v224
	v_mov_b32_e32 v229, v224
	v_mov_b32_e32 v230, v224
	v_mov_b32_e32 v231, v224
	v_mov_b32_e32 v232, v224
	v_mov_b32_e32 v233, v224
	v_mov_b32_e32 v234, v224
	v_mov_b32_e32 v235, v224
	v_mov_b32_e32 v236, v224
	v_mov_b32_e32 v237, v224
	v_mov_b32_e32 v238, v224
	v_mov_b32_e32 v239, v224
	v_sub_f32_e32 v48, v48, v175
	v_sub_f32_e32 v49, v49, v175
	v_sub_f32_e32 v50, v50, v175
	v_sub_f32_e32 v51, v51, v175
	v_sub_f32_e32 v52, v52, v175
	v_sub_f32_e32 v53, v53, v175
	v_sub_f32_e32 v54, v54, v175
	v_sub_f32_e32 v55, v55, v175
	v_sub_f32_e32 v56, v56, v175
	v_sub_f32_e32 v57, v57, v175
	v_sub_f32_e32 v58, v58, v175
	v_sub_f32_e32 v59, v59, v175
	v_sub_f32_e32 v60, v60, v175
	v_sub_f32_e32 v61, v61, v175
	v_sub_f32_e32 v62, v62, v175
	v_sub_f32_e32 v63, v63, v175
	v_sub_f32_e32 v32, v32, v175
	v_sub_f32_e32 v33, v33, v175
	v_sub_f32_e32 v34, v34, v175
	v_sub_f32_e32 v35, v35, v175
	v_sub_f32_e32 v36, v36, v175
	v_sub_f32_e32 v37, v37, v175
	v_sub_f32_e32 v38, v38, v175
	v_sub_f32_e32 v39, v39, v175
	v_sub_f32_e32 v40, v40, v175
	v_sub_f32_e32 v41, v41, v175
	v_sub_f32_e32 v42, v42, v175
	v_sub_f32_e32 v43, v43, v175
	v_sub_f32_e32 v44, v44, v175
	v_sub_f32_e32 v45, v45, v175
	v_sub_f32_e32 v46, v46, v175
	v_sub_f32_e32 v47, v47, v175
	s_mov_b32 s24, 15

.Lat_k2_5:
	s_add_u32 s12, s12, 0x30000
	s_addc_u32 s13, s13, 0
	s_add_i32 m0, s22, 0x13000
	s_nop 0
	global_load_lds_dwordx4 v145, s[14:15]
	s_add_u32 s14, s14, 0x20000
	s_addc_u32 s15, s15, 0
	v_exp_f32_e32 v48, v48
	v_exp_f32_e32 v49, v49
	v_exp_f32_e32 v50, v50
	v_exp_f32_e32 v51, v51
	v_mov_b32_e32 v176, v48
	v_mov_b32_e32 v177, v49
	v_cvt_pk_bf16_f32 v48, v48, v49
	v_add_f32_e32 v176, v50, v176
	v_add_f32_e32 v177, v51, v177
	v_cvt_pk_bf16_f32 v49, v50, v51
	v_exp_f32_e32 v52, v52
	v_exp_f32_e32 v53, v53
	s_waitcnt lgkmcnt(8)
	v_mfma_f32_32x32x16_bf16 v[80:95], v[196:199], v[110:113], v[224:239]
	ds_read_b128 v[196:199], v194 offset:26624
	ds_read_b64_tr_b16 v[240:241], v139 offset:1024
	ds_read_b64_tr_b16 v[242:243], v139 offset:1536
	v_exp_f32_e32 v54, v54
	v_exp_f32_e32 v55, v55
	v_add_f32_e32 v176, v52, v176
	v_add_f32_e32 v177, v53, v177
	v_mfma_f32_32x32x16_bf16 v[64:79], v[200:203], v[110:113], v[224:239]
	ds_read_b128 v[200:203], v194 offset:27136
	ds_read_b64_tr_b16 v[122:123], v139 offset:5120
	ds_read_b64_tr_b16 v[124:125], v139 offset:5632
	v_cvt_pk_bf16_f32 v50, v52, v53
	v_add_f32_e32 v176, v54, v176
	v_add_f32_e32 v177, v55, v177
	v_cvt_pk_bf16_f32 v51, v54, v55
	s_waitcnt lgkmcnt(12)
	v_mfma_f32_32x32x16_bf16 v[80:95], v[204:207], v[106:109], v[80:95]
	ds_read_b128 v[204:207], v194 offset:28672
	v_exp_f32_e32 v56, v56
	v_exp_f32_e32 v57, v57
	v_exp_f32_e32 v58, v58
	v_exp_f32_e32 v59, v59
	v_mfma_f32_32x32x16_bf16 v[64:79], v[208:211], v[106:109], v[64:79]
	ds_read_b128 v[208:211], v194 offset:29184
	v_add_f32_e32 v176, v56, v176
	v_add_f32_e32 v177, v57, v177
	v_cvt_pk_bf16_f32 v52, v56, v57
	v_add_f32_e32 v176, v58, v176
	s_waitcnt lgkmcnt(8)
	v_mfma_f32_32x32x16_bf16 v[80:95], v[212:215], v[114:117], v[80:95]
	ds_read_b128 v[212:215], v194 offset:30720
	v_add_f32_e32 v177, v59, v177
	v_cvt_pk_bf16_f32 v53, v58, v59
	v_exp_f32_e32 v60, v60
	v_exp_f32_e32 v61, v61
	v_mfma_f32_32x32x16_bf16 v[0:15], v[48:51], v[220:223], v[0:15]
	ds_read_b64_tr_b16 v[220:221], v139 offset:2048
	ds_read_b64_tr_b16 v[222:223], v139 offset:2560
	v_exp_f32_e32 v62, v62
	v_exp_f32_e32 v63, v63
	v_add_f32_e32 v176, v60, v176
	v_add_f32_e32 v177, v61, v177
	v_mfma_f32_32x32x16_bf16 v[16:31], v[48:51], v[244:247], v[16:31]
	ds_read_b64_tr_b16 v[244:245], v139 offset:6144
	ds_read_b64_tr_b16 v[246:247], v139 offset:6656
	v_cvt_pk_bf16_f32 v54, v60, v61
	v_add_f32_e32 v176, v62, v176
	v_add_f32_e32 v177, v63, v177
	v_cvt_pk_bf16_f32 v55, v62, v63
	v_mfma_f32_32x32x16_bf16 v[64:79], v[216:219], v[114:117], v[64:79]
	ds_read_b128 v[216:219], v194 offset:31232
	v_exp_f32_e32 v32, v32
	v_exp_f32_e32 v33, v33
	v_exp_f32_e32 v34, v34
	v_exp_f32_e32 v35, v35
	s_waitcnt vmcnt(2)
	s_barrier
	s_waitcnt lgkmcnt(10)
	v_mfma_f32_32x32x16_bf16 v[80:95], v[196:199], v[118:121], v[80:95]
	ds_read_b128 v[196:199], v126 offset:0
	v_add_f32_e32 v176, v32, v176
	v_add_f32_e32 v177, v33, v177
	v_cvt_pk_bf16_f32 v32, v32, v33
	v_add_f32_e32 v176, v34, v176
	v_mfma_f32_32x32x16_bf16 v[64:79], v[200:203], v[118:121], v[64:79]
	ds_read_b128 v[200:203], v126 offset:512
	v_add_f32_e32 v177, v35, v177
	v_cvt_pk_bf16_f32 v33, v34, v35
	v_exp_f32_e32 v36, v36
	v_exp_f32_e32 v37, v37
	s_waitcnt lgkmcnt(10)
	v_mfma_f32_32x32x16_bf16 v[0:15], v[52:55], v[240:243], v[0:15]
	ds_read_b64_tr_b16 v[240:241], v139 offset:3072
	ds_read_b64_tr_b16 v[242:243], v139 offset:3584
	v_exp_f32_e32 v38, v38
	v_exp_f32_e32 v39, v39
	v_add_f32_e32 v176, v36, v176
	v_add_f32_e32 v177, v37, v177
	v_mfma_f32_32x32x16_bf16 v[16:31], v[52:55], v[122:125], v[16:31]
	ds_read_b64_tr_b16 v[122:123], v139 offset:7168
	ds_read_b64_tr_b16 v[124:125], v139 offset:7680
	v_cvt_pk_bf16_f32 v34, v36, v37
	v_add_f32_e32 v176, v38, v176
	v_add_f32_e32 v177, v39, v177
	v_cvt_pk_bf16_f32 v35, v38, v39
	s_waitcnt lgkmcnt(12)
	v_mfma_f32_32x32x16_bf16 v[80:95], v[204:207], v[102:105], v[80:95]
	ds_read_b128 v[204:207], v126 offset:2048
	v_exp_f32_e32 v40, v40
	v_exp_f32_e32 v41, v41
	v_exp_f32_e32 v42, v42
	v_exp_f32_e32 v43, v43
	v_mfma_f32_32x32x16_bf16 v[64:79], v[208:211], v[102:105], v[64:79]
	ds_read_b128 v[208:211], v126 offset:2560
	v_add_f32_e32 v176, v40, v176
	v_add_f32_e32 v177, v41, v177
	v_cvt_pk_bf16_f32 v36, v40, v41
	v_add_f32_e32 v176, v42, v176
	s_waitcnt lgkmcnt(9)
	v_mfma_f32_32x32x16_bf16 v[0:15], v[32:35], v[220:223], v[0:15]
	ds_read_b64_tr_b16 v[220:221], v139 offset:20480
	ds_read_b64_tr_b16 v[222:223], v139 offset:20992
	v_add_f32_e32 v177, v43, v177
	v_cvt_pk_bf16_f32 v37, v42, v43
	v_exp_f32_e32 v44, v44
	v_exp_f32_e32 v45, v45
	v_mfma_f32_32x32x16_bf16 v[16:31], v[32:35], v[244:247], v[16:31]
	ds_read_b64_tr_b16 v[244:245], v139 offset:24576
	ds_read_b64_tr_b16 v[246:247], v139 offset:25088
	v_exp_f32_e32 v46, v46
	v_exp_f32_e32 v47, v47
	v_add_f32_e32 v176, v44, v176
	v_add_f32_e32 v177, v45, v177
	s_waitcnt lgkmcnt(12)
	v_mfma_f32_32x32x16_bf16 v[80:95], v[212:215], v[98:101], v[80:95]
	ds_read_b128 v[212:215], v126 offset:4096
	v_cvt_pk_bf16_f32 v38, v44, v45
	v_add_f32_e32 v176, v46, v176
	v_add_f32_e32 v177, v47, v177
	v_cvt_pk_bf16_f32 v39, v46, v47
	v_mfma_f32_32x32x16_bf16 v[64:79], v[216:219], v[98:101], v[64:79]
	ds_read_b128 v[216:219], v126 offset:4608
	v_add_f32_e32 v175, v176, v177
	v_mov_b32_e32 v178, v175
	v_add_f32_e32 v147, v147, v175
	s_nop 0
	s_waitcnt lgkmcnt(8)
	v_mfma_f32_32x32x16_bf16 v[0:15], v[36:39], v[240:243], v[0:15]
	v_permlane32_swap_b32_e32 v175, v178
	v_add_f32_e32 v175, v175, v178
	v_cmp_lt_f32_e32 vcc, 0x43800000, v175
	v_mfma_f32_32x32x16_bf16 v[16:31], v[36:39], v[122:125], v[16:31]
	s_cbranch_vccz .Lat_nr_6
	v_log_f32_e32 v175, v175
	s_nop 0
	v_max_f32_e32 v175, 0, v175
	v_exp_f32_e64 v178, -v175
	s_and_saveexec_b64 s[4:5], s[2:3]
	ds_write_b32 v143, v178 offset:40960
	s_or_b64 exec, exec, s[4:5]
	s_waitcnt lgkmcnt(0)
	v_add_u32_e32 v179, s33, v191
	v_sub_f32_e32 v224, v224, v175
	v_mul_f32_e32 v147, v147, v178
	ds_read_b128 v[48:51], v179 offset:40960
	ds_read_b128 v[52:55], v179 offset:40992
	ds_read_b128 v[56:59], v179 offset:41024
	ds_read_b128 v[60:63], v179 offset:41056
	s_waitcnt lgkmcnt(0)
	s_nop 15
	v_pk_mul_f32 v[0:1], v[0:1], v[48:49]
	v_pk_mul_f32 v[2:3], v[2:3], v[50:51]
	v_pk_mul_f32 v[4:5], v[4:5], v[52:53]
	v_pk_mul_f32 v[6:7], v[6:7], v[54:55]
	v_pk_mul_f32 v[8:9], v[8:9], v[56:57]
	v_pk_mul_f32 v[10:11], v[10:11], v[58:59]
	v_pk_mul_f32 v[12:13], v[12:13], v[60:61]
	v_pk_mul_f32 v[14:15], v[14:15], v[62:63]
	v_pk_mul_f32 v[16:17], v[16:17], v[48:49]
	v_pk_mul_f32 v[18:19], v[18:19], v[50:51]
	v_pk_mul_f32 v[20:21], v[20:21], v[52:53]
	v_pk_mul_f32 v[22:23], v[22:23], v[54:55]
	v_pk_mul_f32 v[24:25], v[24:25], v[56:57]
	v_pk_mul_f32 v[26:27], v[26:27], v[58:59]
	v_pk_mul_f32 v[28:29], v[28:29], v[60:61]
	v_pk_mul_f32 v[30:31], v[30:31], v[62:63]
	v_mov_b32_e32 v225, v224
	v_mov_b32_e32 v226, v224
	v_mov_b32_e32 v227, v224
	v_mov_b32_e32 v228, v224
	v_mov_b32_e32 v229, v224
	v_mov_b32_e32 v230, v224
	v_mov_b32_e32 v231, v224
	v_mov_b32_e32 v232, v224
	v_mov_b32_e32 v233, v224
	v_mov_b32_e32 v234, v224
	v_mov_b32_e32 v235, v224
	v_mov_b32_e32 v236, v224
	v_mov_b32_e32 v237, v224
	v_mov_b32_e32 v238, v224
	v_mov_b32_e32 v239, v224
	v_sub_f32_e32 v80, v80, v175
	v_sub_f32_e32 v81, v81, v175
	v_sub_f32_e32 v82, v82, v175
	v_sub_f32_e32 v83, v83, v175
	v_sub_f32_e32 v84, v84, v175
	v_sub_f32_e32 v85, v85, v175
	v_sub_f32_e32 v86, v86, v175
	v_sub_f32_e32 v87, v87, v175
	v_sub_f32_e32 v88, v88, v175
	v_sub_f32_e32 v89, v89, v175
	v_sub_f32_e32 v90, v90, v175
	v_sub_f32_e32 v91, v91, v175
	v_sub_f32_e32 v92, v92, v175
	v_sub_f32_e32 v93, v93, v175
	v_sub_f32_e32 v94, v94, v175
	v_sub_f32_e32 v95, v95, v175
	v_sub_f32_e32 v64, v64, v175
	v_sub_f32_e32 v65, v65, v175
	v_sub_f32_e32 v66, v66, v175
	v_sub_f32_e32 v67, v67, v175
	v_sub_f32_e32 v68, v68, v175
	v_sub_f32_e32 v69, v69, v175
	v_sub_f32_e32 v70, v70, v175
	v_sub_f32_e32 v71, v71, v175
	v_sub_f32_e32 v72, v72, v175
	v_sub_f32_e32 v73, v73, v175
	v_sub_f32_e32 v74, v74, v175
	v_sub_f32_e32 v75, v75, v175
	v_sub_f32_e32 v76, v76, v175
	v_sub_f32_e32 v77, v77, v175
	v_sub_f32_e32 v78, v78, v175
	v_sub_f32_e32 v79, v79, v175
.Lat_nr_6:
	s_add_i32 m0, s22, 0x0
	s_cmp_eq_u32 s23, 0
	global_load_lds_dwordx4 v128, s[12:13]
	s_cbranch_scc1 .Lat_k2_7
	s_add_i32 m0, s22, 0x2000
	s_nop 0
	global_load_lds_dwordx4 v129, s[12:13]
.Lat_k2_7:
	s_add_u32 s12, s12, 0x30000
	s_addc_u32 s13, s13, 0
	s_add_i32 m0, s22, 0x18000
	s_nop 0
	global_load_lds_dwordx4 v145, s[14:15]
	s_add_u32 s14, s14, 0x20000
	s_addc_u32 s15, s15, 0
	v_exp_f32_e32 v80, v80
	v_exp_f32_e32 v81, v81
	v_exp_f32_e32 v82, v82
	v_exp_f32_e32 v83, v83
	v_mov_b32_e32 v176, v80
	v_mov_b32_e32 v177, v81
	v_cvt_pk_bf16_f32 v80, v80, v81
	v_add_f32_e32 v176, v82, v176
	v_add_f32_e32 v177, v83, v177
	v_cvt_pk_bf16_f32 v81, v82, v83
	v_exp_f32_e32 v84, v84
	v_exp_f32_e32 v85, v85
	s_waitcnt lgkmcnt(8)
	v_mfma_f32_32x32x16_bf16 v[48:63], v[196:199], v[110:113], v[224:239]
	ds_read_b128 v[196:199], v126 offset:6144
	ds_read_b64_tr_b16 v[240:241], v139 offset:21504
	ds_read_b64_tr_b16 v[242:243], v139 offset:22016
	v_exp_f32_e32 v86, v86
	v_exp_f32_e32 v87, v87
	v_add_f32_e32 v176, v84, v176
	v_add_f32_e32 v177, v85, v177
	v_mfma_f32_32x32x16_bf16 v[32:47], v[200:203], v[110:113], v[224:239]
	ds_read_b128 v[200:203], v126 offset:6656
	ds_read_b64_tr_b16 v[122:123], v139 offset:25600
	ds_read_b64_tr_b16 v[124:125], v139 offset:26112
	v_cvt_pk_bf16_f32 v82, v84, v85
	v_add_f32_e32 v176, v86, v176
	v_add_f32_e32 v177, v87, v177
	v_cvt_pk_bf16_f32 v83, v86, v87
	s_waitcnt lgkmcnt(12)
	v_mfma_f32_32x32x16_bf16 v[48:63], v[204:207], v[106:109], v[48:63]
	ds_read_b128 v[204:207], v126 offset:8192
	v_exp_f32_e32 v88, v88
	v_exp_f32_e32 v89, v89
	v_exp_f32_e32 v90, v90
	v_exp_f32_e32 v91, v91
	v_mfma_f32_32x32x16_bf16 v[32:47], v[208:211], v[106:109], v[32:47]
	ds_read_b128 v[208:211], v126 offset:8704
	v_add_f32_e32 v176, v88, v176
	v_add_f32_e32 v177, v89, v177
	v_cvt_pk_bf16_f32 v84, v88, v89
	v_add_f32_e32 v176, v90, v176
	s_waitcnt lgkmcnt(8)
	v_mfma_f32_32x32x16_bf16 v[48:63], v[212:215], v[114:117], v[48:63]
	ds_read_b128 v[212:215], v126 offset:10240
	v_add_f32_e32 v177, v91, v177
	v_cvt_pk_bf16_f32 v85, v90, v91
	v_exp_f32_e32 v92, v92
	v_exp_f32_e32 v93, v93
	v_mfma_f32_32x32x16_bf16 v[0:15], v[80:83], v[220:223], v[0:15]
	ds_read_b64_tr_b16 v[220:221], v139 offset:22528
	ds_read_b64_tr_b16 v[222:223], v139 offset:23040
	v_exp_f32_e32 v94, v94
	v_exp_f32_e32 v95, v95
	v_add_f32_e32 v176, v92, v176
	v_add_f32_e32 v177, v93, v177
	v_mfma_f32_32x32x16_bf16 v[16:31], v[80:83], v[244:247], v[16:31]
	ds_read_b64_tr_b16 v[244:245], v139 offset:26624
	ds_read_b64_tr_b16 v[246:247], v139 offset:27136
	v_cvt_pk_bf16_f32 v86, v92, v93
	v_add_f32_e32 v176, v94, v176
	v_add_f32_e32 v177, v95, v177
	v_cvt_pk_bf16_f32 v87, v94, v95
	v_mfma_f32_32x32x16_bf16 v[32:47], v[216:219], v[114:117], v[32:47]
	ds_read_b128 v[216:219], v126 offset:10752
	v_exp_f32_e32 v64, v64
	v_exp_f32_e32 v65, v65
	v_exp_f32_e32 v66, v66
	v_exp_f32_e32 v67, v67
	s_waitcnt vmcnt(2)
	s_barrier
	s_waitcnt lgkmcnt(10)
	v_mfma_f32_32x32x16_bf16 v[48:63], v[196:199], v[118:121], v[48:63]
	ds_read_b128 v[196:199], v126 offset:20480
	v_add_f32_e32 v176, v64, v176
	v_add_f32_e32 v177, v65, v177
	v_cvt_pk_bf16_f32 v64, v64, v65
	v_add_f32_e32 v176, v66, v176
	v_mfma_f32_32x32x16_bf16 v[32:47], v[200:203], v[118:121], v[32:47]
	ds_read_b128 v[200:203], v126 offset:20992
	v_add_f32_e32 v177, v67, v177
	v_cvt_pk_bf16_f32 v65, v66, v67
	v_exp_f32_e32 v68, v68
	v_exp_f32_e32 v69, v69
	s_waitcnt lgkmcnt(10)
	v_mfma_f32_32x32x16_bf16 v[0:15], v[84:87], v[240:243], v[0:15]
	ds_read_b64_tr_b16 v[240:241], v139 offset:23552
	ds_read_b64_tr_b16 v[242:243], v139 offset:24064
	v_exp_f32_e32 v70, v70
	v_exp_f32_e32 v71, v71
	v_add_f32_e32 v176, v68, v176
	v_add_f32_e32 v177, v69, v177
	v_mfma_f32_32x32x16_bf16 v[16:31], v[84:87], v[122:125], v[16:31]
	ds_read_b64_tr_b16 v[122:123], v139 offset:27648
	ds_read_b64_tr_b16 v[124:125], v139 offset:28160
	v_cvt_pk_bf16_f32 v66, v68, v69
	v_add_f32_e32 v176, v70, v176
	v_add_f32_e32 v177, v71, v177
	v_cvt_pk_bf16_f32 v67, v70, v71
	s_waitcnt lgkmcnt(12)
	v_mfma_f32_32x32x16_bf16 v[48:63], v[204:207], v[102:105], v[48:63]
	ds_read_b128 v[204:207], v126 offset:22528
	v_exp_f32_e32 v72, v72
	v_exp_f32_e32 v73, v73
	v_exp_f32_e32 v74, v74
	v_exp_f32_e32 v75, v75
	v_mfma_f32_32x32x16_bf16 v[32:47], v[208:211], v[102:105], v[32:47]
	ds_read_b128 v[208:211], v126 offset:23040
	v_add_f32_e32 v176, v72, v176
	v_add_f32_e32 v177, v73, v177
	v_cvt_pk_bf16_f32 v68, v72, v73
	v_add_f32_e32 v176, v74, v176
	s_waitcnt lgkmcnt(9)
	v_mfma_f32_32x32x16_bf16 v[0:15], v[64:67], v[220:223], v[0:15]
	ds_read_b64_tr_b16 v[220:221], v127 offset:0
	ds_read_b64_tr_b16 v[222:223], v127 offset:512
	v_add_f32_e32 v177, v75, v177
	v_cvt_pk_bf16_f32 v69, v74, v75
	v_exp_f32_e32 v76, v76
	v_exp_f32_e32 v77, v77
	v_mfma_f32_32x32x16_bf16 v[16:31], v[64:67], v[244:247], v[16:31]
	ds_read_b64_tr_b16 v[244:245], v127 offset:4096
	ds_read_b64_tr_b16 v[246:247], v127 offset:4608
	v_exp_f32_e32 v78, v78
	v_exp_f32_e32 v79, v79
	v_add_f32_e32 v176, v76, v176
	v_add_f32_e32 v177, v77, v177
	s_waitcnt lgkmcnt(12)
	v_mfma_f32_32x32x16_bf16 v[48:63], v[212:215], v[98:101], v[48:63]
	ds_read_b128 v[212:215], v126 offset:24576
	v_cvt_pk_bf16_f32 v70, v76, v77
	v_add_f32_e32 v176, v78, v176
	v_add_f32_e32 v177, v79, v177
	v_cvt_pk_bf16_f32 v71, v78, v79
	v_mfma_f32_32x32x16_bf16 v[32:47], v[216:219], v[98:101], v[32:47]
	ds_read_b128 v[216:219], v126 offset:25088
	v_add_f32_e32 v175, v176, v177
	v_mov_b32_e32 v178, v175
	v_add_f32_e32 v147, v147, v175
	s_nop 0
	s_waitcnt lgkmcnt(8)
	v_mfma_f32_32x32x16_bf16 v[0:15], v[68:71], v[240:243], v[0:15]
	v_permlane32_swap_b32_e32 v175, v178
	v_add_f32_e32 v175, v175, v178
	v_cmp_lt_f32_e32 vcc, 0x43800000, v175
	v_mfma_f32_32x32x16_bf16 v[16:31], v[68:71], v[122:125], v[16:31]
	s_cbranch_vccz .Lat_nr_8
	v_log_f32_e32 v175, v175
	s_nop 0
	v_max_f32_e32 v175, 0, v175
	v_exp_f32_e64 v178, -v175
	s_and_saveexec_b64 s[4:5], s[2:3]
	ds_write_b32 v143, v178 offset:40960
	s_or_b64 exec, exec, s[4:5]
	s_waitcnt lgkmcnt(0)
	v_add_u32_e32 v179, s33, v191
	v_sub_f32_e32 v224, v224, v175
	v_mul_f32_e32 v147, v147, v178
	ds_read_b128 v[80:83], v179 offset:40960
	ds_read_b128 v[84:87], v179 offset:40992
	ds_read_b128 v[88:91], v179 offset:41024
	ds_read_b128 v[92:95], v179 offset:41056
	s_waitcnt lgkmcnt(0)
	s_nop 15
	v_pk_mul_f32 v[0:1], v[0:1], v[80:81]
	v_pk_mul_f32 v[2:3], v[2:3], v[82:83]
	v_pk_mul_f32 v[4:5], v[4:5], v[84:85]
	v_pk_mul_f32 v[6:7], v[6:7], v[86:87]
	v_pk_mul_f32 v[8:9], v[8:9], v[88:89]
	v_pk_mul_f32 v[10:11], v[10:11], v[90:91]
	v_pk_mul_f32 v[12:13], v[12:13], v[92:93]
	v_pk_mul_f32 v[14:15], v[14:15], v[94:95]
	v_pk_mul_f32 v[16:17], v[16:17], v[80:81]
	v_pk_mul_f32 v[18:19], v[18:19], v[82:83]
	v_pk_mul_f32 v[20:21], v[20:21], v[84:85]
	v_pk_mul_f32 v[22:23], v[22:23], v[86:87]
	v_pk_mul_f32 v[24:25], v[24:25], v[88:89]
	v_pk_mul_f32 v[26:27], v[26:27], v[90:91]
	v_pk_mul_f32 v[28:29], v[28:29], v[92:93]
	v_pk_mul_f32 v[30:31], v[30:31], v[94:95]
	v_mov_b32_e32 v225, v224
	v_mov_b32_e32 v226, v224
	v_mov_b32_e32 v227, v224
	v_mov_b32_e32 v228, v224
	v_mov_b32_e32 v229, v224
	v_mov_b32_e32 v230, v224
	v_mov_b32_e32 v231, v224
	v_mov_b32_e32 v232, v224
	v_mov_b32_e32 v233, v224
	v_mov_b32_e32 v234, v224
	v_mov_b32_e32 v235, v224
	v_mov_b32_e32 v236, v224
	v_mov_b32_e32 v237, v224
	v_mov_b32_e32 v238, v224
	v_mov_b32_e32 v239, v224
	v_sub_f32_e32 v48, v48, v175
	v_sub_f32_e32 v49, v49, v175
	v_sub_f32_e32 v50, v50, v175
	v_sub_f32_e32 v51, v51, v175
	v_sub_f32_e32 v52, v52, v175
	v_sub_f32_e32 v53, v53, v175
	v_sub_f32_e32 v54, v54, v175
	v_sub_f32_e32 v55, v55, v175
	v_sub_f32_e32 v56, v56, v175
	v_sub_f32_e32 v57, v57, v175
	v_sub_f32_e32 v58, v58, v175
	v_sub_f32_e32 v59, v59, v175
	v_sub_f32_e32 v60, v60, v175
	v_sub_f32_e32 v61, v61, v175
	v_sub_f32_e32 v62, v62, v175
	v_sub_f32_e32 v63, v63, v175
	v_sub_f32_e32 v32, v32, v175
	v_sub_f32_e32 v33, v33, v175
	v_sub_f32_e32 v34, v34, v175
	v_sub_f32_e32 v35, v35, v175
	v_sub_f32_e32 v36, v36, v175
	v_sub_f32_e32 v37, v37, v175
	v_sub_f32_e32 v38, v38, v175
	v_sub_f32_e32 v39, v39, v175
	v_sub_f32_e32 v40, v40, v175
	v_sub_f32_e32 v41, v41, v175
	v_sub_f32_e32 v42, v42, v175
	v_sub_f32_e32 v43, v43, v175
	v_sub_f32_e32 v44, v44, v175
	v_sub_f32_e32 v45, v45, v175
	v_sub_f32_e32 v46, v46, v175
	v_sub_f32_e32 v47, v47, v175
.Lat_nr_8:
	s_add_i32 m0, s22, 0x5000
	s_cmp_eq_u32 s23, 0
	global_load_lds_dwordx4 v128, s[12:13]
	s_cbranch_scc1 .Lat_k2_9
	s_add_i32 m0, s22, 0x7000
	s_nop 0
	global_load_lds_dwordx4 v129, s[12:13]
.Lat_k2_9:
	s_add_u32 s12, s12, 0x30000
	s_addc_u32 s13, s13, 0
	s_add_i32 m0, s22, 0x3000
	s_nop 0
	global_load_lds_dwordx4 v145, s[14:15]
	s_add_u32 s14, s14, 0x20000
	s_addc_u32 s15, s15, 0
	v_exp_f32_e32 v48, v48
	v_exp_f32_e32 v49, v49
	v_exp_f32_e32 v50, v50
	v_exp_f32_e32 v51, v51
	v_mov_b32_e32 v176, v48
	v_mov_b32_e32 v177, v49
	v_cvt_pk_bf16_f32 v48, v48, v49
	v_add_f32_e32 v176, v50, v176
	v_add_f32_e32 v177, v51, v177
	v_cvt_pk_bf16_f32 v49, v50, v51
	v_exp_f32_e32 v52, v52
	v_exp_f32_e32 v53, v53
	s_waitcnt lgkmcnt(8)
	v_mfma_f32_32x32x16_bf16 v[80:95], v[196:199], v[110:113], v[224:239]
	ds_read_b128 v[196:199], v126 offset:26624
	ds_read_b64_tr_b16 v[240:241], v127 offset:1024
	ds_read_b64_tr_b16 v[242:243], v127 offset:1536
	v_exp_f32_e32 v54, v54
	v_exp_f32_e32 v55, v55
	v_add_f32_e32 v176, v52, v176
	v_add_f32_e32 v177, v53, v177
	v_mfma_f32_32x32x16_bf16 v[64:79], v[200:203], v[110:113], v[224:239]
	ds_read_b128 v[200:203], v126 offset:27136
	ds_read_b64_tr_b16 v[122:123], v127 offset:5120
	ds_read_b64_tr_b16 v[124:125], v127 offset:5632
	v_cvt_pk_bf16_f32 v50, v52, v53
	v_add_f32_e32 v176, v54, v176
	v_add_f32_e32 v177, v55, v177
	v_cvt_pk_bf16_f32 v51, v54, v55
	s_waitcnt lgkmcnt(12)
	v_mfma_f32_32x32x16_bf16 v[80:95], v[204:207], v[106:109], v[80:95]
	ds_read_b128 v[204:207], v126 offset:28672
	v_exp_f32_e32 v56, v56
	v_exp_f32_e32 v57, v57
	v_exp_f32_e32 v58, v58
	v_exp_f32_e32 v59, v59
	v_mfma_f32_32x32x16_bf16 v[64:79], v[208:211], v[106:109], v[64:79]
	ds_read_b128 v[208:211], v126 offset:29184
	v_add_f32_e32 v176, v56, v176
	v_add_f32_e32 v177, v57, v177
	v_cvt_pk_bf16_f32 v52, v56, v57
	v_add_f32_e32 v176, v58, v176
	s_waitcnt lgkmcnt(8)
	v_mfma_f32_32x32x16_bf16 v[80:95], v[212:215], v[114:117], v[80:95]
	ds_read_b128 v[212:215], v126 offset:30720
	v_add_f32_e32 v177, v59, v177
	v_cvt_pk_bf16_f32 v53, v58, v59
	v_exp_f32_e32 v60, v60
	v_exp_f32_e32 v61, v61
	v_mfma_f32_32x32x16_bf16 v[0:15], v[48:51], v[220:223], v[0:15]
	ds_read_b64_tr_b16 v[220:221], v127 offset:2048
	ds_read_b64_tr_b16 v[222:223], v127 offset:2560
	v_exp_f32_e32 v62, v62
	v_exp_f32_e32 v63, v63
	v_add_f32_e32 v176, v60, v176
	v_add_f32_e32 v177, v61, v177
	v_mfma_f32_32x32x16_bf16 v[16:31], v[48:51], v[244:247], v[16:31]
	ds_read_b64_tr_b16 v[244:245], v127 offset:6144
	ds_read_b64_tr_b16 v[246:247], v127 offset:6656
	v_cvt_pk_bf16_f32 v54, v60, v61
	v_add_f32_e32 v176, v62, v176
	v_add_f32_e32 v177, v63, v177
	v_cvt_pk_bf16_f32 v55, v62, v63
	v_mfma_f32_32x32x16_bf16 v[64:79], v[216:219], v[114:117], v[64:79]
	ds_read_b128 v[216:219], v126 offset:31232
	v_exp_f32_e32 v32, v32
	v_exp_f32_e32 v33, v33
	v_exp_f32_e32 v34, v34
	v_exp_f32_e32 v35, v35
	s_waitcnt vmcnt(2)
	s_barrier
	s_waitcnt lgkmcnt(10)
	v_mfma_f32_32x32x16_bf16 v[80:95], v[196:199], v[118:121], v[80:95]
	ds_read_b128 v[196:199], v194 offset:0
	v_add_f32_e32 v176, v32, v176
	v_add_f32_e32 v177, v33, v177
	v_cvt_pk_bf16_f32 v32, v32, v33
	v_add_f32_e32 v176, v34, v176
	v_mfma_f32_32x32x16_bf16 v[64:79], v[200:203], v[118:121], v[64:79]
	ds_read_b128 v[200:203], v194 offset:512
	v_add_f32_e32 v177, v35, v177
	v_cvt_pk_bf16_f32 v33, v34, v35
	v_exp_f32_e32 v36, v36
	v_exp_f32_e32 v37, v37
	s_waitcnt lgkmcnt(10)
	v_mfma_f32_32x32x16_bf16 v[0:15], v[52:55], v[240:243], v[0:15]
	ds_read_b64_tr_b16 v[240:241], v127 offset:3072
	ds_read_b64_tr_b16 v[242:243], v127 offset:3584
	v_exp_f32_e32 v38, v38
	v_exp_f32_e32 v39, v39
	v_add_f32_e32 v176, v36, v176
	v_add_f32_e32 v177, v37, v177
	v_mfma_f32_32x32x16_bf16 v[16:31], v[52:55], v[122:125], v[16:31]
	ds_read_b64_tr_b16 v[122:123], v127 offset:7168
	ds_read_b64_tr_b16 v[124:125], v127 offset:7680
	v_cvt_pk_bf16_f32 v34, v36, v37
	v_add_f32_e32 v176, v38, v176
	v_add_f32_e32 v177, v39, v177
	v_cvt_pk_bf16_f32 v35, v38, v39
	s_waitcnt lgkmcnt(12)
	v_mfma_f32_32x32x16_bf16 v[80:95], v[204:207], v[102:105], v[80:95]
	ds_read_b128 v[204:207], v194 offset:2048
	v_exp_f32_e32 v40, v40
	v_exp_f32_e32 v41, v41
	v_exp_f32_e32 v42, v42
	v_exp_f32_e32 v43, v43
	v_mfma_f32_32x32x16_bf16 v[64:79], v[208:211], v[102:105], v[64:79]
	ds_read_b128 v[208:211], v194 offset:2560
	v_add_f32_e32 v176, v40, v176
	v_add_f32_e32 v177, v41, v177
	v_cvt_pk_bf16_f32 v36, v40, v41
	v_add_f32_e32 v176, v42, v176
	s_waitcnt lgkmcnt(9)
	v_mfma_f32_32x32x16_bf16 v[0:15], v[32:35], v[220:223], v[0:15]
	ds_read_b64_tr_b16 v[220:221], v127 offset:20480
	ds_read_b64_tr_b16 v[222:223], v127 offset:20992
	v_add_f32_e32 v177, v43, v177
	v_cvt_pk_bf16_f32 v37, v42, v43
	v_exp_f32_e32 v44, v44
	v_exp_f32_e32 v45, v45
	v_mfma_f32_32x32x16_bf16 v[16:31], v[32:35], v[244:247], v[16:31]
	ds_read_b64_tr_b16 v[244:245], v127 offset:24576
	ds_read_b64_tr_b16 v[246:247], v127 offset:25088
	v_exp_f32_e32 v46, v46
	v_exp_f32_e32 v47, v47
	v_add_f32_e32 v176, v44, v176
	v_add_f32_e32 v177, v45, v177
	s_waitcnt lgkmcnt(12)
	v_mfma_f32_32x32x16_bf16 v[80:95], v[212:215], v[98:101], v[80:95]
	ds_read_b128 v[212:215], v194 offset:4096
	v_cvt_pk_bf16_f32 v38, v44, v45
	v_add_f32_e32 v176, v46, v176
	v_add_f32_e32 v177, v47, v177
	v_cvt_pk_bf16_f32 v39, v46, v47
	v_mfma_f32_32x32x16_bf16 v[64:79], v[216:219], v[98:101], v[64:79]
	ds_read_b128 v[216:219], v194 offset:4608
	v_add_f32_e32 v175, v176, v177
	v_mov_b32_e32 v178, v175
	v_add_f32_e32 v147, v147, v175
	s_nop 0
	s_waitcnt lgkmcnt(8)
	v_mfma_f32_32x32x16_bf16 v[0:15], v[36:39], v[240:243], v[0:15]
	v_permlane32_swap_b32_e32 v175, v178
	v_add_f32_e32 v175, v175, v178
	v_cmp_lt_f32_e32 vcc, 0x43800000, v175
	v_mfma_f32_32x32x16_bf16 v[16:31], v[36:39], v[122:125], v[16:31]
	s_cbranch_vccz .Lat_nr_10
	v_log_f32_e32 v175, v175
	s_nop 0
	v_max_f32_e32 v175, 0, v175
	v_exp_f32_e64 v178, -v175
	s_and_saveexec_b64 s[4:5], s[2:3]
	ds_write_b32 v143, v178 offset:40960
	s_or_b64 exec, exec, s[4:5]
	s_waitcnt lgkmcnt(0)
	v_add_u32_e32 v179, s33, v191
	v_sub_f32_e32 v224, v224, v175
	v_mul_f32_e32 v147, v147, v178
	ds_read_b128 v[48:51], v179 offset:40960
	ds_read_b128 v[52:55], v179 offset:40992
	ds_read_b128 v[56:59], v179 offset:41024
	ds_read_b128 v[60:63], v179 offset:41056
	s_waitcnt lgkmcnt(0)
	s_nop 15
	v_pk_mul_f32 v[0:1], v[0:1], v[48:49]
	v_pk_mul_f32 v[2:3], v[2:3], v[50:51]
	v_pk_mul_f32 v[4:5], v[4:5], v[52:53]
	v_pk_mul_f32 v[6:7], v[6:7], v[54:55]
	v_pk_mul_f32 v[8:9], v[8:9], v[56:57]
	v_pk_mul_f32 v[10:11], v[10:11], v[58:59]
	v_pk_mul_f32 v[12:13], v[12:13], v[60:61]
	v_pk_mul_f32 v[14:15], v[14:15], v[62:63]
	v_pk_mul_f32 v[16:17], v[16:17], v[48:49]
	v_pk_mul_f32 v[18:19], v[18:19], v[50:51]
	v_pk_mul_f32 v[20:21], v[20:21], v[52:53]
	v_pk_mul_f32 v[22:23], v[22:23], v[54:55]
	v_pk_mul_f32 v[24:25], v[24:25], v[56:57]
	v_pk_mul_f32 v[26:27], v[26:27], v[58:59]
	v_pk_mul_f32 v[28:29], v[28:29], v[60:61]
	v_pk_mul_f32 v[30:31], v[30:31], v[62:63]
	v_mov_b32_e32 v225, v224
	v_mov_b32_e32 v226, v224
	v_mov_b32_e32 v227, v224
	v_mov_b32_e32 v228, v224
	v_mov_b32_e32 v229, v224
	v_mov_b32_e32 v230, v224
	v_mov_b32_e32 v231, v224
	v_mov_b32_e32 v232, v224
	v_mov_b32_e32 v233, v224
	v_mov_b32_e32 v234, v224
	v_mov_b32_e32 v235, v224
	v_mov_b32_e32 v236, v224
	v_mov_b32_e32 v237, v224
	v_mov_b32_e32 v238, v224
	v_mov_b32_e32 v239, v224
	v_sub_f32_e32 v80, v80, v175
	v_sub_f32_e32 v81, v81, v175
	v_sub_f32_e32 v82, v82, v175
	v_sub_f32_e32 v83, v83, v175
	v_sub_f32_e32 v84, v84, v175
	v_sub_f32_e32 v85, v85, v175
	v_sub_f32_e32 v86, v86, v175
	v_sub_f32_e32 v87, v87, v175
	v_sub_f32_e32 v88, v88, v175
	v_sub_f32_e32 v89, v89, v175
	v_sub_f32_e32 v90, v90, v175
	v_sub_f32_e32 v91, v91, v175
	v_sub_f32_e32 v92, v92, v175
	v_sub_f32_e32 v93, v93, v175
	v_sub_f32_e32 v94, v94, v175
	v_sub_f32_e32 v95, v95, v175
	v_sub_f32_e32 v64, v64, v175
	v_sub_f32_e32 v65, v65, v175
	v_sub_f32_e32 v66, v66, v175
	v_sub_f32_e32 v67, v67, v175
	v_sub_f32_e32 v68, v68, v175
	v_sub_f32_e32 v69, v69, v175
	v_sub_f32_e32 v70, v70, v175
	v_sub_f32_e32 v71, v71, v175
	v_sub_f32_e32 v72, v72, v175
	v_sub_f32_e32 v73, v73, v175
	v_sub_f32_e32 v74, v74, v175
	v_sub_f32_e32 v75, v75, v175
	v_sub_f32_e32 v76, v76, v175
	v_sub_f32_e32 v77, v77, v175
	v_sub_f32_e32 v78, v78, v175
	v_sub_f32_e32 v79, v79, v175
.Lat_nr_10:
	s_add_i32 m0, s22, 0x10000
	s_cmp_eq_u32 s23, 0
	global_load_lds_dwordx4 v128, s[12:13]
	s_cbranch_scc1 .Lat_k2_11
	s_add_i32 m0, s22, 0x12000
	s_nop 0
	global_load_lds_dwordx4 v129, s[12:13]
.Lat_k2_11:
	s_add_u32 s12, s12, 0x30000
	s_addc_u32 s13, s13, 0
	s_add_i32 m0, s22, 0x8000
	s_nop 0
	global_load_lds_dwordx4 v145, s[14:15]
	s_add_u32 s14, s14, 0x20000
	s_addc_u32 s15, s15, 0
	v_exp_f32_e32 v80, v80
	v_exp_f32_e32 v81, v81
	v_exp_f32_e32 v82, v82
	v_exp_f32_e32 v83, v83
	v_mov_b32_e32 v176, v80
	v_mov_b32_e32 v177, v81
	v_cvt_pk_bf16_f32 v80, v80, v81
	v_add_f32_e32 v176, v82, v176
	v_add_f32_e32 v177, v83, v177
	v_cvt_pk_bf16_f32 v81, v82, v83
	v_exp_f32_e32 v84, v84
	v_exp_f32_e32 v85, v85
	s_waitcnt lgkmcnt(8)
	v_mfma_f32_32x32x16_bf16 v[48:63], v[196:199], v[110:113], v[224:239]
	ds_read_b128 v[196:199], v194 offset:6144
	ds_read_b64_tr_b16 v[240:241], v127 offset:21504
	ds_read_b64_tr_b16 v[242:243], v127 offset:22016
	v_exp_f32_e32 v86, v86
	v_exp_f32_e32 v87, v87
	v_add_f32_e32 v176, v84, v176
	v_add_f32_e32 v177, v85, v177
	v_mfma_f32_32x32x16_bf16 v[32:47], v[200:203], v[110:113], v[224:239]
	ds_read_b128 v[200:203], v194 offset:6656
	ds_read_b64_tr_b16 v[122:123], v127 offset:25600
	ds_read_b64_tr_b16 v[124:125], v127 offset:26112
	v_cvt_pk_bf16_f32 v82, v84, v85
	v_add_f32_e32 v176, v86, v176
	v_add_f32_e32 v177, v87, v177
	v_cvt_pk_bf16_f32 v83, v86, v87
	s_waitcnt lgkmcnt(12)
	v_mfma_f32_32x32x16_bf16 v[48:63], v[204:207], v[106:109], v[48:63]
	ds_read_b128 v[204:207], v194 offset:8192
	v_exp_f32_e32 v88, v88
	v_exp_f32_e32 v89, v89
	v_exp_f32_e32 v90, v90
	v_exp_f32_e32 v91, v91
	v_mfma_f32_32x32x16_bf16 v[32:47], v[208:211], v[106:109], v[32:47]
	ds_read_b128 v[208:211], v194 offset:8704
	v_add_f32_e32 v176, v88, v176
	v_add_f32_e32 v177, v89, v177
	v_cvt_pk_bf16_f32 v84, v88, v89
	v_add_f32_e32 v176, v90, v176
	s_waitcnt lgkmcnt(8)
	v_mfma_f32_32x32x16_bf16 v[48:63], v[212:215], v[114:117], v[48:63]
	ds_read_b128 v[212:215], v194 offset:10240
	v_add_f32_e32 v177, v91, v177
	v_cvt_pk_bf16_f32 v85, v90, v91
	v_exp_f32_e32 v92, v92
	v_exp_f32_e32 v93, v93
	v_mfma_f32_32x32x16_bf16 v[0:15], v[80:83], v[220:223], v[0:15]
	ds_read_b64_tr_b16 v[220:221], v127 offset:22528
	ds_read_b64_tr_b16 v[222:223], v127 offset:23040
	v_exp_f32_e32 v94, v94
	v_exp_f32_e32 v95, v95
	v_add_f32_e32 v176, v92, v176
	v_add_f32_e32 v177, v93, v177
	v_mfma_f32_32x32x16_bf16 v[16:31], v[80:83], v[244:247], v[16:31]
	ds_read_b64_tr_b16 v[244:245], v127 offset:26624
	ds_read_b64_tr_b16 v[246:247], v127 offset:27136
	v_cvt_pk_bf16_f32 v86, v92, v93
	v_add_f32_e32 v176, v94, v176
	v_add_f32_e32 v177, v95, v177
	v_cvt_pk_bf16_f32 v87, v94, v95
	v_mfma_f32_32x32x16_bf16 v[32:47], v[216:219], v[114:117], v[32:47]
	ds_read_b128 v[216:219], v194 offset:10752
	v_exp_f32_e32 v64, v64
	v_exp_f32_e32 v65, v65
	v_exp_f32_e32 v66, v66
	v_exp_f32_e32 v67, v67
	s_waitcnt vmcnt(2)
	s_barrier
	s_waitcnt lgkmcnt(10)
	v_mfma_f32_32x32x16_bf16 v[48:63], v[196:199], v[118:121], v[48:63]
	ds_read_b128 v[196:199], v194 offset:20480
	v_add_f32_e32 v176, v64, v176
	v_add_f32_e32 v177, v65, v177
	v_cvt_pk_bf16_f32 v64, v64, v65
	v_add_f32_e32 v176, v66, v176
	v_mfma_f32_32x32x16_bf16 v[32:47], v[200:203], v[118:121], v[32:47]
	ds_read_b128 v[200:203], v194 offset:20992
	v_add_f32_e32 v177, v67, v177
	v_cvt_pk_bf16_f32 v65, v66, v67
	v_exp_f32_e32 v68, v68
	v_exp_f32_e32 v69, v69
	s_waitcnt lgkmcnt(10)
	v_mfma_f32_32x32x16_bf16 v[0:15], v[84:87], v[240:243], v[0:15]
	ds_read_b64_tr_b16 v[240:241], v127 offset:23552
	ds_read_b64_tr_b16 v[242:243], v127 offset:24064
	v_exp_f32_e32 v70, v70
	v_exp_f32_e32 v71, v71
	v_add_f32_e32 v176, v68, v176
	v_add_f32_e32 v177, v69, v177
	v_mfma_f32_32x32x16_bf16 v[16:31], v[84:87], v[122:125], v[16:31]
	ds_read_b64_tr_b16 v[122:123], v127 offset:27648
	ds_read_b64_tr_b16 v[124:125], v127 offset:28160
	v_cvt_pk_bf16_f32 v66, v68, v69
	v_add_f32_e32 v176, v70, v176
	v_add_f32_e32 v177, v71, v177
	v_cvt_pk_bf16_f32 v67, v70, v71
	s_waitcnt lgkmcnt(12)
	v_mfma_f32_32x32x16_bf16 v[48:63], v[204:207], v[102:105], v[48:63]
	ds_read_b128 v[204:207], v194 offset:22528
	v_exp_f32_e32 v72, v72
	v_exp_f32_e32 v73, v73
	v_exp_f32_e32 v74, v74
	v_exp_f32_e32 v75, v75
	v_mfma_f32_32x32x16_bf16 v[32:47], v[208:211], v[102:105], v[32:47]
	ds_read_b128 v[208:211], v194 offset:23040
	v_add_f32_e32 v176, v72, v176
	v_add_f32_e32 v177, v73, v177
	v_cvt_pk_bf16_f32 v68, v72, v73
	v_add_f32_e32 v176, v74, v176
	s_waitcnt lgkmcnt(9)
	v_mfma_f32_32x32x16_bf16 v[0:15], v[64:67], v[220:223], v[0:15]
	ds_read_b64_tr_b16 v[220:221], v139 offset:0
	ds_read_b64_tr_b16 v[222:223], v139 offset:512
	v_add_f32_e32 v177, v75, v177
	v_cvt_pk_bf16_f32 v69, v74, v75
	v_exp_f32_e32 v76, v76
	v_exp_f32_e32 v77, v77
	v_mfma_f32_32x32x16_bf16 v[16:31], v[64:67], v[244:247], v[16:31]
	ds_read_b64_tr_b16 v[244:245], v139 offset:4096
	ds_read_b64_tr_b16 v[246:247], v139 offset:4608
	v_exp_f32_e32 v78, v78
	v_exp_f32_e32 v79, v79
	v_add_f32_e32 v176, v76, v176
	v_add_f32_e32 v177, v77, v177
	s_waitcnt lgkmcnt(12)
	v_mfma_f32_32x32x16_bf16 v[48:63], v[212:215], v[98:101], v[48:63]
	ds_read_b128 v[212:215], v194 offset:24576
	v_cvt_pk_bf16_f32 v70, v76, v77
	v_add_f32_e32 v176, v78, v176
	v_add_f32_e32 v177, v79, v177
	v_cvt_pk_bf16_f32 v71, v78, v79
	v_mfma_f32_32x32x16_bf16 v[32:47], v[216:219], v[98:101], v[32:47]
	ds_read_b128 v[216:219], v194 offset:25088
	v_add_f32_e32 v175, v176, v177
	v_mov_b32_e32 v178, v175
	v_add_f32_e32 v147, v147, v175
	s_nop 0
	s_waitcnt lgkmcnt(8)
	v_mfma_f32_32x32x16_bf16 v[0:15], v[68:71], v[240:243], v[0:15]
	v_permlane32_swap_b32_e32 v175, v178
	v_add_f32_e32 v175, v175, v178
	v_cmp_lt_f32_e32 vcc, 0x43800000, v175
	v_mfma_f32_32x32x16_bf16 v[16:31], v[68:71], v[122:125], v[16:31]
	s_cbranch_vccz .Lat_nr_12
	v_log_f32_e32 v175, v175
	s_nop 0
	v_max_f32_e32 v175, 0, v175
	v_exp_f32_e64 v178, -v175
	s_and_saveexec_b64 s[4:5], s[2:3]
	ds_write_b32 v143, v178 offset:40960
	s_or_b64 exec, exec, s[4:5]
	s_waitcnt lgkmcnt(0)
	v_add_u32_e32 v179, s33, v191
	v_sub_f32_e32 v224, v224, v175
	v_mul_f32_e32 v147, v147, v178
	ds_read_b128 v[80:83], v179 offset:40960
	ds_read_b128 v[84:87], v179 offset:40992
	ds_read_b128 v[88:91], v179 offset:41024
	ds_read_b128 v[92:95], v179 offset:41056
	s_waitcnt lgkmcnt(0)
	s_nop 15
	v_pk_mul_f32 v[0:1], v[0:1], v[80:81]
	v_pk_mul_f32 v[2:3], v[2:3], v[82:83]
	v_pk_mul_f32 v[4:5], v[4:5], v[84:85]
	v_pk_mul_f32 v[6:7], v[6:7], v[86:87]
	v_pk_mul_f32 v[8:9], v[8:9], v[88:89]
	v_pk_mul_f32 v[10:11], v[10:11], v[90:91]
	v_pk_mul_f32 v[12:13], v[12:13], v[92:93]
	v_pk_mul_f32 v[14:15], v[14:15], v[94:95]
	v_pk_mul_f32 v[16:17], v[16:17], v[80:81]
	v_pk_mul_f32 v[18:19], v[18:19], v[82:83]
	v_pk_mul_f32 v[20:21], v[20:21], v[84:85]
	v_pk_mul_f32 v[22:23], v[22:23], v[86:87]
	v_pk_mul_f32 v[24:25], v[24:25], v[88:89]
	v_pk_mul_f32 v[26:27], v[26:27], v[90:91]
	v_pk_mul_f32 v[28:29], v[28:29], v[92:93]
	v_pk_mul_f32 v[30:31], v[30:31], v[94:95]
	v_mov_b32_e32 v225, v224
	v_mov_b32_e32 v226, v224
	v_mov_b32_e32 v227, v224
	v_mov_b32_e32 v228, v224
	v_mov_b32_e32 v229, v224
	v_mov_b32_e32 v230, v224
	v_mov_b32_e32 v231, v224
	v_mov_b32_e32 v232, v224
	v_mov_b32_e32 v233, v224
	v_mov_b32_e32 v234, v224
	v_mov_b32_e32 v235, v224
	v_mov_b32_e32 v236, v224
	v_mov_b32_e32 v237, v224
	v_mov_b32_e32 v238, v224
	v_mov_b32_e32 v239, v224
	v_sub_f32_e32 v48, v48, v175
	v_sub_f32_e32 v49, v49, v175
	v_sub_f32_e32 v50, v50, v175
	v_sub_f32_e32 v51, v51, v175
	v_sub_f32_e32 v52, v52, v175
	v_sub_f32_e32 v53, v53, v175
	v_sub_f32_e32 v54, v54, v175
	v_sub_f32_e32 v55, v55, v175
	v_sub_f32_e32 v56, v56, v175
	v_sub_f32_e32 v57, v57, v175
	v_sub_f32_e32 v58, v58, v175
	v_sub_f32_e32 v59, v59, v175
	v_sub_f32_e32 v60, v60, v175
	v_sub_f32_e32 v61, v61, v175
	v_sub_f32_e32 v62, v62, v175
	v_sub_f32_e32 v63, v63, v175
	v_sub_f32_e32 v32, v32, v175
	v_sub_f32_e32 v33, v33, v175
	v_sub_f32_e32 v34, v34, v175
	v_sub_f32_e32 v35, v35, v175
	v_sub_f32_e32 v36, v36, v175
	v_sub_f32_e32 v37, v37, v175
	v_sub_f32_e32 v38, v38, v175
	v_sub_f32_e32 v39, v39, v175
	v_sub_f32_e32 v40, v40, v175
	v_sub_f32_e32 v41, v41, v175
	v_sub_f32_e32 v42, v42, v175
	v_sub_f32_e32 v43, v43, v175
	v_sub_f32_e32 v44, v44, v175
	v_sub_f32_e32 v45, v45, v175
	v_sub_f32_e32 v46, v46, v175
	v_sub_f32_e32 v47, v47, v175
.Lat_nr_12:
	s_sub_u32 s24, s24, 1
	s_cmp_lg_u32 s24, 0
	s_cbranch_scc1 .Lat_loop_4
	s_add_i32 m0, s22, 0x15000
	s_cmp_eq_u32 s23, 0
	global_load_lds_dwordx4 v128, s[12:13]
	s_cbranch_scc1 .Lat_k2_13
	s_add_i32 m0, s22, 0x17000
	s_nop 0
	global_load_lds_dwordx4 v129, s[12:13]
.Lat_k2_13:
	s_add_i32 m0, s22, 0x13000
	s_nop 0
	global_load_lds_dwordx4 v145, s[14:15]
	s_add_u32 s14, s14, 0x20000
	s_addc_u32 s15, s15, 0
	v_exp_f32_e32 v48, v48
	v_exp_f32_e32 v49, v49
	v_exp_f32_e32 v50, v50
	v_exp_f32_e32 v51, v51
	v_mov_b32_e32 v176, v48
	v_mov_b32_e32 v177, v49
	v_cvt_pk_bf16_f32 v48, v48, v49
	v_add_f32_e32 v176, v50, v176
	v_add_f32_e32 v177, v51, v177
	v_cvt_pk_bf16_f32 v49, v50, v51
	v_exp_f32_e32 v52, v52
	v_exp_f32_e32 v53, v53
	s_waitcnt lgkmcnt(8)
	v_mfma_f32_32x32x16_bf16 v[80:95], v[196:199], v[110:113], v[224:239]
	ds_read_b128 v[196:199], v194 offset:26624
	ds_read_b64_tr_b16 v[240:241], v139 offset:1024
	ds_read_b64_tr_b16 v[242:243], v139 offset:1536
	v_exp_f32_e32 v54, v54
	v_exp_f32_e32 v55, v55
	v_add_f32_e32 v176, v52, v176
	v_add_f32_e32 v177, v53, v177
	v_mfma_f32_32x32x16_bf16 v[64:79], v[200:203], v[110:113], v[224:239]
	ds_read_b128 v[200:203], v194 offset:27136
	ds_read_b64_tr_b16 v[122:123], v139 offset:5120
	ds_read_b64_tr_b16 v[124:125], v139 offset:5632
	v_cvt_pk_bf16_f32 v50, v52, v53
	v_add_f32_e32 v176, v54, v176
	v_add_f32_e32 v177, v55, v177
	v_cvt_pk_bf16_f32 v51, v54, v55
	s_waitcnt lgkmcnt(12)
	v_mfma_f32_32x32x16_bf16 v[80:95], v[204:207], v[106:109], v[80:95]
	ds_read_b128 v[204:207], v194 offset:28672
	v_exp_f32_e32 v56, v56
	v_exp_f32_e32 v57, v57
	v_exp_f32_e32 v58, v58
	v_exp_f32_e32 v59, v59
	v_mfma_f32_32x32x16_bf16 v[64:79], v[208:211], v[106:109], v[64:79]
	ds_read_b128 v[208:211], v194 offset:29184
	v_add_f32_e32 v176, v56, v176
	v_add_f32_e32 v177, v57, v177
	v_cvt_pk_bf16_f32 v52, v56, v57
	v_add_f32_e32 v176, v58, v176
	s_waitcnt lgkmcnt(8)
	v_mfma_f32_32x32x16_bf16 v[80:95], v[212:215], v[114:117], v[80:95]
	ds_read_b128 v[212:215], v194 offset:30720
	v_add_f32_e32 v177, v59, v177
	v_cvt_pk_bf16_f32 v53, v58, v59
	v_exp_f32_e32 v60, v60
	v_exp_f32_e32 v61, v61
	v_mfma_f32_32x32x16_bf16 v[0:15], v[48:51], v[220:223], v[0:15]
	ds_read_b64_tr_b16 v[220:221], v139 offset:2048
	ds_read_b64_tr_b16 v[222:223], v139 offset:2560
	v_exp_f32_e32 v62, v62
	v_exp_f32_e32 v63, v63
	v_add_f32_e32 v176, v60, v176
	v_add_f32_e32 v177, v61, v177
	v_mfma_f32_32x32x16_bf16 v[16:31], v[48:51], v[244:247], v[16:31]
	ds_read_b64_tr_b16 v[244:245], v139 offset:6144
	ds_read_b64_tr_b16 v[246:247], v139 offset:6656
	v_cvt_pk_bf16_f32 v54, v60, v61
	v_add_f32_e32 v176, v62, v176
	v_add_f32_e32 v177, v63, v177
	v_cvt_pk_bf16_f32 v55, v62, v63
	v_mfma_f32_32x32x16_bf16 v[64:79], v[216:219], v[114:117], v[64:79]
	ds_read_b128 v[216:219], v194 offset:31232
	v_exp_f32_e32 v32, v32
	v_exp_f32_e32 v33, v33
	v_exp_f32_e32 v34, v34
	v_exp_f32_e32 v35, v35
	s_waitcnt vmcnt(2)
	s_barrier
	s_waitcnt lgkmcnt(10)
	v_mfma_f32_32x32x16_bf16 v[80:95], v[196:199], v[118:121], v[80:95]
	ds_read_b128 v[196:199], v126 offset:0
	v_add_f32_e32 v176, v32, v176
	v_add_f32_e32 v177, v33, v177
	v_cvt_pk_bf16_f32 v32, v32, v33
	v_add_f32_e32 v176, v34, v176
	v_mfma_f32_32x32x16_bf16 v[64:79], v[200:203], v[118:121], v[64:79]
	ds_read_b128 v[200:203], v126 offset:512
	v_add_f32_e32 v177, v35, v177
	v_cvt_pk_bf16_f32 v33, v34, v35
	v_exp_f32_e32 v36, v36
	v_exp_f32_e32 v37, v37
	s_waitcnt lgkmcnt(10)
	v_mfma_f32_32x32x16_bf16 v[0:15], v[52:55], v[240:243], v[0:15]
	ds_read_b64_tr_b16 v[240:241], v139 offset:3072
	ds_read_b64_tr_b16 v[242:243], v139 offset:3584
	v_exp_f32_e32 v38, v38
	v_exp_f32_e32 v39, v39
	v_add_f32_e32 v176, v36, v176
	v_add_f32_e32 v177, v37, v177
	v_mfma_f32_32x32x16_bf16 v[16:31], v[52:55], v[122:125], v[16:31]
	ds_read_b64_tr_b16 v[122:123], v139 offset:7168
	ds_read_b64_tr_b16 v[124:125], v139 offset:7680
	v_cvt_pk_bf16_f32 v34, v36, v37
	v_add_f32_e32 v176, v38, v176
	v_add_f32_e32 v177, v39, v177
	v_cvt_pk_bf16_f32 v35, v38, v39
	s_waitcnt lgkmcnt(12)
	v_mfma_f32_32x32x16_bf16 v[80:95], v[204:207], v[102:105], v[80:95]
	ds_read_b128 v[204:207], v126 offset:2048
	v_exp_f32_e32 v40, v40
	v_exp_f32_e32 v41, v41
	v_exp_f32_e32 v42, v42
	v_exp_f32_e32 v43, v43
	v_mfma_f32_32x32x16_bf16 v[64:79], v[208:211], v[102:105], v[64:79]
	ds_read_b128 v[208:211], v126 offset:2560
	v_add_f32_e32 v176, v40, v176
	v_add_f32_e32 v177, v41, v177
	v_cvt_pk_bf16_f32 v36, v40, v41
	v_add_f32_e32 v176, v42, v176
	s_waitcnt lgkmcnt(9)
	v_mfma_f32_32x32x16_bf16 v[0:15], v[32:35], v[220:223], v[0:15]
	ds_read_b64_tr_b16 v[220:221], v139 offset:20480
	ds_read_b64_tr_b16 v[222:223], v139 offset:20992
	v_add_f32_e32 v177, v43, v177
	v_cvt_pk_bf16_f32 v37, v42, v43
	v_exp_f32_e32 v44, v44
	v_exp_f32_e32 v45, v45
	v_mfma_f32_32x32x16_bf16 v[16:31], v[32:35], v[244:247], v[16:31]
	ds_read_b64_tr_b16 v[244:245], v139 offset:24576
	ds_read_b64_tr_b16 v[246:247], v139 offset:25088
	v_exp_f32_e32 v46, v46
	v_exp_f32_e32 v47, v47
	v_add_f32_e32 v176, v44, v176
	v_add_f32_e32 v177, v45, v177
	s_waitcnt lgkmcnt(12)
	v_mfma_f32_32x32x16_bf16 v[80:95], v[212:215], v[98:101], v[80:95]
	ds_read_b128 v[212:215], v126 offset:4096
	v_cvt_pk_bf16_f32 v38, v44, v45
	v_add_f32_e32 v176, v46, v176
	v_add_f32_e32 v177, v47, v177
	v_cvt_pk_bf16_f32 v39, v46, v47
	v_mfma_f32_32x32x16_bf16 v[64:79], v[216:219], v[98:101], v[64:79]
	ds_read_b128 v[216:219], v126 offset:4608
	v_add_f32_e32 v175, v176, v177
	v_mov_b32_e32 v178, v175
	v_add_f32_e32 v147, v147, v175
	s_nop 0
	s_waitcnt lgkmcnt(8)
	v_mfma_f32_32x32x16_bf16 v[0:15], v[36:39], v[240:243], v[0:15]
	v_permlane32_swap_b32_e32 v175, v178
	v_add_f32_e32 v175, v175, v178
	v_cmp_lt_f32_e32 vcc, 0x43800000, v175
	v_mfma_f32_32x32x16_bf16 v[16:31], v[36:39], v[122:125], v[16:31]
	s_cbranch_vccz .Lat_nr_14
	v_log_f32_e32 v175, v175
	s_nop 0
	v_max_f32_e32 v175, 0, v175
	v_exp_f32_e64 v178, -v175
	s_and_saveexec_b64 s[4:5], s[2:3]
	ds_write_b32 v143, v178 offset:40960
	s_or_b64 exec, exec, s[4:5]
	s_waitcnt lgkmcnt(0)
	v_add_u32_e32 v179, s33, v191
	v_sub_f32_e32 v224, v224, v175
	v_mul_f32_e32 v147, v147, v178
	ds_read_b128 v[48:51], v179 offset:40960
	ds_read_b128 v[52:55], v179 offset:40992
	ds_read_b128 v[56:59], v179 offset:41024
	ds_read_b128 v[60:63], v179 offset:41056
	s_waitcnt lgkmcnt(0)
	s_nop 15
	v_pk_mul_f32 v[0:1], v[0:1], v[48:49]
	v_pk_mul_f32 v[2:3], v[2:3], v[50:51]
	v_pk_mul_f32 v[4:5], v[4:5], v[52:53]
	v_pk_mul_f32 v[6:7], v[6:7], v[54:55]
	v_pk_mul_f32 v[8:9], v[8:9], v[56:57]
	v_pk_mul_f32 v[10:11], v[10:11], v[58:59]
	v_pk_mul_f32 v[12:13], v[12:13], v[60:61]
	v_pk_mul_f32 v[14:15], v[14:15], v[62:63]
	v_pk_mul_f32 v[16:17], v[16:17], v[48:49]
	v_pk_mul_f32 v[18:19], v[18:19], v[50:51]
	v_pk_mul_f32 v[20:21], v[20:21], v[52:53]
	v_pk_mul_f32 v[22:23], v[22:23], v[54:55]
	v_pk_mul_f32 v[24:25], v[24:25], v[56:57]
	v_pk_mul_f32 v[26:27], v[26:27], v[58:59]
	v_pk_mul_f32 v[28:29], v[28:29], v[60:61]
	v_pk_mul_f32 v[30:31], v[30:31], v[62:63]
	v_mov_b32_e32 v225, v224
	v_mov_b32_e32 v226, v224
	v_mov_b32_e32 v227, v224
	v_mov_b32_e32 v228, v224
	v_mov_b32_e32 v229, v224
	v_mov_b32_e32 v230, v224
	v_mov_b32_e32 v231, v224
	v_mov_b32_e32 v232, v224
	v_mov_b32_e32 v233, v224
	v_mov_b32_e32 v234, v224
	v_mov_b32_e32 v235, v224
	v_mov_b32_e32 v236, v224
	v_mov_b32_e32 v237, v224
	v_mov_b32_e32 v238, v224
	v_mov_b32_e32 v239, v224
	v_sub_f32_e32 v80, v80, v175
	v_sub_f32_e32 v81, v81, v175
	v_sub_f32_e32 v82, v82, v175
	v_sub_f32_e32 v83, v83, v175
	v_sub_f32_e32 v84, v84, v175
	v_sub_f32_e32 v85, v85, v175
	v_sub_f32_e32 v86, v86, v175
	v_sub_f32_e32 v87, v87, v175
	v_sub_f32_e32 v88, v88, v175
	v_sub_f32_e32 v89, v89, v175
	v_sub_f32_e32 v90, v90, v175
	v_sub_f32_e32 v91, v91, v175
	v_sub_f32_e32 v92, v92, v175
	v_sub_f32_e32 v93, v93, v175
	v_sub_f32_e32 v94, v94, v175
	v_sub_f32_e32 v95, v95, v175
	v_sub_f32_e32 v64, v64, v175
	v_sub_f32_e32 v65, v65, v175
	v_sub_f32_e32 v66, v66, v175
	v_sub_f32_e32 v67, v67, v175
	v_sub_f32_e32 v68, v68, v175
	v_sub_f32_e32 v69, v69, v175
	v_sub_f32_e32 v70, v70, v175
	v_sub_f32_e32 v71, v71, v175
	v_sub_f32_e32 v72, v72, v175
	v_sub_f32_e32 v73, v73, v175
	v_sub_f32_e32 v74, v74, v175
	v_sub_f32_e32 v75, v75, v175
	v_sub_f32_e32 v76, v76, v175
	v_sub_f32_e32 v77, v77, v175
	v_sub_f32_e32 v78, v78, v175
	v_sub_f32_e32 v79, v79, v175
.Lat_nr_14:
	s_mov_b64 s[12:13], s[36:37]
	s_add_i32 m0, s22, 0x0
	s_cmp_eq_u32 s23, 0
	global_load_lds_dwordx4 v128, s[12:13]
	s_cbranch_scc1 .Lat_k2_15
	s_add_i32 m0, s22, 0x2000
	s_nop 0
	global_load_lds_dwordx4 v129, s[12:13]
.Lat_k2_15:
	s_add_u32 s12, s12, 0x30000
	s_addc_u32 s13, s13, 0
	s_add_i32 m0, s22, 0x18000
	s_nop 0
	global_load_lds_dwordx4 v145, s[14:15]
	v_exp_f32_e32 v80, v80
	v_exp_f32_e32 v81, v81
	v_exp_f32_e32 v82, v82
	v_exp_f32_e32 v83, v83
	v_mov_b32_e32 v176, v80
	v_mov_b32_e32 v177, v81
	v_cvt_pk_bf16_f32 v80, v80, v81
	v_add_f32_e32 v176, v82, v176
	v_add_f32_e32 v177, v83, v177
	v_cvt_pk_bf16_f32 v81, v82, v83
	v_exp_f32_e32 v84, v84
	v_exp_f32_e32 v85, v85
	s_waitcnt lgkmcnt(8)
	v_mfma_f32_32x32x16_bf16 v[48:63], v[196:199], v[110:113], v[224:239]
	ds_read_b128 v[196:199], v126 offset:6144
	ds_read_b64_tr_b16 v[240:241], v139 offset:21504
	ds_read_b64_tr_b16 v[242:243], v139 offset:22016
	v_exp_f32_e32 v86, v86
	v_exp_f32_e32 v87, v87
	v_add_f32_e32 v176, v84, v176
	v_add_f32_e32 v177, v85, v177
	v_mfma_f32_32x32x16_bf16 v[32:47], v[200:203], v[110:113], v[224:239]
	ds_read_b128 v[200:203], v126 offset:6656
	ds_read_b64_tr_b16 v[122:123], v139 offset:25600
	ds_read_b64_tr_b16 v[124:125], v139 offset:26112
	v_cvt_pk_bf16_f32 v82, v84, v85
	v_add_f32_e32 v176, v86, v176
	v_add_f32_e32 v177, v87, v177
	v_cvt_pk_bf16_f32 v83, v86, v87
	s_waitcnt lgkmcnt(12)
	v_mfma_f32_32x32x16_bf16 v[48:63], v[204:207], v[106:109], v[48:63]
	ds_read_b128 v[204:207], v126 offset:8192
	v_exp_f32_e32 v88, v88
	v_exp_f32_e32 v89, v89
	v_exp_f32_e32 v90, v90
	v_exp_f32_e32 v91, v91
	v_mfma_f32_32x32x16_bf16 v[32:47], v[208:211], v[106:109], v[32:47]
	ds_read_b128 v[208:211], v126 offset:8704
	v_add_f32_e32 v176, v88, v176
	v_add_f32_e32 v177, v89, v177
	v_cvt_pk_bf16_f32 v84, v88, v89
	v_add_f32_e32 v176, v90, v176
	s_waitcnt lgkmcnt(8)
	v_mfma_f32_32x32x16_bf16 v[48:63], v[212:215], v[114:117], v[48:63]
	ds_read_b128 v[212:215], v126 offset:10240
	v_add_f32_e32 v177, v91, v177
	v_cvt_pk_bf16_f32 v85, v90, v91
	v_exp_f32_e32 v92, v92
	v_exp_f32_e32 v93, v93
	v_mfma_f32_32x32x16_bf16 v[0:15], v[80:83], v[220:223], v[0:15]
	ds_read_b64_tr_b16 v[220:221], v139 offset:22528
	ds_read_b64_tr_b16 v[222:223], v139 offset:23040
	v_exp_f32_e32 v94, v94
	v_exp_f32_e32 v95, v95
	v_add_f32_e32 v176, v92, v176
	v_add_f32_e32 v177, v93, v177
	v_mfma_f32_32x32x16_bf16 v[16:31], v[80:83], v[244:247], v[16:31]
	ds_read_b64_tr_b16 v[244:245], v139 offset:26624
	ds_read_b64_tr_b16 v[246:247], v139 offset:27136
	v_cvt_pk_bf16_f32 v86, v92, v93
	v_add_f32_e32 v176, v94, v176
	v_add_f32_e32 v177, v95, v177
	v_cvt_pk_bf16_f32 v87, v94, v95
	v_mfma_f32_32x32x16_bf16 v[32:47], v[216:219], v[114:117], v[32:47]
	ds_read_b128 v[216:219], v126 offset:10752
	v_exp_f32_e32 v64, v64
	v_exp_f32_e32 v65, v65
	v_exp_f32_e32 v66, v66
	v_exp_f32_e32 v67, v67
	s_waitcnt vmcnt(2)
	s_barrier
	s_waitcnt lgkmcnt(10)
	v_mfma_f32_32x32x16_bf16 v[48:63], v[196:199], v[118:121], v[48:63]
	ds_read_b128 v[196:199], v126 offset:20480
	v_add_f32_e32 v176, v64, v176
	v_add_f32_e32 v177, v65, v177
	v_cvt_pk_bf16_f32 v64, v64, v65
	v_add_f32_e32 v176, v66, v176
	v_mfma_f32_32x32x16_bf16 v[32:47], v[200:203], v[118:121], v[32:47]
	ds_read_b128 v[200:203], v126 offset:20992
	v_add_f32_e32 v177, v67, v177
	v_cvt_pk_bf16_f32 v65, v66, v67
	v_exp_f32_e32 v68, v68
	v_exp_f32_e32 v69, v69
	s_waitcnt lgkmcnt(10)
	v_mfma_f32_32x32x16_bf16 v[0:15], v[84:87], v[240:243], v[0:15]
	ds_read_b64_tr_b16 v[240:241], v139 offset:23552
	ds_read_b64_tr_b16 v[242:243], v139 offset:24064
	v_exp_f32_e32 v70, v70
	v_exp_f32_e32 v71, v71
	v_add_f32_e32 v176, v68, v176
	v_add_f32_e32 v177, v69, v177
	v_mfma_f32_32x32x16_bf16 v[16:31], v[84:87], v[122:125], v[16:31]
	ds_read_b64_tr_b16 v[122:123], v139 offset:27648
	ds_read_b64_tr_b16 v[124:125], v139 offset:28160
	v_cvt_pk_bf16_f32 v66, v68, v69
	v_add_f32_e32 v176, v70, v176
	v_add_f32_e32 v177, v71, v177
	v_cvt_pk_bf16_f32 v67, v70, v71
	s_waitcnt lgkmcnt(12)
	v_mfma_f32_32x32x16_bf16 v[48:63], v[204:207], v[102:105], v[48:63]
	ds_read_b128 v[204:207], v126 offset:22528
	v_exp_f32_e32 v72, v72
	v_exp_f32_e32 v73, v73
	v_exp_f32_e32 v74, v74
	v_exp_f32_e32 v75, v75
	v_mfma_f32_32x32x16_bf16 v[32:47], v[208:211], v[102:105], v[32:47]
	ds_read_b128 v[208:211], v126 offset:23040
	v_add_f32_e32 v176, v72, v176
	v_add_f32_e32 v177, v73, v177
	v_cvt_pk_bf16_f32 v68, v72, v73
	v_add_f32_e32 v176, v74, v176
	s_waitcnt lgkmcnt(9)
	v_mfma_f32_32x32x16_bf16 v[0:15], v[64:67], v[220:223], v[0:15]
	ds_read_b64_tr_b16 v[220:221], v127 offset:0
	ds_read_b64_tr_b16 v[222:223], v127 offset:512
	v_add_f32_e32 v177, v75, v177
	v_cvt_pk_bf16_f32 v69, v74, v75
	v_exp_f32_e32 v76, v76
	v_exp_f32_e32 v77, v77
	v_mfma_f32_32x32x16_bf16 v[16:31], v[64:67], v[244:247], v[16:31]
	ds_read_b64_tr_b16 v[244:245], v127 offset:4096
	ds_read_b64_tr_b16 v[246:247], v127 offset:4608
	v_exp_f32_e32 v78, v78
	v_exp_f32_e32 v79, v79
	v_add_f32_e32 v176, v76, v176
	v_add_f32_e32 v177, v77, v177
	s_waitcnt lgkmcnt(12)
	v_mfma_f32_32x32x16_bf16 v[48:63], v[212:215], v[98:101], v[48:63]
	ds_read_b128 v[212:215], v126 offset:24576
	v_cvt_pk_bf16_f32 v70, v76, v77
	v_add_f32_e32 v176, v78, v176
	v_add_f32_e32 v177, v79, v177
	v_cvt_pk_bf16_f32 v71, v78, v79
	v_mfma_f32_32x32x16_bf16 v[32:47], v[216:219], v[98:101], v[32:47]
	ds_read_b128 v[216:219], v126 offset:25088
	v_add_f32_e32 v175, v176, v177
	v_mov_b32_e32 v178, v175
	v_add_f32_e32 v147, v147, v175
	s_nop 0
	s_waitcnt lgkmcnt(8)
	v_mfma_f32_32x32x16_bf16 v[0:15], v[68:71], v[240:243], v[0:15]
	v_permlane32_swap_b32_e32 v175, v178
	v_add_f32_e32 v175, v175, v178
	v_cmp_lt_f32_e32 vcc, 0x43800000, v175
	v_mfma_f32_32x32x16_bf16 v[16:31], v[68:71], v[122:125], v[16:31]
	s_cbranch_vccz .Lat_nr_16
	v_log_f32_e32 v175, v175
	s_nop 0
	v_max_f32_e32 v175, 0, v175
	v_exp_f32_e64 v178, -v175
	s_and_saveexec_b64 s[4:5], s[2:3]
	ds_write_b32 v143, v178 offset:40960
	s_or_b64 exec, exec, s[4:5]
	s_waitcnt lgkmcnt(0)
	v_add_u32_e32 v179, s33, v191
	v_sub_f32_e32 v224, v224, v175
	v_mul_f32_e32 v147, v147, v178
	ds_read_b128 v[80:83], v179 offset:40960
	ds_read_b128 v[84:87], v179 offset:40992
	ds_read_b128 v[88:91], v179 offset:41024
	ds_read_b128 v[92:95], v179 offset:41056
	s_waitcnt lgkmcnt(0)
	s_nop 15
	v_pk_mul_f32 v[0:1], v[0:1], v[80:81]
	v_pk_mul_f32 v[2:3], v[2:3], v[82:83]
	v_pk_mul_f32 v[4:5], v[4:5], v[84:85]
	v_pk_mul_f32 v[6:7], v[6:7], v[86:87]
	v_pk_mul_f32 v[8:9], v[8:9], v[88:89]
	v_pk_mul_f32 v[10:11], v[10:11], v[90:91]
	v_pk_mul_f32 v[12:13], v[12:13], v[92:93]
	v_pk_mul_f32 v[14:15], v[14:15], v[94:95]
	v_pk_mul_f32 v[16:17], v[16:17], v[80:81]
	v_pk_mul_f32 v[18:19], v[18:19], v[82:83]
	v_pk_mul_f32 v[20:21], v[20:21], v[84:85]
	v_pk_mul_f32 v[22:23], v[22:23], v[86:87]
	v_pk_mul_f32 v[24:25], v[24:25], v[88:89]
	v_pk_mul_f32 v[26:27], v[26:27], v[90:91]
	v_pk_mul_f32 v[28:29], v[28:29], v[92:93]
	v_pk_mul_f32 v[30:31], v[30:31], v[94:95]
	v_mov_b32_e32 v225, v224
	v_mov_b32_e32 v226, v224
	v_mov_b32_e32 v227, v224
	v_mov_b32_e32 v228, v224
	v_mov_b32_e32 v229, v224
	v_mov_b32_e32 v230, v224
	v_mov_b32_e32 v231, v224
	v_mov_b32_e32 v232, v224
	v_mov_b32_e32 v233, v224
	v_mov_b32_e32 v234, v224
	v_mov_b32_e32 v235, v224
	v_mov_b32_e32 v236, v224
	v_mov_b32_e32 v237, v224
	v_mov_b32_e32 v238, v224
	v_mov_b32_e32 v239, v224
	v_sub_f32_e32 v48, v48, v175
	v_sub_f32_e32 v49, v49, v175
	v_sub_f32_e32 v50, v50, v175
	v_sub_f32_e32 v51, v51, v175
	v_sub_f32_e32 v52, v52, v175
	v_sub_f32_e32 v53, v53, v175
	v_sub_f32_e32 v54, v54, v175
	v_sub_f32_e32 v55, v55, v175
	v_sub_f32_e32 v56, v56, v175
	v_sub_f32_e32 v57, v57, v175
	v_sub_f32_e32 v58, v58, v175
	v_sub_f32_e32 v59, v59, v175
	v_sub_f32_e32 v60, v60, v175
	v_sub_f32_e32 v61, v61, v175
	v_sub_f32_e32 v62, v62, v175
	v_sub_f32_e32 v63, v63, v175
	v_sub_f32_e32 v32, v32, v175
	v_sub_f32_e32 v33, v33, v175
	v_sub_f32_e32 v34, v34, v175
	v_sub_f32_e32 v35, v35, v175
	v_sub_f32_e32 v36, v36, v175
	v_sub_f32_e32 v37, v37, v175
	v_sub_f32_e32 v38, v38, v175
	v_sub_f32_e32 v39, v39, v175
	v_sub_f32_e32 v40, v40, v175
	v_sub_f32_e32 v41, v41, v175
	v_sub_f32_e32 v42, v42, v175
	v_sub_f32_e32 v43, v43, v175
	v_sub_f32_e32 v44, v44, v175
	v_sub_f32_e32 v45, v45, v175
	v_sub_f32_e32 v46, v46, v175
	v_sub_f32_e32 v47, v47, v175

.Lat_k2_17:
	s_add_u32 s12, s12, 0x30000
	s_addc_u32 s13, s13, 0
	s_mov_b64 s[14:15], s[38:39]
	s_add_i32 m0, s22, 0x3000
	s_nop 0
	global_load_lds_dwordx4 v145, s[14:15]
	s_add_u32 s14, s14, 0x20000
	s_addc_u32 s15, s15, 0
	v_exp_f32_e32 v48, v48
	v_exp_f32_e32 v49, v49
	v_exp_f32_e32 v50, v50
	v_exp_f32_e32 v51, v51
	v_mov_b32_e32 v176, v48
	v_mov_b32_e32 v177, v49
	v_cvt_pk_bf16_f32 v48, v48, v49
	v_add_f32_e32 v176, v50, v176
	v_add_f32_e32 v177, v51, v177
	v_cvt_pk_bf16_f32 v49, v50, v51
	v_exp_f32_e32 v52, v52
	v_exp_f32_e32 v53, v53
	s_waitcnt lgkmcnt(8)
	v_mfma_f32_32x32x16_bf16 v[80:95], v[196:199], v[110:113], v[224:239]
	ds_read_b128 v[196:199], v126 offset:26624
	ds_read_b64_tr_b16 v[240:241], v127 offset:1024
	ds_read_b64_tr_b16 v[242:243], v127 offset:1536
	v_exp_f32_e32 v54, v54
	v_exp_f32_e32 v55, v55
	v_add_f32_e32 v176, v52, v176
	v_add_f32_e32 v177, v53, v177
	v_mfma_f32_32x32x16_bf16 v[64:79], v[200:203], v[110:113], v[224:239]
	ds_read_b128 v[200:203], v126 offset:27136
	ds_read_b64_tr_b16 v[122:123], v127 offset:5120
	ds_read_b64_tr_b16 v[124:125], v127 offset:5632
	v_cvt_pk_bf16_f32 v50, v52, v53
	v_add_f32_e32 v176, v54, v176
	v_add_f32_e32 v177, v55, v177
	v_cvt_pk_bf16_f32 v51, v54, v55
	s_waitcnt lgkmcnt(12)
	v_mfma_f32_32x32x16_bf16 v[80:95], v[204:207], v[106:109], v[80:95]
	ds_read_b128 v[204:207], v126 offset:28672
	v_exp_f32_e32 v56, v56
	v_exp_f32_e32 v57, v57
	v_exp_f32_e32 v58, v58
	v_exp_f32_e32 v59, v59
	v_mfma_f32_32x32x16_bf16 v[64:79], v[208:211], v[106:109], v[64:79]
	ds_read_b128 v[208:211], v126 offset:29184
	v_add_f32_e32 v176, v56, v176
	v_add_f32_e32 v177, v57, v177
	v_cvt_pk_bf16_f32 v52, v56, v57
	v_add_f32_e32 v176, v58, v176
	s_waitcnt lgkmcnt(8)
	v_mfma_f32_32x32x16_bf16 v[80:95], v[212:215], v[114:117], v[80:95]
	ds_read_b128 v[212:215], v126 offset:30720
	v_add_f32_e32 v177, v59, v177
	v_cvt_pk_bf16_f32 v53, v58, v59
	v_exp_f32_e32 v60, v60
	v_exp_f32_e32 v61, v61
	v_mfma_f32_32x32x16_bf16 v[0:15], v[48:51], v[220:223], v[0:15]
	ds_read_b64_tr_b16 v[220:221], v127 offset:2048
	ds_read_b64_tr_b16 v[222:223], v127 offset:2560
	v_exp_f32_e32 v62, v62
	v_exp_f32_e32 v63, v63
	v_add_f32_e32 v176, v60, v176
	v_add_f32_e32 v177, v61, v177
	v_mfma_f32_32x32x16_bf16 v[16:31], v[48:51], v[244:247], v[16:31]
	ds_read_b64_tr_b16 v[244:245], v127 offset:6144
	ds_read_b64_tr_b16 v[246:247], v127 offset:6656
	v_cvt_pk_bf16_f32 v54, v60, v61
	v_add_f32_e32 v176, v62, v176
	v_add_f32_e32 v177, v63, v177
	v_cvt_pk_bf16_f32 v55, v62, v63
	v_mfma_f32_32x32x16_bf16 v[64:79], v[216:219], v[114:117], v[64:79]
	ds_read_b128 v[216:219], v126 offset:31232
	v_exp_f32_e32 v32, v32
	v_exp_f32_e32 v33, v33
	v_exp_f32_e32 v34, v34
	v_exp_f32_e32 v35, v35
	s_waitcnt vmcnt(2)
	s_barrier
	s_waitcnt lgkmcnt(10)
	v_mfma_f32_32x32x16_bf16 v[80:95], v[196:199], v[118:121], v[80:95]
	ds_read_b128 v[196:199], v194 offset:0
	v_add_f32_e32 v176, v32, v176
	v_add_f32_e32 v177, v33, v177
	v_cvt_pk_bf16_f32 v32, v32, v33
	v_add_f32_e32 v176, v34, v176
	v_mfma_f32_32x32x16_bf16 v[64:79], v[200:203], v[118:121], v[64:79]
	ds_read_b128 v[200:203], v194 offset:512
	v_add_f32_e32 v177, v35, v177
	v_cvt_pk_bf16_f32 v33, v34, v35
	v_exp_f32_e32 v36, v36
	v_exp_f32_e32 v37, v37
	s_waitcnt lgkmcnt(10)
	v_mfma_f32_32x32x16_bf16 v[0:15], v[52:55], v[240:243], v[0:15]
	ds_read_b64_tr_b16 v[240:241], v127 offset:3072
	ds_read_b64_tr_b16 v[242:243], v127 offset:3584
	v_exp_f32_e32 v38, v38
	v_exp_f32_e32 v39, v39
	v_add_f32_e32 v176, v36, v176
	v_add_f32_e32 v177, v37, v177
	v_mfma_f32_32x32x16_bf16 v[16:31], v[52:55], v[122:125], v[16:31]
	ds_read_b64_tr_b16 v[122:123], v127 offset:7168
	ds_read_b64_tr_b16 v[124:125], v127 offset:7680
	v_cvt_pk_bf16_f32 v34, v36, v37
	v_add_f32_e32 v176, v38, v176
	v_add_f32_e32 v177, v39, v177
	v_cvt_pk_bf16_f32 v35, v38, v39
	s_waitcnt lgkmcnt(12)
	v_mfma_f32_32x32x16_bf16 v[80:95], v[204:207], v[102:105], v[80:95]
	ds_read_b128 v[204:207], v194 offset:2048
	v_exp_f32_e32 v40, v40
	v_exp_f32_e32 v41, v41
	v_exp_f32_e32 v42, v42
	v_exp_f32_e32 v43, v43
	v_mfma_f32_32x32x16_bf16 v[64:79], v[208:211], v[102:105], v[64:79]
	ds_read_b128 v[208:211], v194 offset:2560
	v_add_f32_e32 v176, v40, v176
	v_add_f32_e32 v177, v41, v177
	v_cvt_pk_bf16_f32 v36, v40, v41
	v_add_f32_e32 v176, v42, v176
	s_waitcnt lgkmcnt(9)
	v_mfma_f32_32x32x16_bf16 v[0:15], v[32:35], v[220:223], v[0:15]
	ds_read_b64_tr_b16 v[220:221], v127 offset:20480
	ds_read_b64_tr_b16 v[222:223], v127 offset:20992
	v_add_f32_e32 v177, v43, v177
	v_cvt_pk_bf16_f32 v37, v42, v43
	v_exp_f32_e32 v44, v44
	v_exp_f32_e32 v45, v45
	v_mfma_f32_32x32x16_bf16 v[16:31], v[32:35], v[244:247], v[16:31]
	ds_read_b64_tr_b16 v[244:245], v127 offset:24576
	ds_read_b64_tr_b16 v[246:247], v127 offset:25088
	v_exp_f32_e32 v46, v46
	v_exp_f32_e32 v47, v47
	v_add_f32_e32 v176, v44, v176
	v_add_f32_e32 v177, v45, v177
	s_waitcnt lgkmcnt(12)
	v_mfma_f32_32x32x16_bf16 v[80:95], v[212:215], v[98:101], v[80:95]
	ds_read_b128 v[212:215], v194 offset:4096
	v_cvt_pk_bf16_f32 v38, v44, v45
	v_add_f32_e32 v176, v46, v176
	v_add_f32_e32 v177, v47, v177
	v_cvt_pk_bf16_f32 v39, v46, v47
	v_mfma_f32_32x32x16_bf16 v[64:79], v[216:219], v[98:101], v[64:79]
	ds_read_b128 v[216:219], v194 offset:4608
	v_add_f32_e32 v175, v176, v177
	v_mov_b32_e32 v178, v175
	v_add_f32_e32 v147, v147, v175
	s_nop 0
	s_waitcnt lgkmcnt(8)
	v_mfma_f32_32x32x16_bf16 v[0:15], v[36:39], v[240:243], v[0:15]
	v_permlane32_swap_b32_e32 v175, v178
	v_add_f32_e32 v175, v175, v178
	v_cmp_lt_f32_e32 vcc, 0x43800000, v175
	v_mfma_f32_32x32x16_bf16 v[16:31], v[36:39], v[122:125], v[16:31]
	s_cbranch_vccz .Lat_nr_18
	v_log_f32_e32 v175, v175
	s_nop 0
	v_max_f32_e32 v175, 0, v175
	v_exp_f32_e64 v178, -v175
	s_and_saveexec_b64 s[4:5], s[2:3]
	ds_write_b32 v143, v178 offset:40960
	s_or_b64 exec, exec, s[4:5]
	s_waitcnt lgkmcnt(0)
	v_add_u32_e32 v179, s33, v191
	v_sub_f32_e32 v224, v224, v175
	v_mul_f32_e32 v147, v147, v178
	ds_read_b128 v[48:51], v179 offset:40960
	ds_read_b128 v[52:55], v179 offset:40992
	ds_read_b128 v[56:59], v179 offset:41024
	ds_read_b128 v[60:63], v179 offset:41056
	s_waitcnt lgkmcnt(0)
	s_nop 15
	v_pk_mul_f32 v[0:1], v[0:1], v[48:49]
	v_pk_mul_f32 v[2:3], v[2:3], v[50:51]
	v_pk_mul_f32 v[4:5], v[4:5], v[52:53]
	v_pk_mul_f32 v[6:7], v[6:7], v[54:55]
	v_pk_mul_f32 v[8:9], v[8:9], v[56:57]
	v_pk_mul_f32 v[10:11], v[10:11], v[58:59]
	v_pk_mul_f32 v[12:13], v[12:13], v[60:61]
	v_pk_mul_f32 v[14:15], v[14:15], v[62:63]
	v_pk_mul_f32 v[16:17], v[16:17], v[48:49]
	v_pk_mul_f32 v[18:19], v[18:19], v[50:51]
	v_pk_mul_f32 v[20:21], v[20:21], v[52:53]
	v_pk_mul_f32 v[22:23], v[22:23], v[54:55]
	v_pk_mul_f32 v[24:25], v[24:25], v[56:57]
	v_pk_mul_f32 v[26:27], v[26:27], v[58:59]
	v_pk_mul_f32 v[28:29], v[28:29], v[60:61]
	v_pk_mul_f32 v[30:31], v[30:31], v[62:63]
	v_mov_b32_e32 v225, v224
	v_mov_b32_e32 v226, v224
	v_mov_b32_e32 v227, v224
	v_mov_b32_e32 v228, v224
	v_mov_b32_e32 v229, v224
	v_mov_b32_e32 v230, v224
	v_mov_b32_e32 v231, v224
	v_mov_b32_e32 v232, v224
	v_mov_b32_e32 v233, v224
	v_mov_b32_e32 v234, v224
	v_mov_b32_e32 v235, v224
	v_mov_b32_e32 v236, v224
	v_mov_b32_e32 v237, v224
	v_mov_b32_e32 v238, v224
	v_mov_b32_e32 v239, v224
	v_sub_f32_e32 v80, v80, v175
	v_sub_f32_e32 v81, v81, v175
	v_sub_f32_e32 v82, v82, v175
	v_sub_f32_e32 v83, v83, v175
	v_sub_f32_e32 v84, v84, v175
	v_sub_f32_e32 v85, v85, v175
	v_sub_f32_e32 v86, v86, v175
	v_sub_f32_e32 v87, v87, v175
	v_sub_f32_e32 v88, v88, v175
	v_sub_f32_e32 v89, v89, v175
	v_sub_f32_e32 v90, v90, v175
	v_sub_f32_e32 v91, v91, v175
	v_sub_f32_e32 v92, v92, v175
	v_sub_f32_e32 v93, v93, v175
	v_sub_f32_e32 v94, v94, v175
	v_sub_f32_e32 v95, v95, v175
	v_sub_f32_e32 v64, v64, v175
	v_sub_f32_e32 v65, v65, v175
	v_sub_f32_e32 v66, v66, v175
	v_sub_f32_e32 v67, v67, v175
	v_sub_f32_e32 v68, v68, v175
	v_sub_f32_e32 v69, v69, v175
	v_sub_f32_e32 v70, v70, v175
	v_sub_f32_e32 v71, v71, v175
	v_sub_f32_e32 v72, v72, v175
	v_sub_f32_e32 v73, v73, v175
	v_sub_f32_e32 v74, v74, v175
	v_sub_f32_e32 v75, v75, v175
	v_sub_f32_e32 v76, v76, v175
	v_sub_f32_e32 v77, v77, v175
	v_sub_f32_e32 v78, v78, v175
	v_sub_f32_e32 v79, v79, v175

.Lat_nr_22:
	s_add_i32 m0, s22, 0x18000
	s_nop 0
	global_load_lds_dwordx4 v145, s[14:15]
	v_exp_f32_e32 v80, v80
	v_exp_f32_e32 v81, v81
	v_exp_f32_e32 v82, v82
	v_exp_f32_e32 v83, v83
	v_mov_b32_e32 v176, v80
	v_mov_b32_e32 v177, v81
	v_cvt_pk_bf16_f32 v80, v80, v81
	v_add_f32_e32 v176, v82, v176
	v_add_f32_e32 v177, v83, v177
	v_cvt_pk_bf16_f32 v81, v82, v83
	v_exp_f32_e32 v84, v84
	v_exp_f32_e32 v85, v85
	s_waitcnt lgkmcnt(8)
	v_mfma_f32_32x32x16_bf16 v[48:63], v[196:199], v[110:113], v[224:239]
	ds_read_b128 v[196:199], v126 offset:6144
	ds_read_b64_tr_b16 v[240:241], v139 offset:21504
	ds_read_b64_tr_b16 v[242:243], v139 offset:22016
	v_exp_f32_e32 v86, v86
	v_exp_f32_e32 v87, v87
	v_add_f32_e32 v176, v84, v176
	v_add_f32_e32 v177, v85, v177
	v_mfma_f32_32x32x16_bf16 v[32:47], v[200:203], v[110:113], v[224:239]
	ds_read_b128 v[200:203], v126 offset:6656
	ds_read_b64_tr_b16 v[122:123], v139 offset:25600
	ds_read_b64_tr_b16 v[124:125], v139 offset:26112
	v_cvt_pk_bf16_f32 v82, v84, v85
	v_add_f32_e32 v176, v86, v176
	v_add_f32_e32 v177, v87, v177
	v_cvt_pk_bf16_f32 v83, v86, v87
	s_waitcnt lgkmcnt(12)
	v_mfma_f32_32x32x16_bf16 v[48:63], v[204:207], v[106:109], v[48:63]
	ds_read_b128 v[204:207], v126 offset:8192
	v_exp_f32_e32 v88, v88
	v_exp_f32_e32 v89, v89
	v_exp_f32_e32 v90, v90
	v_exp_f32_e32 v91, v91
	v_mfma_f32_32x32x16_bf16 v[32:47], v[208:211], v[106:109], v[32:47]
	ds_read_b128 v[208:211], v126 offset:8704
	v_add_f32_e32 v176, v88, v176
	v_add_f32_e32 v177, v89, v177
	v_cvt_pk_bf16_f32 v84, v88, v89
	v_add_f32_e32 v176, v90, v176
	s_waitcnt lgkmcnt(8)
	v_mfma_f32_32x32x16_bf16 v[48:63], v[212:215], v[114:117], v[48:63]
	ds_read_b128 v[212:215], v126 offset:10240
	v_add_f32_e32 v177, v91, v177
	v_cvt_pk_bf16_f32 v85, v90, v91
	v_exp_f32_e32 v92, v92
	v_exp_f32_e32 v93, v93
	v_mfma_f32_32x32x16_bf16 v[0:15], v[80:83], v[220:223], v[0:15]
	ds_read_b64_tr_b16 v[220:221], v139 offset:22528
	ds_read_b64_tr_b16 v[222:223], v139 offset:23040
	v_exp_f32_e32 v94, v94
	v_exp_f32_e32 v95, v95
	v_add_f32_e32 v176, v92, v176
	v_add_f32_e32 v177, v93, v177
	v_mfma_f32_32x32x16_bf16 v[16:31], v[80:83], v[244:247], v[16:31]
	ds_read_b64_tr_b16 v[244:245], v139 offset:26624
	ds_read_b64_tr_b16 v[246:247], v139 offset:27136
	v_cvt_pk_bf16_f32 v86, v92, v93
	v_add_f32_e32 v176, v94, v176
	v_add_f32_e32 v177, v95, v177
	v_cvt_pk_bf16_f32 v87, v94, v95
	v_mfma_f32_32x32x16_bf16 v[32:47], v[216:219], v[114:117], v[32:47]
	ds_read_b128 v[216:219], v126 offset:10752
	v_exp_f32_e32 v64, v64
	v_exp_f32_e32 v65, v65
	v_exp_f32_e32 v66, v66
	v_exp_f32_e32 v67, v67
	s_waitcnt vmcnt(1)
	s_barrier
	s_waitcnt lgkmcnt(10)
	v_mfma_f32_32x32x16_bf16 v[48:63], v[196:199], v[118:121], v[48:63]
	ds_read_b128 v[196:199], v126 offset:20480
	v_add_f32_e32 v176, v64, v176
	v_add_f32_e32 v177, v65, v177
	v_cvt_pk_bf16_f32 v64, v64, v65
	v_add_f32_e32 v176, v66, v176
	v_mfma_f32_32x32x16_bf16 v[32:47], v[200:203], v[118:121], v[32:47]
	ds_read_b128 v[200:203], v126 offset:20992
	v_add_f32_e32 v177, v67, v177
	v_cvt_pk_bf16_f32 v65, v66, v67
	v_exp_f32_e32 v68, v68
	v_exp_f32_e32 v69, v69
	s_waitcnt lgkmcnt(10)
	v_mfma_f32_32x32x16_bf16 v[0:15], v[84:87], v[240:243], v[0:15]
	ds_read_b64_tr_b16 v[240:241], v139 offset:23552
	ds_read_b64_tr_b16 v[242:243], v139 offset:24064
	v_exp_f32_e32 v70, v70
	v_exp_f32_e32 v71, v71
	v_add_f32_e32 v176, v68, v176
	v_add_f32_e32 v177, v69, v177
	v_mfma_f32_32x32x16_bf16 v[16:31], v[84:87], v[122:125], v[16:31]
	ds_read_b64_tr_b16 v[122:123], v139 offset:27648
	ds_read_b64_tr_b16 v[124:125], v139 offset:28160
	v_cvt_pk_bf16_f32 v66, v68, v69
	v_add_f32_e32 v176, v70, v176
	v_add_f32_e32 v177, v71, v177
	v_cvt_pk_bf16_f32 v67, v70, v71
	s_waitcnt lgkmcnt(12)
	v_mfma_f32_32x32x16_bf16 v[48:63], v[204:207], v[102:105], v[48:63]
	ds_read_b128 v[204:207], v126 offset:22528
	v_exp_f32_e32 v72, v72
	v_exp_f32_e32 v73, v73
	v_exp_f32_e32 v74, v74
	v_exp_f32_e32 v75, v75
	v_mfma_f32_32x32x16_bf16 v[32:47], v[208:211], v[102:105], v[32:47]
	ds_read_b128 v[208:211], v126 offset:23040
	v_add_f32_e32 v176, v72, v176
	v_add_f32_e32 v177, v73, v177
	v_cvt_pk_bf16_f32 v68, v72, v73
	v_add_f32_e32 v176, v74, v176
	s_waitcnt lgkmcnt(9)
	v_mfma_f32_32x32x16_bf16 v[0:15], v[64:67], v[220:223], v[0:15]
	ds_read_b64_tr_b16 v[220:221], v127 offset:0
	ds_read_b64_tr_b16 v[222:223], v127 offset:512
	v_add_f32_e32 v177, v75, v177
	v_cvt_pk_bf16_f32 v69, v74, v75
	v_exp_f32_e32 v76, v76
	v_exp_f32_e32 v77, v77
	v_mfma_f32_32x32x16_bf16 v[16:31], v[64:67], v[244:247], v[16:31]
	ds_read_b64_tr_b16 v[244:245], v127 offset:4096
	ds_read_b64_tr_b16 v[246:247], v127 offset:4608
	v_exp_f32_e32 v78, v78
	v_exp_f32_e32 v79, v79
	v_add_f32_e32 v176, v76, v176
	v_add_f32_e32 v177, v77, v177
	s_waitcnt lgkmcnt(12)
	v_mfma_f32_32x32x16_bf16 v[48:63], v[212:215], v[98:101], v[48:63]
	ds_read_b128 v[212:215], v126 offset:24576
	v_cvt_pk_bf16_f32 v70, v76, v77
	v_add_f32_e32 v176, v78, v176
	v_add_f32_e32 v177, v79, v177
	v_cvt_pk_bf16_f32 v71, v78, v79
	v_mfma_f32_32x32x16_bf16 v[32:47], v[216:219], v[98:101], v[32:47]
	ds_read_b128 v[216:219], v126 offset:25088
	v_add_f32_e32 v175, v176, v177
	v_mov_b32_e32 v178, v175
	v_add_f32_e32 v147, v147, v175
	s_nop 0
	s_waitcnt lgkmcnt(8)
	v_mfma_f32_32x32x16_bf16 v[0:15], v[68:71], v[240:243], v[0:15]
	v_permlane32_swap_b32_e32 v175, v178
	v_add_f32_e32 v175, v175, v178
	v_cmp_lt_f32_e32 vcc, 0x43800000, v175
	v_mfma_f32_32x32x16_bf16 v[16:31], v[68:71], v[122:125], v[16:31]
	s_cbranch_vccz .Lat_nr_23
	v_log_f32_e32 v175, v175
	s_nop 0
	v_max_f32_e32 v175, 0, v175
	v_exp_f32_e64 v178, -v175
	s_and_saveexec_b64 s[4:5], s[2:3]
	ds_write_b32 v143, v178 offset:40960
	s_or_b64 exec, exec, s[4:5]
	s_waitcnt lgkmcnt(0)
	v_add_u32_e32 v179, s33, v191
	v_sub_f32_e32 v224, v224, v175
	v_mul_f32_e32 v147, v147, v178
	ds_read_b128 v[80:83], v179 offset:40960
	ds_read_b128 v[84:87], v179 offset:40992
	ds_read_b128 v[88:91], v179 offset:41024
	ds_read_b128 v[92:95], v179 offset:41056
	s_waitcnt lgkmcnt(0)
	s_nop 15
	v_pk_mul_f32 v[0:1], v[0:1], v[80:81]
	v_pk_mul_f32 v[2:3], v[2:3], v[82:83]
	v_pk_mul_f32 v[4:5], v[4:5], v[84:85]
	v_pk_mul_f32 v[6:7], v[6:7], v[86:87]
	v_pk_mul_f32 v[8:9], v[8:9], v[88:89]
	v_pk_mul_f32 v[10:11], v[10:11], v[90:91]
	v_pk_mul_f32 v[12:13], v[12:13], v[92:93]
	v_pk_mul_f32 v[14:15], v[14:15], v[94:95]
	v_pk_mul_f32 v[16:17], v[16:17], v[80:81]
	v_pk_mul_f32 v[18:19], v[18:19], v[82:83]
	v_pk_mul_f32 v[20:21], v[20:21], v[84:85]
	v_pk_mul_f32 v[22:23], v[22:23], v[86:87]
	v_pk_mul_f32 v[24:25], v[24:25], v[88:89]
	v_pk_mul_f32 v[26:27], v[26:27], v[90:91]
	v_pk_mul_f32 v[28:29], v[28:29], v[92:93]
	v_pk_mul_f32 v[30:31], v[30:31], v[94:95]
	v_mov_b32_e32 v225, v224
	v_mov_b32_e32 v226, v224
	v_mov_b32_e32 v227, v224
	v_mov_b32_e32 v228, v224
	v_mov_b32_e32 v229, v224
	v_mov_b32_e32 v230, v224
	v_mov_b32_e32 v231, v224
	v_mov_b32_e32 v232, v224
	v_mov_b32_e32 v233, v224
	v_mov_b32_e32 v234, v224
	v_mov_b32_e32 v235, v224
	v_mov_b32_e32 v236, v224
	v_mov_b32_e32 v237, v224
	v_mov_b32_e32 v238, v224
	v_mov_b32_e32 v239, v224
	v_sub_f32_e32 v48, v48, v175
	v_sub_f32_e32 v49, v49, v175
	v_sub_f32_e32 v50, v50, v175
	v_sub_f32_e32 v51, v51, v175
	v_sub_f32_e32 v52, v52, v175
	v_sub_f32_e32 v53, v53, v175
	v_sub_f32_e32 v54, v54, v175
	v_sub_f32_e32 v55, v55, v175
	v_sub_f32_e32 v56, v56, v175
	v_sub_f32_e32 v57, v57, v175
	v_sub_f32_e32 v58, v58, v175
	v_sub_f32_e32 v59, v59, v175
	v_sub_f32_e32 v60, v60, v175
	v_sub_f32_e32 v61, v61, v175
	v_sub_f32_e32 v62, v62, v175
	v_sub_f32_e32 v63, v63, v175
	v_sub_f32_e32 v32, v32, v175
	v_sub_f32_e32 v33, v33, v175
	v_sub_f32_e32 v34, v34, v175
	v_sub_f32_e32 v35, v35, v175
	v_sub_f32_e32 v36, v36, v175
	v_sub_f32_e32 v37, v37, v175
	v_sub_f32_e32 v38, v38, v175
	v_sub_f32_e32 v39, v39, v175
	v_sub_f32_e32 v40, v40, v175
	v_sub_f32_e32 v41, v41, v175
	v_sub_f32_e32 v42, v42, v175
	v_sub_f32_e32 v43, v43, v175
	v_sub_f32_e32 v44, v44, v175
	v_sub_f32_e32 v45, v45, v175
	v_sub_f32_e32 v46, v46, v175
	v_sub_f32_e32 v47, v47, v175
.Lat_nr_23:
	v_exp_f32_e32 v48, v48
	v_exp_f32_e32 v49, v49
	v_exp_f32_e32 v50, v50
	v_exp_f32_e32 v51, v51
	v_mov_b32_e32 v176, v48
	v_mov_b32_e32 v177, v49
	v_cvt_pk_bf16_f32 v48, v48, v49
	v_add_f32_e32 v176, v50, v176
	v_add_f32_e32 v177, v51, v177
	v_cvt_pk_bf16_f32 v49, v50, v51
	v_exp_f32_e32 v52, v52
	v_exp_f32_e32 v53, v53
	s_waitcnt lgkmcnt(8)
	v_mfma_f32_32x32x16_bf16 v[80:95], v[196:199], v[110:113], v[224:239]
	ds_read_b128 v[196:199], v126 offset:26624
	ds_read_b64_tr_b16 v[240:241], v127 offset:1024
	ds_read_b64_tr_b16 v[242:243], v127 offset:1536
	v_exp_f32_e32 v54, v54
	v_exp_f32_e32 v55, v55
	v_add_f32_e32 v176, v52, v176
	v_add_f32_e32 v177, v53, v177
	v_mfma_f32_32x32x16_bf16 v[64:79], v[200:203], v[110:113], v[224:239]
	ds_read_b128 v[200:203], v126 offset:27136
	ds_read_b64_tr_b16 v[122:123], v127 offset:5120
	ds_read_b64_tr_b16 v[124:125], v127 offset:5632
	v_cvt_pk_bf16_f32 v50, v52, v53
	v_add_f32_e32 v176, v54, v176
	v_add_f32_e32 v177, v55, v177
	v_cvt_pk_bf16_f32 v51, v54, v55
	s_waitcnt lgkmcnt(12)
	v_mfma_f32_32x32x16_bf16 v[80:95], v[204:207], v[106:109], v[80:95]
	ds_read_b128 v[204:207], v126 offset:28672
	v_exp_f32_e32 v56, v56
	v_exp_f32_e32 v57, v57
	v_exp_f32_e32 v58, v58
	v_exp_f32_e32 v59, v59
	v_mfma_f32_32x32x16_bf16 v[64:79], v[208:211], v[106:109], v[64:79]
	ds_read_b128 v[208:211], v126 offset:29184
	v_add_f32_e32 v176, v56, v176
	v_add_f32_e32 v177, v57, v177
	v_cvt_pk_bf16_f32 v52, v56, v57
	v_add_f32_e32 v176, v58, v176
	s_waitcnt lgkmcnt(8)
	v_mfma_f32_32x32x16_bf16 v[80:95], v[212:215], v[114:117], v[80:95]
	ds_read_b128 v[212:215], v126 offset:30720
	v_add_f32_e32 v177, v59, v177
	v_cvt_pk_bf16_f32 v53, v58, v59
	v_exp_f32_e32 v60, v60
	v_exp_f32_e32 v61, v61
	v_mfma_f32_32x32x16_bf16 v[0:15], v[48:51], v[220:223], v[0:15]
	ds_read_b64_tr_b16 v[220:221], v127 offset:2048
	ds_read_b64_tr_b16 v[222:223], v127 offset:2560
	v_exp_f32_e32 v62, v62
	v_exp_f32_e32 v63, v63
	v_add_f32_e32 v176, v60, v176
	v_add_f32_e32 v177, v61, v177
	v_mfma_f32_32x32x16_bf16 v[16:31], v[48:51], v[244:247], v[16:31]
	ds_read_b64_tr_b16 v[244:245], v127 offset:6144
	ds_read_b64_tr_b16 v[246:247], v127 offset:6656
	v_cvt_pk_bf16_f32 v54, v60, v61
	v_add_f32_e32 v176, v62, v176
	v_add_f32_e32 v177, v63, v177
	v_cvt_pk_bf16_f32 v55, v62, v63
	v_mfma_f32_32x32x16_bf16 v[64:79], v[216:219], v[114:117], v[64:79]
	ds_read_b128 v[216:219], v126 offset:31232
	v_exp_f32_e32 v32, v32
	v_exp_f32_e32 v33, v33
	v_exp_f32_e32 v34, v34
	v_exp_f32_e32 v35, v35
	s_waitcnt vmcnt(0)
	s_barrier
	s_waitcnt lgkmcnt(10)
	v_mfma_f32_32x32x16_bf16 v[80:95], v[196:199], v[118:121], v[80:95]
	v_add_f32_e32 v176, v32, v176
	v_add_f32_e32 v177, v33, v177
	v_cvt_pk_bf16_f32 v32, v32, v33
	v_add_f32_e32 v176, v34, v176
	v_mfma_f32_32x32x16_bf16 v[64:79], v[200:203], v[118:121], v[64:79]
	v_add_f32_e32 v177, v35, v177
	v_cvt_pk_bf16_f32 v33, v34, v35
	v_exp_f32_e32 v36, v36
	v_exp_f32_e32 v37, v37
	s_waitcnt lgkmcnt(8)
	v_mfma_f32_32x32x16_bf16 v[0:15], v[52:55], v[240:243], v[0:15]
	ds_read_b64_tr_b16 v[240:241], v127 offset:3072
	ds_read_b64_tr_b16 v[242:243], v127 offset:3584
	v_exp_f32_e32 v38, v38
	v_exp_f32_e32 v39, v39
	v_add_f32_e32 v176, v36, v176
	v_add_f32_e32 v177, v37, v177
	v_mfma_f32_32x32x16_bf16 v[16:31], v[52:55], v[122:125], v[16:31]
	ds_read_b64_tr_b16 v[122:123], v127 offset:7168
	ds_read_b64_tr_b16 v[124:125], v127 offset:7680
	v_cvt_pk_bf16_f32 v34, v36, v37
	v_add_f32_e32 v176, v38, v176
	v_add_f32_e32 v177, v39, v177
	v_cvt_pk_bf16_f32 v35, v38, v39
	s_waitcnt lgkmcnt(10)
	v_mfma_f32_32x32x16_bf16 v[80:95], v[204:207], v[102:105], v[80:95]
	v_exp_f32_e32 v40, v40
	v_exp_f32_e32 v41, v41
	v_exp_f32_e32 v42, v42
	v_exp_f32_e32 v43, v43
	v_mfma_f32_32x32x16_bf16 v[64:79], v[208:211], v[102:105], v[64:79]
	v_add_f32_e32 v176, v40, v176
	v_add_f32_e32 v177, v41, v177
	v_cvt_pk_bf16_f32 v36, v40, v41
	v_add_f32_e32 v176, v42, v176
	s_waitcnt lgkmcnt(5)
	v_mfma_f32_32x32x16_bf16 v[0:15], v[32:35], v[220:223], v[0:15]
	ds_read_b64_tr_b16 v[220:221], v127 offset:20480
	ds_read_b64_tr_b16 v[222:223], v127 offset:20992
	v_add_f32_e32 v177, v43, v177
	v_cvt_pk_bf16_f32 v37, v42, v43
	v_exp_f32_e32 v44, v44
	v_exp_f32_e32 v45, v45
	v_mfma_f32_32x32x16_bf16 v[16:31], v[32:35], v[244:247], v[16:31]
	ds_read_b64_tr_b16 v[244:245], v127 offset:24576
	ds_read_b64_tr_b16 v[246:247], v127 offset:25088
	v_exp_f32_e32 v46, v46
	v_exp_f32_e32 v47, v47
	v_add_f32_e32 v176, v44, v176
	v_add_f32_e32 v177, v45, v177
	s_waitcnt lgkmcnt(8)
	v_mfma_f32_32x32x16_bf16 v[80:95], v[212:215], v[98:101], v[80:95]
	v_cvt_pk_bf16_f32 v38, v44, v45
	v_add_f32_e32 v176, v46, v176
	v_add_f32_e32 v177, v47, v177
	v_cvt_pk_bf16_f32 v39, v46, v47
	v_mfma_f32_32x32x16_bf16 v[64:79], v[216:219], v[98:101], v[64:79]
	v_add_f32_e32 v175, v176, v177
	v_mov_b32_e32 v178, v175
	v_add_f32_e32 v147, v147, v175
	s_nop 0
	s_waitcnt lgkmcnt(4)
	v_mfma_f32_32x32x16_bf16 v[0:15], v[36:39], v[240:243], v[0:15]
	v_permlane32_swap_b32_e32 v175, v178
	v_add_f32_e32 v175, v175, v178
	v_cmp_lt_f32_e32 vcc, 0x43800000, v175
	v_mfma_f32_32x32x16_bf16 v[16:31], v[36:39], v[122:125], v[16:31]
	s_cbranch_vccz .Lat_nr_24
	v_log_f32_e32 v175, v175
	s_nop 0
	v_max_f32_e32 v175, 0, v175
	v_exp_f32_e64 v178, -v175
	s_and_saveexec_b64 s[4:5], s[2:3]
	ds_write_b32 v143, v178 offset:40960
	s_or_b64 exec, exec, s[4:5]
	s_waitcnt lgkmcnt(0)
	v_add_u32_e32 v179, s33, v191
	v_sub_f32_e32 v224, v224, v175
	v_mul_f32_e32 v147, v147, v178
	ds_read_b128 v[48:51], v179 offset:40960
	ds_read_b128 v[52:55], v179 offset:40992
	ds_read_b128 v[56:59], v179 offset:41024
	ds_read_b128 v[60:63], v179 offset:41056
	s_waitcnt lgkmcnt(0)
	s_nop 15
	v_pk_mul_f32 v[0:1], v[0:1], v[48:49]
	v_pk_mul_f32 v[2:3], v[2:3], v[50:51]
	v_pk_mul_f32 v[4:5], v[4:5], v[52:53]
	v_pk_mul_f32 v[6:7], v[6:7], v[54:55]
	v_pk_mul_f32 v[8:9], v[8:9], v[56:57]
	v_pk_mul_f32 v[10:11], v[10:11], v[58:59]
	v_pk_mul_f32 v[12:13], v[12:13], v[60:61]
	v_pk_mul_f32 v[14:15], v[14:15], v[62:63]
	v_pk_mul_f32 v[16:17], v[16:17], v[48:49]
	v_pk_mul_f32 v[18:19], v[18:19], v[50:51]
	v_pk_mul_f32 v[20:21], v[20:21], v[52:53]
	v_pk_mul_f32 v[22:23], v[22:23], v[54:55]
	v_pk_mul_f32 v[24:25], v[24:25], v[56:57]
	v_pk_mul_f32 v[26:27], v[26:27], v[58:59]
	v_pk_mul_f32 v[28:29], v[28:29], v[60:61]
	v_pk_mul_f32 v[30:31], v[30:31], v[62:63]
	v_mov_b32_e32 v225, v224
	v_mov_b32_e32 v226, v224
	v_mov_b32_e32 v227, v224
	v_mov_b32_e32 v228, v224
	v_mov_b32_e32 v229, v224
	v_mov_b32_e32 v230, v224
	v_mov_b32_e32 v231, v224
	v_mov_b32_e32 v232, v224
	v_mov_b32_e32 v233, v224
	v_mov_b32_e32 v234, v224
	v_mov_b32_e32 v235, v224
	v_mov_b32_e32 v236, v224
	v_mov_b32_e32 v237, v224
	v_mov_b32_e32 v238, v224
	v_mov_b32_e32 v239, v224
	v_sub_f32_e32 v80, v80, v175
	v_sub_f32_e32 v81, v81, v175
	v_sub_f32_e32 v82, v82, v175
	v_sub_f32_e32 v83, v83, v175
	v_sub_f32_e32 v84, v84, v175
	v_sub_f32_e32 v85, v85, v175
	v_sub_f32_e32 v86, v86, v175
	v_sub_f32_e32 v87, v87, v175
	v_sub_f32_e32 v88, v88, v175
	v_sub_f32_e32 v89, v89, v175
	v_sub_f32_e32 v90, v90, v175
	v_sub_f32_e32 v91, v91, v175
	v_sub_f32_e32 v92, v92, v175
	v_sub_f32_e32 v93, v93, v175
	v_sub_f32_e32 v94, v94, v175
	v_sub_f32_e32 v95, v95, v175
	v_sub_f32_e32 v64, v64, v175
	v_sub_f32_e32 v65, v65, v175
	v_sub_f32_e32 v66, v66, v175
	v_sub_f32_e32 v67, v67, v175
	v_sub_f32_e32 v68, v68, v175
	v_sub_f32_e32 v69, v69, v175
	v_sub_f32_e32 v70, v70, v175
	v_sub_f32_e32 v71, v71, v175
	v_sub_f32_e32 v72, v72, v175
	v_sub_f32_e32 v73, v73, v175
	v_sub_f32_e32 v74, v74, v175
	v_sub_f32_e32 v75, v75, v175
	v_sub_f32_e32 v76, v76, v175
	v_sub_f32_e32 v77, v77, v175
	v_sub_f32_e32 v78, v78, v175
	v_sub_f32_e32 v79, v79, v175
.Lat_nr_24:
	v_exp_f32_e32 v80, v80
	v_exp_f32_e32 v81, v81
	v_exp_f32_e32 v82, v82
	v_exp_f32_e32 v83, v83
	v_mov_b32_e32 v176, v80
	v_mov_b32_e32 v177, v81
	v_cvt_pk_bf16_f32 v80, v80, v81
	v_add_f32_e32 v176, v82, v176
	v_add_f32_e32 v177, v83, v177
	v_cvt_pk_bf16_f32 v81, v82, v83
	v_exp_f32_e32 v84, v84
	v_exp_f32_e32 v85, v85
	ds_read_b64_tr_b16 v[240:241], v127 offset:21504
	ds_read_b64_tr_b16 v[242:243], v127 offset:22016
	v_exp_f32_e32 v86, v86
	v_exp_f32_e32 v87, v87
	v_add_f32_e32 v176, v84, v176
	v_add_f32_e32 v177, v85, v177
	ds_read_b64_tr_b16 v[122:123], v127 offset:25600
	ds_read_b64_tr_b16 v[124:125], v127 offset:26112
	v_cvt_pk_bf16_f32 v82, v84, v85
	v_add_f32_e32 v176, v86, v176
	v_add_f32_e32 v177, v87, v177
	v_cvt_pk_bf16_f32 v83, v86, v87
	v_exp_f32_e32 v88, v88
	v_exp_f32_e32 v89, v89
	v_exp_f32_e32 v90, v90
	v_exp_f32_e32 v91, v91
	v_add_f32_e32 v176, v88, v176
	v_add_f32_e32 v177, v89, v177
	v_cvt_pk_bf16_f32 v84, v88, v89
	v_add_f32_e32 v176, v90, v176
	v_add_f32_e32 v177, v91, v177
	v_cvt_pk_bf16_f32 v85, v90, v91
	v_exp_f32_e32 v92, v92
	v_exp_f32_e32 v93, v93
	s_waitcnt lgkmcnt(4)
	v_mfma_f32_32x32x16_bf16 v[0:15], v[80:83], v[220:223], v[0:15]
	ds_read_b64_tr_b16 v[220:221], v127 offset:22528
	ds_read_b64_tr_b16 v[222:223], v127 offset:23040
	v_exp_f32_e32 v94, v94
	v_exp_f32_e32 v95, v95
	v_add_f32_e32 v176, v92, v176
	v_add_f32_e32 v177, v93, v177
	v_mfma_f32_32x32x16_bf16 v[16:31], v[80:83], v[244:247], v[16:31]
	ds_read_b64_tr_b16 v[244:245], v127 offset:26624
	ds_read_b64_tr_b16 v[246:247], v127 offset:27136
	v_cvt_pk_bf16_f32 v86, v92, v93
	v_add_f32_e32 v176, v94, v176
	v_add_f32_e32 v177, v95, v177
	v_cvt_pk_bf16_f32 v87, v94, v95
	v_exp_f32_e32 v64, v64
	v_exp_f32_e32 v65, v65
	v_exp_f32_e32 v66, v66
	v_exp_f32_e32 v67, v67
	s_waitcnt vmcnt(0)
	s_barrier
	v_add_f32_e32 v176, v64, v176
	v_add_f32_e32 v177, v65, v177
	v_cvt_pk_bf16_f32 v64, v64, v65
	v_add_f32_e32 v176, v66, v176
	v_add_f32_e32 v177, v67, v177
	v_cvt_pk_bf16_f32 v65, v66, v67
	v_exp_f32_e32 v68, v68
	v_exp_f32_e32 v69, v69
	s_waitcnt lgkmcnt(4)
	v_mfma_f32_32x32x16_bf16 v[0:15], v[84:87], v[240:243], v[0:15]
	ds_read_b64_tr_b16 v[240:241], v127 offset:23552
	ds_read_b64_tr_b16 v[242:243], v127 offset:24064
	v_exp_f32_e32 v70, v70
	v_exp_f32_e32 v71, v71
	v_add_f32_e32 v176, v68, v176
	v_add_f32_e32 v177, v69, v177
	v_mfma_f32_32x32x16_bf16 v[16:31], v[84:87], v[122:125], v[16:31]
	ds_read_b64_tr_b16 v[122:123], v127 offset:27648
	ds_read_b64_tr_b16 v[124:125], v127 offset:28160
	v_cvt_pk_bf16_f32 v66, v68, v69
	v_add_f32_e32 v176, v70, v176
	v_add_f32_e32 v177, v71, v177
	v_cvt_pk_bf16_f32 v67, v70, v71
	v_exp_f32_e32 v72, v72
	v_exp_f32_e32 v73, v73
	v_exp_f32_e32 v74, v74
	v_exp_f32_e32 v75, v75
	v_add_f32_e32 v176, v72, v176
	v_add_f32_e32 v177, v73, v177
	v_cvt_pk_bf16_f32 v68, v72, v73
	v_add_f32_e32 v176, v74, v176
	s_waitcnt lgkmcnt(4)
	v_mfma_f32_32x32x16_bf16 v[0:15], v[64:67], v[220:223], v[0:15]
	v_add_f32_e32 v177, v75, v177
	v_cvt_pk_bf16_f32 v69, v74, v75
	v_exp_f32_e32 v76, v76
	v_exp_f32_e32 v77, v77
	v_mfma_f32_32x32x16_bf16 v[16:31], v[64:67], v[244:247], v[16:31]
	v_exp_f32_e32 v78, v78
	v_exp_f32_e32 v79, v79
	v_add_f32_e32 v176, v76, v176
	v_add_f32_e32 v177, v77, v177
	v_cvt_pk_bf16_f32 v70, v76, v77
	v_add_f32_e32 v176, v78, v176
	v_add_f32_e32 v177, v79, v177
	v_cvt_pk_bf16_f32 v71, v78, v79
	v_add_f32_e32 v175, v176, v177
	v_mov_b32_e32 v178, v175
	v_add_f32_e32 v147, v147, v175
	s_nop 0
	s_waitcnt lgkmcnt(0)
	v_mfma_f32_32x32x16_bf16 v[0:15], v[68:71], v[240:243], v[0:15]
	v_permlane32_swap_b32_e32 v175, v178
	v_add_f32_e32 v175, v175, v178
	v_cmp_lt_f32_e32 vcc, 0x43800000, v175
	v_mfma_f32_32x32x16_bf16 v[16:31], v[68:71], v[122:125], v[16:31]
	s_cbranch_vccz .Lat_nr_25
	v_log_f32_e32 v175, v175
	s_nop 0
	v_max_f32_e32 v175, 0, v175
	v_exp_f32_e64 v178, -v175
	s_and_saveexec_b64 s[4:5], s[2:3]
	ds_write_b32 v143, v178 offset:40960
	s_or_b64 exec, exec, s[4:5]
	s_waitcnt lgkmcnt(0)
	v_add_u32_e32 v179, s33, v191
	v_sub_f32_e32 v224, v224, v175
	v_mul_f32_e32 v147, v147, v178
	ds_read_b128 v[80:83], v179 offset:40960
	ds_read_b128 v[84:87], v179 offset:40992
	ds_read_b128 v[88:91], v179 offset:41024
	ds_read_b128 v[92:95], v179 offset:41056
	s_waitcnt lgkmcnt(0)
	s_nop 15
	v_pk_mul_f32 v[0:1], v[0:1], v[80:81]
	v_pk_mul_f32 v[2:3], v[2:3], v[82:83]
	v_pk_mul_f32 v[4:5], v[4:5], v[84:85]
	v_pk_mul_f32 v[6:7], v[6:7], v[86:87]
	v_pk_mul_f32 v[8:9], v[8:9], v[88:89]
	v_pk_mul_f32 v[10:11], v[10:11], v[90:91]
	v_pk_mul_f32 v[12:13], v[12:13], v[92:93]
	v_pk_mul_f32 v[14:15], v[14:15], v[94:95]
	v_pk_mul_f32 v[16:17], v[16:17], v[80:81]
	v_pk_mul_f32 v[18:19], v[18:19], v[82:83]
	v_pk_mul_f32 v[20:21], v[20:21], v[84:85]
	v_pk_mul_f32 v[22:23], v[22:23], v[86:87]
	v_pk_mul_f32 v[24:25], v[24:25], v[88:89]
	v_pk_mul_f32 v[26:27], v[26:27], v[90:91]
	v_pk_mul_f32 v[28:29], v[28:29], v[92:93]
	v_pk_mul_f32 v[30:31], v[30:31], v[94:95]
	v_mov_b32_e32 v225, v224
	v_mov_b32_e32 v226, v224
	v_mov_b32_e32 v227, v224
	v_mov_b32_e32 v228, v224
	v_mov_b32_e32 v229, v224
	v_mov_b32_e32 v230, v224
	v_mov_b32_e32 v231, v224
	v_mov_b32_e32 v232, v224
	v_mov_b32_e32 v233, v224
	v_mov_b32_e32 v234, v224
	v_mov_b32_e32 v235, v224
	v_mov_b32_e32 v236, v224
	v_mov_b32_e32 v237, v224
	v_mov_b32_e32 v238, v224
	v_mov_b32_e32 v239, v224
.Lat_nr_25:
	v_mov_b32_e32 v32, v147
	s_mov_b32 s10, s27

; DEV unsigned cvt_pk_bf16(float lo, float hi) { unsigned r; asm volatile("v_cvt_pk_bf16_f32 %0, %1, %2" : "=v"(r) : "v"(lo), "v"(hi)); return r; }
; DEV void modnorm_rows(const float* srcX, const float* srcC, int nrows, const float* g, const float* shift, const float* scale, bf16_t* dst, int gw, int NGW, int lane) {
;     for (int row0 = gw; row0 < nrows; row0 += 2 * NGW) {
;         const int row1 = row0 + NGW; const bool has1 = row1 < nrows;
;         const float* xr0 = (row0 < TX) ? srcX + (size_t)row0 * DM : srcC + (size_t)(row0 - TX) * DM;
;         const float* xr1 = !has1 ? xr0 : ((row1 < TX) ? srcX + (size_t)row1 * DM : srcC + (size_t)(row1 - TX) * DM);
;         f32x4 v0[4], v1[4]; float s0 = 0.f, s1 = 0.f;
; #pragma unroll
;         for (int j = 0; j < 4; ++j) { v0[j] = __builtin_nontemporal_load((const f32x4*)(xr0 + 256 * j + 4 * lane)); v1[j] = __builtin_nontemporal_load((const f32x4*)(xr1 + 256 * j + 4 * lane)); }
; #pragma unroll
;         for (int j = 0; j < 4; ++j) { s0 += (v0[j][0] * v0[j][0] + v0[j][1] * v0[j][1]) + (v0[j][2] * v0[j][2] + v0[j][3] * v0[j][3]); s1 += (v1[j][0] * v1[j][0] + v1[j][1] * v1[j][1]) + (v1[j][2] * v1[j][2] + v1[j][3] * v1[j][3]); }
;         const float rstd0 = 1.0f / sqrtf(wave_sum(s0) * (1.f / DM) + EPS), rstd1 = 1.0f / sqrtf(wave_sum(s1) * (1.f / DM) + EPS);
;         const int mr0 = (row0 < TX) ? (row0 >> 12) : 8, mr1 = (row1 < TX) ? (row1 >> 12) : 8;
; #pragma unroll
;         for (int j = 0; j < 4; ++j) { const int col = 256 * j + 4 * lane; const f32x4 gg = *(const f32x4*)(g + col);
;             { const f32x4 sh = *(const f32x4*)(shift + (size_t)mr0 * 6144 + col), sc = *(const f32x4*)(scale + (size_t)mr0 * 6144 + col); f32x4 y;
; #pragma unroll
;                 for (int e = 0; e < 4; ++e) y[e] = (v0[j][e] * rstd0 * gg[e]) * (1.f + sc[e]) + sh[e];
;                 u32x2 w; w.x = cvt_pk_bf16(y[0], y[1]); w.y = cvt_pk_bf16(y[2], y[3]); *(u32x2*)(dst + (size_t)row0 * DM + col) = w; }
;             if (has1) { const f32x4 sh = *(const f32x4*)(shift + (size_t)mr1 * 6144 + col), sc = *(const f32x4*)(scale + (size_t)mr1 * 6144 + col); f32x4 y;
.LBB0_2182:
	s_andn2_b64 vcc, exec, s[2:3]
	s_cbranch_vccnz .LBB0_2200
	s_cmp_eq_u32 s82, 10
	s_cbranch_scc0 .LBB0_2200
	s_cmp_gt_i32 s0, 0x87ff
	s_cbranch_scc1 .LBB0_2200
	v_readlane_b32 s2, v251, 2
	v_readlane_b32 s3, v251, 3
	v_readlane_b32 s1, v251, 1
	v_readlane_b32 s14, v251, 0
	v_readlane_b32 s20, v251, 4
	v_mbcnt_lo_u32_b32 v122, -1, 0
	v_mbcnt_hi_u32_b32 v122, -1, v122
	s_load_dwordx2 s[12:13], s[2:3], 0x110
	s_load_dwordx2 s[16:17], s[2:3], 0x20
	s_lshl_b32 s1, s1, 3
	s_lshl_b32 s14, s14, 3
	s_lshr_b32 s20, s20, 6
	s_add_u32 s14, s14, s20
	s_mov_b32 s15, s14
	v_lshlrev_b32_e32 v123, 3, v122
	v_lshlrev_b32_e32 v122, 4, v122
	v_mov_b32_e32 v140, 0x358637bd
	v_mov_b32_e32 v141, 0x260
	s_waitcnt lgkmcnt(0)
	s_add_u32 s16, s16, 0x1000
	s_addc_u32 s17, s17, 0
	global_load_dwordx4 v[98:101], v122, s[16:17] offset:0
	global_load_dwordx4 v[102:105], v122, s[16:17] offset:1024
	global_load_dwordx4 v[106:109], v122, s[16:17] offset:2048
	global_load_dwordx4 v[110:113], v122, s[16:17] offset:3072
	s_add_u32 s4, s12, 0x1c00000
	s_addc_u32 s5, s13, 0
	s_add_u32 s6, s4, 0x8000000
	s_addc_u32 s7, s5, 0
	s_add_u32 s8, s12, 0x36000
	s_addc_u32 s9, s13, 0
	s_add_u32 s10, s12, 0x37000
	s_addc_u32 s11, s13, 0
	s_add_u32 s12, s12, 0xa400000
	s_addc_u32 s13, s13, 0
	s_cmp_ge_i32 s14, 0x8800
	s_cbranch_scc1 .Lmn10_ni_2
	s_sub_i32 s21, s14, 0x8000
	s_lshr_b32 s20, s14, 12
	s_cmp_lt_i32 s14, 0x8000
	s_cselect_b32 s21, s14, s21
	s_cselect_b32 s20, s20, 8
	s_cselect_b32 s16, s4, s6
	s_cselect_b32 s17, s5, s7
	s_lshl_b32 s21, s21, 12
	s_mul_i32 s20, s20, 0x6000
	s_add_u32 s16, s16, s21
	s_addc_u32 s17, s17, 0
	s_add_u32 s18, s8, s20
	s_addc_u32 s19, s9, 0
	global_load_dwordx4 v[0:3], v122, s[16:17] offset:0 nt
	global_load_dwordx4 v[4:7], v122, s[16:17] offset:1024 nt
	global_load_dwordx4 v[8:11], v122, s[16:17] offset:2048 nt
	global_load_dwordx4 v[12:15], v122, s[16:17] offset:3072 nt
	global_load_dwordx4 v[16:19], v122, s[18:19] offset:0
	global_load_dwordx4 v[20:23], v122, s[18:19] offset:1024
	global_load_dwordx4 v[24:27], v122, s[18:19] offset:2048
	global_load_dwordx4 v[28:31], v122, s[18:19] offset:3072
	s_add_u32 s18, s10, s20
	s_addc_u32 s19, s11, 0
	global_load_dwordx4 v[32:35], v122, s[18:19] offset:0
	global_load_dwordx4 v[36:39], v122, s[18:19] offset:1024
	global_load_dwordx4 v[40:43], v122, s[18:19] offset:2048
	global_load_dwordx4 v[44:47], v122, s[18:19] offset:3072
.Lmn10_ni_2:
	s_add_u32 s14, s14, s1
	s_cmp_ge_i32 s14, 0x8800
	s_cbranch_scc1 .Lmn10_ni_3
	s_sub_i32 s21, s14, 0x8000
	s_lshr_b32 s20, s14, 12
	s_cmp_lt_i32 s14, 0x8000
	s_cselect_b32 s21, s14, s21
	s_cselect_b32 s20, s20, 8
	s_cselect_b32 s16, s4, s6
	s_cselect_b32 s17, s5, s7
	s_lshl_b32 s21, s21, 12
	s_mul_i32 s20, s20, 0x6000
	s_add_u32 s16, s16, s21
	s_addc_u32 s17, s17, 0
	s_add_u32 s18, s8, s20
	s_addc_u32 s19, s9, 0
	global_load_dwordx4 v[48:51], v122, s[16:17] offset:0 nt
	global_load_dwordx4 v[52:55], v122, s[16:17] offset:1024 nt
	global_load_dwordx4 v[56:59], v122, s[16:17] offset:2048 nt
	global_load_dwordx4 v[60:63], v122, s[16:17] offset:3072 nt
	global_load_dwordx4 v[64:67], v122, s[18:19] offset:0
	global_load_dwordx4 v[68:71], v122, s[18:19] offset:1024
	global_load_dwordx4 v[72:75], v122, s[18:19] offset:2048
	global_load_dwordx4 v[76:79], v122, s[18:19] offset:3072
	s_add_u32 s18, s10, s20
	s_addc_u32 s19, s11, 0
	global_load_dwordx4 v[80:83], v122, s[18:19] offset:0
	global_load_dwordx4 v[84:87], v122, s[18:19] offset:1024
	global_load_dwordx4 v[88:91], v122, s[18:19] offset:2048
	global_load_dwordx4 v[92:95], v122, s[18:19] offset:3072
.Lmn10_ni_3:
	s_add_u32 s14, s14, s1
	s_waitcnt vmcnt(24)
	s_cmp_ge_i32 s15, 0x8800
	s_cbranch_scc1 .Lmn10_done_1
	s_add_u32 s20, s15, s1
	s_cmp_ge_i32 s20, 0x8800
	s_cbranch_scc1 .Lmn10_wl_4
	s_waitcnt vmcnt(12)
	s_branch .Lmn10_wj_5

; DEV unsigned cvt_pk_bf16(float lo, float hi) { unsigned r; asm volatile("v_cvt_pk_bf16_f32 %0, %1, %2" : "=v"(r) : "v"(lo), "v"(hi)); return r; }
; DEV void modnorm_rows(const float* srcX, const float* srcC, int nrows, const float* g, const float* shift, const float* scale, bf16_t* dst, int gw, int NGW, int lane) {
;     ...
;         for (int j = 0; j < 4; ++j) { s0 += (v0[j][0] * v0[j][0] + v0[j][1] * v0[j][1]) + (v0[j][2] * v0[j][2] + v0[j][3] * v0[j][3]); s1 += (v1[j][0] * v1[j][0] + v1[j][1] * v1[j][1]) + (v1[j][2] * v1[j][2] + v1[j][3] * v1[j][3]); }
;         const float rstd0 = 1.0f / sqrtf(wave_sum(s0) * (1.f / DM) + EPS), rstd1 = 1.0f / sqrtf(wave_sum(s1) * (1.f / DM) + EPS);
;         const int mr0 = (row0 < TX) ? (row0 >> 12) : 8, mr1 = (row1 < TX) ? (row1 >> 12) : 8;
; #pragma unroll
;         for (int j = 0; j < 4; ++j) { const int col = 256 * j + 4 * lane; const f32x4 gg = *(const f32x4*)(g + col);
;             { const f32x4 sh = *(const f32x4*)(shift + (size_t)mr0 * 6144 + col), sc = *(const f32x4*)(scale + (size_t)mr0 * 6144 + col); f32x4 y;
; #pragma unroll
;                 for (int e = 0; e < 4; ++e) y[e] = (v0[j][e] * rstd0 * gg[e]) * (1.f + sc[e]) + sh[e];
;                 u32x2 w; w.x = cvt_pk_bf16(y[0], y[1]); w.y = cvt_pk_bf16(y[2], y[3]); *(u32x2*)(dst + (size_t)row0 * DM + col) = w; }
;             if (has1) { const f32x4 sh = *(const f32x4*)(shift + (size_t)mr1 * 6144 + col), sc = *(const f32x4*)(scale + (size_t)mr1 * 6144 + col); f32x4 y;
; #pragma unroll
;                 for (int e = 0; e < 4; ++e) y[e] = (v1[j][e] * rstd1 * gg[e]) * (1.f + sc[e]) + sh[e];
;                 u32x2 w; w.x = cvt_pk_bf16(y[0], y[1]); w.y = cvt_pk_bf16(y[2], y[3]); *(u32x2*)(dst + (size_t)row1 * DM + col) = w; } }
.Lmn10_wj_5:
	v_mul_f32_e32 v114, v1, v1
	v_mul_f32_e32 v115, v3, v3
	v_mul_f32_e32 v116, v5, v5
	v_mul_f32_e32 v117, v7, v7
	v_mul_f32_e32 v118, v9, v9
	v_mul_f32_e32 v119, v11, v11
	v_mul_f32_e32 v120, v13, v13
	v_mul_f32_e32 v121, v15, v15
	v_fmac_f32_e32 v114, v0, v0
	v_fmac_f32_e32 v115, v2, v2
	v_fmac_f32_e32 v116, v4, v4
	v_fmac_f32_e32 v117, v6, v6
	v_fmac_f32_e32 v118, v8, v8
	v_fmac_f32_e32 v119, v10, v10
	v_fmac_f32_e32 v120, v12, v12
	v_fmac_f32_e32 v121, v14, v14
	v_add_f32_e32 v114, v114, v115
	v_add_f32_e32 v116, v116, v117
	v_add_f32_e32 v118, v118, v119
	v_add_f32_e32 v120, v120, v121
	v_add_f32_e32 v124, v114, v116
	v_add_f32_e32 v124, v124, v118
	v_add_f32_e32 v124, v124, v120
	v_add_f32_e32 v32, 1.0, v32
	v_add_f32_e32 v33, 1.0, v33
	v_add_f32_dpp v124, v124, v124 quad_perm:[1,0,3,2] row_mask:0xf bank_mask:0xf
	v_add_f32_e32 v34, 1.0, v34
	v_add_f32_e32 v35, 1.0, v35
	v_add_f32_dpp v124, v124, v124 quad_perm:[2,3,0,1] row_mask:0xf bank_mask:0xf
	v_add_f32_e32 v36, 1.0, v36
	v_add_f32_e32 v37, 1.0, v37
	v_add_f32_dpp v124, v124, v124 row_half_mirror row_mask:0xf bank_mask:0xf
	v_add_f32_e32 v38, 1.0, v38
	v_add_f32_e32 v39, 1.0, v39
	v_add_f32_dpp v124, v124, v124 row_mirror row_mask:0xf bank_mask:0xf
	v_add_f32_e32 v40, 1.0, v40
	v_add_f32_e32 v41, 1.0, v41
	v_mov_b32_e32 v125, v124
	v_mov_b32_e32 v126, v124
	v_add_f32_e32 v42, 1.0, v42
	v_add_f32_e32 v43, 1.0, v43
	v_permlane16_swap_b32_e32 v125, v126
	v_add_f32_e32 v124, v125, v126
	v_mov_b32_e32 v125, v124
	v_mov_b32_e32 v126, v124
	v_add_f32_e32 v44, 1.0, v44
	v_add_f32_e32 v45, 1.0, v45
	v_permlane32_swap_b32_e32 v125, v126
	v_add_f32_e32 v124, v125, v126
	v_add_f32_e32 v46, 1.0, v46
	v_add_f32_e32 v47, 1.0, v47
	v_fmamk_f32 v124, v124, 0x3a800000, v140
	v_mul_f32_e32 v125, 0x4f800000, v124
	v_cmp_gt_f32_e32 vcc, 0xf800000, v124
	s_nop 1
	v_cndmask_b32_e32 v124, v124, v125, vcc
	v_sqrt_f32_e32 v127, v124
	s_nop 0
	v_add_u32_e32 v128, -1, v127
	v_add_u32_e32 v129, 1, v127
	v_fma_f32 v134, -v128, v127, v124
	v_fma_f32 v135, -v129, v127, v124
	v_cmp_ge_f32_e64 s[16:17], 0, v134
	v_cmp_lt_f32_e64 s[18:19], 0, v135
	s_nop 1
	v_cndmask_b32_e64 v127, v127, v128, s[16:17]
	v_cndmask_b32_e64 v127, v127, v129, s[18:19]
	v_mul_f32_e32 v125, 0x37800000, v127
	v_cndmask_b32_e32 v127, v127, v125, vcc
	v_cmp_class_f32_e32 vcc, v124, v141
	s_nop 1
	v_cndmask_b32_e32 v127, v127, v124, vcc
	v_div_scale_f32 v136, s[16:17], v127, v127, 1.0
	v_div_scale_f32 v138, vcc, 1.0, v127, 1.0
	v_rcp_f32_e32 v137, v136
	s_nop 0
	v_fma_f32 v134, -v136, v137, 1.0
	v_fmac_f32_e32 v137, v134, v137
	v_mul_f32_e32 v139, v138, v137
	v_fma_f32 v134, -v136, v139, v138
	v_fmac_f32_e32 v139, v134, v137
	v_fma_f32 v134, -v136, v139, v138
	v_div_fmas_f32 v134, v134, v137, v139
	v_div_fixup_f32 v134, v134, v127, 1.0
	v_mul_f32_e32 v0, v0, v134
	v_mul_f32_e32 v1, v1, v134
	v_mul_f32_e32 v2, v2, v134
	v_mul_f32_e32 v3, v3, v134
	v_mul_f32_e32 v4, v4, v134
	v_mul_f32_e32 v5, v5, v134
	v_mul_f32_e32 v6, v6, v134
	v_mul_f32_e32 v7, v7, v134
	v_mul_f32_e32 v8, v8, v134
	v_mul_f32_e32 v9, v9, v134
	v_mul_f32_e32 v10, v10, v134
	v_mul_f32_e32 v11, v11, v134
	v_mul_f32_e32 v12, v12, v134
	v_mul_f32_e32 v13, v13, v134
	v_mul_f32_e32 v14, v14, v134
	v_mul_f32_e32 v15, v15, v134
	v_mul_f32_e32 v0, v98, v0
	v_mul_f32_e32 v1, v99, v1
	v_mul_f32_e32 v2, v100, v2
	v_mul_f32_e32 v3, v101, v3
	v_mul_f32_e32 v4, v102, v4
	v_mul_f32_e32 v5, v103, v5
	v_mul_f32_e32 v6, v104, v6
	v_mul_f32_e32 v7, v105, v7
	v_mul_f32_e32 v8, v106, v8
	v_mul_f32_e32 v9, v107, v9
	v_mul_f32_e32 v10, v108, v10
	v_mul_f32_e32 v11, v109, v11
	v_mul_f32_e32 v12, v110, v12
	v_mul_f32_e32 v13, v111, v13
	v_mul_f32_e32 v14, v112, v14
	v_mul_f32_e32 v15, v113, v15
	v_fma_f32 v0, v0, v32, v16
	v_fma_f32 v1, v1, v33, v17
	v_fma_f32 v2, v2, v34, v18
	v_fma_f32 v3, v3, v35, v19
	v_fma_f32 v4, v4, v36, v20
	v_fma_f32 v5, v5, v37, v21
	v_fma_f32 v6, v6, v38, v22
	v_fma_f32 v7, v7, v39, v23
	v_fma_f32 v8, v8, v40, v24
	v_fma_f32 v9, v9, v41, v25
	v_fma_f32 v10, v10, v42, v26
	v_fma_f32 v11, v11, v43, v27
	v_fma_f32 v12, v12, v44, v28
	v_fma_f32 v13, v13, v45, v29
	v_fma_f32 v14, v14, v46, v30
	v_fma_f32 v15, v15, v47, v31
	v_cvt_pk_bf16_f32 v114, v0, v1
	v_cvt_pk_bf16_f32 v115, v2, v3
	v_cvt_pk_bf16_f32 v116, v4, v5
	v_cvt_pk_bf16_f32 v117, v6, v7
	v_cvt_pk_bf16_f32 v118, v8, v9
	v_cvt_pk_bf16_f32 v119, v10, v11
	v_cvt_pk_bf16_f32 v120, v12, v13
	v_cvt_pk_bf16_f32 v121, v14, v15
	s_lshl_b32 s21, s15, 11
	s_add_u32 s22, s12, s21
	s_addc_u32 s23, s13, 0
	s_cmp_ge_i32 s14, 0x8800
	s_cbranch_scc1 .Lmn10_ni_6
	s_sub_i32 s21, s14, 0x8000
	s_lshr_b32 s20, s14, 12
	s_cmp_lt_i32 s14, 0x8000
	s_cselect_b32 s21, s14, s21
	s_cselect_b32 s20, s20, 8
	s_cselect_b32 s16, s4, s6
	s_cselect_b32 s17, s5, s7
	s_lshl_b32 s21, s21, 12
	s_mul_i32 s20, s20, 0x6000
	s_add_u32 s16, s16, s21
	s_addc_u32 s17, s17, 0
	s_add_u32 s18, s8, s20
	s_addc_u32 s19, s9, 0
	global_load_dwordx4 v[0:3], v122, s[16:17] offset:0 nt
	global_load_dwordx4 v[4:7], v122, s[16:17] offset:1024 nt
	global_load_dwordx4 v[8:11], v122, s[16:17] offset:2048 nt
	global_load_dwordx4 v[12:15], v122, s[16:17] offset:3072 nt
	global_load_dwordx4 v[16:19], v122, s[18:19] offset:0
	global_load_dwordx4 v[20:23], v122, s[18:19] offset:1024
	global_load_dwordx4 v[24:27], v122, s[18:19] offset:2048
	global_load_dwordx4 v[28:31], v122, s[18:19] offset:3072
	s_add_u32 s18, s10, s20
	s_addc_u32 s19, s11, 0
	global_load_dwordx4 v[32:35], v122, s[18:19] offset:0
	global_load_dwordx4 v[36:39], v122, s[18:19] offset:1024
	global_load_dwordx4 v[40:43], v122, s[18:19] offset:2048
	global_load_dwordx4 v[44:47], v122, s[18:19] offset:3072
.Lmn10_ni_6:
	s_add_u32 s14, s14, s1
	global_store_dwordx2 v123, v[114:115], s[22:23] offset:0
	global_store_dwordx2 v123, v[116:117], s[22:23] offset:512
	global_store_dwordx2 v123, v[118:119], s[22:23] offset:1024
	global_store_dwordx2 v123, v[120:121], s[22:23] offset:1536
	s_add_u32 s15, s15, s1
	s_cmp_ge_i32 s15, 0x8800
	s_cbranch_scc1 .Lmn10_done_1
	s_add_u32 s20, s15, s1
	s_cmp_ge_i32 s20, 0x8800
	s_cbranch_scc1 .Lmn10_wl_7
	s_waitcnt vmcnt(16)
	s_branch .Lmn10_wj_8

; DEV unsigned cvt_pk_bf16(float lo, float hi) { unsigned r; asm volatile("v_cvt_pk_bf16_f32 %0, %1, %2" : "=v"(r) : "v"(lo), "v"(hi)); return r; }
; DEV void modnorm_rows(const float* srcX, const float* srcC, int nrows, const float* g, const float* shift, const float* scale, bf16_t* dst, int gw, int NGW, int lane) {
;     ...
;         for (int j = 0; j < 4; ++j) { s0 += (v0[j][0] * v0[j][0] + v0[j][1] * v0[j][1]) + (v0[j][2] * v0[j][2] + v0[j][3] * v0[j][3]); s1 += (v1[j][0] * v1[j][0] + v1[j][1] * v1[j][1]) + (v1[j][2] * v1[j][2] + v1[j][3] * v1[j][3]); }
;         const float rstd0 = 1.0f / sqrtf(wave_sum(s0) * (1.f / DM) + EPS), rstd1 = 1.0f / sqrtf(wave_sum(s1) * (1.f / DM) + EPS);
;         const int mr0 = (row0 < TX) ? (row0 >> 12) : 8, mr1 = (row1 < TX) ? (row1 >> 12) : 8;
; #pragma unroll
;         for (int j = 0; j < 4; ++j) { const int col = 256 * j + 4 * lane; const f32x4 gg = *(const f32x4*)(g + col);
;             { const f32x4 sh = *(const f32x4*)(shift + (size_t)mr0 * 6144 + col), sc = *(const f32x4*)(scale + (size_t)mr0 * 6144 + col); f32x4 y;
; #pragma unroll
;                 for (int e = 0; e < 4; ++e) y[e] = (v0[j][e] * rstd0 * gg[e]) * (1.f + sc[e]) + sh[e];
;                 u32x2 w; w.x = cvt_pk_bf16(y[0], y[1]); w.y = cvt_pk_bf16(y[2], y[3]); *(u32x2*)(dst + (size_t)row0 * DM + col) = w; }
;             if (has1) { const f32x4 sh = *(const f32x4*)(shift + (size_t)mr1 * 6144 + col), sc = *(const f32x4*)(scale + (size_t)mr1 * 6144 + col); f32x4 y;
; #pragma unroll
;                 for (int e = 0; e < 4; ++e) y[e] = (v1[j][e] * rstd1 * gg[e]) * (1.f + sc[e]) + sh[e];
;                 u32x2 w; w.x = cvt_pk_bf16(y[0], y[1]); w.y = cvt_pk_bf16(y[2], y[3]); *(u32x2*)(dst + (size_t)row1 * DM + col) = w; } }
.Lmn10_wj_8:
	v_mul_f32_e32 v114, v49, v49
	v_mul_f32_e32 v115, v51, v51
	v_mul_f32_e32 v116, v53, v53
	v_mul_f32_e32 v117, v55, v55
	v_mul_f32_e32 v118, v57, v57
	v_mul_f32_e32 v119, v59, v59
	v_mul_f32_e32 v120, v61, v61
	v_mul_f32_e32 v121, v63, v63
	v_fmac_f32_e32 v114, v48, v48
	v_fmac_f32_e32 v115, v50, v50
	v_fmac_f32_e32 v116, v52, v52
	v_fmac_f32_e32 v117, v54, v54
	v_fmac_f32_e32 v118, v56, v56
	v_fmac_f32_e32 v119, v58, v58
	v_fmac_f32_e32 v120, v60, v60
	v_fmac_f32_e32 v121, v62, v62
	v_add_f32_e32 v114, v114, v115
	v_add_f32_e32 v116, v116, v117
	v_add_f32_e32 v118, v118, v119
	v_add_f32_e32 v120, v120, v121
	v_add_f32_e32 v124, v114, v116
	v_add_f32_e32 v124, v124, v118
	v_add_f32_e32 v124, v124, v120
	v_add_f32_e32 v80, 1.0, v80
	v_add_f32_e32 v81, 1.0, v81
	v_add_f32_dpp v124, v124, v124 quad_perm:[1,0,3,2] row_mask:0xf bank_mask:0xf
	v_add_f32_e32 v82, 1.0, v82
	v_add_f32_e32 v83, 1.0, v83
	v_add_f32_dpp v124, v124, v124 quad_perm:[2,3,0,1] row_mask:0xf bank_mask:0xf
	v_add_f32_e32 v84, 1.0, v84
	v_add_f32_e32 v85, 1.0, v85
	v_add_f32_dpp v124, v124, v124 row_half_mirror row_mask:0xf bank_mask:0xf
	v_add_f32_e32 v86, 1.0, v86
	v_add_f32_e32 v87, 1.0, v87
	v_add_f32_dpp v124, v124, v124 row_mirror row_mask:0xf bank_mask:0xf
	v_add_f32_e32 v88, 1.0, v88
	v_add_f32_e32 v89, 1.0, v89
	v_mov_b32_e32 v125, v124
	v_mov_b32_e32 v126, v124
	v_add_f32_e32 v90, 1.0, v90
	v_add_f32_e32 v91, 1.0, v91
	v_permlane16_swap_b32_e32 v125, v126
	v_add_f32_e32 v124, v125, v126
	v_mov_b32_e32 v125, v124
	v_mov_b32_e32 v126, v124
	v_add_f32_e32 v92, 1.0, v92
	v_add_f32_e32 v93, 1.0, v93
	v_permlane32_swap_b32_e32 v125, v126
	v_add_f32_e32 v124, v125, v126
	v_add_f32_e32 v94, 1.0, v94
	v_add_f32_e32 v95, 1.0, v95
	v_fmamk_f32 v124, v124, 0x3a800000, v140
	v_mul_f32_e32 v125, 0x4f800000, v124
	v_cmp_gt_f32_e32 vcc, 0xf800000, v124
	s_nop 1
	v_cndmask_b32_e32 v124, v124, v125, vcc
	v_sqrt_f32_e32 v127, v124
	s_nop 0
	v_add_u32_e32 v128, -1, v127
	v_add_u32_e32 v129, 1, v127
	v_fma_f32 v134, -v128, v127, v124
	v_fma_f32 v135, -v129, v127, v124
	v_cmp_ge_f32_e64 s[16:17], 0, v134
	v_cmp_lt_f32_e64 s[18:19], 0, v135
	s_nop 1
	v_cndmask_b32_e64 v127, v127, v128, s[16:17]
	v_cndmask_b32_e64 v127, v127, v129, s[18:19]
	v_mul_f32_e32 v125, 0x37800000, v127
	v_cndmask_b32_e32 v127, v127, v125, vcc
	v_cmp_class_f32_e32 vcc, v124, v141
	s_nop 1
	v_cndmask_b32_e32 v127, v127, v124, vcc
	v_div_scale_f32 v136, s[16:17], v127, v127, 1.0
	v_div_scale_f32 v138, vcc, 1.0, v127, 1.0
	v_rcp_f32_e32 v137, v136
	s_nop 0
	v_fma_f32 v134, -v136, v137, 1.0
	v_fmac_f32_e32 v137, v134, v137
	v_mul_f32_e32 v139, v138, v137
	v_fma_f32 v134, -v136, v139, v138
	v_fmac_f32_e32 v139, v134, v137
	v_fma_f32 v134, -v136, v139, v138
	v_div_fmas_f32 v134, v134, v137, v139
	v_div_fixup_f32 v134, v134, v127, 1.0
	v_mul_f32_e32 v48, v48, v134
	v_mul_f32_e32 v49, v49, v134
	v_mul_f32_e32 v50, v50, v134
	v_mul_f32_e32 v51, v51, v134
	v_mul_f32_e32 v52, v52, v134
	v_mul_f32_e32 v53, v53, v134
	v_mul_f32_e32 v54, v54, v134
	v_mul_f32_e32 v55, v55, v134
	v_mul_f32_e32 v56, v56, v134
	v_mul_f32_e32 v57, v57, v134
	v_mul_f32_e32 v58, v58, v134
	v_mul_f32_e32 v59, v59, v134
	v_mul_f32_e32 v60, v60, v134
	v_mul_f32_e32 v61, v61, v134
	v_mul_f32_e32 v62, v62, v134
	v_mul_f32_e32 v63, v63, v134
	v_mul_f32_e32 v48, v98, v48
	v_mul_f32_e32 v49, v99, v49
	v_mul_f32_e32 v50, v100, v50
	v_mul_f32_e32 v51, v101, v51
	v_mul_f32_e32 v52, v102, v52
	v_mul_f32_e32 v53, v103, v53
	v_mul_f32_e32 v54, v104, v54
	v_mul_f32_e32 v55, v105, v55
	v_mul_f32_e32 v56, v106, v56
	v_mul_f32_e32 v57, v107, v57
	v_mul_f32_e32 v58, v108, v58
	v_mul_f32_e32 v59, v109, v59
	v_mul_f32_e32 v60, v110, v60
	v_mul_f32_e32 v61, v111, v61
	v_mul_f32_e32 v62, v112, v62
	v_mul_f32_e32 v63, v113, v63
	v_fma_f32 v48, v48, v80, v64
	v_fma_f32 v49, v49, v81, v65
	v_fma_f32 v50, v50, v82, v66
	v_fma_f32 v51, v51, v83, v67
	v_fma_f32 v52, v52, v84, v68
	v_fma_f32 v53, v53, v85, v69
	v_fma_f32 v54, v54, v86, v70
	v_fma_f32 v55, v55, v87, v71
	v_fma_f32 v56, v56, v88, v72
	v_fma_f32 v57, v57, v89, v73
	v_fma_f32 v58, v58, v90, v74
	v_fma_f32 v59, v59, v91, v75
	v_fma_f32 v60, v60, v92, v76
	v_fma_f32 v61, v61, v93, v77
	v_fma_f32 v62, v62, v94, v78
	v_fma_f32 v63, v63, v95, v79
	v_cvt_pk_bf16_f32 v114, v48, v49
	v_cvt_pk_bf16_f32 v115, v50, v51
	v_cvt_pk_bf16_f32 v116, v52, v53
	v_cvt_pk_bf16_f32 v117, v54, v55
	v_cvt_pk_bf16_f32 v118, v56, v57
	v_cvt_pk_bf16_f32 v119, v58, v59
	v_cvt_pk_bf16_f32 v120, v60, v61
	v_cvt_pk_bf16_f32 v121, v62, v63
	s_lshl_b32 s21, s15, 11
	s_add_u32 s22, s12, s21
	s_addc_u32 s23, s13, 0
	s_cmp_ge_i32 s14, 0x8800
	s_cbranch_scc1 .Lmn10_ni_9
	s_sub_i32 s21, s14, 0x8000
	s_lshr_b32 s20, s14, 12
	s_cmp_lt_i32 s14, 0x8000
	s_cselect_b32 s21, s14, s21
	s_cselect_b32 s20, s20, 8
	s_cselect_b32 s16, s4, s6
	s_cselect_b32 s17, s5, s7
	s_lshl_b32 s21, s21, 12
	s_mul_i32 s20, s20, 0x6000
	s_add_u32 s16, s16, s21
	s_addc_u32 s17, s17, 0
	s_add_u32 s18, s8, s20
	s_addc_u32 s19, s9, 0
	global_load_dwordx4 v[48:51], v122, s[16:17] offset:0 nt
	global_load_dwordx4 v[52:55], v122, s[16:17] offset:1024 nt
	global_load_dwordx4 v[56:59], v122, s[16:17] offset:2048 nt
	global_load_dwordx4 v[60:63], v122, s[16:17] offset:3072 nt
	global_load_dwordx4 v[64:67], v122, s[18:19] offset:0
	global_load_dwordx4 v[68:71], v122, s[18:19] offset:1024
	global_load_dwordx4 v[72:75], v122, s[18:19] offset:2048
	global_load_dwordx4 v[76:79], v122, s[18:19] offset:3072
	s_add_u32 s18, s10, s20
	s_addc_u32 s19, s11, 0
	global_load_dwordx4 v[80:83], v122, s[18:19] offset:0
	global_load_dwordx4 v[84:87], v122, s[18:19] offset:1024
	global_load_dwordx4 v[88:91], v122, s[18:19] offset:2048
	global_load_dwordx4 v[92:95], v122, s[18:19] offset:3072

; DEV void modnorm_rows(const float* srcX, const float* srcC, int nrows, const float* g, const float* shift, const float* scale, bf16_t* dst, int gw, int NGW, int lane) {
;     for (int row0 = gw; row0 < nrows; row0 += 2 * NGW) {
;         const int row1 = row0 + NGW; const bool has1 = row1 < nrows;
.Lmn10_loop_10:
	s_cmp_ge_i32 s15, 0x8800
	s_cbranch_scc1 .Lmn10_done_1
	s_add_u32 s20, s15, s1
	s_cmp_ge_i32 s20, 0x8800
	s_cbranch_scc1 .Lmn10_wl_11
	s_waitcnt vmcnt(20)
	s_branch .Lmn10_wj_12

; DEV unsigned cvt_pk_bf16(float lo, float hi) { unsigned r; asm volatile("v_cvt_pk_bf16_f32 %0, %1, %2" : "=v"(r) : "v"(lo), "v"(hi)); return r; }
; DEV void modnorm_rows(const float* srcX, const float* srcC, int nrows, const float* g, const float* shift, const float* scale, bf16_t* dst, int gw, int NGW, int lane) {
;     ...
;                 u32x2 w; w.x = cvt_pk_bf16(y[0], y[1]); w.y = cvt_pk_bf16(y[2], y[3]); *(u32x2*)(dst + (size_t)row0 * DM + col) = w; }
;             if (has1) { const f32x4 sh = *(const f32x4*)(shift + (size_t)mr1 * 6144 + col), sc = *(const f32x4*)(scale + (size_t)mr1 * 6144 + col); f32x4 y;
; #pragma unroll
;                 for (int e = 0; e < 4; ++e) y[e] = (v1[j][e] * rstd1 * gg[e]) * (1.f + sc[e]) + sh[e];
;                 u32x2 w; w.x = cvt_pk_bf16(y[0], y[1]); w.y = cvt_pk_bf16(y[2], y[3]); *(u32x2*)(dst + (size_t)row1 * DM + col) = w; } }
;     }
.Lmn10_ni_13:
	s_add_u32 s14, s14, s1
	global_store_dwordx2 v123, v[114:115], s[22:23] offset:0
	global_store_dwordx2 v123, v[116:117], s[22:23] offset:512
	global_store_dwordx2 v123, v[118:119], s[22:23] offset:1024
	global_store_dwordx2 v123, v[120:121], s[22:23] offset:1536
	s_add_u32 s15, s15, s1
	s_cmp_ge_i32 s15, 0x8800
	s_cbranch_scc1 .Lmn10_done_1
	s_add_u32 s20, s15, s1
	s_cmp_ge_i32 s20, 0x8800
	s_cbranch_scc1 .Lmn10_wl_14
	s_waitcnt vmcnt(20)
	s_branch .Lmn10_wj_15

; DEV void grid_barrier(unsigned* cnt, const unsigned target, const int tid) {
;     asm volatile("s_waitcnt vmcnt(0)" ::: "memory");
;     __syncthreads();
;     if (tid == 0) {
;         __builtin_amdgcn_fence(__ATOMIC_RELEASE, "agent");
;         __hip_atomic_fetch_add(cnt, 1u, __ATOMIC_RELAXED, __HIP_MEMORY_SCOPE_AGENT);
; template <int LO, int HI>
; DEV void run_phases(LAS unsigned char* lds, const int ph_lo, const int ph_hi, const int G, const int wave0, unsigned& nbar) {
;     ...
;         if (ph + 1 < ph_hi) { __syncthreads(); if (HI == 1) cg::this_grid().sync(); else { ++nbar; grid_barrier((unsigned*)(ws + WS_BAR), nbar * (unsigned)G, tid); } }
.Lmn10_done_1:
	s_branch .LBB0_2200
.LBB0_2200:
	v_readlane_b32 s2, v251, 7
	s_add_i32 s0, s82, 1
	v_readlane_b32 s3, v251, 8
	s_cmp_ge_i32 s0, s3
	s_cbranch_scc1 .LBB0_1374
	s_waitcnt lgkmcnt(0)
	s_barrier
	s_waitcnt vmcnt(0)
	v_readlane_b32 s0, v251, 5
	s_add_i32 s0, s0, 1
	v_cmp_eq_u32_e32 vcc, 0, v131
	v_writelane_b32 v251, s0, 5
	s_barrier
	s_and_saveexec_b64 s[0:1], vcc
	s_cbranch_execz .LBB0_1373
	s_mov_b64 s[4:5], exec
	v_readlane_b32 s2, v251, 52
	v_mbcnt_lo_u32_b32 v0, s4, 0
	v_readlane_b32 s3, v251, 53
	s_add_u32 s2, s2, 0x300000
	v_mbcnt_hi_u32_b32 v0, s5, v0
	s_addc_u32 s3, s3, 0
	v_cmp_eq_u32_e32 vcc, 0, v0
	buffer_wbl2 sc1
	s_waitcnt vmcnt(0)
	s_and_saveexec_b64 s[6:7], vcc
	s_cbranch_execz .LBB0_2204
	s_bcnt1_i32_b64 s4, s[4:5]
	v_mov_b32_e32 v0, s4
	global_atomic_add v97, v0, s[2:3]
